# k-loops with interleaved reads in Ph1/4/5/6/7, de-serialised residual loads in Ph4/Ph6 exchange epilogues, hoisted rope-table loads in Ph2
# speedup vs baseline: 1.1265x; 1.0588x over previous
.LBB0_199:
	s_or_b64 exec, exec, s[26:27]
	s_lshl_b64 s[40:41], s[0:1], 11
	s_mul_i32 s26, s4, 0xc0
	s_add_u32 s28, s66, s40
	s_addc_u32 s29, s67, s41
	s_ashr_i32 s27, s26, 31
	s_lshl_b64 s[46:47], s[26:27], 11
	s_add_u32 s36, s80, s46
	s_addc_u32 s37, s81, s47
	v_lshrrev_b32_e32 v196, 3, v197
	v_and_b32_e32 v198, 7, v197
	v_lshlrev_b32_e32 v137, 11, v196
	v_lshl_or_b32 v137, v198, 4, v137
	v_add_u32_e32 v138, 0x10000, v137
	v_add_u32_e32 v139, 0x20000, v137
	v_add_u32_e32 v140, 0x30000, v137
	v_add_u32_e32 v141, 0x40000, v137
	v_add_u32_e32 v142, 0x50000, v137
	global_load_dwordx4 v[96:99], v137, s[28:29]
	global_load_dwordx4 v[100:103], v138, s[28:29]
	global_load_dwordx4 v[104:107], v139, s[28:29]
	global_load_dwordx4 v[108:111], v140, s[28:29]
	global_load_dwordx4 v[112:115], v137, s[36:37]
	global_load_dwordx4 v[116:119], v138, s[36:37]
	global_load_dwordx4 v[120:123], v139, s[36:37]
	global_load_dwordx4 v[124:127], v140, s[36:37]
	global_load_dwordx4 v[128:131], v141, s[36:37]
	global_load_dwordx4 v[132:135], v142, s[36:37]
	s_add_u32 s28, s28, 0x80
	s_addc_u32 s29, s29, 0
	s_add_u32 s36, s36, 0x80
	s_addc_u32 s37, s37, 0
	v_bfe_u32 v217, v197, 5, 2
	v_and_b32_e32 v218, 3, v198
	v_xor_b32_e32 v218, v218, v217
	v_lshlrev_b32_e32 v218, 4, v218
	v_lshl_or_b32 v143, v196, 6, v218
	v_lshrrev_b32_e32 v217, 2, v198
	v_lshlrev_b32_e32 v218, 6, v217
	v_xor_b32_e32 v143, v143, v218
	v_mul_u32_u24_e32 v217, 0x5000, v217
	v_add_u32_e32 v143, v143, v217
	v_and_b32_e32 v196, 31, v197
	v_bfe_u32 v198, v197, 5, 1
	v_bfe_u32 v217, v197, 2, 2
	v_xor_b32_e32 v218, v198, v217
	v_xor_b32_e32 v221, 2, v218
	v_lshrrev_b32_e32 v198, 7, v197
	v_lshl_or_b32 v198, v198, 6, v196
	v_lshlrev_b32_e32 v198, 6, v198
	v_lshl_or_b32 v242, v218, 4, v198
	v_lshl_or_b32 v243, v221, 4, v198
	v_bfe_u32 v198, v197, 6, 1
	v_mul_u32_u24_e32 v198, 96, v198
	v_add_u32_e32 v198, v198, v196
	v_lshlrev_b32_e32 v198, 6, v198
	v_add_u32_e32 v198, 0x2000, v198
	v_lshl_or_b32 v244, v218, 4, v198
	v_lshl_or_b32 v245, v221, 4, v198
	v_mov_b64_e32 v[0:1], 0
	v_mov_b64_e32 v[2:3], 0
	v_mov_b64_e32 v[4:5], 0
	v_mov_b64_e32 v[6:7], 0
	v_mov_b64_e32 v[8:9], 0
	v_mov_b64_e32 v[10:11], 0
	v_mov_b64_e32 v[12:13], 0
	v_mov_b64_e32 v[14:15], 0
	v_mov_b64_e32 v[16:17], 0
	v_mov_b64_e32 v[18:19], 0
	v_mov_b64_e32 v[20:21], 0
	v_mov_b64_e32 v[22:23], 0
	v_mov_b64_e32 v[24:25], 0
	v_mov_b64_e32 v[26:27], 0
	v_mov_b64_e32 v[28:29], 0
	v_mov_b64_e32 v[30:31], 0
	v_mov_b64_e32 v[32:33], 0
	v_mov_b64_e32 v[34:35], 0
	v_mov_b64_e32 v[36:37], 0
	v_mov_b64_e32 v[38:39], 0
	v_mov_b64_e32 v[40:41], 0
	v_mov_b64_e32 v[42:43], 0
	v_mov_b64_e32 v[44:45], 0
	v_mov_b64_e32 v[46:47], 0
	v_mov_b64_e32 v[48:49], 0
	v_mov_b64_e32 v[50:51], 0
	v_mov_b64_e32 v[52:53], 0
	v_mov_b64_e32 v[54:55], 0
	v_mov_b64_e32 v[56:57], 0
	v_mov_b64_e32 v[58:59], 0
	v_mov_b64_e32 v[60:61], 0
	v_mov_b64_e32 v[62:63], 0
	v_mov_b64_e32 v[64:65], 0
	v_mov_b64_e32 v[66:67], 0
	v_mov_b64_e32 v[68:69], 0
	v_mov_b64_e32 v[70:71], 0
	v_mov_b64_e32 v[72:73], 0
	v_mov_b64_e32 v[74:75], 0
	v_mov_b64_e32 v[76:77], 0
	v_mov_b64_e32 v[78:79], 0
	v_mov_b64_e32 v[80:81], 0
	v_mov_b64_e32 v[82:83], 0
	v_mov_b64_e32 v[84:85], 0
	v_mov_b64_e32 v[86:87], 0
	v_mov_b64_e32 v[88:89], 0
	v_mov_b64_e32 v[90:91], 0
	v_mov_b64_e32 v[92:93], 0
	v_mov_b64_e32 v[94:95], 0
	s_mov_b32 s38, 0
	s_mov_b32 s39, 0x5000
	s_mov_b32 s5, 0
	s_waitcnt vmcnt(9)
	ds_write_b128 v143, v[96:99]
	s_waitcnt vmcnt(8)
	ds_write_b128 v143, v[100:103] offset:2048
	s_waitcnt vmcnt(7)
	ds_write_b128 v143, v[104:107] offset:4096
	s_waitcnt vmcnt(6)
	ds_write_b128 v143, v[108:111] offset:6144
	s_waitcnt vmcnt(5)
	ds_write_b128 v143, v[112:115] offset:8192
	s_waitcnt vmcnt(4)
	ds_write_b128 v143, v[116:119] offset:10240
	s_waitcnt vmcnt(3)
	ds_write_b128 v143, v[120:123] offset:12288
	s_waitcnt vmcnt(2)
	ds_write_b128 v143, v[124:127] offset:14336
	s_waitcnt vmcnt(1)
	ds_write_b128 v143, v[128:131] offset:16384
	s_waitcnt vmcnt(0)
	ds_write_b128 v143, v[132:135] offset:18432
	v_subrev_u32_e32 v196, 0x5000, v143
	v_add_u32_e32 v198, 0xa000, v143
	v_min_u32_e32 v143, v196, v198
	s_waitcnt lgkmcnt(0)
	s_barrier
.Lg1_loop:
	v_add_u32_e32 v246, s38, v242
	v_add_u32_e32 v247, s38, v243
	v_add_u32_e32 v248, s38, v244
	v_add_u32_e32 v249, s38, v245
	ds_read_b128 v[144:147], v246
	ds_read_b128 v[148:151], v246 offset:2048
	ds_read_b128 v[160:163], v248
	ds_read_b128 v[164:167], v248 offset:2048
	ds_read_b128 v[168:171], v248 offset:4096
	s_setprio 1
	s_waitcnt lgkmcnt(2)
	v_mfma_f32_32x32x16_bf16 v[80:95], v[144:147], v[160:163], v[80:95]
	global_load_dwordx4 v[96:99], v137, s[28:29]
	ds_read_b128 v[152:155], v247
	v_mfma_f32_32x32x16_bf16 v[32:47], v[148:151], v[160:163], v[32:47]
	global_load_dwordx4 v[100:103], v138, s[28:29]
	ds_read_b128 v[156:159], v247 offset:2048
	s_waitcnt lgkmcnt(3)
	v_mfma_f32_32x32x16_bf16 v[64:79], v[144:147], v[164:167], v[64:79]
	global_load_dwordx4 v[104:107], v139, s[28:29]
	ds_read_b128 v[172:175], v249
	v_mfma_f32_32x32x16_bf16 v[16:31], v[148:151], v[164:167], v[16:31]
	global_load_dwordx4 v[108:111], v140, s[28:29]
	ds_read_b128 v[176:179], v249 offset:2048
	s_waitcnt lgkmcnt(4)
	v_mfma_f32_32x32x16_bf16 v[48:63], v[144:147], v[168:171], v[48:63]
	global_load_dwordx4 v[112:115], v137, s[36:37]
	ds_read_b128 v[180:183], v249 offset:4096
	v_mfma_f32_32x32x16_bf16 v[0:15], v[148:151], v[168:171], v[0:15]
	global_load_dwordx4 v[116:119], v138, s[36:37]
	v_xad_u32 v246, v242, 64, s39
	v_xad_u32 v248, v244, 64, s39
	s_waitcnt lgkmcnt(2)
	v_mfma_f32_32x32x16_bf16 v[80:95], v[152:155], v[172:175], v[80:95]
	global_load_dwordx4 v[120:123], v139, s[36:37]
	ds_read_b128 v[144:147], v246
	v_mfma_f32_32x32x16_bf16 v[32:47], v[156:159], v[172:175], v[32:47]
	global_load_dwordx4 v[124:127], v140, s[36:37]
	ds_read_b128 v[148:151], v246 offset:2048
	s_waitcnt lgkmcnt(3)
	v_mfma_f32_32x32x16_bf16 v[64:79], v[152:155], v[176:179], v[64:79]
	global_load_dwordx4 v[128:131], v141, s[36:37]
	ds_read_b128 v[160:163], v248
	v_mfma_f32_32x32x16_bf16 v[16:31], v[156:159], v[176:179], v[16:31]
	global_load_dwordx4 v[132:135], v142, s[36:37]
	ds_read_b128 v[164:167], v248 offset:2048
	s_waitcnt lgkmcnt(4)
	v_mfma_f32_32x32x16_bf16 v[48:63], v[152:155], v[180:183], v[48:63]
	ds_read_b128 v[168:171], v248 offset:4096
	v_mfma_f32_32x32x16_bf16 v[0:15], v[156:159], v[180:183], v[0:15]
	s_setprio 0
	s_barrier
	v_xad_u32 v247, v243, 64, s39
	v_xad_u32 v249, v245, 64, s39
	s_setprio 1
	s_waitcnt lgkmcnt(2)
	v_mfma_f32_32x32x16_bf16 v[80:95], v[144:147], v[160:163], v[80:95]
	ds_read_b128 v[152:155], v247
	v_mfma_f32_32x32x16_bf16 v[32:47], v[148:151], v[160:163], v[32:47]
	ds_read_b128 v[156:159], v247 offset:2048
	s_waitcnt lgkmcnt(3)
	v_mfma_f32_32x32x16_bf16 v[64:79], v[144:147], v[164:167], v[64:79]
	ds_read_b128 v[172:175], v249
	s_waitcnt vmcnt(9)
	ds_write_b128 v143, v[96:99]
	v_mfma_f32_32x32x16_bf16 v[16:31], v[148:151], v[164:167], v[16:31]
	ds_read_b128 v[176:179], v249 offset:2048
	s_waitcnt vmcnt(8)
	ds_write_b128 v143, v[100:103] offset:2048
	s_waitcnt lgkmcnt(6)
	v_mfma_f32_32x32x16_bf16 v[48:63], v[144:147], v[168:171], v[48:63]
	ds_read_b128 v[180:183], v249 offset:4096
	s_waitcnt vmcnt(7)
	ds_write_b128 v143, v[104:107] offset:4096
	v_mfma_f32_32x32x16_bf16 v[0:15], v[148:151], v[168:171], v[0:15]
	s_waitcnt vmcnt(6)
	ds_write_b128 v143, v[108:111] offset:6144
	s_waitcnt lgkmcnt(6)
	v_mfma_f32_32x32x16_bf16 v[80:95], v[152:155], v[172:175], v[80:95]
	s_waitcnt vmcnt(5)
	ds_write_b128 v143, v[112:115] offset:8192
	v_mfma_f32_32x32x16_bf16 v[32:47], v[156:159], v[172:175], v[32:47]
	s_waitcnt vmcnt(4)
	ds_write_b128 v143, v[116:119] offset:10240
	s_waitcnt lgkmcnt(6)
	v_mfma_f32_32x32x16_bf16 v[64:79], v[152:155], v[176:179], v[64:79]
	s_waitcnt vmcnt(3)
	ds_write_b128 v143, v[120:123] offset:12288
	v_mfma_f32_32x32x16_bf16 v[16:31], v[156:159], v[176:179], v[16:31]
	s_waitcnt vmcnt(2)
	ds_write_b128 v143, v[124:127] offset:14336
	s_waitcnt lgkmcnt(6)
	v_mfma_f32_32x32x16_bf16 v[48:63], v[152:155], v[180:183], v[48:63]
	s_waitcnt vmcnt(1)
	ds_write_b128 v143, v[128:131] offset:16384
	v_mfma_f32_32x32x16_bf16 v[0:15], v[156:159], v[180:183], v[0:15]
	s_waitcnt vmcnt(0)
	ds_write_b128 v143, v[132:135] offset:18432
	s_setprio 0
	s_add_u32 s28, s28, 0x80
	s_addc_u32 s29, s29, 0
	s_add_u32 s36, s36, 0x80
	s_addc_u32 s37, s37, 0
	s_sub_i32 s38, s38, 0x5000
	s_cmp_lt_i32 s38, 0
	s_cselect_b32 s40, 0xf000, 0
	s_add_i32 s38, s38, s40
	s_sub_i32 s39, s39, 0x5000
	s_cmp_lt_i32 s39, 0
	s_cselect_b32 s40, 0xf000, 0
	s_add_i32 s39, s39, s40
	v_subrev_u32_e32 v196, 0x5000, v143
	v_add_u32_e32 v198, 0xa000, v143
	v_min_u32_e32 v143, v196, v198
	s_add_i32 s5, s5, 1
	s_cmp_lt_u32 s5, 15
	s_waitcnt lgkmcnt(0)
	s_barrier
	s_cbranch_scc1 .Lg1_loop
	v_add_u32_e32 v246, s38, v242
	v_add_u32_e32 v247, s38, v243
	v_add_u32_e32 v248, s38, v244
	v_add_u32_e32 v249, s38, v245
	ds_read_b128 v[144:147], v246
	ds_read_b128 v[148:151], v246 offset:2048
	ds_read_b128 v[160:163], v248
	ds_read_b128 v[164:167], v248 offset:2048
	ds_read_b128 v[168:171], v248 offset:4096
	s_setprio 1
	s_waitcnt lgkmcnt(2)
	v_mfma_f32_32x32x16_bf16 v[80:95], v[144:147], v[160:163], v[80:95]
	ds_read_b128 v[152:155], v247
	v_mfma_f32_32x32x16_bf16 v[32:47], v[148:151], v[160:163], v[32:47]
	ds_read_b128 v[156:159], v247 offset:2048
	s_waitcnt lgkmcnt(3)
	v_mfma_f32_32x32x16_bf16 v[64:79], v[144:147], v[164:167], v[64:79]
	ds_read_b128 v[172:175], v249
	v_mfma_f32_32x32x16_bf16 v[16:31], v[148:151], v[164:167], v[16:31]
	ds_read_b128 v[176:179], v249 offset:2048
	s_waitcnt lgkmcnt(4)
	v_mfma_f32_32x32x16_bf16 v[48:63], v[144:147], v[168:171], v[48:63]
	ds_read_b128 v[180:183], v249 offset:4096
	v_mfma_f32_32x32x16_bf16 v[0:15], v[148:151], v[168:171], v[0:15]
	v_xad_u32 v246, v242, 64, s39
	v_xad_u32 v248, v244, 64, s39
	s_waitcnt lgkmcnt(2)
	v_mfma_f32_32x32x16_bf16 v[80:95], v[152:155], v[172:175], v[80:95]
	ds_read_b128 v[144:147], v246
	v_mfma_f32_32x32x16_bf16 v[32:47], v[156:159], v[172:175], v[32:47]
	ds_read_b128 v[148:151], v246 offset:2048
	s_waitcnt lgkmcnt(3)
	v_mfma_f32_32x32x16_bf16 v[64:79], v[152:155], v[176:179], v[64:79]
	ds_read_b128 v[160:163], v248
	v_mfma_f32_32x32x16_bf16 v[16:31], v[156:159], v[176:179], v[16:31]
	ds_read_b128 v[164:167], v248 offset:2048
	s_waitcnt lgkmcnt(4)
	v_mfma_f32_32x32x16_bf16 v[48:63], v[152:155], v[180:183], v[48:63]
	ds_read_b128 v[168:171], v248 offset:4096
	v_mfma_f32_32x32x16_bf16 v[0:15], v[156:159], v[180:183], v[0:15]
	s_setprio 0
	v_xad_u32 v247, v243, 64, s39
	v_xad_u32 v249, v245, 64, s39
	s_setprio 1
	s_waitcnt lgkmcnt(2)
	v_mfma_f32_32x32x16_bf16 v[80:95], v[144:147], v[160:163], v[80:95]
	ds_read_b128 v[152:155], v247
	v_mfma_f32_32x32x16_bf16 v[32:47], v[148:151], v[160:163], v[32:47]
	ds_read_b128 v[156:159], v247 offset:2048
	s_waitcnt lgkmcnt(3)
	v_mfma_f32_32x32x16_bf16 v[64:79], v[144:147], v[164:167], v[64:79]
	ds_read_b128 v[172:175], v249
	v_mfma_f32_32x32x16_bf16 v[16:31], v[148:151], v[164:167], v[16:31]
	ds_read_b128 v[176:179], v249 offset:2048
	s_waitcnt lgkmcnt(4)
	v_mfma_f32_32x32x16_bf16 v[48:63], v[144:147], v[168:171], v[48:63]
	ds_read_b128 v[180:183], v249 offset:4096
	v_mfma_f32_32x32x16_bf16 v[0:15], v[148:151], v[168:171], v[0:15]
	s_waitcnt lgkmcnt(2)
	v_mfma_f32_32x32x16_bf16 v[80:95], v[152:155], v[172:175], v[80:95]
	v_mfma_f32_32x32x16_bf16 v[32:47], v[156:159], v[172:175], v[32:47]
	s_waitcnt lgkmcnt(1)
	v_mfma_f32_32x32x16_bf16 v[64:79], v[152:155], v[176:179], v[64:79]
	v_mfma_f32_32x32x16_bf16 v[16:31], v[156:159], v[176:179], v[16:31]
	s_waitcnt lgkmcnt(0)
	v_mfma_f32_32x32x16_bf16 v[48:63], v[152:155], v[180:183], v[48:63]
	v_mfma_f32_32x32x16_bf16 v[0:15], v[156:159], v[180:183], v[0:15]
	s_setprio 0
	s_nop 7
	s_nop 7

.LBB0_268:
	s_or_b64 exec, exec, s[0:1]
	s_mul_i32 s0, s8, 0x1200
	s_mul_hi_i32 s1, s8, 0x1200
	s_add_u32 s0, s70, s0
	s_addc_u32 s1, s71, s1
	s_mul_i32 s9, s36, 0x24000
	v_mov_b32_e32 v26, v197
	s_add_u32 s26, s2, s9
	s_movk_i32 s9, 0x900
	v_ashrrev_i32_e32 v27, 2, v26
	v_and_b32_e32 v28, 3, v26
	v_mul_lo_u32 v0, v27, s9
	v_lshlrev_b32_e32 v1, 3, v28
	v_or_b32_e32 v198, v0, v1
	s_movk_i32 s9, 0x180
	v_mul_lo_u32 v0, v27, s9
	v_lshl_add_u64 v[96:97], v[198:199], 1, s[0:1]
	s_mov_b32 s0, 0x48000
	s_addc_u32 s27, s3, 0
	v_or_b32_e32 v8, v0, v1
	v_add_co_u32_e32 v20, vcc, s0, v96
	v_mov_b32_e32 v9, v199
	s_nop 0
	v_addc_co_u32_e32 v21, vcc, 0, v97, vcc
	v_lshl_add_u64 v[98:99], v[8:9], 1, s[26:27]
	global_load_dwordx4 v[0:3], v[96:97], off
	v_add_co_u32_e32 v22, vcc, s95, v98
	global_load_dwordx4 v[8:11], v[98:99], off
	s_nop 0
	v_addc_co_u32_e32 v23, vcc, 0, v99, vcc
	s_mov_b32 s0, 0x18000
	global_load_dwordx4 v[4:7], v[20:21], off
	global_load_dwordx4 v[12:15], v[22:23], off
	v_add_co_u32_e32 v24, vcc, s0, v98
	s_mov_b64 s[0:1], 0x48000
	s_nop 0
	v_addc_co_u32_e32 v25, vcc, 0, v99, vcc
	global_load_dwordx4 v[16:19], v[24:25], off
	v_mul_lo_u32 v27, v27, s52
	v_lshlrev_b32_e32 v28, 4, v28
	v_lshl_add_u64 v[100:101], v[96:97], 0, s[0:1]
	s_mov_b64 s[0:1], 0xc000
	v_add3_u32 v106, v27, v28, 0
	v_lshl_add_u64 v[102:103], v[98:99], 0, s[0:1]
	s_mov_b64 s[0:1], 0x18000
	v_lshl_add_u64 v[104:105], v[98:99], 0, s[0:1]
	global_load_dwordx4 v[110:113], v[96:97], off offset:64
	global_load_dwordx4 v[114:117], v[98:99], off offset:64
	global_load_dwordx4 v[118:121], v[20:21], off offset:64
	global_load_dwordx4 v[122:125], v[22:23], off offset:64
	global_load_dwordx4 v[130:133], v[24:25], off offset:64
	v_readfirstlane_b32 s0, v26
	s_bfe_i32 s1, s0, 0x10006
	s_lshr_b32 s0, s0, 1
	s_and_b32 s1, s1, 0x60
	s_and_b32 s0, s0, 0xfffffc0
	s_waitcnt vmcnt(9)
	ds_write_b128 v106, v[0:3]
	s_waitcnt vmcnt(8)
	ds_write_b128 v106, v[8:11] offset:10240
	s_waitcnt vmcnt(7)
	ds_write_b128 v106, v[4:7] offset:5120
	s_waitcnt vmcnt(6)
	ds_write_b128 v106, v[12:15] offset:15360
	s_waitcnt vmcnt(5)
	ds_write_b128 v106, v[16:19] offset:20480
	s_waitcnt lgkmcnt(0)
	s_barrier
	global_load_dwordx4 v[134:137], v[96:97], off offset:128
	global_load_dwordx4 v[138:141], v[100:101], off offset:128
	global_load_dwordx4 v[144:147], v[98:99], off offset:128
	global_load_dwordx4 v[148:151], v[102:103], off offset:128
	global_load_dwordx4 v[152:155], v[104:105], off offset:128
	v_and_b32_e32 v0, 31, v26
	v_lshrrev_b32_e32 v1, 1, v26
	v_or_b32_e32 v2, s1, v0
	v_or_b32_e32 v0, s0, v0
	v_and_b32_e32 v1, 16, v1
	v_mul_u32_u24_e32 v2, 0x50, v2
	v_mul_lo_u32 v0, v0, s52
	v_add3_u32 v108, v0, v1, 0
	v_add3_u32 v107, v2, v1, 0
	ds_read_b128 v[0:3], v108
	ds_read_b128 v[156:159], v108 offset:32
	ds_read_b128 v[4:7], v108 offset:2560
	ds_read_b128 v[160:163], v108 offset:2592
	ds_read_b128 v[8:11], v107 offset:10240
	ds_read_b128 v[164:167], v107 offset:10272
	ds_read_b128 v[12:15], v107 offset:12800
	ds_read_b128 v[168:171], v107 offset:12832
	ds_read_b128 v[172:175], v107 offset:15360
	ds_read_b128 v[176:179], v107 offset:15392
	s_setprio 1
	s_waitcnt lgkmcnt(5)
	v_mfma_f32_32x32x16_bf16 v[80:95], v[0:3], v[8:11], 0
	v_mfma_f32_32x32x16_bf16 v[32:47], v[4:7], v[8:11], 0
	s_waitcnt lgkmcnt(3)
	v_mfma_f32_32x32x16_bf16 v[64:79], v[0:3], v[12:15], 0
	v_mfma_f32_32x32x16_bf16 v[16:31], v[4:7], v[12:15], 0
	s_waitcnt lgkmcnt(1)
	v_mfma_f32_32x32x16_bf16 v[48:63], v[0:3], v[172:175], 0
	v_mfma_f32_32x32x16_bf16 v[0:15], v[4:7], v[172:175], 0
	v_mfma_f32_32x32x16_bf16 v[80:95], v[156:159], v[164:167], v[80:95]
	v_mfma_f32_32x32x16_bf16 v[32:47], v[160:163], v[164:167], v[32:47]
	v_mfma_f32_32x32x16_bf16 v[64:79], v[156:159], v[168:171], v[64:79]
	v_mfma_f32_32x32x16_bf16 v[16:31], v[160:163], v[168:171], v[16:31]
	s_waitcnt lgkmcnt(0)
	v_mfma_f32_32x32x16_bf16 v[48:63], v[156:159], v[176:179], v[48:63]
	v_mfma_f32_32x32x16_bf16 v[0:15], v[160:163], v[176:179], v[0:15]
	s_setprio 0
	s_waitcnt vmcnt(9)
	ds_write_b128 v106, v[110:113] offset:30720
	s_waitcnt vmcnt(7)
	ds_write_b128 v106, v[118:121] offset:35840
	ds_write_b128 v106, v[114:117] offset:40960
	s_waitcnt vmcnt(6)
	ds_write_b128 v106, v[122:125] offset:46080
	s_waitcnt vmcnt(5)
	ds_write_b128 v106, v[130:133] offset:51200
	s_waitcnt lgkmcnt(0)
	s_barrier
	global_load_dwordx4 v[110:113], v[96:97], off offset:192
	global_load_dwordx4 v[114:117], v[100:101], off offset:192
	global_load_dwordx4 v[118:121], v[98:99], off offset:192
	global_load_dwordx4 v[122:125], v[102:103], off offset:192
	global_load_dwordx4 v[130:133], v[104:105], off offset:192
	ds_read_b128 v[156:159], v108 offset:30720
	ds_read_b128 v[160:163], v108 offset:30752
	ds_read_b128 v[164:167], v108 offset:33280
	ds_read_b128 v[168:171], v108 offset:33312
	ds_read_b128 v[172:175], v107 offset:40960
	ds_read_b128 v[176:179], v107 offset:40992
	ds_read_b128 v[180:183], v107 offset:43520
	ds_read_b128 v[184:187], v107 offset:43552
	ds_read_b128 v[188:191], v107 offset:46080
	ds_read_b128 v[192:195], v107 offset:46112
	s_setprio 1
	s_waitcnt lgkmcnt(5)
	v_mfma_f32_32x32x16_bf16 v[80:95], v[156:159], v[172:175], v[80:95]
	v_mfma_f32_32x32x16_bf16 v[32:47], v[164:167], v[172:175], v[32:47]
	s_waitcnt lgkmcnt(3)
	v_mfma_f32_32x32x16_bf16 v[64:79], v[156:159], v[180:183], v[64:79]
	v_mfma_f32_32x32x16_bf16 v[16:31], v[164:167], v[180:183], v[16:31]
	s_waitcnt lgkmcnt(1)
	v_mfma_f32_32x32x16_bf16 v[48:63], v[156:159], v[188:191], v[48:63]
	v_mfma_f32_32x32x16_bf16 v[0:15], v[164:167], v[188:191], v[0:15]
	v_mfma_f32_32x32x16_bf16 v[80:95], v[160:163], v[176:179], v[80:95]
	v_mfma_f32_32x32x16_bf16 v[32:47], v[168:171], v[176:179], v[32:47]
	v_mfma_f32_32x32x16_bf16 v[64:79], v[160:163], v[184:187], v[64:79]
	v_mfma_f32_32x32x16_bf16 v[16:31], v[168:171], v[184:187], v[16:31]
	s_waitcnt lgkmcnt(0)
	v_mfma_f32_32x32x16_bf16 v[48:63], v[160:163], v[192:195], v[48:63]
	v_mfma_f32_32x32x16_bf16 v[0:15], v[168:171], v[192:195], v[0:15]
	s_setprio 0
	s_waitcnt vmcnt(9)
	ds_write_b128 v106, v[134:137]
	s_waitcnt vmcnt(8)
	ds_write_b128 v106, v[138:141] offset:5120
	s_waitcnt vmcnt(7)
	ds_write_b128 v106, v[144:147] offset:10240
	s_waitcnt vmcnt(6)
	ds_write_b128 v106, v[148:151] offset:15360
	s_waitcnt vmcnt(5)
	ds_write_b128 v106, v[152:155] offset:20480
	s_waitcnt lgkmcnt(0)
	s_barrier
	global_load_dwordx4 v[134:137], v[96:97], off offset:256
	global_load_dwordx4 v[138:141], v[100:101], off offset:256
	global_load_dwordx4 v[144:147], v[98:99], off offset:256
	global_load_dwordx4 v[148:151], v[102:103], off offset:256
	global_load_dwordx4 v[152:155], v[104:105], off offset:256
	ds_read_b128 v[156:159], v108
	ds_read_b128 v[160:163], v108 offset:32
	ds_read_b128 v[164:167], v108 offset:2560
	ds_read_b128 v[168:171], v108 offset:2592
	ds_read_b128 v[172:175], v107 offset:10240
	ds_read_b128 v[176:179], v107 offset:10272
	ds_read_b128 v[180:183], v107 offset:12800
	ds_read_b128 v[184:187], v107 offset:12832
	ds_read_b128 v[188:191], v107 offset:15360
	ds_read_b128 v[192:195], v107 offset:15392
	s_setprio 1
	s_waitcnt lgkmcnt(5)
	v_mfma_f32_32x32x16_bf16 v[80:95], v[156:159], v[172:175], v[80:95]
	v_mfma_f32_32x32x16_bf16 v[32:47], v[164:167], v[172:175], v[32:47]
	s_waitcnt lgkmcnt(3)
	v_mfma_f32_32x32x16_bf16 v[64:79], v[156:159], v[180:183], v[64:79]
	v_mfma_f32_32x32x16_bf16 v[16:31], v[164:167], v[180:183], v[16:31]
	s_waitcnt lgkmcnt(1)
	v_mfma_f32_32x32x16_bf16 v[48:63], v[156:159], v[188:191], v[48:63]
	v_mfma_f32_32x32x16_bf16 v[0:15], v[164:167], v[188:191], v[0:15]
	v_mfma_f32_32x32x16_bf16 v[80:95], v[160:163], v[176:179], v[80:95]
	v_mfma_f32_32x32x16_bf16 v[32:47], v[168:171], v[176:179], v[32:47]
	v_mfma_f32_32x32x16_bf16 v[64:79], v[160:163], v[184:187], v[64:79]
	v_mfma_f32_32x32x16_bf16 v[16:31], v[168:171], v[184:187], v[16:31]
	s_waitcnt lgkmcnt(0)
	v_mfma_f32_32x32x16_bf16 v[48:63], v[160:163], v[192:195], v[48:63]
	v_mfma_f32_32x32x16_bf16 v[0:15], v[168:171], v[192:195], v[0:15]
	s_setprio 0
	s_waitcnt vmcnt(9)
	ds_write_b128 v106, v[110:113] offset:30720
	s_waitcnt vmcnt(8)
	ds_write_b128 v106, v[114:117] offset:35840
	s_waitcnt vmcnt(7)
	ds_write_b128 v106, v[118:121] offset:40960
	s_waitcnt vmcnt(6)
	ds_write_b128 v106, v[122:125] offset:46080
	s_waitcnt vmcnt(5)
	ds_write_b128 v106, v[130:133] offset:51200
	s_waitcnt lgkmcnt(0)
	s_barrier
	global_load_dwordx4 v[110:113], v[96:97], off offset:320
	global_load_dwordx4 v[114:117], v[100:101], off offset:320
	global_load_dwordx4 v[118:121], v[98:99], off offset:320
	global_load_dwordx4 v[122:125], v[102:103], off offset:320
	global_load_dwordx4 v[130:133], v[104:105], off offset:320
	ds_read_b128 v[156:159], v108 offset:30720
	ds_read_b128 v[160:163], v108 offset:30752
	ds_read_b128 v[164:167], v108 offset:33280
	ds_read_b128 v[168:171], v108 offset:33312
	ds_read_b128 v[172:175], v107 offset:40960
	ds_read_b128 v[176:179], v107 offset:40992
	ds_read_b128 v[180:183], v107 offset:43520
	ds_read_b128 v[184:187], v107 offset:43552
	ds_read_b128 v[188:191], v107 offset:46080
	ds_read_b128 v[192:195], v107 offset:46112
	s_setprio 1
	s_waitcnt lgkmcnt(5)
	v_mfma_f32_32x32x16_bf16 v[80:95], v[156:159], v[172:175], v[80:95]
	v_mfma_f32_32x32x16_bf16 v[32:47], v[164:167], v[172:175], v[32:47]
	s_waitcnt lgkmcnt(3)
	v_mfma_f32_32x32x16_bf16 v[64:79], v[156:159], v[180:183], v[64:79]
	v_mfma_f32_32x32x16_bf16 v[16:31], v[164:167], v[180:183], v[16:31]
	s_waitcnt lgkmcnt(1)
	v_mfma_f32_32x32x16_bf16 v[48:63], v[156:159], v[188:191], v[48:63]
	v_mfma_f32_32x32x16_bf16 v[0:15], v[164:167], v[188:191], v[0:15]
	v_mfma_f32_32x32x16_bf16 v[80:95], v[160:163], v[176:179], v[80:95]
	v_mfma_f32_32x32x16_bf16 v[32:47], v[168:171], v[176:179], v[32:47]
	v_mfma_f32_32x32x16_bf16 v[64:79], v[160:163], v[184:187], v[64:79]
	v_mfma_f32_32x32x16_bf16 v[16:31], v[168:171], v[184:187], v[16:31]
	s_waitcnt lgkmcnt(0)
	v_mfma_f32_32x32x16_bf16 v[48:63], v[160:163], v[192:195], v[48:63]
	v_mfma_f32_32x32x16_bf16 v[0:15], v[168:171], v[192:195], v[0:15]
	s_setprio 0
	s_waitcnt vmcnt(9)
	ds_write_b128 v106, v[134:137]
	s_waitcnt vmcnt(8)
	ds_write_b128 v106, v[138:141] offset:5120
	s_waitcnt vmcnt(7)
	ds_write_b128 v106, v[144:147] offset:10240
	s_waitcnt vmcnt(6)
	ds_write_b128 v106, v[148:151] offset:15360
	s_waitcnt vmcnt(5)
	ds_write_b128 v106, v[152:155] offset:20480
	s_waitcnt lgkmcnt(0)
	s_barrier
	global_load_dwordx4 v[134:137], v[96:97], off offset:384
	global_load_dwordx4 v[138:141], v[100:101], off offset:384
	global_load_dwordx4 v[144:147], v[98:99], off offset:384
	global_load_dwordx4 v[148:151], v[102:103], off offset:384
	global_load_dwordx4 v[152:155], v[104:105], off offset:384
	ds_read_b128 v[156:159], v108
	ds_read_b128 v[160:163], v108 offset:32
	ds_read_b128 v[164:167], v108 offset:2560
	ds_read_b128 v[168:171], v108 offset:2592
	ds_read_b128 v[172:175], v107 offset:10240
	ds_read_b128 v[176:179], v107 offset:10272
	ds_read_b128 v[180:183], v107 offset:12800
	ds_read_b128 v[184:187], v107 offset:12832
	ds_read_b128 v[188:191], v107 offset:15360
	ds_read_b128 v[192:195], v107 offset:15392
	s_setprio 1
	s_waitcnt lgkmcnt(5)
	v_mfma_f32_32x32x16_bf16 v[80:95], v[156:159], v[172:175], v[80:95]
	v_mfma_f32_32x32x16_bf16 v[32:47], v[164:167], v[172:175], v[32:47]
	s_waitcnt lgkmcnt(3)
	v_mfma_f32_32x32x16_bf16 v[64:79], v[156:159], v[180:183], v[64:79]
	v_mfma_f32_32x32x16_bf16 v[16:31], v[164:167], v[180:183], v[16:31]
	s_waitcnt lgkmcnt(1)
	v_mfma_f32_32x32x16_bf16 v[48:63], v[156:159], v[188:191], v[48:63]
	v_mfma_f32_32x32x16_bf16 v[0:15], v[164:167], v[188:191], v[0:15]
	v_mfma_f32_32x32x16_bf16 v[80:95], v[160:163], v[176:179], v[80:95]
	v_mfma_f32_32x32x16_bf16 v[32:47], v[168:171], v[176:179], v[32:47]
	v_mfma_f32_32x32x16_bf16 v[64:79], v[160:163], v[184:187], v[64:79]
	v_mfma_f32_32x32x16_bf16 v[16:31], v[168:171], v[184:187], v[16:31]
	s_waitcnt lgkmcnt(0)
	v_mfma_f32_32x32x16_bf16 v[48:63], v[160:163], v[192:195], v[48:63]
	v_mfma_f32_32x32x16_bf16 v[0:15], v[168:171], v[192:195], v[0:15]
	s_setprio 0
	s_waitcnt vmcnt(9)
	ds_write_b128 v106, v[110:113] offset:30720
	s_waitcnt vmcnt(8)
	ds_write_b128 v106, v[114:117] offset:35840
	s_waitcnt vmcnt(7)
	ds_write_b128 v106, v[118:121] offset:40960
	s_waitcnt vmcnt(6)
	ds_write_b128 v106, v[122:125] offset:46080
	s_waitcnt vmcnt(5)
	ds_write_b128 v106, v[130:133] offset:51200
	s_waitcnt lgkmcnt(0)
	s_barrier
	global_load_dwordx4 v[110:113], v[96:97], off offset:448
	global_load_dwordx4 v[114:117], v[100:101], off offset:448
	global_load_dwordx4 v[118:121], v[98:99], off offset:448
	global_load_dwordx4 v[122:125], v[102:103], off offset:448
	global_load_dwordx4 v[130:133], v[104:105], off offset:448
	ds_read_b128 v[156:159], v108 offset:30720
	ds_read_b128 v[160:163], v108 offset:30752
	ds_read_b128 v[164:167], v108 offset:33280
	ds_read_b128 v[168:171], v108 offset:33312
	ds_read_b128 v[172:175], v107 offset:40960
	ds_read_b128 v[176:179], v107 offset:40992
	ds_read_b128 v[180:183], v107 offset:43520
	ds_read_b128 v[184:187], v107 offset:43552
	ds_read_b128 v[188:191], v107 offset:46080
	ds_read_b128 v[192:195], v107 offset:46112
	s_setprio 1
	s_waitcnt lgkmcnt(5)
	v_mfma_f32_32x32x16_bf16 v[80:95], v[156:159], v[172:175], v[80:95]
	v_mfma_f32_32x32x16_bf16 v[32:47], v[164:167], v[172:175], v[32:47]
	s_waitcnt lgkmcnt(3)
	v_mfma_f32_32x32x16_bf16 v[64:79], v[156:159], v[180:183], v[64:79]
	v_mfma_f32_32x32x16_bf16 v[16:31], v[164:167], v[180:183], v[16:31]
	s_waitcnt lgkmcnt(1)
	v_mfma_f32_32x32x16_bf16 v[48:63], v[156:159], v[188:191], v[48:63]
	v_mfma_f32_32x32x16_bf16 v[0:15], v[164:167], v[188:191], v[0:15]
	v_mfma_f32_32x32x16_bf16 v[80:95], v[160:163], v[176:179], v[80:95]
	v_mfma_f32_32x32x16_bf16 v[32:47], v[168:171], v[176:179], v[32:47]
	v_mfma_f32_32x32x16_bf16 v[64:79], v[160:163], v[184:187], v[64:79]
	v_mfma_f32_32x32x16_bf16 v[16:31], v[168:171], v[184:187], v[16:31]
	s_waitcnt lgkmcnt(0)
	v_mfma_f32_32x32x16_bf16 v[48:63], v[160:163], v[192:195], v[48:63]
	v_mfma_f32_32x32x16_bf16 v[0:15], v[168:171], v[192:195], v[0:15]
	s_setprio 0
	s_waitcnt vmcnt(9)
	ds_write_b128 v106, v[134:137]
	s_waitcnt vmcnt(8)
	ds_write_b128 v106, v[138:141] offset:5120
	s_waitcnt vmcnt(7)
	ds_write_b128 v106, v[144:147] offset:10240
	s_waitcnt vmcnt(6)
	ds_write_b128 v106, v[148:151] offset:15360
	s_waitcnt vmcnt(5)
	ds_write_b128 v106, v[152:155] offset:20480
	s_waitcnt lgkmcnt(0)
	s_barrier
	global_load_dwordx4 v[134:137], v[96:97], off offset:512
	global_load_dwordx4 v[138:141], v[100:101], off offset:512
	global_load_dwordx4 v[144:147], v[98:99], off offset:512
	global_load_dwordx4 v[148:151], v[102:103], off offset:512
	global_load_dwordx4 v[152:155], v[104:105], off offset:512
	ds_read_b128 v[156:159], v108
	ds_read_b128 v[160:163], v108 offset:32
	ds_read_b128 v[164:167], v108 offset:2560
	ds_read_b128 v[168:171], v108 offset:2592
	ds_read_b128 v[172:175], v107 offset:10240
	ds_read_b128 v[176:179], v107 offset:10272
	ds_read_b128 v[180:183], v107 offset:12800
	ds_read_b128 v[184:187], v107 offset:12832
	ds_read_b128 v[188:191], v107 offset:15360
	ds_read_b128 v[192:195], v107 offset:15392
	s_setprio 1
	s_waitcnt lgkmcnt(5)
	v_mfma_f32_32x32x16_bf16 v[80:95], v[156:159], v[172:175], v[80:95]
	v_mfma_f32_32x32x16_bf16 v[32:47], v[164:167], v[172:175], v[32:47]
	s_waitcnt lgkmcnt(3)
	v_mfma_f32_32x32x16_bf16 v[64:79], v[156:159], v[180:183], v[64:79]
	v_mfma_f32_32x32x16_bf16 v[16:31], v[164:167], v[180:183], v[16:31]
	s_waitcnt lgkmcnt(1)
	v_mfma_f32_32x32x16_bf16 v[48:63], v[156:159], v[188:191], v[48:63]
	v_mfma_f32_32x32x16_bf16 v[0:15], v[164:167], v[188:191], v[0:15]
	v_mfma_f32_32x32x16_bf16 v[80:95], v[160:163], v[176:179], v[80:95]
	v_mfma_f32_32x32x16_bf16 v[32:47], v[168:171], v[176:179], v[32:47]
	v_mfma_f32_32x32x16_bf16 v[64:79], v[160:163], v[184:187], v[64:79]
	v_mfma_f32_32x32x16_bf16 v[16:31], v[168:171], v[184:187], v[16:31]
	s_waitcnt lgkmcnt(0)
	v_mfma_f32_32x32x16_bf16 v[48:63], v[160:163], v[192:195], v[48:63]
	v_mfma_f32_32x32x16_bf16 v[0:15], v[168:171], v[192:195], v[0:15]
	s_setprio 0
	s_waitcnt vmcnt(9)
	ds_write_b128 v106, v[110:113] offset:30720
	s_waitcnt vmcnt(8)
	ds_write_b128 v106, v[114:117] offset:35840
	s_waitcnt vmcnt(7)
	ds_write_b128 v106, v[118:121] offset:40960
	s_waitcnt vmcnt(6)
	ds_write_b128 v106, v[122:125] offset:46080
	s_waitcnt vmcnt(5)
	ds_write_b128 v106, v[130:133] offset:51200
	s_waitcnt lgkmcnt(0)
	s_barrier
	global_load_dwordx4 v[110:113], v[96:97], off offset:576
	global_load_dwordx4 v[114:117], v[100:101], off offset:576
	global_load_dwordx4 v[118:121], v[98:99], off offset:576
	global_load_dwordx4 v[122:125], v[102:103], off offset:576
	global_load_dwordx4 v[130:133], v[104:105], off offset:576
	ds_read_b128 v[156:159], v108 offset:30720
	ds_read_b128 v[160:163], v108 offset:30752
	ds_read_b128 v[164:167], v108 offset:33280
	ds_read_b128 v[168:171], v108 offset:33312
	ds_read_b128 v[172:175], v107 offset:40960
	ds_read_b128 v[176:179], v107 offset:40992
	ds_read_b128 v[180:183], v107 offset:43520
	ds_read_b128 v[184:187], v107 offset:43552
	ds_read_b128 v[188:191], v107 offset:46080
	ds_read_b128 v[192:195], v107 offset:46112
	s_setprio 1
	s_waitcnt lgkmcnt(5)
	v_mfma_f32_32x32x16_bf16 v[80:95], v[156:159], v[172:175], v[80:95]
	v_mfma_f32_32x32x16_bf16 v[32:47], v[164:167], v[172:175], v[32:47]
	s_waitcnt lgkmcnt(3)
	v_mfma_f32_32x32x16_bf16 v[64:79], v[156:159], v[180:183], v[64:79]
	v_mfma_f32_32x32x16_bf16 v[16:31], v[164:167], v[180:183], v[16:31]
	s_waitcnt lgkmcnt(1)
	v_mfma_f32_32x32x16_bf16 v[48:63], v[156:159], v[188:191], v[48:63]
	v_mfma_f32_32x32x16_bf16 v[0:15], v[164:167], v[188:191], v[0:15]
	v_mfma_f32_32x32x16_bf16 v[80:95], v[160:163], v[176:179], v[80:95]
	v_mfma_f32_32x32x16_bf16 v[32:47], v[168:171], v[176:179], v[32:47]
	v_mfma_f32_32x32x16_bf16 v[64:79], v[160:163], v[184:187], v[64:79]
	v_mfma_f32_32x32x16_bf16 v[16:31], v[168:171], v[184:187], v[16:31]
	s_waitcnt lgkmcnt(0)
	v_mfma_f32_32x32x16_bf16 v[48:63], v[160:163], v[192:195], v[48:63]
	v_mfma_f32_32x32x16_bf16 v[0:15], v[168:171], v[192:195], v[0:15]
	s_setprio 0
	s_waitcnt vmcnt(9)
	ds_write_b128 v106, v[134:137]
	s_waitcnt vmcnt(8)
	ds_write_b128 v106, v[138:141] offset:5120
	s_waitcnt vmcnt(7)
	ds_write_b128 v106, v[144:147] offset:10240
	s_waitcnt vmcnt(6)
	ds_write_b128 v106, v[148:151] offset:15360
	s_waitcnt vmcnt(5)
	ds_write_b128 v106, v[152:155] offset:20480
	s_waitcnt lgkmcnt(0)
	s_barrier
	global_load_dwordx4 v[134:137], v[96:97], off offset:640
	global_load_dwordx4 v[138:141], v[100:101], off offset:640
	global_load_dwordx4 v[144:147], v[98:99], off offset:640
	global_load_dwordx4 v[148:151], v[102:103], off offset:640
	global_load_dwordx4 v[152:155], v[104:105], off offset:640
	ds_read_b128 v[156:159], v108
	ds_read_b128 v[160:163], v108 offset:32
	ds_read_b128 v[164:167], v108 offset:2560
	ds_read_b128 v[168:171], v108 offset:2592
	ds_read_b128 v[172:175], v107 offset:10240
	ds_read_b128 v[176:179], v107 offset:10272
	ds_read_b128 v[180:183], v107 offset:12800
	ds_read_b128 v[184:187], v107 offset:12832
	ds_read_b128 v[188:191], v107 offset:15360
	ds_read_b128 v[192:195], v107 offset:15392
	s_setprio 1
	s_waitcnt lgkmcnt(5)
	v_mfma_f32_32x32x16_bf16 v[80:95], v[156:159], v[172:175], v[80:95]
	v_mfma_f32_32x32x16_bf16 v[32:47], v[164:167], v[172:175], v[32:47]
	s_waitcnt lgkmcnt(3)
	v_mfma_f32_32x32x16_bf16 v[64:79], v[156:159], v[180:183], v[64:79]
	v_mfma_f32_32x32x16_bf16 v[16:31], v[164:167], v[180:183], v[16:31]
	s_waitcnt lgkmcnt(1)
	v_mfma_f32_32x32x16_bf16 v[48:63], v[156:159], v[188:191], v[48:63]
	v_mfma_f32_32x32x16_bf16 v[0:15], v[164:167], v[188:191], v[0:15]
	v_mfma_f32_32x32x16_bf16 v[80:95], v[160:163], v[176:179], v[80:95]
	v_mfma_f32_32x32x16_bf16 v[32:47], v[168:171], v[176:179], v[32:47]
	v_mfma_f32_32x32x16_bf16 v[64:79], v[160:163], v[184:187], v[64:79]
	v_mfma_f32_32x32x16_bf16 v[16:31], v[168:171], v[184:187], v[16:31]
	s_waitcnt lgkmcnt(0)
	v_mfma_f32_32x32x16_bf16 v[48:63], v[160:163], v[192:195], v[48:63]
	v_mfma_f32_32x32x16_bf16 v[0:15], v[168:171], v[192:195], v[0:15]
	s_setprio 0
	s_waitcnt vmcnt(9)
	ds_write_b128 v106, v[110:113] offset:30720
	s_waitcnt vmcnt(8)
	ds_write_b128 v106, v[114:117] offset:35840
	s_waitcnt vmcnt(7)
	ds_write_b128 v106, v[118:121] offset:40960
	s_waitcnt vmcnt(6)
	ds_write_b128 v106, v[122:125] offset:46080
	s_waitcnt vmcnt(5)
	ds_write_b128 v106, v[130:133] offset:51200
	s_waitcnt lgkmcnt(0)
	s_barrier
	global_load_dwordx4 v[110:113], v[96:97], off offset:704
	global_load_dwordx4 v[114:117], v[100:101], off offset:704
	s_nop 0
	global_load_dwordx4 v[96:99], v[98:99], off offset:704
	s_nop 0
	global_load_dwordx4 v[100:103], v[102:103], off offset:704
	s_nop 0
	global_load_dwordx4 v[118:121], v[104:105], off offset:704
	ds_read_b128 v[122:125], v108 offset:30720
	ds_read_b128 v[130:133], v108 offset:30752
	ds_read_b128 v[156:159], v108 offset:33280
	ds_read_b128 v[160:163], v108 offset:33312
	ds_read_b128 v[164:167], v107 offset:40960
	ds_read_b128 v[168:171], v107 offset:40992
	ds_read_b128 v[172:175], v107 offset:43520
	ds_read_b128 v[176:179], v107 offset:43552
	ds_read_b128 v[180:183], v107 offset:46080
	ds_read_b128 v[184:187], v107 offset:46112
	s_setprio 1
	s_waitcnt lgkmcnt(5)
	v_mfma_f32_32x32x16_bf16 v[80:95], v[122:125], v[164:167], v[80:95]
	v_mfma_f32_32x32x16_bf16 v[32:47], v[156:159], v[164:167], v[32:47]
	s_waitcnt lgkmcnt(3)
	v_mfma_f32_32x32x16_bf16 v[64:79], v[122:125], v[172:175], v[64:79]
	v_mfma_f32_32x32x16_bf16 v[16:31], v[156:159], v[172:175], v[16:31]
	s_waitcnt lgkmcnt(1)
	v_mfma_f32_32x32x16_bf16 v[48:63], v[122:125], v[180:183], v[48:63]
	v_mfma_f32_32x32x16_bf16 v[0:15], v[156:159], v[180:183], v[0:15]
	v_mfma_f32_32x32x16_bf16 v[80:95], v[130:133], v[168:171], v[80:95]
	v_mfma_f32_32x32x16_bf16 v[32:47], v[160:163], v[168:171], v[32:47]
	v_mfma_f32_32x32x16_bf16 v[64:79], v[130:133], v[176:179], v[64:79]
	v_mfma_f32_32x32x16_bf16 v[16:31], v[160:163], v[176:179], v[16:31]
	s_waitcnt lgkmcnt(0)
	v_mfma_f32_32x32x16_bf16 v[48:63], v[130:133], v[184:187], v[48:63]
	v_mfma_f32_32x32x16_bf16 v[0:15], v[160:163], v[184:187], v[0:15]
	s_setprio 0
	s_waitcnt vmcnt(9)
	ds_write_b128 v106, v[134:137]
	s_waitcnt vmcnt(8)
	ds_write_b128 v106, v[138:141] offset:5120
	s_waitcnt vmcnt(7)
	ds_write_b128 v106, v[144:147] offset:10240
	s_waitcnt vmcnt(6)
	ds_write_b128 v106, v[148:151] offset:15360
	s_waitcnt vmcnt(5)
	ds_write_b128 v106, v[152:155] offset:20480
	s_waitcnt lgkmcnt(0)
	s_barrier
	ds_read_b128 v[122:125], v108
	ds_read_b128 v[130:133], v108 offset:32
	ds_read_b128 v[134:137], v108 offset:2560
	ds_read_b128 v[138:141], v108 offset:2592
	ds_read_b128 v[144:147], v107 offset:10240
	ds_read_b128 v[148:151], v107 offset:10272
	ds_read_b128 v[152:155], v107 offset:12800
	ds_read_b128 v[156:159], v107 offset:12832
	ds_read_b128 v[160:163], v107 offset:15360
	ds_read_b128 v[164:167], v107 offset:15392
	s_setprio 1
	s_waitcnt lgkmcnt(5)
	v_mfma_f32_32x32x16_bf16 v[80:95], v[122:125], v[144:147], v[80:95]
	v_mfma_f32_32x32x16_bf16 v[32:47], v[134:137], v[144:147], v[32:47]
	s_waitcnt lgkmcnt(3)
	v_mfma_f32_32x32x16_bf16 v[64:79], v[122:125], v[152:155], v[64:79]
	v_mfma_f32_32x32x16_bf16 v[16:31], v[134:137], v[152:155], v[16:31]
	s_waitcnt lgkmcnt(1)
	v_mfma_f32_32x32x16_bf16 v[48:63], v[122:125], v[160:163], v[48:63]
	v_mfma_f32_32x32x16_bf16 v[0:15], v[134:137], v[160:163], v[0:15]
	v_mfma_f32_32x32x16_bf16 v[80:95], v[130:133], v[148:151], v[80:95]
	v_mfma_f32_32x32x16_bf16 v[32:47], v[138:141], v[148:151], v[32:47]
	v_mfma_f32_32x32x16_bf16 v[64:79], v[130:133], v[156:159], v[64:79]
	v_mfma_f32_32x32x16_bf16 v[16:31], v[138:141], v[156:159], v[16:31]
	s_waitcnt lgkmcnt(0)
	v_mfma_f32_32x32x16_bf16 v[48:63], v[130:133], v[164:167], v[48:63]
	v_mfma_f32_32x32x16_bf16 v[0:15], v[138:141], v[164:167], v[0:15]
	s_setprio 0
	s_waitcnt vmcnt(4)
	ds_write_b128 v106, v[110:113] offset:30720
	s_waitcnt vmcnt(3)
	ds_write_b128 v106, v[114:117] offset:35840
	s_waitcnt vmcnt(2)
	ds_write_b128 v106, v[96:99] offset:40960
	s_waitcnt vmcnt(1)
	ds_write_b128 v106, v[100:103] offset:46080
	s_waitcnt vmcnt(0)
	ds_write_b128 v106, v[118:121] offset:51200
	s_waitcnt lgkmcnt(0)
	s_barrier
	ds_read_b128 v[96:99], v108 offset:30720
	ds_read_b128 v[100:103], v108 offset:30752
	ds_read_b128 v[110:113], v108 offset:33280
	ds_read_b128 v[114:117], v108 offset:33312
	ds_read_b128 v[118:121], v107 offset:40960
	ds_read_b128 v[122:125], v107 offset:40992
	ds_read_b128 v[130:133], v107 offset:43520
	ds_read_b128 v[134:137], v107 offset:43552
	ds_read_b128 v[138:141], v107 offset:46080
	ds_read_b128 v[104:107], v107 offset:46112
	s_setprio 1
	s_waitcnt lgkmcnt(5)
	v_mfma_f32_32x32x16_bf16 v[80:95], v[96:99], v[118:121], v[80:95]
	v_mfma_f32_32x32x16_bf16 v[32:47], v[110:113], v[118:121], v[32:47]
	s_waitcnt lgkmcnt(3)
	v_mfma_f32_32x32x16_bf16 v[64:79], v[96:99], v[130:133], v[64:79]
	v_mfma_f32_32x32x16_bf16 v[16:31], v[110:113], v[130:133], v[16:31]
	s_waitcnt lgkmcnt(1)
	v_mfma_f32_32x32x16_bf16 v[48:63], v[96:99], v[138:141], v[48:63]
	v_mfma_f32_32x32x16_bf16 v[0:15], v[110:113], v[138:141], v[0:15]
	v_mfma_f32_32x32x16_bf16 v[80:95], v[100:103], v[122:125], v[80:95]
	v_mfma_f32_32x32x16_bf16 v[32:47], v[114:117], v[122:125], v[32:47]
	v_mfma_f32_32x32x16_bf16 v[64:79], v[100:103], v[134:137], v[64:79]
	v_mfma_f32_32x32x16_bf16 v[16:31], v[114:117], v[134:137], v[16:31]
	s_waitcnt lgkmcnt(0)
	v_mfma_f32_32x32x16_bf16 v[48:63], v[100:103], v[104:107], v[48:63]
	v_mfma_f32_32x32x16_bf16 v[0:15], v[114:117], v[104:107], v[0:15]
	s_setprio 0
	s_lshl_b32 s1, s7, 8
	s_add_i32 s1, s1, 0
	v_lshl_add_u32 v98, v143, 4, s1
	s_lshl_b32 s1, s7, 6
	s_add_i32 s1, s1, s8
	s_and_b32 s7, s1, 0xfc0
	s_ashr_i32 s1, s1, 9
	s_lshl_b32 s0, s36, 1
	s_and_b32 s1, s1, -8
	v_add_u32_e32 v121, 0x12000, v98
	s_barrier
	s_or_b32 s0, s1, s0
	ds_read_b128 v[98:101], v121
	ds_read_b128 v[102:105], v121 offset:32
	s_or_b32 s0, s0, s6
	s_ashr_i32 s1, s0, 31
	s_lshl_b64 s[26:27], s[0:1], 12
	v_readlane_b32 s0, v252, 52
	v_lshl_or_b32 v120, v143, 2, s7
	v_lshlrev_b32_e32 v198, 1, v142
	v_readlane_b32 s1, v252, 53
	s_waitcnt lgkmcnt(1)
	v_mul_f32_e32 v148, 0x3e16c740, v98
	v_mul_f32_e32 v80, v80, v148
	v_lshl_add_u64 v[96:97], s[0:1], 0, v[198:199]
	v_or_b32_e32 v98, s26, v120
	v_cvt_pk_bf16_f32 v80, v80, s0
	v_mad_u64_u32 v[118:119], s[0:1], v98, s83, v[96:97]
	v_mul_f32_e32 v149, 0x3e16c740, v99
	v_mad_i32_i24 v119, s27, v220, v119
	v_or_b32_e32 v150, 1, v120
	global_store_short v[118:119], v80, off
	v_mul_f32_e32 v80, v81, v149
	v_or_b32_e32 v81, s26, v150
	v_cvt_pk_bf16_f32 v80, v80, s0
	v_mad_u64_u32 v[116:117], s[0:1], v81, s83, v[96:97]
	v_mul_f32_e32 v145, 0x3e16c740, v100
	v_mad_i32_i24 v117, s27, v220, v117
	v_or_b32_e32 v146, 2, v120
	global_store_short v[116:117], v80, off
	v_mul_f32_e32 v80, v82, v145
	v_or_b32_e32 v81, s26, v146
	v_cvt_pk_bf16_f32 v80, v80, s0
	v_mad_u64_u32 v[114:115], s[0:1], v81, s83, v[96:97]
	v_mul_f32_e32 v143, 0x3e16c740, v101
	v_mad_i32_i24 v115, s27, v220, v115
	v_or_b32_e32 v144, 3, v120
	global_store_short v[114:115], v80, off
	v_mul_f32_e32 v80, v83, v143
	v_or_b32_e32 v81, s26, v144
	v_cvt_pk_bf16_f32 v80, v80, s0
	v_mad_u64_u32 v[112:113], s[0:1], v81, s83, v[96:97]
	v_cmp_gt_u32_e32 vcc, 16, v142
	s_waitcnt lgkmcnt(0)
	v_mul_f32_e32 v141, 0x3e16c740, v102
	v_mad_i32_i24 v113, s27, v220, v113
	v_or_b32_e32 v142, 8, v120
	global_store_short v[112:113], v80, off
	v_mul_f32_e32 v80, v84, v141
	v_or_b32_e32 v81, s26, v142
	v_cvt_pk_bf16_f32 v80, v80, s0
	v_mad_u64_u32 v[110:111], s[0:1], v81, s83, v[96:97]
	v_mul_f32_e32 v138, 0x3e16c740, v103
	v_mad_i32_i24 v111, s27, v220, v111
	v_or_b32_e32 v140, 9, v120
	ds_read_b128 v[100:103], v121 offset:64
	global_store_short v[110:111], v80, off
	v_mul_f32_e32 v80, v85, v138
	v_or_b32_e32 v81, s26, v140
	v_cvt_pk_bf16_f32 v80, v80, s0
	v_mad_u64_u32 v[108:109], s[0:1], v81, s83, v[96:97]
	v_mul_f32_e32 v136, 0x3e16c740, v104
	v_mad_i32_i24 v109, s27, v220, v109
	v_or_b32_e32 v139, 10, v120
	global_store_short v[108:109], v80, off
	v_mul_f32_e32 v80, v86, v136
	v_or_b32_e32 v81, s26, v139
	v_cvt_pk_bf16_f32 v80, v80, s0
	v_mad_u64_u32 v[106:107], s[0:1], v81, s83, v[96:97]
	v_and_b32_e32 v147, 15, v128
	v_mul_f32_e32 v134, 0x3e16c740, v105
	s_waitcnt lgkmcnt(0)
	v_mul_f32_e32 v132, 0x3e16c740, v100
	v_mul_f32_e32 v130, 0x3e16c740, v101
	v_mul_f32_e32 v128, 0x3e16c740, v102
	v_mul_f32_e32 v126, 0x3e16c740, v103
	ds_read_b128 v[100:103], v121 offset:96
	v_mad_i32_i24 v107, s27, v220, v107
	v_or_b32_e32 v137, 11, v120
	global_store_short v[106:107], v80, off
	v_mul_f32_e32 v80, v87, v134
	v_or_b32_e32 v81, s26, v137
	v_cvt_pk_bf16_f32 v80, v80, s0
	v_mad_u64_u32 v[104:105], s[0:1], v81, s83, v[96:97]
	v_mad_i32_i24 v105, s27, v220, v105
	v_or_b32_e32 v135, 16, v120
	global_store_short v[104:105], v80, off
	v_mul_f32_e32 v80, v88, v132
	v_or_b32_e32 v81, s26, v135
	s_waitcnt lgkmcnt(0)
	v_mul_f32_e32 v123, 0x3e16c740, v102
	v_mul_f32_e32 v122, 0x3e16c740, v103
	v_cvt_pk_bf16_f32 v80, v80, s0
	v_mad_u64_u32 v[102:103], s[0:1], v81, s83, v[96:97]
	v_mad_i32_i24 v103, s27, v220, v103
	v_or_b32_e32 v133, 17, v120
	global_store_short v[102:103], v80, off
	v_mul_f32_e32 v80, v89, v130
	v_or_b32_e32 v81, s26, v133
	v_mul_f32_e32 v125, 0x3e16c740, v100
	v_mul_f32_e32 v124, 0x3e16c740, v101
	v_cvt_pk_bf16_f32 v80, v80, s0
	v_mad_u64_u32 v[100:101], s[0:1], v81, s83, v[96:97]
	v_mad_i32_i24 v101, s27, v220, v101
	v_or_b32_e32 v131, 18, v120
	global_store_short v[100:101], v80, off
	v_mul_f32_e32 v80, v90, v128
	v_or_b32_e32 v81, s26, v131
	v_cvt_pk_bf16_f32 v80, v80, s0
	v_mad_u64_u32 v[98:99], s[0:1], v81, s83, v[96:97]
	v_mad_i32_i24 v99, s27, v220, v99
	v_or_b32_e32 v129, 19, v120
	global_store_short v[98:99], v80, off
	v_mul_f32_e32 v80, v91, v126
	v_or_b32_e32 v81, s26, v129
	v_cvt_pk_bf16_f32 v80, v80, s0
	v_mad_u64_u32 v[88:89], s[0:1], v81, s83, v[96:97]
	v_mad_i32_i24 v89, s27, v220, v89
	v_or_b32_e32 v127, 24, v120
	global_store_short v[88:89], v80, off
	v_mul_f32_e32 v80, v92, v125
	v_or_b32_e32 v81, s26, v127
	v_cvt_pk_bf16_f32 v80, v80, s0
	v_mad_u64_u32 v[86:87], s[0:1], v81, s83, v[96:97]
	v_mad_i32_i24 v87, s27, v220, v87
	v_or_b32_e32 v92, 25, v120
	global_store_short v[86:87], v80, off
	v_mul_f32_e32 v80, v93, v124
	v_or_b32_e32 v81, s26, v92
	v_cvt_pk_bf16_f32 v80, v80, s0
	v_mad_u64_u32 v[84:85], s[0:1], v81, s83, v[96:97]
	v_mad_i32_i24 v85, s27, v220, v85
	v_or_b32_e32 v91, 26, v120
	global_store_short v[84:85], v80, off
	v_mul_f32_e32 v80, v94, v123
	v_or_b32_e32 v81, s26, v91
	v_cvt_pk_bf16_f32 v80, v80, s0
	v_mad_u64_u32 v[82:83], s[0:1], v81, s83, v[96:97]
	v_mad_i32_i24 v83, s27, v220, v83
	global_store_short v[82:83], v80, off
	v_or_b32_e32 v90, 27, v120
	v_mul_f32_e32 v80, v95, v122
	v_cvt_pk_bf16_f32 v93, v80, s0
	v_or_b32_e32 v80, s26, v90
	v_mad_u64_u32 v[80:81], s[0:1], v80, s83, v[96:97]
	v_mul_f32_e32 v64, v64, v148
	s_nop 0
	v_cvt_pk_bf16_f32 v64, v64, s0
	global_store_short v[118:119], v64, off offset:64
	v_mul_f32_e32 v64, v65, v149
	v_cvt_pk_bf16_f32 v64, v64, s0
	global_store_short v[116:117], v64, off offset:64
	v_mul_f32_e32 v64, v66, v145
	v_cvt_pk_bf16_f32 v64, v64, s0
	global_store_short v[114:115], v64, off offset:64
	v_mul_f32_e32 v64, v67, v143
	v_cvt_pk_bf16_f32 v64, v64, s0
	global_store_short v[112:113], v64, off offset:64
	v_mul_f32_e32 v64, v68, v141
	v_cvt_pk_bf16_f32 v64, v64, s0
	global_store_short v[110:111], v64, off offset:64
	v_mul_f32_e32 v64, v69, v138
	v_cvt_pk_bf16_f32 v64, v64, s0
	global_store_short v[108:109], v64, off offset:64
	v_mul_f32_e32 v64, v70, v136
	v_cvt_pk_bf16_f32 v64, v64, s0
	global_store_short v[106:107], v64, off offset:64
	v_mul_f32_e32 v64, v71, v134
	v_cvt_pk_bf16_f32 v64, v64, s0
	global_store_short v[104:105], v64, off offset:64
	v_mul_f32_e32 v64, v72, v132
	v_cvt_pk_bf16_f32 v64, v64, s0
	global_store_short v[102:103], v64, off offset:64
	v_mul_f32_e32 v64, v73, v130
	v_cvt_pk_bf16_f32 v64, v64, s0
	global_store_short v[100:101], v64, off offset:64
	v_mul_f32_e32 v64, v74, v128
	v_cvt_pk_bf16_f32 v64, v64, s0
	global_store_short v[98:99], v64, off offset:64
	v_mul_f32_e32 v64, v75, v126
	v_cvt_pk_bf16_f32 v64, v64, s0
	global_store_short v[88:89], v64, off offset:64
	v_mul_f32_e32 v64, v76, v125
	v_cvt_pk_bf16_f32 v64, v64, s0
	global_store_short v[86:87], v64, off offset:64
	v_mul_f32_e32 v64, v77, v124
	v_cvt_pk_bf16_f32 v64, v64, s0
	global_store_short v[84:85], v64, off offset:64
	v_mul_f32_e32 v64, v78, v123
	v_cvt_pk_bf16_f32 v64, v64, s0
	global_store_short v[82:83], v64, off offset:64
	v_mul_f32_e32 v64, v79, v122
	v_mad_i32_i24 v81, s27, v220, v81
	v_cvt_pk_bf16_f32 v64, v64, s0
	v_and_b32_e32 v65, 64, v219
	global_store_short v[80:81], v64, off offset:64
	v_xor_b32_e32 v64, 16, v219
	v_add_u32_e32 v65, 64, v65
	v_lshlrev_b32_e32 v71, 2, v147
	global_store_short v[80:81], v93, off
	v_cmp_lt_i32_e64 s[0:1], v64, v65
	v_lshl_or_b32 v202, v120, 6, v71
	global_load_dword v151, v202, s[62:63]
	global_load_dword v222, v202, s[64:65]
	global_load_dword v152, v202, s[62:63] offset:64
	global_load_dword v223, v202, s[64:65] offset:64
	global_load_dword v153, v202, s[62:63] offset:128
	global_load_dword v224, v202, s[64:65] offset:128
	global_load_dword v154, v202, s[62:63] offset:192
	global_load_dword v225, v202, s[64:65] offset:192
	global_load_dword v155, v202, s[62:63] offset:512
	global_load_dword v226, v202, s[64:65] offset:512
	global_load_dword v156, v202, s[62:63] offset:576
	global_load_dword v227, v202, s[64:65] offset:576
	global_load_dword v157, v202, s[62:63] offset:640
	global_load_dword v228, v202, s[64:65] offset:640
	global_load_dword v158, v202, s[62:63] offset:704
	global_load_dword v229, v202, s[64:65] offset:704
	global_load_dword v159, v202, s[62:63] offset:1024
	global_load_dword v230, v202, s[64:65] offset:1024
	global_load_dword v160, v202, s[62:63] offset:1088
	global_load_dword v231, v202, s[64:65] offset:1088
	global_load_dword v161, v202, s[62:63] offset:1152
	global_load_dword v232, v202, s[64:65] offset:1152
	global_load_dword v162, v202, s[62:63] offset:1216
	global_load_dword v233, v202, s[64:65] offset:1216
	global_load_dword v163, v202, s[62:63] offset:1536
	global_load_dword v234, v202, s[64:65] offset:1536
	global_load_dword v164, v202, s[62:63] offset:1600
	global_load_dword v235, v202, s[64:65] offset:1600
	global_load_dword v165, v202, s[62:63] offset:1664
	global_load_dword v236, v202, s[64:65] offset:1664
	global_load_dword v166, v202, s[62:63] offset:1728
	global_load_dword v237, v202, s[64:65] offset:1728
	global_load_dword v167, v202, s[62:63] offset:2048
	global_load_dword v238, v202, s[64:65] offset:2048
	global_load_dword v168, v202, s[62:63] offset:2112
	global_load_dword v239, v202, s[64:65] offset:2112
	global_load_dword v169, v202, s[62:63] offset:2176
	global_load_dword v240, v202, s[64:65] offset:2176
	global_load_dword v170, v202, s[62:63] offset:2240
	global_load_dword v241, v202, s[64:65] offset:2240
	global_load_dword v171, v202, s[62:63] offset:2560
	global_load_dword v242, v202, s[64:65] offset:2560
	global_load_dword v172, v202, s[62:63] offset:2624
	global_load_dword v243, v202, s[64:65] offset:2624
	global_load_dword v173, v202, s[62:63] offset:2688
	global_load_dword v244, v202, s[64:65] offset:2688
	global_load_dword v174, v202, s[62:63] offset:2752
	global_load_dword v245, v202, s[64:65] offset:2752
	global_load_dword v175, v202, s[62:63] offset:3072
	global_load_dword v246, v202, s[64:65] offset:3072
	global_load_dword v176, v202, s[62:63] offset:3136
	global_load_dword v247, v202, s[64:65] offset:3136
	global_load_dword v177, v202, s[62:63] offset:3200
	global_load_dword v248, v202, s[64:65] offset:3200
	global_load_dword v178, v202, s[62:63] offset:3264
	global_load_dword v249, v202, s[64:65] offset:3264
	global_load_dword v179, v202, s[62:63] offset:3584
	global_load_dword v250, v202, s[64:65] offset:3584
	global_load_dword v180, v202, s[62:63] offset:3648
	global_load_dword v251, v202, s[64:65] offset:3648
	global_load_dword v181, v202, s[62:63] offset:3712
	global_load_dword v200, v202, s[64:65] offset:3712
	global_load_dword v182, v202, s[62:63] offset:3776
	global_load_dword v201, v202, s[64:65] offset:3776
	v_cndmask_b32_e64 v64, v219, v64, s[0:1]
	v_mul_f32_e32 v48, v48, v148
	v_lshlrev_b32_e32 v70, 2, v64
	ds_bpermute_b32 v64, v70, v48
	v_or_b32_e32 v94, 35, v120
	v_or_b32_e32 v79, 51, v120
	v_or_b32_e32 v77, 56, v120
	s_waitcnt vmcnt(62) lgkmcnt(0)
	v_mul_f32_e32 v64, v222, v64
	v_cndmask_b32_e64 v64, v64, -v64, vcc
	v_fmac_f32_e32 v64, v48, v151
	v_cvt_pk_bf16_f32 v48, v64, s0
	global_store_short v[118:119], v48, off offset:128
	v_mul_f32_e32 v48, v49, v149
	ds_bpermute_b32 v49, v70, v48
	s_waitcnt vmcnt(61) lgkmcnt(0)
	v_mul_f32_e32 v49, v223, v49
	v_cndmask_b32_e64 v49, v49, -v49, vcc
	v_fmac_f32_e32 v49, v48, v152
	v_cvt_pk_bf16_f32 v48, v49, s0
	global_store_short v[116:117], v48, off offset:128
	v_mul_f32_e32 v48, v50, v145
	ds_bpermute_b32 v49, v70, v48
	s_waitcnt vmcnt(60) lgkmcnt(0)
	v_mul_f32_e32 v49, v224, v49
	v_cndmask_b32_e64 v49, v49, -v49, vcc
	v_fmac_f32_e32 v49, v48, v153
	v_cvt_pk_bf16_f32 v48, v49, s0
	global_store_short v[114:115], v48, off offset:128
	v_mul_f32_e32 v48, v51, v143
	ds_bpermute_b32 v49, v70, v48
	s_waitcnt vmcnt(59) lgkmcnt(0)
	v_mul_f32_e32 v49, v225, v49
	v_cndmask_b32_e64 v49, v49, -v49, vcc
	v_fmac_f32_e32 v49, v48, v154
	v_cvt_pk_bf16_f32 v48, v49, s0
	global_store_short v[112:113], v48, off offset:128
	v_mul_f32_e32 v48, v52, v141
	ds_bpermute_b32 v49, v70, v48
	s_waitcnt vmcnt(58) lgkmcnt(0)
	v_mul_f32_e32 v49, v226, v49
	v_cndmask_b32_e64 v49, v49, -v49, vcc
	v_fmac_f32_e32 v49, v48, v155
	v_cvt_pk_bf16_f32 v48, v49, s0
	global_store_short v[110:111], v48, off offset:128
	v_mul_f32_e32 v48, v53, v138
	ds_bpermute_b32 v49, v70, v48
	s_waitcnt vmcnt(57) lgkmcnt(0)
	v_mul_f32_e32 v49, v227, v49
	v_cndmask_b32_e64 v49, v49, -v49, vcc
	v_fmac_f32_e32 v49, v48, v156
	v_cvt_pk_bf16_f32 v48, v49, s0
	global_store_short v[108:109], v48, off offset:128
	v_mul_f32_e32 v48, v54, v136
	ds_bpermute_b32 v49, v70, v48
	s_waitcnt vmcnt(56) lgkmcnt(0)
	v_mul_f32_e32 v49, v228, v49
	v_cndmask_b32_e64 v49, v49, -v49, vcc
	v_fmac_f32_e32 v49, v48, v157
	v_cvt_pk_bf16_f32 v48, v49, s0
	global_store_short v[106:107], v48, off offset:128
	v_mul_f32_e32 v48, v55, v134
	ds_bpermute_b32 v49, v70, v48
	s_waitcnt vmcnt(55) lgkmcnt(0)
	v_mul_f32_e32 v49, v229, v49
	v_cndmask_b32_e64 v49, v49, -v49, vcc
	v_fmac_f32_e32 v49, v48, v158
	v_cvt_pk_bf16_f32 v48, v49, s0
	global_store_short v[104:105], v48, off offset:128
	v_mul_f32_e32 v48, v56, v132
	ds_bpermute_b32 v49, v70, v48
	s_waitcnt vmcnt(54) lgkmcnt(0)
	v_mul_f32_e32 v49, v230, v49
	v_cndmask_b32_e64 v49, v49, -v49, vcc
	v_fmac_f32_e32 v49, v48, v159
	v_cvt_pk_bf16_f32 v48, v49, s0
	global_store_short v[102:103], v48, off offset:128
	v_mul_f32_e32 v48, v57, v130
	ds_bpermute_b32 v49, v70, v48
	v_or_b32_e32 v102, 33, v120
	s_waitcnt vmcnt(53) lgkmcnt(0)
	v_mul_f32_e32 v49, v231, v49
	v_cndmask_b32_e64 v49, v49, -v49, vcc
	v_fmac_f32_e32 v49, v48, v160
	v_cvt_pk_bf16_f32 v48, v49, s0
	global_store_short v[100:101], v48, off offset:128
	v_mul_f32_e32 v48, v58, v128
	ds_bpermute_b32 v49, v70, v48
	v_or_b32_e32 v100, 32, v120
	s_waitcnt vmcnt(52) lgkmcnt(0)
	v_mul_f32_e32 v49, v232, v49
	v_cndmask_b32_e64 v49, v49, -v49, vcc
	v_fmac_f32_e32 v49, v48, v161
	v_cvt_pk_bf16_f32 v48, v49, s0
	global_store_short v[98:99], v48, off offset:128
	v_mul_f32_e32 v48, v59, v126
	ds_bpermute_b32 v49, v70, v48
	v_or_b32_e32 v98, 34, v120
	s_waitcnt vmcnt(51) lgkmcnt(0)
	v_mul_f32_e32 v49, v233, v49
	v_cndmask_b32_e64 v49, v49, -v49, vcc
	v_fmac_f32_e32 v49, v48, v162
	v_cvt_pk_bf16_f32 v48, v49, s0
	global_store_short v[88:89], v48, off offset:128
	v_mul_f32_e32 v48, v60, v125
	ds_bpermute_b32 v49, v70, v48
	v_or_b32_e32 v89, 42, v120
	s_waitcnt vmcnt(50) lgkmcnt(0)
	v_mul_f32_e32 v49, v234, v49
	v_cndmask_b32_e64 v49, v49, -v49, vcc
	v_fmac_f32_e32 v49, v48, v163
	v_cvt_pk_bf16_f32 v48, v49, s0
	global_store_short v[86:87], v48, off offset:128
	v_mul_f32_e32 v48, v61, v124
	ds_bpermute_b32 v49, v70, v48
	v_or_b32_e32 v92, 40, v120
	v_or_b32_e32 v87, 43, v120
	s_waitcnt vmcnt(49) lgkmcnt(0)
	v_mul_f32_e32 v49, v235, v49
	v_cndmask_b32_e64 v49, v49, -v49, vcc
	v_fmac_f32_e32 v49, v48, v164
	v_cvt_pk_bf16_f32 v48, v49, s0
	global_store_short v[84:85], v48, off offset:128
	v_mul_f32_e32 v48, v62, v123
	ds_bpermute_b32 v49, v70, v48
	v_or_b32_e32 v85, 48, v120
	s_waitcnt vmcnt(48) lgkmcnt(0)
	v_mul_f32_e32 v49, v236, v49
	v_cndmask_b32_e64 v49, v49, -v49, vcc
	v_fmac_f32_e32 v49, v48, v165
	v_cvt_pk_bf16_f32 v48, v49, s0
	global_store_short v[82:83], v48, off offset:128
	v_mul_f32_e32 v48, v63, v122
	ds_bpermute_b32 v49, v70, v48
	v_or_b32_e32 v90, 41, v120
	v_or_b32_e32 v83, 49, v120
	s_waitcnt vmcnt(47) lgkmcnt(0)
	v_mul_f32_e32 v49, v237, v49
	v_cndmask_b32_e64 v49, v49, -v49, vcc
	v_fmac_f32_e32 v49, v48, v166
	v_cvt_pk_bf16_f32 v48, v49, s0
	global_store_short v[80:81], v48, off offset:128
	ds_read_b128 v[48:51], v121 offset:128
	ds_read_b128 v[52:55], v121 offset:160
	v_or_b32_e32 v81, 50, v120
	s_waitcnt lgkmcnt(1)
	v_mul_f32_e32 v99, 0x3e16c740, v48
	v_mul_f32_e32 v32, v32, v99
	v_or_b32_e32 v48, s26, v100
	v_cvt_pk_bf16_f32 v32, v32, s0
	v_mad_u64_u32 v[68:69], s[0:1], v48, s83, v[96:97]
	v_mul_f32_e32 v101, 0x3e16c740, v49
	v_mad_i32_i24 v69, s27, v220, v69
	global_store_short v[68:69], v32, off
	v_mul_f32_e32 v32, v33, v101
	v_or_b32_e32 v33, s26, v102
	v_cvt_pk_bf16_f32 v32, v32, s0
	v_mad_u64_u32 v[66:67], s[0:1], v33, s83, v[96:97]
	v_mul_f32_e32 v95, 0x3e16c740, v50
	v_mad_i32_i24 v67, s27, v220, v67
	global_store_short v[66:67], v32, off
	v_mul_f32_e32 v32, v34, v95
	v_or_b32_e32 v33, s26, v98
	v_cvt_pk_bf16_f32 v32, v32, s0
	v_mad_u64_u32 v[64:65], s[0:1], v33, s83, v[96:97]
	v_mul_f32_e32 v93, 0x3e16c740, v51
	v_mad_i32_i24 v65, s27, v220, v65
	global_store_short v[64:65], v32, off
	v_mul_f32_e32 v32, v35, v93
	v_or_b32_e32 v33, s26, v94
	v_cvt_pk_bf16_f32 v32, v32, s0
	v_mad_u64_u32 v[62:63], s[0:1], v33, s83, v[96:97]
	s_waitcnt lgkmcnt(0)
	v_mul_f32_e32 v91, 0x3e16c740, v52
	v_mad_i32_i24 v63, s27, v220, v63
	global_store_short v[62:63], v32, off
	v_mul_f32_e32 v32, v36, v91
	v_or_b32_e32 v33, s26, v92
	v_cvt_pk_bf16_f32 v32, v32, s0
	v_mad_u64_u32 v[60:61], s[0:1], v33, s83, v[96:97]
	v_mul_f32_e32 v88, 0x3e16c740, v53
	v_mad_i32_i24 v61, s27, v220, v61
	ds_read_b128 v[50:53], v121 offset:192
	global_store_short v[60:61], v32, off
	v_mul_f32_e32 v32, v37, v88
	v_or_b32_e32 v33, s26, v90
	v_cvt_pk_bf16_f32 v32, v32, s0
	v_mad_u64_u32 v[58:59], s[0:1], v33, s83, v[96:97]
	v_mul_f32_e32 v86, 0x3e16c740, v54
	v_mad_i32_i24 v59, s27, v220, v59
	global_store_short v[58:59], v32, off
	v_mul_f32_e32 v32, v38, v86
	v_or_b32_e32 v33, s26, v89
	v_cvt_pk_bf16_f32 v32, v32, s0
	v_mad_u64_u32 v[56:57], s[0:1], v33, s83, v[96:97]
	v_mul_f32_e32 v84, 0x3e16c740, v55
	s_waitcnt lgkmcnt(0)
	v_mul_f32_e32 v82, 0x3e16c740, v50
	v_mul_f32_e32 v80, 0x3e16c740, v51
	v_mul_f32_e32 v78, 0x3e16c740, v52
	v_mul_f32_e32 v76, 0x3e16c740, v53
	ds_read_b128 v[50:53], v121 offset:224
	v_mad_i32_i24 v57, s27, v220, v57
	global_store_short v[56:57], v32, off
	v_mul_f32_e32 v32, v39, v84
	v_or_b32_e32 v33, s26, v87
	v_cvt_pk_bf16_f32 v32, v32, s0
	v_mad_u64_u32 v[54:55], s[0:1], v33, s83, v[96:97]
	v_mad_i32_i24 v55, s27, v220, v55
	global_store_short v[54:55], v32, off
	v_mul_f32_e32 v32, v40, v82
	v_or_b32_e32 v33, s26, v85
	s_waitcnt lgkmcnt(0)
	v_mul_f32_e32 v73, 0x3e16c740, v52
	v_mul_f32_e32 v72, 0x3e16c740, v53
	v_cvt_pk_bf16_f32 v32, v32, s0
	v_mad_u64_u32 v[52:53], s[0:1], v33, s83, v[96:97]
	v_mad_i32_i24 v53, s27, v220, v53
	global_store_short v[52:53], v32, off
	v_mul_f32_e32 v32, v41, v80
	v_or_b32_e32 v33, s26, v83
	v_mul_f32_e32 v75, 0x3e16c740, v50
	v_mul_f32_e32 v74, 0x3e16c740, v51
	v_cvt_pk_bf16_f32 v32, v32, s0
	v_mad_u64_u32 v[50:51], s[0:1], v33, s83, v[96:97]
	v_mad_i32_i24 v51, s27, v220, v51
	global_store_short v[50:51], v32, off
	v_mul_f32_e32 v32, v42, v78
	v_or_b32_e32 v33, s26, v81
	v_cvt_pk_bf16_f32 v32, v32, s0
	v_mad_u64_u32 v[48:49], s[0:1], v33, s83, v[96:97]
	v_mad_i32_i24 v49, s27, v220, v49
	global_store_short v[48:49], v32, off
	v_mul_f32_e32 v32, v43, v76
	v_or_b32_e32 v33, s26, v79
	v_cvt_pk_bf16_f32 v32, v32, s0
	v_mad_u64_u32 v[40:41], s[0:1], v33, s83, v[96:97]
	v_mad_i32_i24 v41, s27, v220, v41
	global_store_short v[40:41], v32, off
	v_mul_f32_e32 v32, v44, v75
	v_or_b32_e32 v33, s26, v77
	v_cvt_pk_bf16_f32 v32, v32, s0
	v_mad_u64_u32 v[38:39], s[0:1], v33, s83, v[96:97]
	v_mad_i32_i24 v39, s27, v220, v39
	v_or_b32_e32 v44, 57, v120
	global_store_short v[38:39], v32, off
	v_mul_f32_e32 v32, v45, v74
	v_or_b32_e32 v33, s26, v44
	v_cvt_pk_bf16_f32 v32, v32, s0
	v_mad_u64_u32 v[36:37], s[0:1], v33, s83, v[96:97]
	v_mad_i32_i24 v37, s27, v220, v37
	v_or_b32_e32 v43, 58, v120
	global_store_short v[36:37], v32, off
	v_mul_f32_e32 v32, v46, v73
	v_or_b32_e32 v33, s26, v43
	v_cvt_pk_bf16_f32 v32, v32, s0
	v_mad_u64_u32 v[34:35], s[0:1], v33, s83, v[96:97]
	v_mad_i32_i24 v35, s27, v220, v35
	global_store_short v[34:35], v32, off
	v_or_b32_e32 v42, 59, v120
	v_mul_f32_e32 v32, v47, v72
	v_cvt_pk_bf16_f32 v45, v32, s0
	v_or_b32_e32 v32, s26, v42
	v_mad_u64_u32 v[32:33], s[0:1], v32, s83, v[96:97]
	v_mul_f32_e32 v16, v16, v99
	s_nop 0
	v_cvt_pk_bf16_f32 v16, v16, s0
	global_store_short v[68:69], v16, off offset:64
	v_mul_f32_e32 v16, v17, v101
	v_cvt_pk_bf16_f32 v16, v16, s0
	global_store_short v[66:67], v16, off offset:64
	v_mul_f32_e32 v16, v18, v95
	v_cvt_pk_bf16_f32 v16, v16, s0
	global_store_short v[64:65], v16, off offset:64
	v_mul_f32_e32 v16, v19, v93
	v_cvt_pk_bf16_f32 v16, v16, s0
	global_store_short v[62:63], v16, off offset:64
	v_mul_f32_e32 v16, v20, v91
	v_cvt_pk_bf16_f32 v16, v16, s0
	global_store_short v[60:61], v16, off offset:64
	v_mul_f32_e32 v16, v21, v88
	v_cvt_pk_bf16_f32 v16, v16, s0
	global_store_short v[58:59], v16, off offset:64
	v_mul_f32_e32 v16, v22, v86
	v_cvt_pk_bf16_f32 v16, v16, s0
	global_store_short v[56:57], v16, off offset:64
	v_mul_f32_e32 v16, v23, v84
	v_cvt_pk_bf16_f32 v16, v16, s0
	global_store_short v[54:55], v16, off offset:64
	v_mul_f32_e32 v16, v24, v82
	v_cvt_pk_bf16_f32 v16, v16, s0
	global_store_short v[52:53], v16, off offset:64
	v_mul_f32_e32 v16, v25, v80
	v_cvt_pk_bf16_f32 v16, v16, s0
	global_store_short v[50:51], v16, off offset:64
	v_mul_f32_e32 v16, v26, v78
	v_cvt_pk_bf16_f32 v16, v16, s0
	global_store_short v[48:49], v16, off offset:64
	v_mul_f32_e32 v16, v27, v76
	v_cvt_pk_bf16_f32 v16, v16, s0
	global_store_short v[40:41], v16, off offset:64
	v_mul_f32_e32 v16, v28, v75
	v_cvt_pk_bf16_f32 v16, v16, s0
	global_store_short v[38:39], v16, off offset:64
	v_mul_f32_e32 v16, v29, v74
	v_cvt_pk_bf16_f32 v16, v16, s0
	global_store_short v[36:37], v16, off offset:64
	v_mul_f32_e32 v16, v30, v73
	v_cvt_pk_bf16_f32 v16, v16, s0
	global_store_short v[34:35], v16, off offset:64
	v_mul_f32_e32 v16, v31, v72
	v_mad_i32_i24 v33, s27, v220, v33
	v_cvt_pk_bf16_f32 v16, v16, s0
	global_store_short v[32:33], v45, off
	global_store_short v[32:33], v16, off offset:64
	v_mul_f32_e32 v0, v0, v99
	ds_bpermute_b32 v16, v70, v0
	s_waitcnt vmcnt(62) lgkmcnt(0)
	v_mul_f32_e32 v16, v238, v16
	v_cndmask_b32_e64 v16, v16, -v16, vcc
	v_fmac_f32_e32 v16, v0, v167
	v_cvt_pk_bf16_f32 v0, v16, s0
	global_store_short v[68:69], v0, off offset:128
	v_mul_f32_e32 v0, v1, v101
	ds_bpermute_b32 v1, v70, v0
	s_waitcnt vmcnt(62) lgkmcnt(0)
	v_mul_f32_e32 v1, v239, v1
	v_cndmask_b32_e64 v1, v1, -v1, vcc
	v_fmac_f32_e32 v1, v0, v168
	v_cvt_pk_bf16_f32 v0, v1, s0
	global_store_short v[66:67], v0, off offset:128
	v_mul_f32_e32 v0, v2, v95
	ds_bpermute_b32 v1, v70, v0
	s_waitcnt vmcnt(62) lgkmcnt(0)
	v_mul_f32_e32 v1, v240, v1
	v_cndmask_b32_e64 v1, v1, -v1, vcc
	v_fmac_f32_e32 v1, v0, v169
	v_cvt_pk_bf16_f32 v0, v1, s0
	global_store_short v[64:65], v0, off offset:128
	v_mul_f32_e32 v0, v3, v93
	ds_bpermute_b32 v1, v70, v0
	s_waitcnt vmcnt(62) lgkmcnt(0)
	v_mul_f32_e32 v1, v241, v1
	v_cndmask_b32_e64 v1, v1, -v1, vcc
	v_fmac_f32_e32 v1, v0, v170
	v_cvt_pk_bf16_f32 v0, v1, s0
	global_store_short v[62:63], v0, off offset:128
	v_mul_f32_e32 v0, v4, v91
	ds_bpermute_b32 v1, v70, v0
	s_waitcnt vmcnt(62) lgkmcnt(0)
	v_mul_f32_e32 v1, v242, v1
	v_cndmask_b32_e64 v1, v1, -v1, vcc
	v_fmac_f32_e32 v1, v0, v171
	v_cvt_pk_bf16_f32 v0, v1, s0
	global_store_short v[60:61], v0, off offset:128
	v_mul_f32_e32 v0, v5, v88
	ds_bpermute_b32 v1, v70, v0
	s_waitcnt vmcnt(62) lgkmcnt(0)
	v_mul_f32_e32 v1, v243, v1
	v_cndmask_b32_e64 v1, v1, -v1, vcc
	v_fmac_f32_e32 v1, v0, v172
	v_cvt_pk_bf16_f32 v0, v1, s0
	global_store_short v[58:59], v0, off offset:128
	v_mul_f32_e32 v0, v6, v86
	ds_bpermute_b32 v1, v70, v0
	s_waitcnt vmcnt(62) lgkmcnt(0)
	v_mul_f32_e32 v1, v244, v1
	v_cndmask_b32_e64 v1, v1, -v1, vcc
	v_fmac_f32_e32 v1, v0, v173
	v_cvt_pk_bf16_f32 v0, v1, s0
	global_store_short v[56:57], v0, off offset:128
	v_mul_f32_e32 v0, v7, v84
	ds_bpermute_b32 v1, v70, v0
	s_waitcnt vmcnt(62) lgkmcnt(0)
	v_mul_f32_e32 v1, v245, v1
	v_cndmask_b32_e64 v1, v1, -v1, vcc
	v_fmac_f32_e32 v1, v0, v174
	v_cvt_pk_bf16_f32 v0, v1, s0
	global_store_short v[54:55], v0, off offset:128
	v_mul_f32_e32 v0, v8, v82
	ds_bpermute_b32 v1, v70, v0
	s_waitcnt vmcnt(62) lgkmcnt(0)
	v_mul_f32_e32 v1, v246, v1
	v_cndmask_b32_e64 v1, v1, -v1, vcc
	v_fmac_f32_e32 v1, v0, v175
	v_cvt_pk_bf16_f32 v0, v1, s0
	global_store_short v[52:53], v0, off offset:128
	v_mul_f32_e32 v0, v9, v80
	ds_bpermute_b32 v1, v70, v0
	s_waitcnt vmcnt(62) lgkmcnt(0)
	v_mul_f32_e32 v1, v247, v1
	v_cndmask_b32_e64 v1, v1, -v1, vcc
	v_fmac_f32_e32 v1, v0, v176
	v_cvt_pk_bf16_f32 v0, v1, s0
	global_store_short v[50:51], v0, off offset:128
	v_mul_f32_e32 v0, v10, v78
	ds_bpermute_b32 v1, v70, v0
	s_waitcnt vmcnt(62) lgkmcnt(0)
	v_mul_f32_e32 v1, v248, v1
	v_cndmask_b32_e64 v1, v1, -v1, vcc
	v_fmac_f32_e32 v1, v0, v177
	v_cvt_pk_bf16_f32 v0, v1, s0
	global_store_short v[48:49], v0, off offset:128
	v_mul_f32_e32 v0, v11, v76
	ds_bpermute_b32 v1, v70, v0
	s_waitcnt vmcnt(62) lgkmcnt(0)
	v_mul_f32_e32 v1, v249, v1
	v_cndmask_b32_e64 v1, v1, -v1, vcc
	v_fmac_f32_e32 v1, v0, v178
	v_cvt_pk_bf16_f32 v0, v1, s0
	global_store_short v[40:41], v0, off offset:128
	v_mul_f32_e32 v0, v12, v75
	ds_bpermute_b32 v1, v70, v0
	s_waitcnt vmcnt(62) lgkmcnt(0)
	v_mul_f32_e32 v1, v250, v1
	v_cndmask_b32_e64 v1, v1, -v1, vcc
	v_fmac_f32_e32 v1, v0, v179
	v_cvt_pk_bf16_f32 v0, v1, s0
	global_store_short v[38:39], v0, off offset:128
	v_mul_f32_e32 v0, v13, v74
	ds_bpermute_b32 v1, v70, v0
	s_waitcnt vmcnt(62) lgkmcnt(0)
	v_mul_f32_e32 v1, v251, v1
	v_cndmask_b32_e64 v1, v1, -v1, vcc
	v_fmac_f32_e32 v1, v0, v180
	v_cvt_pk_bf16_f32 v0, v1, s0
	global_store_short v[36:37], v0, off offset:128
	v_mul_f32_e32 v0, v14, v73
	ds_bpermute_b32 v1, v70, v0
	s_waitcnt vmcnt(62) lgkmcnt(0)
	v_mul_f32_e32 v1, v200, v1
	v_cndmask_b32_e64 v1, v1, -v1, vcc
	v_fmac_f32_e32 v1, v0, v181
	v_cvt_pk_bf16_f32 v0, v1, s0
	global_store_short v[34:35], v0, off offset:128
	v_mul_f32_e32 v0, v15, v72
	ds_bpermute_b32 v1, v70, v0
	s_waitcnt vmcnt(62) lgkmcnt(0)
	v_mul_f32_e32 v1, v201, v1
	v_cndmask_b32_e64 v1, v1, -v1, vcc
	v_fmac_f32_e32 v1, v0, v182
	v_cvt_pk_bf16_f32 v0, v1, s0
	global_store_short v[32:33], v0, off offset:128

.LBB0_406:
	s_lshl_b32 s6, s5, 5
	s_and_b32 s26, s6, 0xffffff80
	s_lshl_b32 s6, s5, 8
	s_ashr_i32 s27, s26, 31
	s_and_b32 s68, s6, 0x300
	s_lshl_b64 s[8:9], s[26:27], 11
	v_readlane_b32 s7, v252, 50
	v_readlane_b32 s0, v252, 51
	s_nop 1
	s_add_u32 s28, s7, s8
	s_addc_u32 s29, s0, s9
	s_lshl_b32 s7, s68, 11
	s_add_u32 s38, s80, s7
	s_addc_u32 s39, s81, 0
	v_lshrrev_b32_e32 v196, 3, v197
	v_and_b32_e32 v198, 7, v197
	v_lshlrev_b32_e32 v176, 11, v196
	v_lshl_or_b32 v176, v198, 4, v176
	v_add_u32_e32 v177, 0x10000, v176
	v_add_u32_e32 v178, 0x20000, v176
	v_add_u32_e32 v179, 0x30000, v176
	v_add_u32_e32 v180, 0x40000, v176
	v_add_u32_e32 v181, 0x50000, v176
	v_add_u32_e32 v182, 0x60000, v176
	v_add_u32_e32 v184, 0x70000, v176
	global_load_dwordx4 v[128:131], v176, s[28:29]
	global_load_dwordx4 v[132:135], v177, s[28:29]
	global_load_dwordx4 v[136:139], v178, s[28:29]
	global_load_dwordx4 v[140:143], v179, s[28:29]
	global_load_dwordx4 v[144:147], v176, s[38:39]
	global_load_dwordx4 v[148:151], v177, s[38:39]
	global_load_dwordx4 v[152:155], v178, s[38:39]
	global_load_dwordx4 v[156:159], v179, s[38:39]
	global_load_dwordx4 v[160:163], v180, s[38:39]
	global_load_dwordx4 v[164:167], v181, s[38:39]
	global_load_dwordx4 v[168:171], v182, s[38:39]
	global_load_dwordx4 v[172:175], v184, s[38:39]
	s_add_u32 s28, s28, 0x80
	s_addc_u32 s29, s29, 0
	s_add_u32 s38, s38, 0x80
	s_addc_u32 s39, s39, 0
	v_bfe_u32 v217, v197, 5, 2
	v_and_b32_e32 v218, 3, v198
	v_xor_b32_e32 v218, v218, v217
	v_lshlrev_b32_e32 v218, 4, v218
	v_lshl_or_b32 v185, v196, 6, v218
	v_lshrrev_b32_e32 v217, 2, v198
	v_lshlrev_b32_e32 v218, 6, v217
	v_xor_b32_e32 v185, v185, v218
	v_mul_u32_u24_e32 v217, 0x6000, v217
	v_add_u32_e32 v185, v185, v217
	v_and_b32_e32 v196, 31, v197
	v_bfe_u32 v198, v197, 5, 1
	v_bfe_u32 v217, v197, 2, 2
	v_xor_b32_e32 v218, v198, v217
	v_xor_b32_e32 v221, 2, v218
	v_lshrrev_b32_e32 v198, 7, v197
	v_lshl_or_b32 v198, v198, 6, v196
	v_lshlrev_b32_e32 v198, 6, v198
	v_lshl_or_b32 v186, v218, 4, v198
	v_lshl_or_b32 v187, v221, 4, v198
	v_bfe_u32 v198, v197, 6, 1
	v_mul_u32_u24_e32 v198, 128, v198
	v_add_u32_e32 v198, v198, v196
	v_lshlrev_b32_e32 v198, 6, v198
	v_add_u32_e32 v198, 0x2000, v198
	v_lshl_or_b32 v188, v218, 4, v198
	v_lshl_or_b32 v189, v221, 4, v198
	v_mov_b64_e32 v[0:1], 0
	v_mov_b64_e32 v[2:3], 0
	v_mov_b64_e32 v[4:5], 0
	v_mov_b64_e32 v[6:7], 0
	v_mov_b64_e32 v[8:9], 0
	v_mov_b64_e32 v[10:11], 0
	v_mov_b64_e32 v[12:13], 0
	v_mov_b64_e32 v[14:15], 0
	v_mov_b64_e32 v[16:17], 0
	v_mov_b64_e32 v[18:19], 0
	v_mov_b64_e32 v[20:21], 0
	v_mov_b64_e32 v[22:23], 0
	v_mov_b64_e32 v[24:25], 0
	v_mov_b64_e32 v[26:27], 0
	v_mov_b64_e32 v[28:29], 0
	v_mov_b64_e32 v[30:31], 0
	v_mov_b64_e32 v[32:33], 0
	v_mov_b64_e32 v[34:35], 0
	v_mov_b64_e32 v[36:37], 0
	v_mov_b64_e32 v[38:39], 0
	v_mov_b64_e32 v[40:41], 0
	v_mov_b64_e32 v[42:43], 0
	v_mov_b64_e32 v[44:45], 0
	v_mov_b64_e32 v[46:47], 0
	v_mov_b64_e32 v[48:49], 0
	v_mov_b64_e32 v[50:51], 0
	v_mov_b64_e32 v[52:53], 0
	v_mov_b64_e32 v[54:55], 0
	v_mov_b64_e32 v[56:57], 0
	v_mov_b64_e32 v[58:59], 0
	v_mov_b64_e32 v[60:61], 0
	v_mov_b64_e32 v[62:63], 0
	v_mov_b64_e32 v[64:65], 0
	v_mov_b64_e32 v[66:67], 0
	v_mov_b64_e32 v[68:69], 0
	v_mov_b64_e32 v[70:71], 0
	v_mov_b64_e32 v[72:73], 0
	v_mov_b64_e32 v[74:75], 0
	v_mov_b64_e32 v[76:77], 0
	v_mov_b64_e32 v[78:79], 0
	v_mov_b64_e32 v[80:81], 0
	v_mov_b64_e32 v[82:83], 0
	v_mov_b64_e32 v[84:85], 0
	v_mov_b64_e32 v[86:87], 0
	v_mov_b64_e32 v[88:89], 0
	v_mov_b64_e32 v[90:91], 0
	v_mov_b64_e32 v[92:93], 0
	v_mov_b64_e32 v[94:95], 0
	v_mov_b64_e32 v[96:97], 0
	v_mov_b64_e32 v[98:99], 0
	v_mov_b64_e32 v[100:101], 0
	v_mov_b64_e32 v[102:103], 0
	v_mov_b64_e32 v[104:105], 0
	v_mov_b64_e32 v[106:107], 0
	v_mov_b64_e32 v[108:109], 0
	v_mov_b64_e32 v[110:111], 0
	v_mov_b64_e32 v[112:113], 0
	v_mov_b64_e32 v[114:115], 0
	v_mov_b64_e32 v[116:117], 0
	v_mov_b64_e32 v[118:119], 0
	v_mov_b64_e32 v[120:121], 0
	v_mov_b64_e32 v[122:123], 0
	v_mov_b64_e32 v[124:125], 0
	v_mov_b64_e32 v[126:127], 0
	s_mov_b32 s40, 0
	s_mov_b32 s41, 0x6000
	s_mov_b32 s7, 0
	s_waitcnt vmcnt(11)
	ds_write_b128 v185, v[128:131]
	s_waitcnt vmcnt(10)
	ds_write_b128 v185, v[132:135] offset:2048
	s_waitcnt vmcnt(9)
	ds_write_b128 v185, v[136:139] offset:4096
	s_waitcnt vmcnt(8)
	ds_write_b128 v185, v[140:143] offset:6144
	s_waitcnt vmcnt(7)
	ds_write_b128 v185, v[144:147] offset:8192
	s_waitcnt vmcnt(6)
	ds_write_b128 v185, v[148:151] offset:10240
	s_waitcnt vmcnt(5)
	ds_write_b128 v185, v[152:155] offset:12288
	s_waitcnt vmcnt(4)
	ds_write_b128 v185, v[156:159] offset:14336
	s_waitcnt vmcnt(3)
	ds_write_b128 v185, v[160:163] offset:16384
	s_waitcnt vmcnt(2)
	ds_write_b128 v185, v[164:167] offset:18432
	s_waitcnt vmcnt(1)
	ds_write_b128 v185, v[168:171] offset:20480
	s_waitcnt vmcnt(0)
	ds_write_b128 v185, v[172:175] offset:22528
	v_subrev_u32_e32 v196, 0x6000, v185
	v_add_u32_e32 v198, 0xc000, v185
	v_min_u32_e32 v185, v196, v198
	s_waitcnt lgkmcnt(0)
	s_barrier
.Lg4_loop:
	v_add_u32_e32 v190, s40, v186
	v_add_u32_e32 v191, s40, v187
	v_add_u32_e32 v250, s40, v188
	v_add_u32_e32 v251, s40, v189
	ds_read_b128 v[200:203], v190
	ds_read_b128 v[204:207], v190 offset:2048
	ds_read_b128 v[222:225], v250
	ds_read_b128 v[226:229], v250 offset:2048
	ds_read_b128 v[230:233], v250 offset:4096
	ds_read_b128 v[234:237], v250 offset:6144
	s_setprio 1
	s_waitcnt lgkmcnt(3)
	v_mfma_f32_32x32x16_bf16 v[112:127], v[200:203], v[222:225], v[112:127]
	global_load_dwordx4 v[128:131], v176, s[28:29]
	ds_read_b128 v[208:211], v191
	v_mfma_f32_32x32x16_bf16 v[48:63], v[204:207], v[222:225], v[48:63]
	global_load_dwordx4 v[132:135], v177, s[28:29]
	ds_read_b128 v[212:215], v191 offset:2048
	s_waitcnt lgkmcnt(4)
	v_mfma_f32_32x32x16_bf16 v[96:111], v[200:203], v[226:229], v[96:111]
	global_load_dwordx4 v[136:139], v178, s[28:29]
	ds_read_b128 v[238:241], v251
	v_mfma_f32_32x32x16_bf16 v[32:47], v[204:207], v[226:229], v[32:47]
	global_load_dwordx4 v[140:143], v179, s[28:29]
	ds_read_b128 v[242:245], v251 offset:2048
	s_waitcnt lgkmcnt(5)
	v_mfma_f32_32x32x16_bf16 v[80:95], v[200:203], v[230:233], v[80:95]
	global_load_dwordx4 v[144:147], v176, s[38:39]
	ds_read_b128 v[246:249], v251 offset:4096
	v_mfma_f32_32x32x16_bf16 v[16:31], v[204:207], v[230:233], v[16:31]
	global_load_dwordx4 v[148:151], v177, s[38:39]
	ds_read_b128 v[192:195], v251 offset:6144
	s_waitcnt lgkmcnt(6)
	v_mfma_f32_32x32x16_bf16 v[64:79], v[200:203], v[234:237], v[64:79]
	global_load_dwordx4 v[152:155], v178, s[38:39]
	v_mfma_f32_32x32x16_bf16 v[0:15], v[204:207], v[234:237], v[0:15]
	global_load_dwordx4 v[156:159], v179, s[38:39]
	v_xad_u32 v190, v186, 64, s41
	v_xad_u32 v250, v188, 64, s41
	s_waitcnt lgkmcnt(3)
	v_mfma_f32_32x32x16_bf16 v[112:127], v[208:211], v[238:241], v[112:127]
	global_load_dwordx4 v[160:163], v180, s[38:39]
	ds_read_b128 v[200:203], v190
	v_mfma_f32_32x32x16_bf16 v[48:63], v[212:215], v[238:241], v[48:63]
	global_load_dwordx4 v[164:167], v181, s[38:39]
	ds_read_b128 v[204:207], v190 offset:2048
	s_waitcnt lgkmcnt(4)
	v_mfma_f32_32x32x16_bf16 v[96:111], v[208:211], v[242:245], v[96:111]
	global_load_dwordx4 v[168:171], v182, s[38:39]
	ds_read_b128 v[222:225], v250
	v_mfma_f32_32x32x16_bf16 v[32:47], v[212:215], v[242:245], v[32:47]
	global_load_dwordx4 v[172:175], v184, s[38:39]
	ds_read_b128 v[226:229], v250 offset:2048
	s_waitcnt lgkmcnt(5)
	v_mfma_f32_32x32x16_bf16 v[80:95], v[208:211], v[246:249], v[80:95]
	ds_read_b128 v[230:233], v250 offset:4096
	v_mfma_f32_32x32x16_bf16 v[16:31], v[212:215], v[246:249], v[16:31]
	ds_read_b128 v[234:237], v250 offset:6144
	s_waitcnt lgkmcnt(6)
	v_mfma_f32_32x32x16_bf16 v[64:79], v[208:211], v[192:195], v[64:79]
	v_mfma_f32_32x32x16_bf16 v[0:15], v[212:215], v[192:195], v[0:15]
	s_setprio 0
	s_barrier
	v_xad_u32 v191, v187, 64, s41
	v_xad_u32 v251, v189, 64, s41
	s_setprio 1
	s_waitcnt lgkmcnt(3)
	v_mfma_f32_32x32x16_bf16 v[112:127], v[200:203], v[222:225], v[112:127]
	ds_read_b128 v[208:211], v191
	v_mfma_f32_32x32x16_bf16 v[48:63], v[204:207], v[222:225], v[48:63]
	ds_read_b128 v[212:215], v191 offset:2048
	s_waitcnt lgkmcnt(4)
	v_mfma_f32_32x32x16_bf16 v[96:111], v[200:203], v[226:229], v[96:111]
	ds_read_b128 v[238:241], v251
	s_waitcnt vmcnt(11)
	ds_write_b128 v185, v[128:131]
	v_mfma_f32_32x32x16_bf16 v[32:47], v[204:207], v[226:229], v[32:47]
	ds_read_b128 v[242:245], v251 offset:2048
	s_waitcnt vmcnt(10)
	ds_write_b128 v185, v[132:135] offset:2048
	s_waitcnt lgkmcnt(7)
	v_mfma_f32_32x32x16_bf16 v[80:95], v[200:203], v[230:233], v[80:95]
	ds_read_b128 v[246:249], v251 offset:4096
	s_waitcnt vmcnt(9)
	ds_write_b128 v185, v[136:139] offset:4096
	v_mfma_f32_32x32x16_bf16 v[16:31], v[204:207], v[230:233], v[16:31]
	ds_read_b128 v[192:195], v251 offset:6144
	s_waitcnt vmcnt(8)
	ds_write_b128 v185, v[140:143] offset:6144
	s_waitcnt lgkmcnt(10)
	v_mfma_f32_32x32x16_bf16 v[64:79], v[200:203], v[234:237], v[64:79]
	s_waitcnt vmcnt(7)
	ds_write_b128 v185, v[144:147] offset:8192
	v_mfma_f32_32x32x16_bf16 v[0:15], v[204:207], v[234:237], v[0:15]
	s_waitcnt vmcnt(6)
	ds_write_b128 v185, v[148:151] offset:10240
	s_waitcnt lgkmcnt(9)
	v_mfma_f32_32x32x16_bf16 v[112:127], v[208:211], v[238:241], v[112:127]
	s_waitcnt vmcnt(5)
	ds_write_b128 v185, v[152:155] offset:12288
	v_mfma_f32_32x32x16_bf16 v[48:63], v[212:215], v[238:241], v[48:63]
	s_waitcnt vmcnt(4)
	ds_write_b128 v185, v[156:159] offset:14336
	s_waitcnt lgkmcnt(9)
	v_mfma_f32_32x32x16_bf16 v[96:111], v[208:211], v[242:245], v[96:111]
	s_waitcnt vmcnt(3)
	ds_write_b128 v185, v[160:163] offset:16384
	v_mfma_f32_32x32x16_bf16 v[32:47], v[212:215], v[242:245], v[32:47]
	s_waitcnt vmcnt(2)
	ds_write_b128 v185, v[164:167] offset:18432
	s_waitcnt lgkmcnt(9)
	v_mfma_f32_32x32x16_bf16 v[80:95], v[208:211], v[246:249], v[80:95]
	s_waitcnt vmcnt(1)
	ds_write_b128 v185, v[168:171] offset:20480
	v_mfma_f32_32x32x16_bf16 v[16:31], v[212:215], v[246:249], v[16:31]
	s_waitcnt vmcnt(0)
	ds_write_b128 v185, v[172:175] offset:22528
	s_waitcnt lgkmcnt(9)
	v_mfma_f32_32x32x16_bf16 v[64:79], v[208:211], v[192:195], v[64:79]
	v_mfma_f32_32x32x16_bf16 v[0:15], v[212:215], v[192:195], v[0:15]
	s_setprio 0
	s_add_u32 s28, s28, 0x80
	s_addc_u32 s29, s29, 0
	s_add_u32 s38, s38, 0x80
	s_addc_u32 s39, s39, 0
	s_sub_i32 s40, s40, 0x6000
	s_cmp_lt_i32 s40, 0
	s_cselect_b32 s42, 0x12000, 0
	s_add_i32 s40, s40, s42
	s_sub_i32 s41, s41, 0x6000
	s_cmp_lt_i32 s41, 0
	s_cselect_b32 s42, 0x12000, 0
	s_add_i32 s41, s41, s42
	v_subrev_u32_e32 v196, 0x6000, v185
	v_add_u32_e32 v198, 0xc000, v185
	v_min_u32_e32 v185, v196, v198
	s_add_i32 s7, s7, 1
	s_cmp_lt_u32 s7, 15
	s_waitcnt lgkmcnt(0)
	s_barrier
	s_cbranch_scc1 .Lg4_loop
	v_add_u32_e32 v190, s40, v186
	v_add_u32_e32 v191, s40, v187
	v_add_u32_e32 v250, s40, v188
	v_add_u32_e32 v251, s40, v189
	ds_read_b128 v[200:203], v190
	ds_read_b128 v[204:207], v190 offset:2048
	ds_read_b128 v[222:225], v250
	ds_read_b128 v[226:229], v250 offset:2048
	ds_read_b128 v[230:233], v250 offset:4096
	ds_read_b128 v[234:237], v250 offset:6144
	s_setprio 1
	s_waitcnt lgkmcnt(3)
	v_mfma_f32_32x32x16_bf16 v[112:127], v[200:203], v[222:225], v[112:127]
	ds_read_b128 v[208:211], v191
	v_mfma_f32_32x32x16_bf16 v[48:63], v[204:207], v[222:225], v[48:63]
	ds_read_b128 v[212:215], v191 offset:2048
	s_waitcnt lgkmcnt(4)
	v_mfma_f32_32x32x16_bf16 v[96:111], v[200:203], v[226:229], v[96:111]
	ds_read_b128 v[238:241], v251
	v_mfma_f32_32x32x16_bf16 v[32:47], v[204:207], v[226:229], v[32:47]
	ds_read_b128 v[242:245], v251 offset:2048
	s_waitcnt lgkmcnt(5)
	v_mfma_f32_32x32x16_bf16 v[80:95], v[200:203], v[230:233], v[80:95]
	ds_read_b128 v[246:249], v251 offset:4096
	v_mfma_f32_32x32x16_bf16 v[16:31], v[204:207], v[230:233], v[16:31]
	ds_read_b128 v[192:195], v251 offset:6144
	s_waitcnt lgkmcnt(6)
	v_mfma_f32_32x32x16_bf16 v[64:79], v[200:203], v[234:237], v[64:79]
	v_mfma_f32_32x32x16_bf16 v[0:15], v[204:207], v[234:237], v[0:15]
	v_xad_u32 v190, v186, 64, s41
	v_xad_u32 v250, v188, 64, s41
	s_waitcnt lgkmcnt(3)
	v_mfma_f32_32x32x16_bf16 v[112:127], v[208:211], v[238:241], v[112:127]
	ds_read_b128 v[200:203], v190
	v_mfma_f32_32x32x16_bf16 v[48:63], v[212:215], v[238:241], v[48:63]
	ds_read_b128 v[204:207], v190 offset:2048
	s_waitcnt lgkmcnt(4)
	v_mfma_f32_32x32x16_bf16 v[96:111], v[208:211], v[242:245], v[96:111]
	ds_read_b128 v[222:225], v250
	v_mfma_f32_32x32x16_bf16 v[32:47], v[212:215], v[242:245], v[32:47]
	ds_read_b128 v[226:229], v250 offset:2048
	s_waitcnt lgkmcnt(5)
	v_mfma_f32_32x32x16_bf16 v[80:95], v[208:211], v[246:249], v[80:95]
	ds_read_b128 v[230:233], v250 offset:4096
	v_mfma_f32_32x32x16_bf16 v[16:31], v[212:215], v[246:249], v[16:31]
	ds_read_b128 v[234:237], v250 offset:6144
	s_waitcnt lgkmcnt(6)
	v_mfma_f32_32x32x16_bf16 v[64:79], v[208:211], v[192:195], v[64:79]
	v_mfma_f32_32x32x16_bf16 v[0:15], v[212:215], v[192:195], v[0:15]
	s_setprio 0
	v_xad_u32 v191, v187, 64, s41
	v_xad_u32 v251, v189, 64, s41
	s_setprio 1
	s_waitcnt lgkmcnt(3)
	v_mfma_f32_32x32x16_bf16 v[112:127], v[200:203], v[222:225], v[112:127]
	ds_read_b128 v[208:211], v191
	v_mfma_f32_32x32x16_bf16 v[48:63], v[204:207], v[222:225], v[48:63]
	ds_read_b128 v[212:215], v191 offset:2048
	s_waitcnt lgkmcnt(4)
	v_mfma_f32_32x32x16_bf16 v[96:111], v[200:203], v[226:229], v[96:111]
	ds_read_b128 v[238:241], v251
	v_mfma_f32_32x32x16_bf16 v[32:47], v[204:207], v[226:229], v[32:47]
	ds_read_b128 v[242:245], v251 offset:2048
	s_waitcnt lgkmcnt(5)
	v_mfma_f32_32x32x16_bf16 v[80:95], v[200:203], v[230:233], v[80:95]
	ds_read_b128 v[246:249], v251 offset:4096
	v_mfma_f32_32x32x16_bf16 v[16:31], v[204:207], v[230:233], v[16:31]
	ds_read_b128 v[192:195], v251 offset:6144
	s_waitcnt lgkmcnt(6)
	v_mfma_f32_32x32x16_bf16 v[64:79], v[200:203], v[234:237], v[64:79]
	v_mfma_f32_32x32x16_bf16 v[0:15], v[204:207], v[234:237], v[0:15]
	s_waitcnt lgkmcnt(3)
	v_mfma_f32_32x32x16_bf16 v[112:127], v[208:211], v[238:241], v[112:127]
	v_mfma_f32_32x32x16_bf16 v[48:63], v[212:215], v[238:241], v[48:63]
	s_waitcnt lgkmcnt(2)
	v_mfma_f32_32x32x16_bf16 v[96:111], v[208:211], v[242:245], v[96:111]
	v_mfma_f32_32x32x16_bf16 v[32:47], v[212:215], v[242:245], v[32:47]
	s_waitcnt lgkmcnt(1)
	v_mfma_f32_32x32x16_bf16 v[80:95], v[208:211], v[246:249], v[80:95]
	v_mfma_f32_32x32x16_bf16 v[16:31], v[212:215], v[246:249], v[16:31]
	s_waitcnt lgkmcnt(0)
	v_mfma_f32_32x32x16_bf16 v[64:79], v[208:211], v[192:195], v[64:79]
	v_mfma_f32_32x32x16_bf16 v[0:15], v[212:215], v[192:195], v[0:15]
	s_setprio 0
	s_nop 7
	s_nop 7

.LBB0_424:
	s_or_b64 exec, exec, s[48:49]
	s_lshl_b32 s0, s9, 7
	s_add_u32 s1, s66, s8
	s_addc_u32 s8, s67, 0
	s_lshl_b32 s9, s0, 1
	s_add_u32 s48, s1, s9
	s_addc_u32 s49, s8, 0
	s_or_b32 s68, s0, s68
	s_lshl_b32 s0, s7, 2
	s_add_i32 s39, s0, 0
	s_add_i32 s39, s39, 0x12200
	s_lshl_b32 s0, s6, 2
	v_readlane_b32 s1, v253, 62
	s_add_u32 s26, s1, s0
	v_readlane_b32 s0, v253, 63
	s_addc_u32 s27, s0, 0
	v_mov_b32_e32 v134, v130
	s_add_u32 s28, s48, s28
	s_waitcnt lgkmcnt(0)
	s_barrier
	s_addc_u32 s29, s49, s29
	v_ashrrev_i32_e32 v135, 31, v134
	v_lshl_add_u64 v[134:135], v[134:135], 1, s[28:29]
	global_load_ushort v137, v[134:135], off offset:64
	s_waitcnt vmcnt(8)
	v_lshlrev_b32_e32 v147, 16, v166
	v_add_co_u32_e64 v144, s[0:1], s96, v134
	v_lshlrev_b32_e32 v187, 16, v165
	s_nop 0
	v_addc_co_u32_e64 v145, s[0:1], 0, v135, s[0:1]
	v_lshlrev_b32_e32 v186, 16, v164
	v_lshlrev_b32_e32 v185, 16, v163
	v_lshlrev_b32_e32 v184, 16, v162
	v_lshlrev_b32_e32 v175, 16, v159
	v_lshlrev_b32_e32 v183, 16, v161
	v_lshlrev_b32_e32 v182, 16, v160
	s_waitcnt vmcnt(7)
	v_lshlrev_b32_e32 v146, 16, v167
	v_mov_b32_e32 v167, v158
	s_waitcnt vmcnt(6)
	v_lshlrev_b32_e32 v142, 16, v168
	s_waitcnt vmcnt(5)
	v_lshlrev_b32_e32 v140, 16, v169
	s_waitcnt vmcnt(4)
	v_lshlrev_b32_e32 v139, 16, v170
	s_waitcnt vmcnt(3)
	v_lshlrev_b32_e32 v136, 16, v171
	v_lshlrev_b32_e32 v174, 16, v131
	s_waitcnt vmcnt(1)
	v_lshlrev_b32_e32 v129, 16, v173
	v_lshlrev_b32_e32 v131, 16, v172
	s_waitcnt vmcnt(0)
	v_lshlrev_b32_e32 v166, 16, v137
	global_load_ushort v165, v[134:135], off offset:2112
	s_waitcnt vmcnt(1)
	global_load_ushort v164, v[144:145], off offset:64
	s_waitcnt vmcnt(2)
	global_load_ushort v163, v[144:145], off offset:2112
	v_add_co_u32_e64 v144, s[0:1], s94, v134
	s_waitcnt vmcnt(3)
	v_addc_co_u32_e64 v145, s[0:1], 0, v135, s[0:1]
	global_load_ushort v162, v[144:145], off offset:64
	s_waitcnt vmcnt(4)
	global_load_ushort v159, v[144:145], off offset:2112
	v_add_co_u32_e64 v144, s[0:1], s57, v134
	s_waitcnt vmcnt(5)
	v_addc_co_u32_e64 v145, s[0:1], 0, v135, s[0:1]
	global_load_ushort v161, v[144:145], off offset:64
	s_waitcnt vmcnt(6)
	global_load_ushort v160, v[144:145], off offset:2112
	v_add_co_u32_e64 v144, s[0:1], s35, v134
	s_waitcnt vmcnt(7)
	v_addc_co_u32_e64 v145, s[0:1], 0, v135, s[0:1]
	global_load_ushort v150, v[144:145], off offset:64
	v_add_co_u32_e64 v148, s[0:1], s58, v134
	s_waitcnt vmcnt(8)
	global_load_ushort v137, v[144:145], off offset:2112
	v_addc_co_u32_e64 v149, s[0:1], 0, v135, s[0:1]
	s_waitcnt vmcnt(0)
	v_lshlrev_b32_e32 v144, 16, v137
	global_load_ushort v151, v[148:149], off offset:64
	s_waitcnt vmcnt(1)
	global_load_ushort v145, v[148:149], off offset:2112
	v_add_co_u32_e64 v148, s[0:1], s95, v134
	s_waitcnt vmcnt(2)
	v_addc_co_u32_e64 v149, s[0:1], 0, v135, s[0:1]
	global_load_ushort v137, v[148:149], off offset:64
	v_add_co_u32_e64 v134, s[0:1], s59, v134
	s_nop 1
	v_addc_co_u32_e64 v135, s[0:1], 0, v135, s[0:1]
	global_load_ushort v138, v[134:135], off offset:64
	s_waitcnt vmcnt(1)
	v_lshlrev_b32_e32 v143, 16, v137
	global_load_ushort v137, v[148:149], off offset:2112
	s_waitcnt vmcnt(1)
	v_lshlrev_b32_e32 v141, 16, v138
	global_load_ushort v134, v[134:135], off offset:2112
	s_waitcnt vmcnt(1)
	v_lshlrev_b32_e32 v137, 16, v137
	s_waitcnt vmcnt(0)
	v_lshlrev_b32_e32 v138, 16, v134
	v_mov_b32_e32 v134, v128
	s_nop 0
	v_add_u32_e32 v134, s68, v134
	v_ashrrev_i32_e32 v135, 31, v134
	v_lshl_add_u64 v[148:149], v[134:135], 2, s[36:37]
	global_load_dword v188, v[148:149], off
	v_lshl_add_u32 v148, v167, 2, s38
	v_lshl_add_u32 v167, v167, 4, s39
	ds_read_b128 v[168:171], v167
	ds_read_b128 v[178:181], v167 offset:32
	v_ashrrev_i32_e32 v149, 31, v148
	v_lshlrev_b64 v[148:149], 11, v[148:149]
	v_lshl_add_u64 v[148:149], s[66:67], 0, v[148:149]
	s_waitcnt lgkmcnt(1)
	v_mul_f32_e32 v112, v112, v168
	v_lshl_add_u64 v[134:135], v[134:135], 1, v[148:149]
	s_waitcnt vmcnt(0)
	v_fmac_f32_e32 v174, v188, v112
	v_cvt_pk_bf16_f32 v112, v174, s0
	v_lshlrev_b32_e32 v177, 16, v112
	global_store_short v[134:135], v112, off
	v_mul_f32_e32 v112, v113, v169
	v_fmac_f32_e32 v175, v188, v112
	v_cvt_pk_bf16_f32 v112, v175, s0
	v_lshlrev_b32_e32 v176, 16, v112
	global_store_short v[134:135], v112, off offset:2048
	v_mul_f32_e32 v112, v114, v170
	v_fmac_f32_e32 v182, v188, v112
	v_cvt_pk_bf16_f32 v114, v182, s0
	v_add_co_u32_e64 v112, s[0:1], s96, v134
	v_lshlrev_b32_e32 v175, 16, v114
	s_nop 0
	v_addc_co_u32_e64 v113, s[0:1], 0, v135, s[0:1]
	global_store_short v[112:113], v114, off
	v_mul_f32_e32 v114, v115, v171
	v_fmac_f32_e32 v183, v188, v114
	v_cvt_pk_bf16_f32 v114, v183, s0
	global_store_short v[112:113], v114, off offset:2048
	s_waitcnt lgkmcnt(0)
	v_mul_f32_e32 v112, v116, v178
	v_fmac_f32_e32 v184, v188, v112
	v_cvt_pk_bf16_f32 v116, v184, s0
	v_add_co_u32_e64 v112, s[0:1], s94, v134
	v_lshlrev_b32_e32 v174, 16, v114
	s_nop 0
	v_addc_co_u32_e64 v113, s[0:1], 0, v135, s[0:1]
	v_add_co_u32_e64 v114, s[0:1], s57, v134
	v_lshlrev_b32_e32 v173, 16, v116
	s_nop 0
	v_addc_co_u32_e64 v115, s[0:1], 0, v135, s[0:1]
	global_store_short v[114:115], v116, off offset:-4096
	v_mul_f32_e32 v116, v117, v179
	v_fmac_f32_e32 v185, v188, v116
	v_cvt_pk_bf16_f32 v117, v185, s0
	global_store_short v[112:113], v117, off offset:2048
	v_mul_f32_e32 v112, v118, v180
	v_fmac_f32_e32 v186, v188, v112
	v_cvt_pk_bf16_f32 v112, v186, s0
	v_lshlrev_b32_e32 v172, 16, v112
	global_store_short v[114:115], v112, off
	v_mul_f32_e32 v112, v119, v181
	v_fmac_f32_e32 v187, v188, v112
	v_cvt_pk_bf16_f32 v112, v187, s0
	v_lshlrev_b32_e32 v116, 16, v117
	v_lshlrev_b32_e32 v117, 16, v112
	global_store_short v[114:115], v112, off offset:2048
	ds_read_b128 v[112:115], v167 offset:64
	s_waitcnt lgkmcnt(0)
	v_mul_f32_e32 v112, v120, v112
	v_fmac_f32_e32 v147, v188, v112
	v_cvt_pk_bf16_f32 v112, v147, s0
	v_add_co_u32_e64 v118, s[0:1], s35, v134
	v_lshlrev_b32_e32 v170, 16, v112
	s_nop 0
	v_addc_co_u32_e64 v119, s[0:1], 0, v135, s[0:1]
	v_add_co_u32_e64 v148, s[0:1], s58, v134
	s_nop 1
	v_addc_co_u32_e64 v149, s[0:1], 0, v135, s[0:1]
	global_store_short v[148:149], v112, off offset:-4096
	v_mul_f32_e32 v112, v121, v113
	v_fmac_f32_e32 v146, v188, v112
	v_cvt_pk_bf16_f32 v112, v146, s0
	v_lshlrev_b32_e32 v171, 16, v112
	global_store_short v[118:119], v112, off offset:2048
	v_mul_f32_e32 v112, v122, v114
	v_fmac_f32_e32 v142, v188, v112
	v_cvt_pk_bf16_f32 v112, v142, s0
	v_lshlrev_b32_e32 v169, 16, v112
	global_store_short v[148:149], v112, off
	v_mul_f32_e32 v112, v123, v115
	v_fmac_f32_e32 v140, v188, v112
	v_cvt_pk_bf16_f32 v112, v140, s0
	v_lshlrev_b32_e32 v168, 16, v112
	global_store_short v[148:149], v112, off offset:2048
	ds_read_b128 v[112:115], v167 offset:96
	s_waitcnt lgkmcnt(0)
	v_mul_f32_e32 v112, v124, v112
	v_fmac_f32_e32 v139, v188, v112
	v_cvt_pk_bf16_f32 v112, v139, s0
	v_add_co_u32_e64 v118, s[0:1], s95, v134
	v_lshlrev_b32_e32 v167, 16, v112
	s_nop 0
	v_addc_co_u32_e64 v119, s[0:1], 0, v135, s[0:1]
	v_add_co_u32_e64 v120, s[0:1], s59, v134
	s_nop 1
	v_addc_co_u32_e64 v121, s[0:1], 0, v135, s[0:1]
	global_store_short v[120:121], v112, off offset:-4096
	v_mul_f32_e32 v112, v125, v113
	v_fmac_f32_e32 v136, v188, v112
	v_cvt_pk_bf16_f32 v112, v136, s0
	v_lshlrev_b32_e32 v124, 16, v112
	global_store_short v[118:119], v112, off offset:2048
	v_mul_f32_e32 v112, v126, v114
	v_fmac_f32_e32 v131, v188, v112
	v_cvt_pk_bf16_f32 v112, v131, s0
	v_lshlrev_b32_e32 v123, 16, v112
	global_store_short v[120:121], v112, off
	v_mul_f32_e32 v112, v127, v115
	v_fmac_f32_e32 v129, v188, v112
	v_cvt_pk_bf16_f32 v112, v129, s0
	v_lshlrev_b32_e32 v122, 16, v112
	global_store_short v[120:121], v112, off offset:2048
	v_mov_b32_e32 v112, v130
	v_mov_b32_e32 v127, v158
	v_ashrrev_i32_e32 v113, 31, v112
	v_lshl_add_u64 v[112:113], v[112:113], 1, s[28:29]
	global_load_ushort v149, v[112:113], off offset:128
	s_waitcnt vmcnt(17)
	global_load_ushort v147, v[112:113], off offset:2176
	s_waitcnt vmcnt(18)
	v_add_co_u32_e64 v114, s[0:1], s96, v112
	s_nop 1
	v_addc_co_u32_e64 v115, s[0:1], 0, v113, s[0:1]
	global_load_ushort v148, v[114:115], off offset:128
	s_waitcnt vmcnt(19)
	global_load_ushort v139, v[114:115], off offset:2176
	s_waitcnt vmcnt(20)
	v_add_co_u32_e64 v114, s[0:1], s94, v112
	s_nop 1
	v_addc_co_u32_e64 v115, s[0:1], 0, v113, s[0:1]
	global_load_ushort v142, v[114:115], off offset:128
	s_waitcnt vmcnt(21)
	global_load_ushort v136, v[114:115], off offset:2176
	s_waitcnt vmcnt(22)
	v_add_co_u32_e64 v114, s[0:1], s57, v112
	s_nop 1
	v_addc_co_u32_e64 v115, s[0:1], 0, v113, s[0:1]
	global_load_ushort v146, v[114:115], off offset:128
	s_waitcnt vmcnt(23)
	global_load_ushort v140, v[114:115], off offset:2176
	s_waitcnt vmcnt(24)
	v_add_co_u32_e64 v114, s[0:1], s35, v112
	s_nop 1
	v_addc_co_u32_e64 v115, s[0:1], 0, v113, s[0:1]
	global_load_ushort v129, v[114:115], off offset:128
	s_waitcnt vmcnt(25)
	global_load_ushort v125, v[114:115], off offset:2176
	s_waitcnt vmcnt(26)
	v_add_co_u32_e64 v114, s[0:1], s58, v112
	s_nop 1
	v_addc_co_u32_e64 v115, s[0:1], 0, v113, s[0:1]
	global_load_ushort v135, v[114:115], off offset:128
	s_waitcnt vmcnt(27)
	global_load_ushort v131, v[114:115], off offset:2176
	s_waitcnt vmcnt(28)
	v_add_co_u32_e64 v114, s[0:1], s95, v112
	s_nop 1
	v_addc_co_u32_e64 v115, s[0:1], 0, v113, s[0:1]
	global_load_ushort v118, v[114:115], off offset:128
	v_add_co_u32_e64 v112, s[0:1], s59, v112
	global_load_ushort v114, v[114:115], off offset:2176
	s_nop 0
	v_addc_co_u32_e64 v113, s[0:1], 0, v113, s[0:1]
	s_waitcnt vmcnt(1)
	v_lshlrev_b32_e32 v120, 16, v118
	s_waitcnt vmcnt(0)
	v_lshlrev_b32_e32 v118, 16, v114
	global_load_ushort v121, v[112:113], off offset:128
	s_waitcnt vmcnt(1)
	global_load_ushort v119, v[112:113], off offset:2176
	s_waitcnt vmcnt(2)
	v_mov_b32_e32 v112, v128
	s_nop 0
	v_ashrrev_i32_e32 v113, 31, v112
	v_lshl_add_u64 v[112:113], v[112:113], 0, s[68:69]
	v_lshl_add_u64 v[114:115], v[112:113], 2, s[36:37]
	global_load_dword v126, v[114:115], off offset:128
	v_lshl_add_u32 v114, v127, 2, s38
	v_lshl_add_u32 v127, v127, 4, s39
	ds_read_b128 v[178:181], v127
	ds_read_b128 v[182:185], v127 offset:32
	v_ashrrev_i32_e32 v115, 31, v114
	v_lshlrev_b64 v[114:115], 11, v[114:115]
	v_lshl_add_u64 v[114:115], s[66:67], 0, v[114:115]
	s_waitcnt lgkmcnt(1)
	v_mul_f32_e32 v96, v96, v178
	v_lshl_add_u64 v[112:113], v[112:113], 1, v[114:115]
	v_mul_f32_e32 v99, v99, v181
	s_waitcnt lgkmcnt(0)
	v_mul_f32_e32 v101, v101, v183
	s_waitcnt vmcnt(0)
	v_fmac_f32_e32 v166, v126, v96
	v_cvt_pk_bf16_f32 v96, v166, s0
	v_lshlrev_b32_e32 v114, 16, v96
	global_store_short v[112:113], v96, off offset:64
	v_mul_f32_e32 v96, v97, v179
	s_waitcnt vmcnt(49)
	v_lshlrev_b32_e32 v165, 16, v165
	v_fmac_f32_e32 v165, v126, v96
	v_cvt_pk_bf16_f32 v96, v165, s0
	v_lshlrev_b32_e32 v97, 16, v96
	global_store_short v[112:113], v96, off offset:2112
	v_mul_f32_e32 v96, v98, v180
	s_waitcnt vmcnt(49)
	v_lshlrev_b32_e32 v164, 16, v164
	v_fmac_f32_e32 v164, v126, v96
	v_cvt_pk_bf16_f32 v98, v164, s0
	v_add_co_u32_e64 v96, s[0:1], s96, v112
	v_mul_f32_e32 v115, v97, v97
	s_nop 0
	v_addc_co_u32_e64 v97, s[0:1], 0, v113, s[0:1]
	s_waitcnt vmcnt(48)
	v_lshlrev_b32_e32 v163, 16, v163
	v_fmac_f32_e32 v163, v126, v99
	s_nop 0
	v_cvt_pk_bf16_f32 v99, v163, s0
	global_store_short v[96:97], v98, off offset:64
	global_store_short v[96:97], v99, off offset:2112
	v_mul_f32_e32 v96, v100, v182
	s_waitcnt vmcnt(49)
	v_lshlrev_b32_e32 v162, 16, v162
	v_fmac_f32_e32 v162, v126, v96
	v_cvt_pk_bf16_f32 v100, v162, s0
	v_add_co_u32_e64 v96, s[0:1], s94, v112
	s_waitcnt vmcnt(48)
	v_lshlrev_b32_e32 v159, 16, v159
	v_fmac_f32_e32 v159, v126, v101
	s_nop 0
	v_addc_co_u32_e64 v97, s[0:1], 0, v113, s[0:1]
	v_lshlrev_b32_e32 v134, 16, v98
	s_nop 0
	v_cvt_pk_bf16_f32 v101, v159, s0
	v_mul_f32_e32 v98, v134, v134
	v_lshlrev_b32_e32 v134, 16, v99
	global_store_short v[96:97], v100, off offset:64
	global_store_short v[96:97], v101, off offset:2112
	v_mul_f32_e32 v96, v102, v184
	v_mul_f32_e32 v99, v134, v134
	v_lshlrev_b32_e32 v134, 16, v100
	s_waitcnt vmcnt(49)
	v_lshlrev_b32_e32 v161, 16, v161
	v_fmac_f32_e32 v161, v126, v96
	v_mul_f32_e32 v100, v134, v134
	v_lshlrev_b32_e32 v134, 16, v101
	v_cvt_pk_bf16_f32 v102, v161, s0
	v_add_co_u32_e64 v96, s[0:1], s57, v112
	v_mul_f32_e32 v101, v134, v134
	s_nop 0
	v_addc_co_u32_e64 v97, s[0:1], 0, v113, s[0:1]
	v_fmac_f32_e32 v101, v116, v116
	v_lshlrev_b32_e32 v116, 16, v102
	global_store_short v[96:97], v102, off offset:64
	v_mul_f32_e32 v102, v103, v185
	s_waitcnt vmcnt(49)
	v_lshlrev_b32_e32 v160, 16, v160
	v_fmac_f32_e32 v160, v126, v102
	v_cvt_pk_bf16_f32 v102, v160, s0
	ds_read_b128 v[160:163], v127 offset:64
	global_store_short v[96:97], v102, off offset:2112
	v_lshlrev_b32_e32 v103, 16, v102
	v_mul_f32_e32 v102, v103, v103
	v_fmac_f32_e32 v102, v117, v117
	s_waitcnt lgkmcnt(0)
	v_mul_f32_e32 v96, v104, v160
	s_waitcnt vmcnt(49)
	v_lshlrev_b32_e32 v150, 16, v150
	v_fmac_f32_e32 v150, v126, v96
	v_cvt_pk_bf16_f32 v103, v150, s0
	v_add_co_u32_e64 v96, s[0:1], s35, v112
	v_lshlrev_b32_e32 v104, 16, v103
	s_nop 0
	v_addc_co_u32_e64 v97, s[0:1], 0, v113, s[0:1]
	global_store_short v[96:97], v103, off offset:64
	v_mul_f32_e32 v103, v105, v161
	v_fmac_f32_e32 v144, v126, v103
	v_cvt_pk_bf16_f32 v103, v144, s0
	global_store_short v[96:97], v103, off offset:2112
	v_mul_f32_e32 v96, v106, v162
	s_waitcnt vmcnt(49)
	v_lshlrev_b32_e32 v151, 16, v151
	v_fmac_f32_e32 v151, v126, v96
	v_mul_f32_e32 v117, v104, v104
	v_lshlrev_b32_e32 v104, 16, v103
	v_cvt_pk_bf16_f32 v103, v151, s0
	v_add_co_u32_e64 v96, s[0:1], s58, v112
	v_mul_f32_e32 v105, v104, v104
	s_nop 0
	v_addc_co_u32_e64 v97, s[0:1], 0, v113, s[0:1]
	v_lshlrev_b32_e32 v104, 16, v103
	global_store_short v[96:97], v103, off offset:64
	v_mul_f32_e32 v103, v107, v163
	ds_read_b128 v[160:163], v127 offset:96
	s_waitcnt vmcnt(49)
	v_lshlrev_b32_e32 v145, 16, v145
	v_fmac_f32_e32 v145, v126, v103
	v_cvt_pk_bf16_f32 v103, v145, s0
	global_store_short v[96:97], v103, off offset:2112
	v_lshlrev_b32_e32 v106, 16, v103
	s_waitcnt lgkmcnt(0)
	v_mul_f32_e32 v96, v108, v160
	v_fmac_f32_e32 v143, v126, v96
	v_mul_f32_e32 v103, v106, v106
	v_cvt_pk_bf16_f32 v106, v143, s0
	v_add_co_u32_e64 v96, s[0:1], s95, v112
	v_lshlrev_b32_e32 v107, 16, v106
	s_nop 0
	v_addc_co_u32_e64 v97, s[0:1], 0, v113, s[0:1]
	global_store_short v[96:97], v106, off offset:64
	v_mul_f32_e32 v106, v107, v107
	v_mul_f32_e32 v107, v109, v161
	v_fmac_f32_e32 v137, v126, v107
	v_cvt_pk_bf16_f32 v107, v137, s0
	global_store_short v[96:97], v107, off offset:2112
	v_mul_f32_e32 v96, v110, v162
	v_lshlrev_b32_e32 v108, 16, v107
	v_fmac_f32_e32 v141, v126, v96
	v_mul_f32_e32 v107, v108, v108
	v_cvt_pk_bf16_f32 v108, v141, s0
	v_add_co_u32_e64 v96, s[0:1], s59, v112
	v_lshlrev_b32_e32 v109, 16, v108
	s_nop 0
	v_addc_co_u32_e64 v97, s[0:1], 0, v113, s[0:1]
	global_store_short v[96:97], v108, off offset:64
	v_mul_f32_e32 v108, v109, v109
	v_mul_f32_e32 v109, v111, v163
	v_fmac_f32_e32 v138, v126, v109
	v_cvt_pk_bf16_f32 v109, v138, s0
	global_store_short v[96:97], v109, off offset:2112
	v_mov_b32_e32 v96, v130
	v_lshlrev_b32_e32 v110, 16, v109
	v_ashrrev_i32_e32 v97, 31, v96
	v_lshl_add_u64 v[96:97], v[96:97], 1, s[28:29]
	v_mul_f32_e32 v109, v110, v110
	global_load_ushort v110, v[96:97], off offset:192
	v_fmac_f32_e32 v108, v123, v123
	v_fmac_f32_e32 v109, v122, v122
	v_fmac_f32_e32 v107, v124, v124
	v_mov_b32_e32 v159, v158
	v_fmac_f32_e32 v106, v167, v167
	v_fmac_f32_e32 v115, v176, v176
	v_fmac_f32_e32 v99, v174, v174
	v_fmac_f32_e32 v100, v173, v173
	v_mul_f32_e32 v116, v116, v116
	v_fmac_f32_e32 v116, v172, v172
	v_fmac_f32_e32 v105, v171, v171
	v_fmac_f32_e32 v103, v168, v168
	v_mul_f32_e32 v104, v104, v104
	v_fmac_f32_e32 v104, v169, v169
	v_fmac_f32_e32 v117, v170, v170
	s_or_b32 s28, s38, 32
	s_ashr_i32 s29, s28, 31
	v_mul_f32_e32 v114, v114, v114
	v_fmac_f32_e32 v114, v177, v177
	v_fmac_f32_e32 v98, v175, v175
	s_waitcnt vmcnt(0)
	v_lshlrev_b32_e32 v123, 16, v110
	global_load_ushort v122, v[96:97], off offset:2240
	s_waitcnt vmcnt(1)
	v_add_co_u32_e64 v110, s[0:1], s96, v96
	s_nop 1
	v_addc_co_u32_e64 v111, s[0:1], 0, v97, s[0:1]
	global_load_ushort v126, v[110:111], off offset:192
	s_waitcnt vmcnt(2)
	global_load_ushort v124, v[110:111], off offset:2240
	s_waitcnt vmcnt(3)
	v_add_co_u32_e64 v110, s[0:1], s94, v96
	s_nop 1
	v_addc_co_u32_e64 v111, s[0:1], 0, v97, s[0:1]
	global_load_ushort v134, v[110:111], off offset:192
	s_waitcnt vmcnt(4)
	global_load_ushort v127, v[110:111], off offset:2240
	s_waitcnt vmcnt(5)
	v_add_co_u32_e64 v110, s[0:1], s57, v96
	s_nop 1
	v_addc_co_u32_e64 v111, s[0:1], 0, v97, s[0:1]
	global_load_ushort v145, v[110:111], off offset:192
	s_waitcnt vmcnt(6)
	global_load_ushort v143, v[110:111], off offset:2240
	s_waitcnt vmcnt(7)
	v_add_co_u32_e64 v110, s[0:1], s35, v96
	s_nop 1
	v_addc_co_u32_e64 v111, s[0:1], 0, v97, s[0:1]
	global_load_ushort v138, v[110:111], off offset:192
	s_waitcnt vmcnt(8)
	global_load_ushort v137, v[110:111], off offset:2240
	s_waitcnt vmcnt(9)
	v_add_co_u32_e64 v110, s[0:1], s58, v96
	s_nop 1
	v_addc_co_u32_e64 v111, s[0:1], 0, v97, s[0:1]
	global_load_ushort v144, v[110:111], off offset:192
	s_waitcnt vmcnt(10)
	global_load_ushort v141, v[110:111], off offset:2240
	v_add_co_u32_e64 v112, s[0:1], s95, v96
	s_waitcnt vmcnt(11)
	v_addc_co_u32_e64 v113, s[0:1], 0, v97, s[0:1]
	global_load_ushort v111, v[112:113], off offset:192
	v_add_co_u32_e64 v96, s[0:1], s59, v96
	s_waitcnt vmcnt(12)
	v_addc_co_u32_e64 v97, s[0:1], 0, v97, s[0:1]
	global_load_ushort v110, v[112:113], off offset:2240
	s_waitcnt vmcnt(13)
	global_load_ushort v113, v[96:97], off offset:192
	s_waitcnt vmcnt(14)
	global_load_ushort v112, v[96:97], off offset:2240
	s_waitcnt vmcnt(15)
	v_mov_b32_e32 v96, v128
	s_nop 0
	v_ashrrev_i32_e32 v97, 31, v96
	v_lshl_add_u64 v[96:97], v[96:97], 0, s[68:69]
	v_lshl_add_u64 v[150:151], v[96:97], 2, s[36:37]
	global_load_dword v150, v[150:151], off offset:256
	v_lshl_add_u32 v160, v159, 2, s38
	v_ashrrev_i32_e32 v161, 31, v160
	v_lshlrev_b64 v[160:161], 11, v[160:161]
	v_lshl_add_u64 v[160:161], s[66:67], 0, v[160:161]
	v_lshl_add_u32 v151, v159, 4, s39
	v_lshl_add_u64 v[96:97], v[96:97], 1, v[160:161]
	ds_read_b128 v[160:163], v151
	ds_read_b128 v[164:167], v151 offset:32
	s_waitcnt lgkmcnt(1)
	v_mul_f32_e32 v80, v80, v160
	s_waitcnt vmcnt(0)
	s_waitcnt vmcnt(49)
	v_lshlrev_b32_e32 v149, 16, v149
	v_fmac_f32_e32 v149, v150, v80
	v_cvt_pk_bf16_f32 v80, v149, s0
	v_lshlrev_b32_e32 v149, 16, v80
	global_store_short v[96:97], v80, off offset:128
	v_mul_f32_e32 v80, v81, v161
	s_waitcnt vmcnt(49)
	v_lshlrev_b32_e32 v147, 16, v147
	v_fmac_f32_e32 v147, v150, v80
	v_cvt_pk_bf16_f32 v80, v147, s0
	v_lshlrev_b32_e32 v81, 16, v80
	global_store_short v[96:97], v80, off offset:2176
	v_mul_f32_e32 v80, v82, v162
	s_waitcnt vmcnt(49)
	v_lshlrev_b32_e32 v148, 16, v148
	v_fmac_f32_e32 v148, v150, v80
	v_cvt_pk_bf16_f32 v82, v148, s0
	v_add_co_u32_e64 v80, s[0:1], s96, v96
	v_fmac_f32_e32 v115, v81, v81
	s_nop 0
	v_addc_co_u32_e64 v81, s[0:1], 0, v97, s[0:1]
	v_lshlrev_b32_e32 v147, 16, v82
	global_store_short v[80:81], v82, off offset:128
	v_mul_f32_e32 v82, v83, v163
	s_waitcnt vmcnt(49)
	v_lshlrev_b32_e32 v139, 16, v139
	v_fmac_f32_e32 v139, v150, v82
	v_cvt_pk_bf16_f32 v82, v139, s0
	global_store_short v[80:81], v82, off offset:2176
	s_waitcnt lgkmcnt(0)
	v_mul_f32_e32 v80, v84, v164
	s_waitcnt vmcnt(49)
	v_lshlrev_b32_e32 v142, 16, v142
	v_fmac_f32_e32 v142, v150, v80
	v_lshlrev_b32_e32 v83, 16, v82
	v_cvt_pk_bf16_f32 v82, v142, s0
	v_add_co_u32_e64 v80, s[0:1], s94, v96
	v_fmac_f32_e32 v99, v83, v83
	s_nop 0
	v_addc_co_u32_e64 v81, s[0:1], 0, v97, s[0:1]
	v_lshlrev_b32_e32 v83, 16, v82
	global_store_short v[80:81], v82, off offset:128
	v_mul_f32_e32 v82, v85, v165
	s_waitcnt vmcnt(49)
	v_lshlrev_b32_e32 v136, 16, v136
	v_fmac_f32_e32 v136, v150, v82
	v_cvt_pk_bf16_f32 v82, v136, s0
	global_store_short v[80:81], v82, off offset:2176
	v_mul_f32_e32 v80, v86, v166
	s_waitcnt vmcnt(49)
	v_lshlrev_b32_e32 v146, 16, v146
	v_fmac_f32_e32 v146, v150, v80
	v_fmac_f32_e32 v100, v83, v83
	v_lshlrev_b32_e32 v83, 16, v82
	v_cvt_pk_bf16_f32 v82, v146, s0
	v_add_co_u32_e64 v80, s[0:1], s57, v96
	v_fmac_f32_e32 v101, v83, v83
	s_nop 0
	v_addc_co_u32_e64 v81, s[0:1], 0, v97, s[0:1]
	v_lshlrev_b32_e32 v83, 16, v82
	global_store_short v[80:81], v82, off offset:128
	v_mul_f32_e32 v82, v87, v167
	s_waitcnt vmcnt(49)
	v_lshlrev_b32_e32 v140, 16, v140
	v_fmac_f32_e32 v140, v150, v82
	v_cvt_pk_bf16_f32 v82, v140, s0
	v_fmac_f32_e32 v116, v83, v83
	v_lshlrev_b32_e32 v83, 16, v82
	global_store_short v[80:81], v82, off offset:2176
	v_fmac_f32_e32 v102, v83, v83
	ds_read_b128 v[80:83], v151 offset:64
	v_fmac_f32_e32 v114, v149, v149
	v_fmac_f32_e32 v98, v147, v147
	s_waitcnt lgkmcnt(0)
	v_mul_f32_e32 v80, v88, v80
	s_waitcnt vmcnt(49)
	v_lshlrev_b32_e32 v129, 16, v129
	v_fmac_f32_e32 v129, v150, v80
	v_cvt_pk_bf16_f32 v80, v129, s0
	v_add_co_u32_e64 v84, s[0:1], s35, v96
	v_lshlrev_b32_e32 v86, 16, v80
	s_nop 0
	v_addc_co_u32_e64 v85, s[0:1], 0, v97, s[0:1]
	global_store_short v[84:85], v80, off offset:128
	v_mul_f32_e32 v80, v89, v81
	s_waitcnt vmcnt(49)
	v_lshlrev_b32_e32 v125, 16, v125
	v_fmac_f32_e32 v125, v150, v80
	v_cvt_pk_bf16_f32 v80, v125, s0
	v_lshlrev_b32_e32 v81, 16, v80
	global_store_short v[84:85], v80, off offset:2176
	v_mul_f32_e32 v80, v90, v82
	s_waitcnt vmcnt(49)
	v_lshlrev_b32_e32 v135, 16, v135
	v_fmac_f32_e32 v135, v150, v80
	v_cvt_pk_bf16_f32 v82, v135, s0
	v_add_co_u32_e64 v80, s[0:1], s58, v96
	v_fmac_f32_e32 v105, v81, v81
	s_nop 0
	v_addc_co_u32_e64 v81, s[0:1], 0, v97, s[0:1]
	v_lshlrev_b32_e32 v84, 16, v82
	global_store_short v[80:81], v82, off offset:128
	v_mul_f32_e32 v82, v91, v83
	s_waitcnt vmcnt(49)
	v_lshlrev_b32_e32 v131, 16, v131
	v_fmac_f32_e32 v131, v150, v82
	v_cvt_pk_bf16_f32 v82, v131, s0
	v_lshlrev_b32_e32 v83, 16, v82
	global_store_short v[80:81], v82, off offset:2176
	v_fmac_f32_e32 v103, v83, v83
	ds_read_b128 v[80:83], v151 offset:96
	v_fmac_f32_e32 v104, v84, v84
	v_fmac_f32_e32 v117, v86, v86
	v_mov_b32_e32 v125, v158
	s_waitcnt lgkmcnt(0)
	v_mul_f32_e32 v80, v92, v80
	v_fmac_f32_e32 v120, v150, v80
	v_cvt_pk_bf16_f32 v80, v120, s0
	v_add_co_u32_e64 v84, s[0:1], s95, v96
	v_lshlrev_b32_e32 v86, 16, v80
	s_nop 0
	v_addc_co_u32_e64 v85, s[0:1], 0, v97, s[0:1]
	global_store_short v[84:85], v80, off offset:128
	v_mul_f32_e32 v80, v93, v81
	v_fmac_f32_e32 v118, v150, v80
	v_cvt_pk_bf16_f32 v80, v118, s0
	v_lshlrev_b32_e32 v81, 16, v80
	global_store_short v[84:85], v80, off offset:2176
	v_mul_f32_e32 v80, v94, v82
	s_waitcnt vmcnt(49)
	v_lshlrev_b32_e32 v121, 16, v121
	v_fmac_f32_e32 v121, v150, v80
	v_cvt_pk_bf16_f32 v82, v121, s0
	v_add_co_u32_e64 v80, s[0:1], s59, v96
	v_fmac_f32_e32 v107, v81, v81
	s_nop 0
	v_addc_co_u32_e64 v81, s[0:1], 0, v97, s[0:1]
	v_lshlrev_b32_e32 v84, 16, v82
	global_store_short v[80:81], v82, off offset:128
	v_mul_f32_e32 v82, v95, v83
	s_waitcnt vmcnt(49)
	v_lshlrev_b32_e32 v119, 16, v119
	v_fmac_f32_e32 v119, v150, v82
	v_cvt_pk_bf16_f32 v82, v119, s0
	s_lshl_b64 s[0:1], s[28:29], 11
	global_store_short v[80:81], v82, off offset:2176
	v_mov_b32_e32 v80, v130
	s_add_u32 s50, s48, s0
	s_addc_u32 s51, s49, s1
	v_ashrrev_i32_e32 v81, 31, v80
	v_lshl_add_u64 v[80:81], v[80:81], 1, s[50:51]
	v_fmac_f32_e32 v106, v86, v86
	v_add_co_u32_e64 v86, s[0:1], s96, v80
	v_lshlrev_b32_e32 v83, 16, v82
	s_nop 0
	v_addc_co_u32_e64 v87, s[0:1], 0, v81, s[0:1]
	v_add_co_u32_e64 v88, s[0:1], s94, v80
	v_fmac_f32_e32 v109, v83, v83
	s_nop 0
	v_addc_co_u32_e64 v89, s[0:1], 0, v81, s[0:1]
	v_add_co_u32_e64 v90, s[0:1], s57, v80
	global_load_ushort v82, v[80:81], off
	global_load_ushort v83, v[80:81], off offset:2048
	v_addc_co_u32_e64 v91, s[0:1], 0, v81, s[0:1]
	v_add_co_u32_e64 v92, s[0:1], s35, v80
	v_fmac_f32_e32 v108, v84, v84
	s_nop 0
	v_addc_co_u32_e64 v93, s[0:1], 0, v81, s[0:1]
	v_add_co_u32_e64 v94, s[0:1], s58, v80
	global_load_ushort v84, v[86:87], off
	global_load_ushort v85, v[86:87], off offset:2048
	v_addc_co_u32_e64 v95, s[0:1], 0, v81, s[0:1]
	v_add_co_u32_e64 v96, s[0:1], s95, v80
	global_load_ushort v86, v[90:91], off offset:-4096
	global_load_ushort v87, v[88:89], off offset:2048
	s_nop 0
	global_load_ushort v88, v[90:91], off
	global_load_ushort v89, v[90:91], off offset:2048
	v_addc_co_u32_e64 v97, s[0:1], 0, v81, s[0:1]
	v_add_co_u32_e64 v80, s[0:1], s59, v80
	global_load_ushort v90, v[94:95], off offset:-4096
	global_load_ushort v91, v[92:93], off offset:2048
	s_nop 0
	global_load_ushort v92, v[94:95], off
	global_load_ushort v93, v[94:95], off offset:2048
	v_addc_co_u32_e64 v81, s[0:1], 0, v81, s[0:1]
	global_load_ushort v94, v[80:81], off offset:-4096
	global_load_ushort v95, v[96:97], off offset:2048
	s_nop 0
	global_load_ushort v96, v[80:81], off
	global_load_ushort v97, v[80:81], off offset:2048
	v_mov_b32_e32 v80, v128
	s_nop 0
	v_ashrrev_i32_e32 v81, 31, v80
	v_lshl_add_u64 v[80:81], v[80:81], 0, s[68:69]
	v_lshl_add_u64 v[118:119], v[80:81], 2, s[36:37]
	global_load_dword v118, v[118:119], off offset:384
	v_lshl_add_u32 v119, v125, 4, s39
	ds_read_b128 v[146:149], v119
	ds_read_b128 v[160:163], v119 offset:32
	v_lshl_add_u32 v120, v125, 2, s38
	v_ashrrev_i32_e32 v121, 31, v120
	v_lshlrev_b64 v[120:121], 11, v[120:121]
	s_waitcnt lgkmcnt(1)
	v_mul_f32_e32 v64, v64, v146
	v_lshl_add_u64 v[120:121], s[66:67], 0, v[120:121]
	v_lshl_add_u64 v[80:81], v[80:81], 1, v[120:121]
	s_waitcnt vmcnt(0)
	v_fmac_f32_e32 v123, v118, v64
	v_mul_f32_e32 v64, v65, v147
	s_waitcnt vmcnt(48)
	v_lshlrev_b32_e32 v122, 16, v122
	v_fmac_f32_e32 v122, v118, v64
	v_mul_f32_e32 v64, v66, v148
	s_waitcnt vmcnt(47)
	v_lshlrev_b32_e32 v126, 16, v126
	v_fmac_f32_e32 v126, v118, v64
	v_cvt_pk_bf16_f32 v120, v123, s0
	v_cvt_pk_bf16_f32 v121, v122, s0
	v_cvt_pk_bf16_f32 v122, v126, s0
	v_add_co_u32_e64 v64, s[0:1], s96, v80
	v_mul_f32_e32 v66, v67, v149
	s_nop 0
	v_addc_co_u32_e64 v65, s[0:1], 0, v81, s[0:1]
	s_waitcnt vmcnt(46)
	v_lshlrev_b32_e32 v124, 16, v124
	v_fmac_f32_e32 v124, v118, v66
	s_nop 0
	v_cvt_pk_bf16_f32 v123, v124, s0
	global_store_short v[64:65], v122, off offset:192
	global_store_short v[64:65], v123, off offset:2240
	s_waitcnt lgkmcnt(0)
	v_mul_f32_e32 v64, v68, v160
	s_waitcnt vmcnt(47)
	v_lshlrev_b32_e32 v134, 16, v134
	v_fmac_f32_e32 v134, v118, v64
	v_cvt_pk_bf16_f32 v124, v134, s0
	v_add_co_u32_e64 v64, s[0:1], s94, v80
	v_mul_f32_e32 v66, v69, v161
	s_nop 0
	v_addc_co_u32_e64 v65, s[0:1], 0, v81, s[0:1]
	s_waitcnt vmcnt(46)
	v_lshlrev_b32_e32 v127, 16, v127
	v_fmac_f32_e32 v127, v118, v66
	s_nop 0
	v_cvt_pk_bf16_f32 v125, v127, s0
	global_store_short v[64:65], v124, off offset:192
	global_store_short v[64:65], v125, off offset:2240
	v_mul_f32_e32 v64, v70, v162
	s_waitcnt vmcnt(47)
	v_lshlrev_b32_e32 v145, 16, v145
	v_fmac_f32_e32 v145, v118, v64
	v_cvt_pk_bf16_f32 v70, v145, s0
	v_add_co_u32_e64 v64, s[0:1], s57, v80
	v_mul_f32_e32 v66, v71, v163
	s_nop 0
	v_addc_co_u32_e64 v65, s[0:1], 0, v81, s[0:1]
	s_waitcnt vmcnt(46)
	v_lshlrev_b32_e32 v143, 16, v143
	v_fmac_f32_e32 v143, v118, v66
	s_nop 0
	v_cvt_pk_bf16_f32 v71, v143, s0
	global_store_short v[64:65], v70, off offset:192
	global_store_short v[64:65], v71, off offset:2240
	ds_read_b128 v[64:67], v119 offset:64
	global_store_short v[80:81], v120, off offset:192
	global_store_short v[80:81], v121, off offset:2240
	s_waitcnt lgkmcnt(0)
	v_mul_f32_e32 v64, v72, v64
	s_waitcnt vmcnt(49)
	v_lshlrev_b32_e32 v138, 16, v138
	v_fmac_f32_e32 v138, v118, v64
	v_mul_f32_e32 v64, v73, v65
	v_cvt_pk_bf16_f32 v72, v138, s0
	v_add_co_u32_e64 v68, s[0:1], s35, v80
	s_waitcnt vmcnt(48)
	v_lshlrev_b32_e32 v137, 16, v137
	v_fmac_f32_e32 v137, v118, v64
	v_mul_f32_e32 v64, v74, v66
	v_addc_co_u32_e64 v69, s[0:1], 0, v81, s[0:1]
	s_waitcnt vmcnt(47)
	v_lshlrev_b32_e32 v144, 16, v144
	v_fmac_f32_e32 v144, v118, v64
	s_nop 0
	v_cvt_pk_bf16_f32 v73, v137, s0
	v_cvt_pk_bf16_f32 v74, v144, s0
	v_add_co_u32_e64 v64, s[0:1], s58, v80
	v_mul_f32_e32 v66, v75, v67
	s_nop 0
	v_addc_co_u32_e64 v65, s[0:1], 0, v81, s[0:1]
	s_waitcnt vmcnt(46)
	v_lshlrev_b32_e32 v141, 16, v141
	v_fmac_f32_e32 v141, v118, v66
	s_nop 0
	v_cvt_pk_bf16_f32 v75, v141, s0
	global_store_short v[64:65], v74, off offset:192
	global_store_short v[64:65], v75, off offset:2240
	ds_read_b128 v[64:67], v119 offset:96
	global_store_short v[68:69], v72, off offset:192
	global_store_short v[68:69], v73, off offset:2240
	s_waitcnt lgkmcnt(0)
	v_mul_f32_e32 v64, v76, v64
	s_waitcnt vmcnt(49)
	v_lshlrev_b32_e32 v111, 16, v111
	v_fmac_f32_e32 v111, v118, v64
	v_mul_f32_e32 v64, v77, v65
	v_cvt_pk_bf16_f32 v76, v111, s0
	v_add_co_u32_e64 v68, s[0:1], s95, v80
	s_waitcnt vmcnt(48)
	v_lshlrev_b32_e32 v110, 16, v110
	v_fmac_f32_e32 v110, v118, v64
	v_mul_f32_e32 v64, v78, v66
	v_addc_co_u32_e64 v69, s[0:1], 0, v81, s[0:1]
	s_waitcnt vmcnt(47)
	v_lshlrev_b32_e32 v113, 16, v113
	v_fmac_f32_e32 v113, v118, v64
	s_nop 0
	v_cvt_pk_bf16_f32 v77, v110, s0
	v_cvt_pk_bf16_f32 v66, v113, s0
	v_add_co_u32_e64 v64, s[0:1], s59, v80
	v_mul_f32_e32 v67, v79, v67
	s_nop 0
	v_addc_co_u32_e64 v65, s[0:1], 0, v81, s[0:1]
	s_waitcnt vmcnt(46)
	v_lshlrev_b32_e32 v112, 16, v112
	v_fmac_f32_e32 v112, v118, v67
	s_nop 0
	v_cvt_pk_bf16_f32 v67, v112, s0
	global_store_short v[64:65], v66, off offset:192
	global_store_short v[64:65], v67, off offset:2240
	v_lshlrev_b32_e32 v64, 16, v67
	v_fmac_f32_e32 v109, v64, v64
	v_lshlrev_b32_e32 v64, 16, v66
	v_fmac_f32_e32 v108, v64, v64
	v_lshlrev_b32_e32 v64, 16, v77
	v_fmac_f32_e32 v107, v64, v64
	v_lshlrev_b32_e32 v64, 16, v76
	v_fmac_f32_e32 v106, v64, v64
	v_lshlrev_b32_e32 v64, 16, v75
	v_fmac_f32_e32 v103, v64, v64
	v_lshlrev_b32_e32 v64, 16, v74
	v_fmac_f32_e32 v104, v64, v64
	v_lshlrev_b32_e32 v64, 16, v73
	v_fmac_f32_e32 v105, v64, v64
	v_lshlrev_b32_e32 v64, 16, v72
	v_fmac_f32_e32 v117, v64, v64
	v_lshlrev_b32_e32 v64, 16, v71
	v_fmac_f32_e32 v102, v64, v64
	v_lshlrev_b32_e32 v64, 16, v70
	v_fmac_f32_e32 v116, v64, v64
	v_lshlrev_b32_e32 v64, 16, v125
	v_fmac_f32_e32 v101, v64, v64
	v_lshlrev_b32_e32 v64, 16, v124
	v_fmac_f32_e32 v100, v64, v64
	v_lshlrev_b32_e32 v64, 16, v123
	v_fmac_f32_e32 v99, v64, v64
	v_lshlrev_b32_e32 v64, 16, v122
	v_fmac_f32_e32 v98, v64, v64
	v_lshlrev_b32_e32 v64, 16, v121
	v_fmac_f32_e32 v115, v64, v64
	v_lshlrev_b32_e32 v64, 16, v120
	v_fmac_f32_e32 v114, v64, v64
	v_cndmask_b32_e64 v65, v114, v117, s[46:47]
	ds_bpermute_b32 v65, v157, v65
	v_cndmask_b32_e64 v66, v115, v105, s[46:47]
	ds_bpermute_b32 v66, v157, v66
	v_cndmask_b32_e64 v67, v98, v104, s[46:47]
	global_store_short v[68:69], v76, off offset:192
	global_store_short v[68:69], v77, off offset:2240
	ds_bpermute_b32 v67, v157, v67
	v_cndmask_b32_e64 v68, v99, v103, s[46:47]
	ds_bpermute_b32 v68, v157, v68
	v_cndmask_b32_e64 v69, v100, v106, s[46:47]
	v_cndmask_b32_e64 v64, v117, v114, s[46:47]
	ds_bpermute_b32 v69, v157, v69
	v_cndmask_b32_e64 v70, v101, v107, s[46:47]
	s_waitcnt lgkmcnt(4)
	v_add_f32_e32 v64, v64, v65
	v_cndmask_b32_e64 v65, v105, v115, s[46:47]
	ds_bpermute_b32 v70, v157, v70
	v_cndmask_b32_e64 v71, v116, v108, s[46:47]
	s_waitcnt lgkmcnt(4)
	v_add_f32_e32 v65, v65, v66
	v_cndmask_b32_e64 v66, v104, v98, s[46:47]
	ds_bpermute_b32 v71, v157, v71
	v_cndmask_b32_e64 v72, v102, v109, s[46:47]
	s_waitcnt lgkmcnt(4)
	v_add_f32_e32 v66, v66, v67
	v_cndmask_b32_e64 v67, v103, v99, s[46:47]
	ds_bpermute_b32 v72, v157, v72
	s_waitcnt lgkmcnt(4)
	v_add_f32_e32 v67, v67, v68
	v_cndmask_b32_e64 v68, v106, v100, s[46:47]
	s_waitcnt lgkmcnt(3)
	v_add_f32_e32 v68, v68, v69
	v_cndmask_b32_e64 v69, v107, v101, s[46:47]
	s_waitcnt lgkmcnt(2)
	v_add_f32_e32 v69, v69, v70
	v_cndmask_b32_e64 v70, v108, v116, s[46:47]
	s_waitcnt lgkmcnt(1)
	v_add_f32_e32 v70, v70, v71
	v_cndmask_b32_e64 v71, v109, v102, s[46:47]
	s_waitcnt lgkmcnt(0)
	v_add_f32_e32 v71, v71, v72
	v_cndmask_b32_e64 v72, v68, v64, s[44:45]
	v_cndmask_b32_e64 v64, v64, v68, s[44:45]
	v_cndmask_b32_e64 v68, v69, v65, s[44:45]
	v_cndmask_b32_e64 v65, v65, v69, s[44:45]
	ds_bpermute_b32 v65, v156, v65
	ds_bpermute_b32 v64, v156, v64
	s_waitcnt lgkmcnt(1)
	v_add_f32_e32 v65, v68, v65
	v_cndmask_b32_e64 v68, v70, v66, s[44:45]
	v_cndmask_b32_e64 v66, v66, v70, s[44:45]
	ds_bpermute_b32 v66, v156, v66
	s_waitcnt lgkmcnt(1)
	v_add_f32_e32 v64, v72, v64
	s_waitcnt lgkmcnt(0)
	v_add_f32_e32 v66, v68, v66
	v_cndmask_b32_e64 v68, v71, v67, s[44:45]
	v_cndmask_b32_e64 v67, v67, v71, s[44:45]
	ds_bpermute_b32 v67, v156, v67
	s_waitcnt lgkmcnt(0)
	v_add_f32_e32 v67, v68, v67
	v_cndmask_b32_e64 v68, v66, v64, s[42:43]
	v_cndmask_b32_e64 v64, v64, v66, s[42:43]
	v_cndmask_b32_e64 v66, v67, v65, s[42:43]
	v_cndmask_b32_e64 v65, v65, v67, s[42:43]
	ds_bpermute_b32 v64, v155, v64
	ds_bpermute_b32 v65, v155, v65
	s_waitcnt lgkmcnt(1)
	v_add_f32_e32 v64, v68, v64
	s_waitcnt lgkmcnt(0)
	v_add_f32_e32 v65, v66, v65
	v_cndmask_b32_e64 v66, v65, v64, s[40:41]
	v_cndmask_b32_e64 v64, v64, v65, s[40:41]
	ds_bpermute_b32 v64, v154, v64
	s_waitcnt lgkmcnt(0)
	v_add_f32_e32 v64, v66, v64
	ds_bpermute_b32 v65, v153, v64
	s_and_saveexec_b64 s[0:1], vcc
	s_cbranch_execz .LBB0_426
	v_lshlrev_b64 v[66:67], 6, v[132:133]
	v_lshl_add_u64 v[66:67], s[26:27], 0, v[66:67]
	s_waitcnt lgkmcnt(0)
	v_add_f32_e32 v64, v64, v65
	global_store_dword v[66:67], v64, off
.LBB0_426:
	s_or_b64 exec, exec, s[0:1]
	v_mov_b32_e32 v64, v130
	v_lshlrev_b32_e32 v108, 16, v85
	s_waitcnt lgkmcnt(0)
	v_ashrrev_i32_e32 v65, 31, v64
	v_lshl_add_u64 v[64:65], v[64:65], 1, s[50:51]
	global_load_ushort v66, v[64:65], off offset:64
	v_lshlrev_b32_e32 v103, 16, v84
	v_lshlrev_b32_e32 v98, 16, v82
	v_lshlrev_b32_e32 v99, 16, v83
	v_lshlrev_b32_e32 v102, 16, v87
	v_lshlrev_b32_e32 v101, 16, v88
	v_lshlrev_b32_e32 v100, 16, v89
	v_lshlrev_b32_e32 v89, 16, v90
	v_lshlrev_b32_e32 v88, 16, v91
	v_lshlrev_b32_e32 v87, 16, v92
	v_mov_b32_e32 v92, v158
	v_lshlrev_b32_e32 v109, 16, v86
	v_lshlrev_b32_e32 v86, 16, v93
	v_lshlrev_b32_e32 v68, 16, v97
	v_lshlrev_b32_e32 v71, 16, v95
	v_lshlrev_b32_e32 v73, 16, v94
	v_lshlrev_b32_e32 v70, 16, v96
	s_waitcnt vmcnt(0)
	v_lshlrev_b32_e32 v85, 16, v66
	global_load_ushort v84, v[64:65], off offset:2112
	s_waitcnt vmcnt(1)
	v_add_co_u32_e64 v66, s[0:1], s96, v64
	s_nop 1
	v_addc_co_u32_e64 v67, s[0:1], 0, v65, s[0:1]
	global_load_ushort v83, v[66:67], off offset:64
	s_waitcnt vmcnt(2)
	global_load_ushort v82, v[66:67], off offset:2112
	s_waitcnt vmcnt(3)
	v_add_co_u32_e64 v66, s[0:1], s94, v64
	s_nop 1
	v_addc_co_u32_e64 v67, s[0:1], 0, v65, s[0:1]
	global_load_ushort v81, v[66:67], off offset:64
	s_waitcnt vmcnt(4)
	global_load_ushort v78, v[66:67], off offset:2112
	s_waitcnt vmcnt(5)
	v_add_co_u32_e64 v66, s[0:1], s57, v64
	s_nop 1
	v_addc_co_u32_e64 v67, s[0:1], 0, v65, s[0:1]
	global_load_ushort v80, v[66:67], off offset:64
	s_waitcnt vmcnt(6)
	global_load_ushort v79, v[66:67], off offset:2112
	s_waitcnt vmcnt(7)
	v_add_co_u32_e64 v66, s[0:1], s35, v64
	s_nop 1
	v_addc_co_u32_e64 v67, s[0:1], 0, v65, s[0:1]
	global_load_ushort v76, v[66:67], off offset:64
	s_waitcnt vmcnt(8)
	global_load_ushort v74, v[66:67], off offset:2112
	s_waitcnt vmcnt(9)
	v_add_co_u32_e64 v66, s[0:1], s58, v64
	s_nop 1
	v_addc_co_u32_e64 v67, s[0:1], 0, v65, s[0:1]
	global_load_ushort v77, v[66:67], off offset:64
	s_waitcnt vmcnt(10)
	global_load_ushort v75, v[66:67], off offset:2112
	s_waitcnt vmcnt(11)
	v_add_co_u32_e64 v66, s[0:1], s95, v64
	s_nop 1
	v_addc_co_u32_e64 v67, s[0:1], 0, v65, s[0:1]
	v_add_co_u32_e64 v64, s[0:1], s59, v64
	global_load_ushort v69, v[66:67], off offset:64
	s_nop 0
	v_addc_co_u32_e64 v65, s[0:1], 0, v65, s[0:1]
	global_load_ushort v66, v[66:67], off offset:2112
	s_waitcnt vmcnt(1)
	v_lshlrev_b32_e32 v72, 16, v69
	global_load_ushort v67, v[64:65], off offset:64
	s_waitcnt vmcnt(1)
	v_lshlrev_b32_e32 v66, 16, v66
	global_load_ushort v64, v[64:65], off offset:2112
	s_waitcnt vmcnt(1)
	v_lshlrev_b32_e32 v69, 16, v67
	s_waitcnt vmcnt(0)
	v_lshlrev_b32_e32 v67, 16, v64
	v_mov_b32_e32 v64, v128
	s_nop 0
	v_add_u32_e32 v64, s68, v64
	v_ashrrev_i32_e32 v65, 31, v64
	v_lshl_add_u64 v[90:91], v[64:65], 2, s[36:37]
	global_load_dword v110, v[90:91], off
	v_lshl_add_u32 v90, v92, 2, s28
	v_ashrrev_i32_e32 v91, 31, v90
	v_lshlrev_b64 v[90:91], 11, v[90:91]
	v_lshl_add_u64 v[90:91], s[66:67], 0, v[90:91]
	v_lshl_add_u32 v111, v92, 4, s39
	v_lshl_add_u64 v[64:65], v[64:65], 1, v[90:91]
	ds_read_b128 v[90:93], v111 offset:128
	ds_read_b128 v[104:107], v111 offset:160
	s_waitcnt lgkmcnt(1)
	v_mul_f32_e32 v48, v48, v90
	s_waitcnt vmcnt(0)
	v_fmac_f32_e32 v98, v110, v48
	v_cvt_pk_bf16_f32 v48, v98, s0
	v_lshlrev_b32_e32 v97, 16, v48
	global_store_short v[64:65], v48, off
	v_mul_f32_e32 v48, v49, v91
	v_fmac_f32_e32 v99, v110, v48
	v_cvt_pk_bf16_f32 v48, v99, s0
	v_lshlrev_b32_e32 v95, 16, v48
	global_store_short v[64:65], v48, off offset:2048
	v_mul_f32_e32 v48, v50, v92
	v_fmac_f32_e32 v103, v110, v48
	v_cvt_pk_bf16_f32 v50, v103, s0
	v_add_co_u32_e64 v48, s[0:1], s96, v64
	v_lshlrev_b32_e32 v94, 16, v50
	s_nop 0
	v_addc_co_u32_e64 v49, s[0:1], 0, v65, s[0:1]
	global_store_short v[48:49], v50, off
	v_mul_f32_e32 v50, v51, v93
	v_fmac_f32_e32 v108, v110, v50
	v_cvt_pk_bf16_f32 v50, v108, s0
	global_store_short v[48:49], v50, off offset:2048
	s_waitcnt lgkmcnt(0)
	v_mul_f32_e32 v48, v52, v104
	v_fmac_f32_e32 v109, v110, v48
	v_cvt_pk_bf16_f32 v52, v109, s0
	v_add_co_u32_e64 v48, s[0:1], s94, v64
	v_lshlrev_b32_e32 v99, 16, v50
	s_nop 0
	v_addc_co_u32_e64 v49, s[0:1], 0, v65, s[0:1]
	v_add_co_u32_e64 v50, s[0:1], s57, v64
	v_lshlrev_b32_e32 v98, 16, v52
	s_nop 0
	v_addc_co_u32_e64 v51, s[0:1], 0, v65, s[0:1]
	global_store_short v[50:51], v52, off offset:-4096
	v_mul_f32_e32 v52, v53, v105
	v_fmac_f32_e32 v102, v110, v52
	v_cvt_pk_bf16_f32 v53, v102, s0
	global_store_short v[48:49], v53, off offset:2048
	v_mul_f32_e32 v48, v54, v106
	v_fmac_f32_e32 v101, v110, v48
	v_cvt_pk_bf16_f32 v48, v101, s0
	v_lshlrev_b32_e32 v96, 16, v48
	global_store_short v[50:51], v48, off
	v_mul_f32_e32 v48, v55, v107
	v_fmac_f32_e32 v100, v110, v48
	v_cvt_pk_bf16_f32 v48, v100, s0
	v_lshlrev_b32_e32 v52, 16, v53
	v_lshlrev_b32_e32 v53, 16, v48
	global_store_short v[50:51], v48, off offset:2048
	ds_read_b128 v[48:51], v111 offset:192
	s_waitcnt lgkmcnt(0)
	v_mul_f32_e32 v48, v56, v48
	v_fmac_f32_e32 v89, v110, v48
	v_cvt_pk_bf16_f32 v48, v89, s0
	v_add_co_u32_e64 v54, s[0:1], s35, v64
	v_lshlrev_b32_e32 v92, 16, v48
	s_nop 0
	v_addc_co_u32_e64 v55, s[0:1], 0, v65, s[0:1]
	v_add_co_u32_e64 v100, s[0:1], s58, v64
	s_nop 1
	v_addc_co_u32_e64 v101, s[0:1], 0, v65, s[0:1]
	global_store_short v[100:101], v48, off offset:-4096
	v_mul_f32_e32 v48, v57, v49
	v_fmac_f32_e32 v88, v110, v48
	v_cvt_pk_bf16_f32 v48, v88, s0
	v_lshlrev_b32_e32 v93, 16, v48
	global_store_short v[54:55], v48, off offset:2048
	v_mul_f32_e32 v48, v58, v50
	v_fmac_f32_e32 v87, v110, v48
	v_cvt_pk_bf16_f32 v48, v87, s0
	v_lshlrev_b32_e32 v91, 16, v48
	global_store_short v[100:101], v48, off
	v_mul_f32_e32 v48, v59, v51
	v_fmac_f32_e32 v86, v110, v48
	v_cvt_pk_bf16_f32 v48, v86, s0
	v_lshlrev_b32_e32 v90, 16, v48
	global_store_short v[100:101], v48, off offset:2048
	ds_read_b128 v[48:51], v111 offset:224
	v_mov_b32_e32 v101, v158
	s_waitcnt lgkmcnt(0)
	v_mul_f32_e32 v48, v60, v48
	v_fmac_f32_e32 v73, v110, v48
	v_cvt_pk_bf16_f32 v48, v73, s0
	v_add_co_u32_e64 v54, s[0:1], s95, v64
	v_lshlrev_b32_e32 v89, 16, v48
	s_nop 0
	v_addc_co_u32_e64 v55, s[0:1], 0, v65, s[0:1]
	v_add_co_u32_e64 v56, s[0:1], s59, v64
	s_nop 1
	v_addc_co_u32_e64 v57, s[0:1], 0, v65, s[0:1]
	global_store_short v[56:57], v48, off offset:-4096
	v_mul_f32_e32 v48, v61, v49
	v_fmac_f32_e32 v71, v110, v48
	v_cvt_pk_bf16_f32 v48, v71, s0
	v_lshlrev_b32_e32 v88, 16, v48
	global_store_short v[54:55], v48, off offset:2048
	v_mul_f32_e32 v48, v62, v50
	v_fmac_f32_e32 v70, v110, v48
	v_cvt_pk_bf16_f32 v48, v70, s0
	v_lshlrev_b32_e32 v87, 16, v48
	global_store_short v[56:57], v48, off
	v_mul_f32_e32 v48, v63, v51
	v_fmac_f32_e32 v68, v110, v48
	v_cvt_pk_bf16_f32 v48, v68, s0
	v_lshlrev_b32_e32 v86, 16, v48
	global_store_short v[56:57], v48, off offset:2048
	v_mov_b32_e32 v48, v130
	s_nop 0
	v_ashrrev_i32_e32 v49, 31, v48
	v_lshl_add_u64 v[48:49], v[48:49], 1, s[50:51]
	global_load_ushort v73, v[48:49], off offset:128
	s_waitcnt vmcnt(17)
	global_load_ushort v70, v[48:49], off offset:2176
	s_waitcnt vmcnt(18)
	v_add_co_u32_e64 v50, s[0:1], s96, v48
	s_nop 1
	v_addc_co_u32_e64 v51, s[0:1], 0, v49, s[0:1]
	global_load_ushort v71, v[50:51], off offset:128
	s_waitcnt vmcnt(19)
	global_load_ushort v63, v[50:51], off offset:2176
	s_waitcnt vmcnt(20)
	v_add_co_u32_e64 v50, s[0:1], s94, v48
	s_nop 1
	v_addc_co_u32_e64 v51, s[0:1], 0, v49, s[0:1]
	global_load_ushort v65, v[50:51], off offset:128
	s_waitcnt vmcnt(21)
	global_load_ushort v62, v[50:51], off offset:2176
	s_waitcnt vmcnt(22)
	v_add_co_u32_e64 v50, s[0:1], s57, v48
	s_nop 1
	v_addc_co_u32_e64 v51, s[0:1], 0, v49, s[0:1]
	global_load_ushort v68, v[50:51], off offset:128
	s_waitcnt vmcnt(23)
	global_load_ushort v64, v[50:51], off offset:2176
	s_waitcnt vmcnt(24)
	v_add_co_u32_e64 v50, s[0:1], s35, v48
	s_nop 1
	v_addc_co_u32_e64 v51, s[0:1], 0, v49, s[0:1]
	global_load_ushort v59, v[50:51], off offset:128
	s_waitcnt vmcnt(25)
	global_load_ushort v58, v[50:51], off offset:2176
	s_waitcnt vmcnt(26)
	v_add_co_u32_e64 v50, s[0:1], s58, v48
	s_nop 1
	v_addc_co_u32_e64 v51, s[0:1], 0, v49, s[0:1]
	global_load_ushort v61, v[50:51], off offset:128
	s_waitcnt vmcnt(27)
	global_load_ushort v60, v[50:51], off offset:2176
	s_waitcnt vmcnt(28)
	v_add_co_u32_e64 v50, s[0:1], s95, v48
	s_nop 1
	v_addc_co_u32_e64 v51, s[0:1], 0, v49, s[0:1]
	global_load_ushort v54, v[50:51], off offset:128
	v_add_co_u32_e64 v48, s[0:1], s59, v48
	global_load_ushort v50, v[50:51], off offset:2176
	s_nop 0
	v_addc_co_u32_e64 v49, s[0:1], 0, v49, s[0:1]
	s_waitcnt vmcnt(1)
	v_lshlrev_b32_e32 v56, 16, v54
	s_waitcnt vmcnt(0)
	v_lshlrev_b32_e32 v54, 16, v50
	global_load_ushort v57, v[48:49], off offset:128
	s_waitcnt vmcnt(1)
	global_load_ushort v55, v[48:49], off offset:2176
	s_waitcnt vmcnt(2)
	v_mov_b32_e32 v48, v128
	s_nop 0
	v_ashrrev_i32_e32 v49, 31, v48
	v_lshl_add_u64 v[48:49], v[48:49], 0, s[68:69]
	v_lshl_add_u64 v[50:51], v[48:49], 2, s[36:37]
	global_load_dword v100, v[50:51], off offset:128
	v_lshl_add_u32 v50, v101, 2, s28
	v_lshl_add_u32 v101, v101, 4, s39
	ds_read_b128 v[102:105], v101 offset:128
	ds_read_b128 v[106:109], v101 offset:160
	v_ashrrev_i32_e32 v51, 31, v50
	v_lshlrev_b64 v[50:51], 11, v[50:51]
	v_lshl_add_u64 v[50:51], s[66:67], 0, v[50:51]
	s_waitcnt lgkmcnt(1)
	v_mul_f32_e32 v32, v32, v102
	v_lshl_add_u64 v[48:49], v[48:49], 1, v[50:51]
	v_mul_f32_e32 v35, v35, v105
	s_waitcnt lgkmcnt(0)
	v_mul_f32_e32 v37, v37, v107
	s_waitcnt vmcnt(0)
	v_fmac_f32_e32 v85, v100, v32
	v_cvt_pk_bf16_f32 v32, v85, s0
	v_lshlrev_b32_e32 v50, 16, v32
	global_store_short v[48:49], v32, off offset:64
	v_mul_f32_e32 v32, v33, v103
	s_waitcnt vmcnt(49)
	v_lshlrev_b32_e32 v84, 16, v84
	v_fmac_f32_e32 v84, v100, v32
	v_cvt_pk_bf16_f32 v32, v84, s0
	v_lshlrev_b32_e32 v33, 16, v32
	global_store_short v[48:49], v32, off offset:2112
	v_mul_f32_e32 v32, v34, v104
	s_waitcnt vmcnt(49)
	v_lshlrev_b32_e32 v83, 16, v83
	v_fmac_f32_e32 v83, v100, v32
	v_cvt_pk_bf16_f32 v34, v83, s0
	v_add_co_u32_e64 v32, s[0:1], s96, v48
	v_mul_f32_e32 v51, v33, v33
	s_nop 0
	v_addc_co_u32_e64 v33, s[0:1], 0, v49, s[0:1]
	s_waitcnt vmcnt(48)
	v_lshlrev_b32_e32 v82, 16, v82
	v_fmac_f32_e32 v82, v100, v35
	s_nop 0
	v_cvt_pk_bf16_f32 v35, v82, s0
	global_store_short v[32:33], v34, off offset:64
	global_store_short v[32:33], v35, off offset:2112
	v_mul_f32_e32 v32, v36, v106
	s_waitcnt vmcnt(49)
	v_lshlrev_b32_e32 v81, 16, v81
	v_fmac_f32_e32 v81, v100, v32
	v_cvt_pk_bf16_f32 v36, v81, s0
	v_add_co_u32_e64 v32, s[0:1], s94, v48
	s_waitcnt vmcnt(48)
	v_lshlrev_b32_e32 v78, 16, v78
	v_fmac_f32_e32 v78, v100, v37
	s_nop 0
	v_addc_co_u32_e64 v33, s[0:1], 0, v49, s[0:1]
	global_store_short v[32:33], v36, off offset:64
	s_nop 0
	v_cvt_pk_bf16_f32 v37, v78, s0
	global_store_short v[32:33], v37, off offset:2112
	v_mul_f32_e32 v32, v38, v108
	s_waitcnt vmcnt(49)
	v_lshlrev_b32_e32 v80, 16, v80
	v_fmac_f32_e32 v80, v100, v32
	v_lshlrev_b32_e32 v78, 16, v37
	v_cvt_pk_bf16_f32 v38, v80, s0
	v_add_co_u32_e64 v32, s[0:1], s57, v48
	v_mul_f32_e32 v37, v78, v78
	s_nop 0
	v_addc_co_u32_e64 v33, s[0:1], 0, v49, s[0:1]
	v_fmac_f32_e32 v37, v52, v52
	v_lshlrev_b32_e32 v52, 16, v38
	global_store_short v[32:33], v38, off offset:64
	v_mul_f32_e32 v38, v39, v109
	v_lshlrev_b32_e32 v81, 16, v36
	s_waitcnt vmcnt(49)
	v_lshlrev_b32_e32 v79, 16, v79
	v_fmac_f32_e32 v79, v100, v38
	v_mul_f32_e32 v36, v81, v81
	v_cvt_pk_bf16_f32 v38, v79, s0
	ds_read_b128 v[78:81], v101 offset:192
	global_store_short v[32:33], v38, off offset:2112
	v_lshlrev_b32_e32 v39, 16, v38
	v_mul_f32_e32 v38, v39, v39
	v_fmac_f32_e32 v38, v53, v53
	s_waitcnt lgkmcnt(0)
	v_mul_f32_e32 v32, v40, v78
	s_waitcnt vmcnt(49)
	v_lshlrev_b32_e32 v76, 16, v76
	v_fmac_f32_e32 v76, v100, v32
	v_cvt_pk_bf16_f32 v39, v76, s0
	v_add_co_u32_e64 v32, s[0:1], s35, v48
	v_lshlrev_b32_e32 v40, 16, v39
	s_nop 0
	v_addc_co_u32_e64 v33, s[0:1], 0, v49, s[0:1]
	global_store_short v[32:33], v39, off offset:64
	v_mul_f32_e32 v39, v41, v79
	s_waitcnt vmcnt(49)
	v_lshlrev_b32_e32 v74, 16, v74
	v_fmac_f32_e32 v74, v100, v39
	v_cvt_pk_bf16_f32 v39, v74, s0
	global_store_short v[32:33], v39, off offset:2112
	v_mul_f32_e32 v32, v42, v80
	s_waitcnt vmcnt(49)
	v_lshlrev_b32_e32 v77, 16, v77
	v_fmac_f32_e32 v77, v100, v32
	v_mul_f32_e32 v53, v40, v40
	v_lshlrev_b32_e32 v40, 16, v39
	v_cvt_pk_bf16_f32 v39, v77, s0
	v_add_co_u32_e64 v32, s[0:1], s58, v48
	v_mul_f32_e32 v41, v40, v40
	s_nop 0
	v_addc_co_u32_e64 v33, s[0:1], 0, v49, s[0:1]
	v_lshlrev_b32_e32 v40, 16, v39
	global_store_short v[32:33], v39, off offset:64
	v_mul_f32_e32 v39, v43, v81
	s_waitcnt vmcnt(49)
	v_lshlrev_b32_e32 v75, 16, v75
	v_fmac_f32_e32 v75, v100, v39
	v_cvt_pk_bf16_f32 v39, v75, s0
	ds_read_b128 v[74:77], v101 offset:224
	global_store_short v[32:33], v39, off offset:2112
	v_lshlrev_b32_e32 v42, 16, v39
	v_mul_f32_e32 v39, v42, v42
	v_lshlrev_b32_e32 v83, 16, v34
	s_waitcnt lgkmcnt(0)
	v_mul_f32_e32 v32, v44, v74
	v_fmac_f32_e32 v72, v100, v32
	v_cvt_pk_bf16_f32 v42, v72, s0
	v_add_co_u32_e64 v32, s[0:1], s95, v48
	v_lshlrev_b32_e32 v43, 16, v42
	s_nop 0
	v_addc_co_u32_e64 v33, s[0:1], 0, v49, s[0:1]
	global_store_short v[32:33], v42, off offset:64
	v_mul_f32_e32 v42, v43, v43
	v_mul_f32_e32 v43, v45, v75
	v_fmac_f32_e32 v66, v100, v43
	v_cvt_pk_bf16_f32 v43, v66, s0
	global_store_short v[32:33], v43, off offset:2112
	v_mul_f32_e32 v32, v46, v76
	v_lshlrev_b32_e32 v44, 16, v43
	v_fmac_f32_e32 v69, v100, v32
	v_mul_f32_e32 v43, v44, v44
	v_cvt_pk_bf16_f32 v44, v69, s0
	v_add_co_u32_e64 v32, s[0:1], s59, v48
	v_lshlrev_b32_e32 v45, 16, v44
	s_nop 0
	v_addc_co_u32_e64 v33, s[0:1], 0, v49, s[0:1]
	global_store_short v[32:33], v44, off offset:64
	v_mul_f32_e32 v44, v45, v45
	v_mul_f32_e32 v45, v47, v77
	v_fmac_f32_e32 v67, v100, v45
	v_cvt_pk_bf16_f32 v45, v67, s0
	global_store_short v[32:33], v45, off offset:2112
	v_lshlrev_b32_e32 v46, 16, v45
	v_ashrrev_i32_e32 v131, 31, v130
	v_lshl_add_u64 v[32:33], v[130:131], 1, s[50:51]
	v_mul_f32_e32 v45, v46, v46
	global_load_ushort v46, v[32:33], off offset:192
	v_lshlrev_b32_e32 v82, 16, v35
	v_mul_f32_e32 v34, v83, v83
	v_mul_f32_e32 v35, v82, v82
	v_fmac_f32_e32 v45, v86, v86
	v_mov_b32_e32 v86, v158
	v_mul_f32_e32 v40, v40, v40
	v_fmac_f32_e32 v40, v91, v91
	v_fmac_f32_e32 v39, v90, v90
	v_fmac_f32_e32 v42, v89, v89
	v_fmac_f32_e32 v43, v88, v88
	v_fmac_f32_e32 v44, v87, v87
	v_fmac_f32_e32 v51, v95, v95
	v_fmac_f32_e32 v35, v99, v99
	v_fmac_f32_e32 v36, v98, v98
	v_mul_f32_e32 v52, v52, v52
	v_fmac_f32_e32 v52, v96, v96
	v_fmac_f32_e32 v41, v93, v93
	v_fmac_f32_e32 v53, v92, v92
	v_mul_f32_e32 v50, v50, v50
	v_fmac_f32_e32 v50, v97, v97
	v_fmac_f32_e32 v34, v94, v94
	s_waitcnt vmcnt(0)
	v_lshlrev_b32_e32 v67, 16, v46
	global_load_ushort v66, v[32:33], off offset:2240
	s_waitcnt vmcnt(1)
	v_add_co_u32_e64 v46, s[0:1], s96, v32
	s_nop 1
	v_addc_co_u32_e64 v47, s[0:1], 0, v33, s[0:1]
	global_load_ushort v72, v[46:47], off offset:192
	s_waitcnt vmcnt(2)
	global_load_ushort v69, v[46:47], off offset:2240
	s_waitcnt vmcnt(3)
	v_add_co_u32_e64 v46, s[0:1], s94, v32
	s_nop 1
	v_addc_co_u32_e64 v47, s[0:1], 0, v33, s[0:1]
	global_load_ushort v75, v[46:47], off offset:192
	s_waitcnt vmcnt(4)
	global_load_ushort v74, v[46:47], off offset:2240
	s_waitcnt vmcnt(5)
	v_add_co_u32_e64 v46, s[0:1], s57, v32
	s_nop 1
	v_addc_co_u32_e64 v47, s[0:1], 0, v33, s[0:1]
	global_load_ushort v81, v[46:47], off offset:192
	s_waitcnt vmcnt(6)
	global_load_ushort v79, v[46:47], off offset:2240
	s_waitcnt vmcnt(7)
	v_add_co_u32_e64 v46, s[0:1], s35, v32
	s_nop 1
	v_addc_co_u32_e64 v47, s[0:1], 0, v33, s[0:1]
	global_load_ushort v77, v[46:47], off offset:192
	s_waitcnt vmcnt(8)
	global_load_ushort v76, v[46:47], off offset:2240
	s_waitcnt vmcnt(9)
	v_add_co_u32_e64 v46, s[0:1], s58, v32
	s_nop 1
	v_addc_co_u32_e64 v47, s[0:1], 0, v33, s[0:1]
	global_load_ushort v80, v[46:47], off offset:192
	s_waitcnt vmcnt(10)
	global_load_ushort v78, v[46:47], off offset:2240
	v_add_co_u32_e64 v48, s[0:1], s95, v32
	s_waitcnt vmcnt(11)
	v_addc_co_u32_e64 v49, s[0:1], 0, v33, s[0:1]
	global_load_ushort v47, v[48:49], off offset:192
	v_add_co_u32_e64 v32, s[0:1], s59, v32
	s_waitcnt vmcnt(12)
	v_addc_co_u32_e64 v33, s[0:1], 0, v33, s[0:1]
	global_load_ushort v46, v[48:49], off offset:2240
	s_waitcnt vmcnt(13)
	global_load_ushort v49, v[32:33], off offset:192
	s_waitcnt vmcnt(14)
	global_load_ushort v48, v[32:33], off offset:2240
	s_waitcnt vmcnt(15)
	v_mov_b32_e32 v32, v128
	s_nop 0
	v_ashrrev_i32_e32 v33, 31, v32
	v_lshl_add_u64 v[32:33], v[32:33], 0, s[68:69]
	v_lshl_add_u64 v[82:83], v[32:33], 2, s[36:37]
	global_load_dword v82, v[82:83], off offset:256
	v_lshl_add_u32 v84, v86, 2, s28
	v_ashrrev_i32_e32 v85, 31, v84
	v_lshlrev_b64 v[84:85], 11, v[84:85]
	v_lshl_add_u64 v[84:85], s[66:67], 0, v[84:85]
	v_lshl_add_u32 v83, v86, 4, s39
	v_lshl_add_u64 v[32:33], v[32:33], 1, v[84:85]
	ds_read_b128 v[84:87], v83 offset:128
	ds_read_b128 v[88:91], v83 offset:160
	s_waitcnt lgkmcnt(1)
	v_mul_f32_e32 v16, v16, v84
	s_waitcnt vmcnt(0)
	s_waitcnt vmcnt(49)
	v_lshlrev_b32_e32 v73, 16, v73
	v_fmac_f32_e32 v73, v82, v16
	v_cvt_pk_bf16_f32 v16, v73, s0
	v_lshlrev_b32_e32 v73, 16, v16
	global_store_short v[32:33], v16, off offset:128
	v_mul_f32_e32 v16, v17, v85
	s_waitcnt vmcnt(49)
	v_lshlrev_b32_e32 v70, 16, v70
	v_fmac_f32_e32 v70, v82, v16
	v_cvt_pk_bf16_f32 v16, v70, s0
	v_lshlrev_b32_e32 v17, 16, v16
	global_store_short v[32:33], v16, off offset:2176
	v_mul_f32_e32 v16, v18, v86
	s_waitcnt vmcnt(49)
	v_lshlrev_b32_e32 v71, 16, v71
	v_fmac_f32_e32 v71, v82, v16
	v_cvt_pk_bf16_f32 v18, v71, s0
	v_add_co_u32_e64 v16, s[0:1], s96, v32
	v_fmac_f32_e32 v51, v17, v17
	s_nop 0
	v_addc_co_u32_e64 v17, s[0:1], 0, v33, s[0:1]
	v_lshlrev_b32_e32 v70, 16, v18
	global_store_short v[16:17], v18, off offset:128
	v_mul_f32_e32 v18, v19, v87
	s_waitcnt vmcnt(49)
	v_lshlrev_b32_e32 v63, 16, v63
	v_fmac_f32_e32 v63, v82, v18
	v_cvt_pk_bf16_f32 v18, v63, s0
	global_store_short v[16:17], v18, off offset:2176
	s_waitcnt lgkmcnt(0)
	v_mul_f32_e32 v16, v20, v88
	s_waitcnt vmcnt(49)
	v_lshlrev_b32_e32 v65, 16, v65
	v_fmac_f32_e32 v65, v82, v16
	v_lshlrev_b32_e32 v19, 16, v18
	v_cvt_pk_bf16_f32 v18, v65, s0
	v_add_co_u32_e64 v16, s[0:1], s94, v32
	v_fmac_f32_e32 v35, v19, v19
	s_nop 0
	v_addc_co_u32_e64 v17, s[0:1], 0, v33, s[0:1]
	v_lshlrev_b32_e32 v19, 16, v18
	global_store_short v[16:17], v18, off offset:128
	v_mul_f32_e32 v18, v21, v89
	s_waitcnt vmcnt(49)
	v_lshlrev_b32_e32 v62, 16, v62
	v_fmac_f32_e32 v62, v82, v18
	v_cvt_pk_bf16_f32 v18, v62, s0
	global_store_short v[16:17], v18, off offset:2176
	v_mul_f32_e32 v16, v22, v90
	s_waitcnt vmcnt(49)
	v_lshlrev_b32_e32 v68, 16, v68
	v_fmac_f32_e32 v68, v82, v16
	v_fmac_f32_e32 v36, v19, v19
	v_lshlrev_b32_e32 v19, 16, v18
	v_cvt_pk_bf16_f32 v18, v68, s0
	v_add_co_u32_e64 v16, s[0:1], s57, v32
	v_fmac_f32_e32 v37, v19, v19
	s_nop 0
	v_addc_co_u32_e64 v17, s[0:1], 0, v33, s[0:1]
	v_lshlrev_b32_e32 v19, 16, v18
	global_store_short v[16:17], v18, off offset:128
	v_mul_f32_e32 v18, v23, v91
	s_waitcnt vmcnt(49)
	v_lshlrev_b32_e32 v64, 16, v64
	v_fmac_f32_e32 v64, v82, v18
	v_cvt_pk_bf16_f32 v18, v64, s0
	v_fmac_f32_e32 v52, v19, v19
	v_lshlrev_b32_e32 v19, 16, v18
	global_store_short v[16:17], v18, off offset:2176
	v_fmac_f32_e32 v38, v19, v19
	ds_read_b128 v[16:19], v83 offset:192
	v_fmac_f32_e32 v50, v73, v73
	v_fmac_f32_e32 v34, v70, v70
	s_waitcnt lgkmcnt(0)
	v_mul_f32_e32 v16, v24, v16
	s_waitcnt vmcnt(49)
	v_lshlrev_b32_e32 v59, 16, v59
	v_fmac_f32_e32 v59, v82, v16
	v_cvt_pk_bf16_f32 v16, v59, s0
	v_add_co_u32_e64 v20, s[0:1], s35, v32
	v_lshlrev_b32_e32 v22, 16, v16
	s_nop 0
	v_addc_co_u32_e64 v21, s[0:1], 0, v33, s[0:1]
	global_store_short v[20:21], v16, off offset:128
	v_mul_f32_e32 v16, v25, v17
	s_waitcnt vmcnt(49)
	v_lshlrev_b32_e32 v58, 16, v58
	v_fmac_f32_e32 v58, v82, v16
	v_cvt_pk_bf16_f32 v16, v58, s0
	v_lshlrev_b32_e32 v17, 16, v16
	global_store_short v[20:21], v16, off offset:2176
	v_mul_f32_e32 v16, v26, v18
	s_waitcnt vmcnt(49)
	v_lshlrev_b32_e32 v61, 16, v61
	v_fmac_f32_e32 v61, v82, v16
	v_cvt_pk_bf16_f32 v18, v61, s0
	v_add_co_u32_e64 v16, s[0:1], s58, v32
	v_fmac_f32_e32 v41, v17, v17
	s_nop 0
	v_addc_co_u32_e64 v17, s[0:1], 0, v33, s[0:1]
	v_lshlrev_b32_e32 v20, 16, v18
	global_store_short v[16:17], v18, off offset:128
	v_mul_f32_e32 v18, v27, v19
	s_waitcnt vmcnt(49)
	v_lshlrev_b32_e32 v60, 16, v60
	v_fmac_f32_e32 v60, v82, v18
	v_cvt_pk_bf16_f32 v18, v60, s0
	v_lshlrev_b32_e32 v19, 16, v18
	global_store_short v[16:17], v18, off offset:2176
	v_fmac_f32_e32 v39, v19, v19
	ds_read_b128 v[16:19], v83 offset:224
	v_fmac_f32_e32 v40, v20, v20
	v_fmac_f32_e32 v53, v22, v22
	s_waitcnt lgkmcnt(0)
	v_mul_f32_e32 v16, v28, v16
	v_fmac_f32_e32 v56, v82, v16
	v_cvt_pk_bf16_f32 v16, v56, s0
	v_add_co_u32_e64 v20, s[0:1], s95, v32
	v_lshlrev_b32_e32 v22, 16, v16
	s_nop 0
	v_addc_co_u32_e64 v21, s[0:1], 0, v33, s[0:1]
	global_store_short v[20:21], v16, off offset:128
	v_mul_f32_e32 v16, v29, v17
	v_fmac_f32_e32 v54, v82, v16
	v_cvt_pk_bf16_f32 v16, v54, s0
	v_lshlrev_b32_e32 v17, 16, v16
	global_store_short v[20:21], v16, off offset:2176
	v_mul_f32_e32 v16, v30, v18
	s_waitcnt vmcnt(49)
	v_lshlrev_b32_e32 v57, 16, v57
	v_fmac_f32_e32 v57, v82, v16
	v_cvt_pk_bf16_f32 v18, v57, s0
	v_add_co_u32_e64 v16, s[0:1], s59, v32
	v_fmac_f32_e32 v43, v17, v17
	s_nop 0
	v_addc_co_u32_e64 v17, s[0:1], 0, v33, s[0:1]
	v_lshlrev_b32_e32 v20, 16, v18
	global_store_short v[16:17], v18, off offset:128
	v_mul_f32_e32 v18, v31, v19
	s_waitcnt vmcnt(49)
	v_lshlrev_b32_e32 v55, 16, v55
	v_fmac_f32_e32 v55, v82, v18
	v_cvt_pk_bf16_f32 v18, v55, s0
	global_store_short v[16:17], v18, off offset:2176
	v_lshlrev_b32_e32 v19, 16, v18
	v_ashrrev_i32_e32 v129, 31, v128
	v_lshl_add_u64 v[16:17], v[128:129], 0, s[68:69]
	v_fmac_f32_e32 v45, v19, v19
	v_lshl_add_u64 v[18:19], v[16:17], 2, s[36:37]
	global_load_dword v18, v[18:19], off offset:384
	v_fmac_f32_e32 v44, v20, v20
	v_lshl_add_u32 v20, v158, 2, s28
	v_ashrrev_i32_e32 v21, 31, v20
	v_lshlrev_b64 v[20:21], 11, v[20:21]
	v_lshl_add_u64 v[20:21], s[66:67], 0, v[20:21]
	v_lshl_add_u32 v19, v158, 4, s39
	v_fmac_f32_e32 v42, v22, v22
	v_lshl_add_u64 v[16:17], v[16:17], 1, v[20:21]
	ds_read_b128 v[20:23], v19 offset:128
	ds_read_b128 v[24:27], v19 offset:160
	s_waitcnt lgkmcnt(1)
	v_mul_f32_e32 v0, v0, v20
	s_waitcnt vmcnt(0)
	v_fmac_f32_e32 v67, v18, v0
	v_mul_f32_e32 v0, v1, v21
	s_waitcnt vmcnt(32)
	v_lshlrev_b32_e32 v66, 16, v66
	v_fmac_f32_e32 v66, v18, v0
	v_mul_f32_e32 v0, v2, v22
	s_waitcnt vmcnt(31)
	v_lshlrev_b32_e32 v72, 16, v72
	v_fmac_f32_e32 v72, v18, v0
	v_cvt_pk_bf16_f32 v20, v67, s0
	v_cvt_pk_bf16_f32 v21, v66, s0
	v_cvt_pk_bf16_f32 v22, v72, s0
	v_add_co_u32_e64 v0, s[0:1], s96, v16
	v_mul_f32_e32 v2, v3, v23
	s_nop 0
	v_addc_co_u32_e64 v1, s[0:1], 0, v17, s[0:1]
	s_waitcnt vmcnt(30)
	v_lshlrev_b32_e32 v69, 16, v69
	v_fmac_f32_e32 v69, v18, v2
	s_nop 0
	v_cvt_pk_bf16_f32 v23, v69, s0
	global_store_short v[0:1], v22, off offset:192
	global_store_short v[0:1], v23, off offset:2240
	s_waitcnt lgkmcnt(0)
	v_mul_f32_e32 v0, v4, v24
	s_waitcnt vmcnt(31)
	v_lshlrev_b32_e32 v75, 16, v75
	v_fmac_f32_e32 v75, v18, v0
	v_cvt_pk_bf16_f32 v24, v75, s0
	v_add_co_u32_e64 v0, s[0:1], s94, v16
	v_mul_f32_e32 v2, v5, v25
	s_nop 0
	v_addc_co_u32_e64 v1, s[0:1], 0, v17, s[0:1]
	s_waitcnt vmcnt(30)
	v_lshlrev_b32_e32 v74, 16, v74
	v_fmac_f32_e32 v74, v18, v2
	s_nop 0
	v_cvt_pk_bf16_f32 v25, v74, s0
	global_store_short v[0:1], v24, off offset:192
	global_store_short v[0:1], v25, off offset:2240
	v_mul_f32_e32 v0, v6, v26
	s_waitcnt vmcnt(31)
	v_lshlrev_b32_e32 v81, 16, v81
	v_fmac_f32_e32 v81, v18, v0
	v_cvt_pk_bf16_f32 v6, v81, s0
	v_add_co_u32_e64 v0, s[0:1], s57, v16
	v_mul_f32_e32 v2, v7, v27
	s_nop 0
	v_addc_co_u32_e64 v1, s[0:1], 0, v17, s[0:1]
	s_waitcnt vmcnt(30)
	v_lshlrev_b32_e32 v79, 16, v79
	v_fmac_f32_e32 v79, v18, v2
	s_nop 0
	v_cvt_pk_bf16_f32 v7, v79, s0
	global_store_short v[0:1], v6, off offset:192
	global_store_short v[0:1], v7, off offset:2240
	ds_read_b128 v[0:3], v19 offset:192
	global_store_short v[16:17], v20, off offset:192
	global_store_short v[16:17], v21, off offset:2240
	s_waitcnt lgkmcnt(0)
	v_mul_f32_e32 v0, v8, v0
	s_waitcnt vmcnt(33)
	v_lshlrev_b32_e32 v77, 16, v77
	v_fmac_f32_e32 v77, v18, v0
	v_mul_f32_e32 v0, v9, v1
	v_cvt_pk_bf16_f32 v8, v77, s0
	v_add_co_u32_e64 v4, s[0:1], s35, v16
	s_waitcnt vmcnt(32)
	v_lshlrev_b32_e32 v76, 16, v76
	v_fmac_f32_e32 v76, v18, v0
	v_mul_f32_e32 v0, v10, v2
	v_addc_co_u32_e64 v5, s[0:1], 0, v17, s[0:1]
	s_waitcnt vmcnt(31)
	v_lshlrev_b32_e32 v80, 16, v80
	v_fmac_f32_e32 v80, v18, v0
	s_nop 0
	v_cvt_pk_bf16_f32 v9, v76, s0
	v_cvt_pk_bf16_f32 v10, v80, s0
	v_add_co_u32_e64 v0, s[0:1], s58, v16
	v_mul_f32_e32 v2, v11, v3
	s_nop 0
	v_addc_co_u32_e64 v1, s[0:1], 0, v17, s[0:1]
	s_waitcnt vmcnt(30)
	v_lshlrev_b32_e32 v78, 16, v78
	v_fmac_f32_e32 v78, v18, v2
	s_nop 0
	v_cvt_pk_bf16_f32 v11, v78, s0
	global_store_short v[0:1], v10, off offset:192
	global_store_short v[0:1], v11, off offset:2240
	ds_read_b128 v[0:3], v19 offset:224
	global_store_short v[4:5], v8, off offset:192
	global_store_short v[4:5], v9, off offset:2240
	s_waitcnt lgkmcnt(0)
	v_mul_f32_e32 v0, v12, v0
	s_waitcnt vmcnt(33)
	v_lshlrev_b32_e32 v47, 16, v47
	v_fmac_f32_e32 v47, v18, v0
	v_mul_f32_e32 v0, v13, v1
	v_cvt_pk_bf16_f32 v12, v47, s0
	v_add_co_u32_e64 v4, s[0:1], s95, v16
	s_waitcnt vmcnt(32)
	v_lshlrev_b32_e32 v46, 16, v46
	v_fmac_f32_e32 v46, v18, v0
	v_mul_f32_e32 v0, v14, v2
	v_addc_co_u32_e64 v5, s[0:1], 0, v17, s[0:1]
	s_waitcnt vmcnt(31)
	v_lshlrev_b32_e32 v49, 16, v49
	v_fmac_f32_e32 v49, v18, v0
	s_nop 0
	v_cvt_pk_bf16_f32 v13, v46, s0
	v_cvt_pk_bf16_f32 v2, v49, s0
	v_add_co_u32_e64 v0, s[0:1], s59, v16
	v_mul_f32_e32 v3, v15, v3
	s_nop 0
	v_addc_co_u32_e64 v1, s[0:1], 0, v17, s[0:1]
	s_waitcnt vmcnt(30)
	v_lshlrev_b32_e32 v48, 16, v48
	v_fmac_f32_e32 v48, v18, v3
	s_nop 0
	v_cvt_pk_bf16_f32 v3, v48, s0
	global_store_short v[0:1], v2, off offset:192
	global_store_short v[0:1], v3, off offset:2240
	v_lshlrev_b32_e32 v0, 16, v20
	v_fmac_f32_e32 v50, v0, v0
	v_lshlrev_b32_e32 v0, 16, v21
	v_fmac_f32_e32 v51, v0, v0
	v_lshlrev_b32_e32 v0, 16, v22
	v_fmac_f32_e32 v34, v0, v0
	v_lshlrev_b32_e32 v0, 16, v23
	v_fmac_f32_e32 v35, v0, v0
	v_lshlrev_b32_e32 v0, 16, v24
	v_fmac_f32_e32 v36, v0, v0
	v_lshlrev_b32_e32 v0, 16, v25
	v_fmac_f32_e32 v37, v0, v0
	v_lshlrev_b32_e32 v0, 16, v6
	v_fmac_f32_e32 v52, v0, v0
	v_lshlrev_b32_e32 v0, 16, v7
	v_fmac_f32_e32 v38, v0, v0
	v_lshlrev_b32_e32 v0, 16, v8
	v_fmac_f32_e32 v53, v0, v0
	v_lshlrev_b32_e32 v0, 16, v9
	v_fmac_f32_e32 v41, v0, v0
	v_lshlrev_b32_e32 v0, 16, v10
	v_fmac_f32_e32 v40, v0, v0
	v_lshlrev_b32_e32 v0, 16, v11
	v_fmac_f32_e32 v39, v0, v0
	v_lshlrev_b32_e32 v0, 16, v12
	v_fmac_f32_e32 v42, v0, v0
	v_lshlrev_b32_e32 v0, 16, v13
	v_cndmask_b32_e64 v1, v50, v53, s[46:47]
	v_fmac_f32_e32 v43, v0, v0
	v_lshlrev_b32_e32 v0, 16, v2
	ds_bpermute_b32 v1, v157, v1
	v_cndmask_b32_e64 v2, v51, v41, s[46:47]
	v_fmac_f32_e32 v44, v0, v0
	v_lshlrev_b32_e32 v0, 16, v3
	ds_bpermute_b32 v2, v157, v2
	v_cndmask_b32_e64 v3, v34, v40, s[46:47]
	global_store_short v[4:5], v12, off offset:192
	global_store_short v[4:5], v13, off offset:2240
	ds_bpermute_b32 v3, v157, v3
	v_cndmask_b32_e64 v4, v35, v39, s[46:47]
	ds_bpermute_b32 v4, v157, v4
	v_cndmask_b32_e64 v5, v36, v42, s[46:47]
	v_fmac_f32_e32 v45, v0, v0
	v_cndmask_b32_e64 v0, v53, v50, s[46:47]
	ds_bpermute_b32 v5, v157, v5
	v_cndmask_b32_e64 v6, v37, v43, s[46:47]
	s_waitcnt lgkmcnt(4)
	v_add_f32_e32 v0, v0, v1
	v_cndmask_b32_e64 v1, v41, v51, s[46:47]
	ds_bpermute_b32 v6, v157, v6
	v_cndmask_b32_e64 v7, v52, v44, s[46:47]
	s_waitcnt lgkmcnt(4)
	v_add_f32_e32 v1, v1, v2
	v_cndmask_b32_e64 v2, v40, v34, s[46:47]
	ds_bpermute_b32 v7, v157, v7
	v_cndmask_b32_e64 v8, v38, v45, s[46:47]
	s_waitcnt lgkmcnt(4)
	v_add_f32_e32 v2, v2, v3
	v_cndmask_b32_e64 v3, v39, v35, s[46:47]
	ds_bpermute_b32 v8, v157, v8
	s_waitcnt lgkmcnt(4)
	v_add_f32_e32 v3, v3, v4
	v_cndmask_b32_e64 v4, v42, v36, s[46:47]
	s_waitcnt lgkmcnt(3)
	v_add_f32_e32 v4, v4, v5
	v_cndmask_b32_e64 v5, v43, v37, s[46:47]
	s_waitcnt lgkmcnt(2)
	v_add_f32_e32 v5, v5, v6
	v_cndmask_b32_e64 v6, v44, v52, s[46:47]
	s_waitcnt lgkmcnt(1)
	v_add_f32_e32 v6, v6, v7
	v_cndmask_b32_e64 v7, v45, v38, s[46:47]
	s_waitcnt lgkmcnt(0)
	v_add_f32_e32 v7, v7, v8
	v_cndmask_b32_e64 v8, v4, v0, s[44:45]
	v_cndmask_b32_e64 v0, v0, v4, s[44:45]
	v_cndmask_b32_e64 v4, v5, v1, s[44:45]
	v_cndmask_b32_e64 v1, v1, v5, s[44:45]
	ds_bpermute_b32 v1, v156, v1
	ds_bpermute_b32 v0, v156, v0
	s_waitcnt lgkmcnt(1)
	v_add_f32_e32 v1, v4, v1
	v_cndmask_b32_e64 v4, v6, v2, s[44:45]
	v_cndmask_b32_e64 v2, v2, v6, s[44:45]
	ds_bpermute_b32 v2, v156, v2
	s_waitcnt lgkmcnt(1)
	v_add_f32_e32 v0, v8, v0
	s_waitcnt lgkmcnt(0)
	v_add_f32_e32 v2, v4, v2
	v_cndmask_b32_e64 v4, v7, v3, s[44:45]
	v_cndmask_b32_e64 v3, v3, v7, s[44:45]
	ds_bpermute_b32 v3, v156, v3
	s_waitcnt lgkmcnt(0)
	v_add_f32_e32 v3, v4, v3
	v_cndmask_b32_e64 v4, v2, v0, s[42:43]
	v_cndmask_b32_e64 v0, v0, v2, s[42:43]
	v_cndmask_b32_e64 v2, v3, v1, s[42:43]
	v_cndmask_b32_e64 v1, v1, v3, s[42:43]
	ds_bpermute_b32 v0, v155, v0
	ds_bpermute_b32 v1, v155, v1
	s_waitcnt lgkmcnt(1)
	v_add_f32_e32 v0, v4, v0
	s_waitcnt lgkmcnt(0)
	v_add_f32_e32 v1, v2, v1
	v_cndmask_b32_e64 v2, v1, v0, s[40:41]
	v_cndmask_b32_e64 v0, v0, v1, s[40:41]
	ds_bpermute_b32 v0, v154, v0
	s_waitcnt lgkmcnt(0)
	v_add_f32_e32 v0, v2, v0
	ds_bpermute_b32 v1, v153, v0
	s_and_saveexec_b64 s[0:1], vcc
	s_cbranch_execz .LBB0_405
	v_or_b32_e32 v2, s28, v152
	v_ashrrev_i32_e32 v3, 31, v2
	v_lshlrev_b64 v[2:3], 6, v[2:3]
	v_lshl_add_u64 v[2:3], s[26:27], 0, v[2:3]
	s_waitcnt lgkmcnt(0)
	v_add_f32_e32 v0, v0, v1
	global_store_dword v[2:3], v0, off
	s_branch .LBB0_405

.LBB0_488:
	s_or_b64 exec, exec, s[26:27]
	s_lshl_b32 s6, s7, 8
	s_lshl_b64 s[40:41], s[0:1], 11
	s_add_u32 s26, s66, s40
	s_addc_u32 s27, s67, s41
	s_lshl_b32 s7, s7, 19
	s_add_u32 s28, s2, s7
	s_addc_u32 s29, s3, 0
	v_lshrrev_b32_e32 v196, 3, v197
	v_and_b32_e32 v198, 7, v197
	v_lshlrev_b32_e32 v178, 11, v196
	v_lshl_or_b32 v178, v198, 4, v178
	v_add_u32_e32 v179, 0x10000, v178
	v_add_u32_e32 v180, 0x20000, v178
	v_add_u32_e32 v181, 0x30000, v178
	v_add_u32_e32 v182, 0x40000, v178
	v_add_u32_e32 v183, 0x50000, v178
	v_add_u32_e32 v184, 0x60000, v178
	v_add_u32_e32 v185, 0x70000, v178
	global_load_dwordx4 v[128:131], v178, s[26:27]
	global_load_dwordx4 v[132:135], v179, s[26:27]
	global_load_dwordx4 v[136:139], v180, s[26:27]
	global_load_dwordx4 v[140:143], v181, s[26:27]
	global_load_dwordx4 v[144:147], v178, s[28:29]
	global_load_dwordx4 v[148:151], v179, s[28:29]
	global_load_dwordx4 v[152:155], v180, s[28:29]
	global_load_dwordx4 v[156:159], v181, s[28:29]
	global_load_dwordx4 v[160:163], v182, s[28:29]
	global_load_dwordx4 v[164:167], v183, s[28:29]
	global_load_dwordx4 v[168:171], v184, s[28:29]
	global_load_dwordx4 v[172:175], v185, s[28:29]
	s_add_u32 s26, s26, 0x80
	s_addc_u32 s27, s27, 0
	s_add_u32 s28, s28, 0x80
	s_addc_u32 s29, s29, 0
	v_bfe_u32 v217, v197, 5, 2
	v_and_b32_e32 v218, 3, v198
	v_xor_b32_e32 v218, v218, v217
	v_lshlrev_b32_e32 v218, 4, v218
	v_lshl_or_b32 v177, v196, 6, v218
	v_lshrrev_b32_e32 v217, 2, v198
	v_lshlrev_b32_e32 v218, 6, v217
	v_xor_b32_e32 v177, v177, v218
	v_mul_u32_u24_e32 v217, 0x6000, v217
	v_add_u32_e32 v177, v177, v217
	v_and_b32_e32 v196, 31, v197
	v_bfe_u32 v198, v197, 5, 1
	v_bfe_u32 v217, v197, 2, 2
	v_xor_b32_e32 v218, v198, v217
	v_xor_b32_e32 v221, 2, v218
	v_lshrrev_b32_e32 v198, 7, v197
	v_lshl_or_b32 v198, v198, 6, v196
	v_lshlrev_b32_e32 v198, 6, v198
	v_lshl_or_b32 v186, v218, 4, v198
	v_lshl_or_b32 v187, v221, 4, v198
	v_bfe_u32 v198, v197, 6, 1
	v_mul_u32_u24_e32 v198, 128, v198
	v_add_u32_e32 v198, v198, v196
	v_lshlrev_b32_e32 v198, 6, v198
	v_add_u32_e32 v198, 0x2000, v198
	v_lshl_or_b32 v188, v218, 4, v198
	v_lshl_or_b32 v189, v221, 4, v198
	v_mov_b64_e32 v[0:1], 0
	v_mov_b64_e32 v[2:3], 0
	v_mov_b64_e32 v[4:5], 0
	v_mov_b64_e32 v[6:7], 0
	v_mov_b64_e32 v[8:9], 0
	v_mov_b64_e32 v[10:11], 0
	v_mov_b64_e32 v[12:13], 0
	v_mov_b64_e32 v[14:15], 0
	v_mov_b64_e32 v[16:17], 0
	v_mov_b64_e32 v[18:19], 0
	v_mov_b64_e32 v[20:21], 0
	v_mov_b64_e32 v[22:23], 0
	v_mov_b64_e32 v[24:25], 0
	v_mov_b64_e32 v[26:27], 0
	v_mov_b64_e32 v[28:29], 0
	v_mov_b64_e32 v[30:31], 0
	v_mov_b64_e32 v[32:33], 0
	v_mov_b64_e32 v[34:35], 0
	v_mov_b64_e32 v[36:37], 0
	v_mov_b64_e32 v[38:39], 0
	v_mov_b64_e32 v[40:41], 0
	v_mov_b64_e32 v[42:43], 0
	v_mov_b64_e32 v[44:45], 0
	v_mov_b64_e32 v[46:47], 0
	v_mov_b64_e32 v[48:49], 0
	v_mov_b64_e32 v[50:51], 0
	v_mov_b64_e32 v[52:53], 0
	v_mov_b64_e32 v[54:55], 0
	v_mov_b64_e32 v[56:57], 0
	v_mov_b64_e32 v[58:59], 0
	v_mov_b64_e32 v[60:61], 0
	v_mov_b64_e32 v[62:63], 0
	v_mov_b64_e32 v[64:65], 0
	v_mov_b64_e32 v[66:67], 0
	v_mov_b64_e32 v[68:69], 0
	v_mov_b64_e32 v[70:71], 0
	v_mov_b64_e32 v[72:73], 0
	v_mov_b64_e32 v[74:75], 0
	v_mov_b64_e32 v[76:77], 0
	v_mov_b64_e32 v[78:79], 0
	v_mov_b64_e32 v[80:81], 0
	v_mov_b64_e32 v[82:83], 0
	v_mov_b64_e32 v[84:85], 0
	v_mov_b64_e32 v[86:87], 0
	v_mov_b64_e32 v[88:89], 0
	v_mov_b64_e32 v[90:91], 0
	v_mov_b64_e32 v[92:93], 0
	v_mov_b64_e32 v[94:95], 0
	v_mov_b64_e32 v[96:97], 0
	v_mov_b64_e32 v[98:99], 0
	v_mov_b64_e32 v[100:101], 0
	v_mov_b64_e32 v[102:103], 0
	v_mov_b64_e32 v[104:105], 0
	v_mov_b64_e32 v[106:107], 0
	v_mov_b64_e32 v[108:109], 0
	v_mov_b64_e32 v[110:111], 0
	v_mov_b64_e32 v[112:113], 0
	v_mov_b64_e32 v[114:115], 0
	v_mov_b64_e32 v[116:117], 0
	v_mov_b64_e32 v[118:119], 0
	v_mov_b64_e32 v[120:121], 0
	v_mov_b64_e32 v[122:123], 0
	v_mov_b64_e32 v[124:125], 0
	v_mov_b64_e32 v[126:127], 0
	s_mov_b32 s36, 0
	s_mov_b32 s37, 0x6000
	s_mov_b32 s1, 0
	s_waitcnt vmcnt(11)
	ds_write_b128 v177, v[128:131]
	s_waitcnt vmcnt(10)
	ds_write_b128 v177, v[132:135] offset:2048
	s_waitcnt vmcnt(9)
	ds_write_b128 v177, v[136:139] offset:4096
	s_waitcnt vmcnt(8)
	ds_write_b128 v177, v[140:143] offset:6144
	s_waitcnt vmcnt(7)
	ds_write_b128 v177, v[144:147] offset:8192
	s_waitcnt vmcnt(6)
	ds_write_b128 v177, v[148:151] offset:10240
	s_waitcnt vmcnt(5)
	ds_write_b128 v177, v[152:155] offset:12288
	s_waitcnt vmcnt(4)
	ds_write_b128 v177, v[156:159] offset:14336
	s_waitcnt vmcnt(3)
	ds_write_b128 v177, v[160:163] offset:16384
	s_waitcnt vmcnt(2)
	ds_write_b128 v177, v[164:167] offset:18432
	s_waitcnt vmcnt(1)
	ds_write_b128 v177, v[168:171] offset:20480
	s_waitcnt vmcnt(0)
	ds_write_b128 v177, v[172:175] offset:22528
	v_subrev_u32_e32 v196, 0x6000, v177
	v_add_u32_e32 v198, 0xc000, v177
	v_min_u32_e32 v177, v196, v198
	s_waitcnt lgkmcnt(0)
	s_barrier
.Lg5_loop:
	v_add_u32_e32 v190, s36, v186
	v_add_u32_e32 v191, s36, v187
	v_add_u32_e32 v250, s36, v188
	v_add_u32_e32 v251, s36, v189
	ds_read_b128 v[200:203], v190
	ds_read_b128 v[204:207], v190 offset:2048
	ds_read_b128 v[222:225], v250
	ds_read_b128 v[226:229], v250 offset:2048
	ds_read_b128 v[230:233], v250 offset:4096
	ds_read_b128 v[234:237], v250 offset:6144
	s_setprio 1
	s_waitcnt lgkmcnt(3)
	v_mfma_f32_32x32x16_bf16 v[112:127], v[200:203], v[222:225], v[112:127]
	global_load_dwordx4 v[128:131], v178, s[26:27]
	ds_read_b128 v[208:211], v191
	v_mfma_f32_32x32x16_bf16 v[48:63], v[204:207], v[222:225], v[48:63]
	global_load_dwordx4 v[132:135], v179, s[26:27]
	ds_read_b128 v[212:215], v191 offset:2048
	s_waitcnt lgkmcnt(4)
	v_mfma_f32_32x32x16_bf16 v[96:111], v[200:203], v[226:229], v[96:111]
	global_load_dwordx4 v[136:139], v180, s[26:27]
	ds_read_b128 v[238:241], v251
	v_mfma_f32_32x32x16_bf16 v[32:47], v[204:207], v[226:229], v[32:47]
	global_load_dwordx4 v[140:143], v181, s[26:27]
	ds_read_b128 v[242:245], v251 offset:2048
	s_waitcnt lgkmcnt(5)
	v_mfma_f32_32x32x16_bf16 v[80:95], v[200:203], v[230:233], v[80:95]
	global_load_dwordx4 v[144:147], v178, s[28:29]
	ds_read_b128 v[246:249], v251 offset:4096
	v_mfma_f32_32x32x16_bf16 v[16:31], v[204:207], v[230:233], v[16:31]
	global_load_dwordx4 v[148:151], v179, s[28:29]
	ds_read_b128 v[192:195], v251 offset:6144
	s_waitcnt lgkmcnt(6)
	v_mfma_f32_32x32x16_bf16 v[64:79], v[200:203], v[234:237], v[64:79]
	global_load_dwordx4 v[152:155], v180, s[28:29]
	v_mfma_f32_32x32x16_bf16 v[0:15], v[204:207], v[234:237], v[0:15]
	global_load_dwordx4 v[156:159], v181, s[28:29]
	v_xad_u32 v190, v186, 64, s37
	v_xad_u32 v250, v188, 64, s37
	s_waitcnt lgkmcnt(3)
	v_mfma_f32_32x32x16_bf16 v[112:127], v[208:211], v[238:241], v[112:127]
	global_load_dwordx4 v[160:163], v182, s[28:29]
	ds_read_b128 v[200:203], v190
	v_mfma_f32_32x32x16_bf16 v[48:63], v[212:215], v[238:241], v[48:63]
	global_load_dwordx4 v[164:167], v183, s[28:29]
	ds_read_b128 v[204:207], v190 offset:2048
	s_waitcnt lgkmcnt(4)
	v_mfma_f32_32x32x16_bf16 v[96:111], v[208:211], v[242:245], v[96:111]
	global_load_dwordx4 v[168:171], v184, s[28:29]
	ds_read_b128 v[222:225], v250
	v_mfma_f32_32x32x16_bf16 v[32:47], v[212:215], v[242:245], v[32:47]
	global_load_dwordx4 v[172:175], v185, s[28:29]
	ds_read_b128 v[226:229], v250 offset:2048
	s_waitcnt lgkmcnt(5)
	v_mfma_f32_32x32x16_bf16 v[80:95], v[208:211], v[246:249], v[80:95]
	ds_read_b128 v[230:233], v250 offset:4096
	v_mfma_f32_32x32x16_bf16 v[16:31], v[212:215], v[246:249], v[16:31]
	ds_read_b128 v[234:237], v250 offset:6144
	s_waitcnt lgkmcnt(6)
	v_mfma_f32_32x32x16_bf16 v[64:79], v[208:211], v[192:195], v[64:79]
	v_mfma_f32_32x32x16_bf16 v[0:15], v[212:215], v[192:195], v[0:15]
	s_setprio 0
	s_barrier
	v_xad_u32 v191, v187, 64, s37
	v_xad_u32 v251, v189, 64, s37
	s_setprio 1
	s_waitcnt lgkmcnt(3)
	v_mfma_f32_32x32x16_bf16 v[112:127], v[200:203], v[222:225], v[112:127]
	ds_read_b128 v[208:211], v191
	v_mfma_f32_32x32x16_bf16 v[48:63], v[204:207], v[222:225], v[48:63]
	ds_read_b128 v[212:215], v191 offset:2048
	s_waitcnt lgkmcnt(4)
	v_mfma_f32_32x32x16_bf16 v[96:111], v[200:203], v[226:229], v[96:111]
	ds_read_b128 v[238:241], v251
	s_waitcnt vmcnt(11)
	ds_write_b128 v177, v[128:131]
	v_mfma_f32_32x32x16_bf16 v[32:47], v[204:207], v[226:229], v[32:47]
	ds_read_b128 v[242:245], v251 offset:2048
	s_waitcnt vmcnt(10)
	ds_write_b128 v177, v[132:135] offset:2048
	s_waitcnt lgkmcnt(7)
	v_mfma_f32_32x32x16_bf16 v[80:95], v[200:203], v[230:233], v[80:95]
	ds_read_b128 v[246:249], v251 offset:4096
	s_waitcnt vmcnt(9)
	ds_write_b128 v177, v[136:139] offset:4096
	v_mfma_f32_32x32x16_bf16 v[16:31], v[204:207], v[230:233], v[16:31]
	ds_read_b128 v[192:195], v251 offset:6144
	s_waitcnt vmcnt(8)
	ds_write_b128 v177, v[140:143] offset:6144
	s_waitcnt lgkmcnt(10)
	v_mfma_f32_32x32x16_bf16 v[64:79], v[200:203], v[234:237], v[64:79]
	s_waitcnt vmcnt(7)
	ds_write_b128 v177, v[144:147] offset:8192
	v_mfma_f32_32x32x16_bf16 v[0:15], v[204:207], v[234:237], v[0:15]
	s_waitcnt vmcnt(6)
	ds_write_b128 v177, v[148:151] offset:10240
	s_waitcnt lgkmcnt(9)
	v_mfma_f32_32x32x16_bf16 v[112:127], v[208:211], v[238:241], v[112:127]
	s_waitcnt vmcnt(5)
	ds_write_b128 v177, v[152:155] offset:12288
	v_mfma_f32_32x32x16_bf16 v[48:63], v[212:215], v[238:241], v[48:63]
	s_waitcnt vmcnt(4)
	ds_write_b128 v177, v[156:159] offset:14336
	s_waitcnt lgkmcnt(9)
	v_mfma_f32_32x32x16_bf16 v[96:111], v[208:211], v[242:245], v[96:111]
	s_waitcnt vmcnt(3)
	ds_write_b128 v177, v[160:163] offset:16384
	v_mfma_f32_32x32x16_bf16 v[32:47], v[212:215], v[242:245], v[32:47]
	s_waitcnt vmcnt(2)
	ds_write_b128 v177, v[164:167] offset:18432
	s_waitcnt lgkmcnt(9)
	v_mfma_f32_32x32x16_bf16 v[80:95], v[208:211], v[246:249], v[80:95]
	s_waitcnt vmcnt(1)
	ds_write_b128 v177, v[168:171] offset:20480
	v_mfma_f32_32x32x16_bf16 v[16:31], v[212:215], v[246:249], v[16:31]
	s_waitcnt vmcnt(0)
	ds_write_b128 v177, v[172:175] offset:22528
	s_waitcnt lgkmcnt(9)
	v_mfma_f32_32x32x16_bf16 v[64:79], v[208:211], v[192:195], v[64:79]
	v_mfma_f32_32x32x16_bf16 v[0:15], v[212:215], v[192:195], v[0:15]
	s_setprio 0
	s_add_u32 s26, s26, 0x80
	s_addc_u32 s27, s27, 0
	s_add_u32 s28, s28, 0x80
	s_addc_u32 s29, s29, 0
	s_sub_i32 s36, s36, 0x6000
	s_cmp_lt_i32 s36, 0
	s_cselect_b32 s38, 0x12000, 0
	s_add_i32 s36, s36, s38
	s_sub_i32 s37, s37, 0x6000
	s_cmp_lt_i32 s37, 0
	s_cselect_b32 s38, 0x12000, 0
	s_add_i32 s37, s37, s38
	v_subrev_u32_e32 v196, 0x6000, v177
	v_add_u32_e32 v198, 0xc000, v177
	v_min_u32_e32 v177, v196, v198
	s_add_i32 s1, s1, 1
	s_cmp_lt_u32 s1, 15
	s_waitcnt lgkmcnt(0)
	s_barrier
	s_cbranch_scc1 .Lg5_loop
	v_add_u32_e32 v190, s36, v186
	v_add_u32_e32 v191, s36, v187
	v_add_u32_e32 v250, s36, v188
	v_add_u32_e32 v251, s36, v189
	ds_read_b128 v[200:203], v190
	ds_read_b128 v[204:207], v190 offset:2048
	ds_read_b128 v[222:225], v250
	ds_read_b128 v[226:229], v250 offset:2048
	ds_read_b128 v[230:233], v250 offset:4096
	ds_read_b128 v[234:237], v250 offset:6144
	s_setprio 1
	s_waitcnt lgkmcnt(3)
	v_mfma_f32_32x32x16_bf16 v[112:127], v[200:203], v[222:225], v[112:127]
	ds_read_b128 v[208:211], v191
	v_mfma_f32_32x32x16_bf16 v[48:63], v[204:207], v[222:225], v[48:63]
	ds_read_b128 v[212:215], v191 offset:2048
	s_waitcnt lgkmcnt(4)
	v_mfma_f32_32x32x16_bf16 v[96:111], v[200:203], v[226:229], v[96:111]
	ds_read_b128 v[238:241], v251
	v_mfma_f32_32x32x16_bf16 v[32:47], v[204:207], v[226:229], v[32:47]
	ds_read_b128 v[242:245], v251 offset:2048
	s_waitcnt lgkmcnt(5)
	v_mfma_f32_32x32x16_bf16 v[80:95], v[200:203], v[230:233], v[80:95]
	ds_read_b128 v[246:249], v251 offset:4096
	v_mfma_f32_32x32x16_bf16 v[16:31], v[204:207], v[230:233], v[16:31]
	ds_read_b128 v[192:195], v251 offset:6144
	s_waitcnt lgkmcnt(6)
	v_mfma_f32_32x32x16_bf16 v[64:79], v[200:203], v[234:237], v[64:79]
	v_mfma_f32_32x32x16_bf16 v[0:15], v[204:207], v[234:237], v[0:15]
	v_xad_u32 v190, v186, 64, s37
	v_xad_u32 v250, v188, 64, s37
	s_waitcnt lgkmcnt(3)
	v_mfma_f32_32x32x16_bf16 v[112:127], v[208:211], v[238:241], v[112:127]
	ds_read_b128 v[200:203], v190
	v_mfma_f32_32x32x16_bf16 v[48:63], v[212:215], v[238:241], v[48:63]
	ds_read_b128 v[204:207], v190 offset:2048
	s_waitcnt lgkmcnt(4)
	v_mfma_f32_32x32x16_bf16 v[96:111], v[208:211], v[242:245], v[96:111]
	ds_read_b128 v[222:225], v250
	v_mfma_f32_32x32x16_bf16 v[32:47], v[212:215], v[242:245], v[32:47]
	ds_read_b128 v[226:229], v250 offset:2048
	s_waitcnt lgkmcnt(5)
	v_mfma_f32_32x32x16_bf16 v[80:95], v[208:211], v[246:249], v[80:95]
	ds_read_b128 v[230:233], v250 offset:4096
	v_mfma_f32_32x32x16_bf16 v[16:31], v[212:215], v[246:249], v[16:31]
	ds_read_b128 v[234:237], v250 offset:6144
	s_waitcnt lgkmcnt(6)
	v_mfma_f32_32x32x16_bf16 v[64:79], v[208:211], v[192:195], v[64:79]
	v_mfma_f32_32x32x16_bf16 v[0:15], v[212:215], v[192:195], v[0:15]
	s_setprio 0
	v_xad_u32 v191, v187, 64, s37
	v_xad_u32 v251, v189, 64, s37
	s_setprio 1
	s_waitcnt lgkmcnt(3)
	v_mfma_f32_32x32x16_bf16 v[112:127], v[200:203], v[222:225], v[112:127]
	ds_read_b128 v[208:211], v191
	v_mfma_f32_32x32x16_bf16 v[48:63], v[204:207], v[222:225], v[48:63]
	ds_read_b128 v[212:215], v191 offset:2048
	s_waitcnt lgkmcnt(4)
	v_mfma_f32_32x32x16_bf16 v[96:111], v[200:203], v[226:229], v[96:111]
	ds_read_b128 v[238:241], v251
	v_mfma_f32_32x32x16_bf16 v[32:47], v[204:207], v[226:229], v[32:47]
	ds_read_b128 v[242:245], v251 offset:2048
	s_waitcnt lgkmcnt(5)
	v_mfma_f32_32x32x16_bf16 v[80:95], v[200:203], v[230:233], v[80:95]
	ds_read_b128 v[246:249], v251 offset:4096
	v_mfma_f32_32x32x16_bf16 v[16:31], v[204:207], v[230:233], v[16:31]
	ds_read_b128 v[192:195], v251 offset:6144
	s_waitcnt lgkmcnt(6)
	v_mfma_f32_32x32x16_bf16 v[64:79], v[200:203], v[234:237], v[64:79]
	v_mfma_f32_32x32x16_bf16 v[0:15], v[204:207], v[234:237], v[0:15]
	s_waitcnt lgkmcnt(3)
	v_mfma_f32_32x32x16_bf16 v[112:127], v[208:211], v[238:241], v[112:127]
	v_mfma_f32_32x32x16_bf16 v[48:63], v[212:215], v[238:241], v[48:63]
	s_waitcnt lgkmcnt(2)
	v_mfma_f32_32x32x16_bf16 v[96:111], v[208:211], v[242:245], v[96:111]
	v_mfma_f32_32x32x16_bf16 v[32:47], v[212:215], v[242:245], v[32:47]
	s_waitcnt lgkmcnt(1)
	v_mfma_f32_32x32x16_bf16 v[80:95], v[208:211], v[246:249], v[80:95]
	v_mfma_f32_32x32x16_bf16 v[16:31], v[212:215], v[246:249], v[16:31]
	s_waitcnt lgkmcnt(0)
	v_mfma_f32_32x32x16_bf16 v[64:79], v[208:211], v[192:195], v[64:79]
	v_mfma_f32_32x32x16_bf16 v[0:15], v[212:215], v[192:195], v[0:15]
	s_setprio 0
	s_nop 7
	s_nop 7
	s_branch .LBB0_482

.LBB0_551:
	s_lshl_b32 s6, s5, 5
	s_and_b32 s26, s6, 0xffffff80
	s_lshl_b32 s6, s5, 8
	s_ashr_i32 s27, s26, 31
	s_and_b32 s68, s6, 0x300
	s_lshl_b64 s[8:9], s[26:27], 13
	s_add_u32 s28, s70, s8
	s_addc_u32 s29, s71, s9
	s_lshl_b32 s7, s68, 13
	s_add_u32 s38, s80, s7
	s_addc_u32 s39, s81, 0
	v_lshrrev_b32_e32 v196, 3, v197
	v_and_b32_e32 v198, 7, v197
	v_lshlrev_b32_e32 v176, 13, v196
	v_lshl_or_b32 v176, v198, 4, v176
	v_add_u32_e32 v177, 0x40000, v176
	v_add_u32_e32 v178, 0x80000, v176
	v_add_u32_e32 v179, 0xc0000, v176
	v_add_u32_e32 v180, 0x100000, v176
	v_add_u32_e32 v181, 0x140000, v176
	v_add_u32_e32 v182, 0x180000, v176
	v_add_u32_e32 v184, 0x1c0000, v176
	global_load_dwordx4 v[128:131], v176, s[28:29]
	global_load_dwordx4 v[132:135], v177, s[28:29]
	global_load_dwordx4 v[136:139], v178, s[28:29]
	global_load_dwordx4 v[140:143], v179, s[28:29]
	global_load_dwordx4 v[144:147], v176, s[38:39]
	global_load_dwordx4 v[148:151], v177, s[38:39]
	global_load_dwordx4 v[152:155], v178, s[38:39]
	global_load_dwordx4 v[156:159], v179, s[38:39]
	global_load_dwordx4 v[160:163], v180, s[38:39]
	global_load_dwordx4 v[164:167], v181, s[38:39]
	global_load_dwordx4 v[168:171], v182, s[38:39]
	global_load_dwordx4 v[172:175], v184, s[38:39]
	s_add_u32 s28, s28, 0x80
	s_addc_u32 s29, s29, 0
	s_add_u32 s38, s38, 0x80
	s_addc_u32 s39, s39, 0
	v_bfe_u32 v217, v197, 5, 2
	v_and_b32_e32 v218, 3, v198
	v_xor_b32_e32 v218, v218, v217
	v_lshlrev_b32_e32 v218, 4, v218
	v_lshl_or_b32 v185, v196, 6, v218
	v_lshrrev_b32_e32 v217, 2, v198
	v_lshlrev_b32_e32 v218, 6, v217
	v_xor_b32_e32 v185, v185, v218
	v_mul_u32_u24_e32 v217, 0x6000, v217
	v_add_u32_e32 v185, v185, v217
	v_and_b32_e32 v196, 31, v197
	v_bfe_u32 v198, v197, 5, 1
	v_bfe_u32 v217, v197, 2, 2
	v_xor_b32_e32 v218, v198, v217
	v_xor_b32_e32 v221, 2, v218
	v_lshrrev_b32_e32 v198, 7, v197
	v_lshl_or_b32 v198, v198, 6, v196
	v_lshlrev_b32_e32 v198, 6, v198
	v_lshl_or_b32 v186, v218, 4, v198
	v_lshl_or_b32 v187, v221, 4, v198
	v_bfe_u32 v198, v197, 6, 1
	v_mul_u32_u24_e32 v198, 128, v198
	v_add_u32_e32 v198, v198, v196
	v_lshlrev_b32_e32 v198, 6, v198
	v_add_u32_e32 v198, 0x2000, v198
	v_lshl_or_b32 v188, v218, 4, v198
	v_lshl_or_b32 v189, v221, 4, v198
	v_mov_b64_e32 v[0:1], 0
	v_mov_b64_e32 v[2:3], 0
	v_mov_b64_e32 v[4:5], 0
	v_mov_b64_e32 v[6:7], 0
	v_mov_b64_e32 v[8:9], 0
	v_mov_b64_e32 v[10:11], 0
	v_mov_b64_e32 v[12:13], 0
	v_mov_b64_e32 v[14:15], 0
	v_mov_b64_e32 v[16:17], 0
	v_mov_b64_e32 v[18:19], 0
	v_mov_b64_e32 v[20:21], 0
	v_mov_b64_e32 v[22:23], 0
	v_mov_b64_e32 v[24:25], 0
	v_mov_b64_e32 v[26:27], 0
	v_mov_b64_e32 v[28:29], 0
	v_mov_b64_e32 v[30:31], 0
	v_mov_b64_e32 v[32:33], 0
	v_mov_b64_e32 v[34:35], 0
	v_mov_b64_e32 v[36:37], 0
	v_mov_b64_e32 v[38:39], 0
	v_mov_b64_e32 v[40:41], 0
	v_mov_b64_e32 v[42:43], 0
	v_mov_b64_e32 v[44:45], 0
	v_mov_b64_e32 v[46:47], 0
	v_mov_b64_e32 v[48:49], 0
	v_mov_b64_e32 v[50:51], 0
	v_mov_b64_e32 v[52:53], 0
	v_mov_b64_e32 v[54:55], 0
	v_mov_b64_e32 v[56:57], 0
	v_mov_b64_e32 v[58:59], 0
	v_mov_b64_e32 v[60:61], 0
	v_mov_b64_e32 v[62:63], 0
	v_mov_b64_e32 v[64:65], 0
	v_mov_b64_e32 v[66:67], 0
	v_mov_b64_e32 v[68:69], 0
	v_mov_b64_e32 v[70:71], 0
	v_mov_b64_e32 v[72:73], 0
	v_mov_b64_e32 v[74:75], 0
	v_mov_b64_e32 v[76:77], 0
	v_mov_b64_e32 v[78:79], 0
	v_mov_b64_e32 v[80:81], 0
	v_mov_b64_e32 v[82:83], 0
	v_mov_b64_e32 v[84:85], 0
	v_mov_b64_e32 v[86:87], 0
	v_mov_b64_e32 v[88:89], 0
	v_mov_b64_e32 v[90:91], 0
	v_mov_b64_e32 v[92:93], 0
	v_mov_b64_e32 v[94:95], 0
	v_mov_b64_e32 v[96:97], 0
	v_mov_b64_e32 v[98:99], 0
	v_mov_b64_e32 v[100:101], 0
	v_mov_b64_e32 v[102:103], 0
	v_mov_b64_e32 v[104:105], 0
	v_mov_b64_e32 v[106:107], 0
	v_mov_b64_e32 v[108:109], 0
	v_mov_b64_e32 v[110:111], 0
	v_mov_b64_e32 v[112:113], 0
	v_mov_b64_e32 v[114:115], 0
	v_mov_b64_e32 v[116:117], 0
	v_mov_b64_e32 v[118:119], 0
	v_mov_b64_e32 v[120:121], 0
	v_mov_b64_e32 v[122:123], 0
	v_mov_b64_e32 v[124:125], 0
	v_mov_b64_e32 v[126:127], 0
	s_mov_b32 s40, 0
	s_mov_b32 s41, 0x6000
	s_mov_b32 s7, 0
	s_waitcnt vmcnt(11)
	ds_write_b128 v185, v[128:131]
	s_waitcnt vmcnt(10)
	ds_write_b128 v185, v[132:135] offset:2048
	s_waitcnt vmcnt(9)
	ds_write_b128 v185, v[136:139] offset:4096
	s_waitcnt vmcnt(8)
	ds_write_b128 v185, v[140:143] offset:6144
	s_waitcnt vmcnt(7)
	ds_write_b128 v185, v[144:147] offset:8192
	s_waitcnt vmcnt(6)
	ds_write_b128 v185, v[148:151] offset:10240
	s_waitcnt vmcnt(5)
	ds_write_b128 v185, v[152:155] offset:12288
	s_waitcnt vmcnt(4)
	ds_write_b128 v185, v[156:159] offset:14336
	s_waitcnt vmcnt(3)
	ds_write_b128 v185, v[160:163] offset:16384
	s_waitcnt vmcnt(2)
	ds_write_b128 v185, v[164:167] offset:18432
	s_waitcnt vmcnt(1)
	ds_write_b128 v185, v[168:171] offset:20480
	s_waitcnt vmcnt(0)
	ds_write_b128 v185, v[172:175] offset:22528
	v_subrev_u32_e32 v196, 0x6000, v185
	v_add_u32_e32 v198, 0xc000, v185
	v_min_u32_e32 v185, v196, v198
	s_waitcnt lgkmcnt(0)
	s_barrier
.Lg6_loop:
	v_add_u32_e32 v190, s40, v186
	v_add_u32_e32 v191, s40, v187
	v_add_u32_e32 v250, s40, v188
	v_add_u32_e32 v251, s40, v189
	ds_read_b128 v[200:203], v190
	ds_read_b128 v[204:207], v190 offset:2048
	ds_read_b128 v[222:225], v250
	ds_read_b128 v[226:229], v250 offset:2048
	ds_read_b128 v[230:233], v250 offset:4096
	ds_read_b128 v[234:237], v250 offset:6144
	s_setprio 1
	s_waitcnt lgkmcnt(3)
	v_mfma_f32_32x32x16_bf16 v[112:127], v[200:203], v[222:225], v[112:127]
	global_load_dwordx4 v[128:131], v176, s[28:29]
	ds_read_b128 v[208:211], v191
	v_mfma_f32_32x32x16_bf16 v[48:63], v[204:207], v[222:225], v[48:63]
	global_load_dwordx4 v[132:135], v177, s[28:29]
	ds_read_b128 v[212:215], v191 offset:2048
	s_waitcnt lgkmcnt(4)
	v_mfma_f32_32x32x16_bf16 v[96:111], v[200:203], v[226:229], v[96:111]
	global_load_dwordx4 v[136:139], v178, s[28:29]
	ds_read_b128 v[238:241], v251
	v_mfma_f32_32x32x16_bf16 v[32:47], v[204:207], v[226:229], v[32:47]
	global_load_dwordx4 v[140:143], v179, s[28:29]
	ds_read_b128 v[242:245], v251 offset:2048
	s_waitcnt lgkmcnt(5)
	v_mfma_f32_32x32x16_bf16 v[80:95], v[200:203], v[230:233], v[80:95]
	global_load_dwordx4 v[144:147], v176, s[38:39]
	ds_read_b128 v[246:249], v251 offset:4096
	v_mfma_f32_32x32x16_bf16 v[16:31], v[204:207], v[230:233], v[16:31]
	global_load_dwordx4 v[148:151], v177, s[38:39]
	ds_read_b128 v[192:195], v251 offset:6144
	s_waitcnt lgkmcnt(6)
	v_mfma_f32_32x32x16_bf16 v[64:79], v[200:203], v[234:237], v[64:79]
	global_load_dwordx4 v[152:155], v178, s[38:39]
	v_mfma_f32_32x32x16_bf16 v[0:15], v[204:207], v[234:237], v[0:15]
	global_load_dwordx4 v[156:159], v179, s[38:39]
	v_xad_u32 v190, v186, 64, s41
	v_xad_u32 v250, v188, 64, s41
	s_waitcnt lgkmcnt(3)
	v_mfma_f32_32x32x16_bf16 v[112:127], v[208:211], v[238:241], v[112:127]
	global_load_dwordx4 v[160:163], v180, s[38:39]
	ds_read_b128 v[200:203], v190
	v_mfma_f32_32x32x16_bf16 v[48:63], v[212:215], v[238:241], v[48:63]
	global_load_dwordx4 v[164:167], v181, s[38:39]
	ds_read_b128 v[204:207], v190 offset:2048
	s_waitcnt lgkmcnt(4)
	v_mfma_f32_32x32x16_bf16 v[96:111], v[208:211], v[242:245], v[96:111]
	global_load_dwordx4 v[168:171], v182, s[38:39]
	ds_read_b128 v[222:225], v250
	v_mfma_f32_32x32x16_bf16 v[32:47], v[212:215], v[242:245], v[32:47]
	global_load_dwordx4 v[172:175], v184, s[38:39]
	ds_read_b128 v[226:229], v250 offset:2048
	s_waitcnt lgkmcnt(5)
	v_mfma_f32_32x32x16_bf16 v[80:95], v[208:211], v[246:249], v[80:95]
	ds_read_b128 v[230:233], v250 offset:4096
	v_mfma_f32_32x32x16_bf16 v[16:31], v[212:215], v[246:249], v[16:31]
	ds_read_b128 v[234:237], v250 offset:6144
	s_waitcnt lgkmcnt(6)
	v_mfma_f32_32x32x16_bf16 v[64:79], v[208:211], v[192:195], v[64:79]
	v_mfma_f32_32x32x16_bf16 v[0:15], v[212:215], v[192:195], v[0:15]
	s_setprio 0
	s_barrier
	v_xad_u32 v191, v187, 64, s41
	v_xad_u32 v251, v189, 64, s41
	s_setprio 1
	s_waitcnt lgkmcnt(3)
	v_mfma_f32_32x32x16_bf16 v[112:127], v[200:203], v[222:225], v[112:127]
	ds_read_b128 v[208:211], v191
	v_mfma_f32_32x32x16_bf16 v[48:63], v[204:207], v[222:225], v[48:63]
	ds_read_b128 v[212:215], v191 offset:2048
	s_waitcnt lgkmcnt(4)
	v_mfma_f32_32x32x16_bf16 v[96:111], v[200:203], v[226:229], v[96:111]
	ds_read_b128 v[238:241], v251
	s_waitcnt vmcnt(11)
	ds_write_b128 v185, v[128:131]
	v_mfma_f32_32x32x16_bf16 v[32:47], v[204:207], v[226:229], v[32:47]
	ds_read_b128 v[242:245], v251 offset:2048
	s_waitcnt vmcnt(10)
	ds_write_b128 v185, v[132:135] offset:2048
	s_waitcnt lgkmcnt(7)
	v_mfma_f32_32x32x16_bf16 v[80:95], v[200:203], v[230:233], v[80:95]
	ds_read_b128 v[246:249], v251 offset:4096
	s_waitcnt vmcnt(9)
	ds_write_b128 v185, v[136:139] offset:4096
	v_mfma_f32_32x32x16_bf16 v[16:31], v[204:207], v[230:233], v[16:31]
	ds_read_b128 v[192:195], v251 offset:6144
	s_waitcnt vmcnt(8)
	ds_write_b128 v185, v[140:143] offset:6144
	s_waitcnt lgkmcnt(10)
	v_mfma_f32_32x32x16_bf16 v[64:79], v[200:203], v[234:237], v[64:79]
	s_waitcnt vmcnt(7)
	ds_write_b128 v185, v[144:147] offset:8192
	v_mfma_f32_32x32x16_bf16 v[0:15], v[204:207], v[234:237], v[0:15]
	s_waitcnt vmcnt(6)
	ds_write_b128 v185, v[148:151] offset:10240
	s_waitcnt lgkmcnt(9)
	v_mfma_f32_32x32x16_bf16 v[112:127], v[208:211], v[238:241], v[112:127]
	s_waitcnt vmcnt(5)
	ds_write_b128 v185, v[152:155] offset:12288
	v_mfma_f32_32x32x16_bf16 v[48:63], v[212:215], v[238:241], v[48:63]
	s_waitcnt vmcnt(4)
	ds_write_b128 v185, v[156:159] offset:14336
	s_waitcnt lgkmcnt(9)
	v_mfma_f32_32x32x16_bf16 v[96:111], v[208:211], v[242:245], v[96:111]
	s_waitcnt vmcnt(3)
	ds_write_b128 v185, v[160:163] offset:16384
	v_mfma_f32_32x32x16_bf16 v[32:47], v[212:215], v[242:245], v[32:47]
	s_waitcnt vmcnt(2)
	ds_write_b128 v185, v[164:167] offset:18432
	s_waitcnt lgkmcnt(9)
	v_mfma_f32_32x32x16_bf16 v[80:95], v[208:211], v[246:249], v[80:95]
	s_waitcnt vmcnt(1)
	ds_write_b128 v185, v[168:171] offset:20480
	v_mfma_f32_32x32x16_bf16 v[16:31], v[212:215], v[246:249], v[16:31]
	s_waitcnt vmcnt(0)
	ds_write_b128 v185, v[172:175] offset:22528
	s_waitcnt lgkmcnt(9)
	v_mfma_f32_32x32x16_bf16 v[64:79], v[208:211], v[192:195], v[64:79]
	v_mfma_f32_32x32x16_bf16 v[0:15], v[212:215], v[192:195], v[0:15]
	s_setprio 0
	s_add_u32 s28, s28, 0x80
	s_addc_u32 s29, s29, 0
	s_add_u32 s38, s38, 0x80
	s_addc_u32 s39, s39, 0
	s_sub_i32 s40, s40, 0x6000
	s_cmp_lt_i32 s40, 0
	s_cselect_b32 s42, 0x12000, 0
	s_add_i32 s40, s40, s42
	s_sub_i32 s41, s41, 0x6000
	s_cmp_lt_i32 s41, 0
	s_cselect_b32 s42, 0x12000, 0
	s_add_i32 s41, s41, s42
	v_subrev_u32_e32 v196, 0x6000, v185
	v_add_u32_e32 v198, 0xc000, v185
	v_min_u32_e32 v185, v196, v198
	s_add_i32 s7, s7, 1
	s_cmp_lt_u32 s7, 63
	s_waitcnt lgkmcnt(0)
	s_barrier
	s_cbranch_scc1 .Lg6_loop
	v_add_u32_e32 v190, s40, v186
	v_add_u32_e32 v191, s40, v187
	v_add_u32_e32 v250, s40, v188
	v_add_u32_e32 v251, s40, v189
	ds_read_b128 v[200:203], v190
	ds_read_b128 v[204:207], v190 offset:2048
	ds_read_b128 v[222:225], v250
	ds_read_b128 v[226:229], v250 offset:2048
	ds_read_b128 v[230:233], v250 offset:4096
	ds_read_b128 v[234:237], v250 offset:6144
	s_setprio 1
	s_waitcnt lgkmcnt(3)
	v_mfma_f32_32x32x16_bf16 v[112:127], v[200:203], v[222:225], v[112:127]
	ds_read_b128 v[208:211], v191
	v_mfma_f32_32x32x16_bf16 v[48:63], v[204:207], v[222:225], v[48:63]
	ds_read_b128 v[212:215], v191 offset:2048
	s_waitcnt lgkmcnt(4)
	v_mfma_f32_32x32x16_bf16 v[96:111], v[200:203], v[226:229], v[96:111]
	ds_read_b128 v[238:241], v251
	v_mfma_f32_32x32x16_bf16 v[32:47], v[204:207], v[226:229], v[32:47]
	ds_read_b128 v[242:245], v251 offset:2048
	s_waitcnt lgkmcnt(5)
	v_mfma_f32_32x32x16_bf16 v[80:95], v[200:203], v[230:233], v[80:95]
	ds_read_b128 v[246:249], v251 offset:4096
	v_mfma_f32_32x32x16_bf16 v[16:31], v[204:207], v[230:233], v[16:31]
	ds_read_b128 v[192:195], v251 offset:6144
	s_waitcnt lgkmcnt(6)
	v_mfma_f32_32x32x16_bf16 v[64:79], v[200:203], v[234:237], v[64:79]
	v_mfma_f32_32x32x16_bf16 v[0:15], v[204:207], v[234:237], v[0:15]
	v_xad_u32 v190, v186, 64, s41
	v_xad_u32 v250, v188, 64, s41
	s_waitcnt lgkmcnt(3)
	v_mfma_f32_32x32x16_bf16 v[112:127], v[208:211], v[238:241], v[112:127]
	ds_read_b128 v[200:203], v190
	v_mfma_f32_32x32x16_bf16 v[48:63], v[212:215], v[238:241], v[48:63]
	ds_read_b128 v[204:207], v190 offset:2048
	s_waitcnt lgkmcnt(4)
	v_mfma_f32_32x32x16_bf16 v[96:111], v[208:211], v[242:245], v[96:111]
	ds_read_b128 v[222:225], v250
	v_mfma_f32_32x32x16_bf16 v[32:47], v[212:215], v[242:245], v[32:47]
	ds_read_b128 v[226:229], v250 offset:2048
	s_waitcnt lgkmcnt(5)
	v_mfma_f32_32x32x16_bf16 v[80:95], v[208:211], v[246:249], v[80:95]
	ds_read_b128 v[230:233], v250 offset:4096
	v_mfma_f32_32x32x16_bf16 v[16:31], v[212:215], v[246:249], v[16:31]
	ds_read_b128 v[234:237], v250 offset:6144
	s_waitcnt lgkmcnt(6)
	v_mfma_f32_32x32x16_bf16 v[64:79], v[208:211], v[192:195], v[64:79]
	v_mfma_f32_32x32x16_bf16 v[0:15], v[212:215], v[192:195], v[0:15]
	s_setprio 0
	v_xad_u32 v191, v187, 64, s41
	v_xad_u32 v251, v189, 64, s41
	s_setprio 1
	s_waitcnt lgkmcnt(3)
	v_mfma_f32_32x32x16_bf16 v[112:127], v[200:203], v[222:225], v[112:127]
	ds_read_b128 v[208:211], v191
	v_mfma_f32_32x32x16_bf16 v[48:63], v[204:207], v[222:225], v[48:63]
	ds_read_b128 v[212:215], v191 offset:2048
	s_waitcnt lgkmcnt(4)
	v_mfma_f32_32x32x16_bf16 v[96:111], v[200:203], v[226:229], v[96:111]
	ds_read_b128 v[238:241], v251
	v_mfma_f32_32x32x16_bf16 v[32:47], v[204:207], v[226:229], v[32:47]
	ds_read_b128 v[242:245], v251 offset:2048
	s_waitcnt lgkmcnt(5)
	v_mfma_f32_32x32x16_bf16 v[80:95], v[200:203], v[230:233], v[80:95]
	ds_read_b128 v[246:249], v251 offset:4096
	v_mfma_f32_32x32x16_bf16 v[16:31], v[204:207], v[230:233], v[16:31]
	ds_read_b128 v[192:195], v251 offset:6144
	s_waitcnt lgkmcnt(6)
	v_mfma_f32_32x32x16_bf16 v[64:79], v[200:203], v[234:237], v[64:79]
	v_mfma_f32_32x32x16_bf16 v[0:15], v[204:207], v[234:237], v[0:15]
	s_waitcnt lgkmcnt(3)
	v_mfma_f32_32x32x16_bf16 v[112:127], v[208:211], v[238:241], v[112:127]
	v_mfma_f32_32x32x16_bf16 v[48:63], v[212:215], v[238:241], v[48:63]
	s_waitcnt lgkmcnt(2)
	v_mfma_f32_32x32x16_bf16 v[96:111], v[208:211], v[242:245], v[96:111]
	v_mfma_f32_32x32x16_bf16 v[32:47], v[212:215], v[242:245], v[32:47]
	s_waitcnt lgkmcnt(1)
	v_mfma_f32_32x32x16_bf16 v[80:95], v[208:211], v[246:249], v[80:95]
	v_mfma_f32_32x32x16_bf16 v[16:31], v[212:215], v[246:249], v[16:31]
	s_waitcnt lgkmcnt(0)
	v_mfma_f32_32x32x16_bf16 v[64:79], v[208:211], v[192:195], v[64:79]
	v_mfma_f32_32x32x16_bf16 v[0:15], v[212:215], v[192:195], v[0:15]
	s_setprio 0
	s_nop 7
	s_nop 7

.LBB0_569:
	s_or_b64 exec, exec, s[48:49]
	s_lshl_b32 s0, s9, 7
	s_add_u32 s1, s66, s8
	s_addc_u32 s8, s67, 0
	s_lshl_b32 s9, s0, 1
	s_add_u32 s46, s1, s9
	s_addc_u32 s47, s8, 0
	s_or_b32 s68, s0, s68
	s_lshl_b32 s0, s7, 2
	s_add_i32 s37, s0, 0
	s_add_i32 s37, s37, 0x12200
	s_lshl_b32 s0, s6, 2
	v_readlane_b32 s1, v254, 5
	s_add_u32 s26, s1, s0
	v_readlane_b32 s0, v254, 6
	s_addc_u32 s27, s0, 0
	v_mov_b32_e32 v134, v130
	s_add_u32 s28, s46, s28
	s_waitcnt lgkmcnt(0)
	s_barrier
	s_addc_u32 s29, s47, s29
	v_ashrrev_i32_e32 v135, 31, v134
	v_lshl_add_u64 v[134:135], v[134:135], 1, s[28:29]
	global_load_ushort v137, v[134:135], off offset:64
	s_waitcnt vmcnt(8)
	v_lshlrev_b32_e32 v147, 16, v166
	v_add_co_u32_e64 v144, s[0:1], s96, v134
	v_lshlrev_b32_e32 v187, 16, v165
	s_nop 0
	v_addc_co_u32_e64 v145, s[0:1], 0, v135, s[0:1]
	v_lshlrev_b32_e32 v186, 16, v164
	v_lshlrev_b32_e32 v185, 16, v163
	v_lshlrev_b32_e32 v184, 16, v162
	v_lshlrev_b32_e32 v175, 16, v159
	v_lshlrev_b32_e32 v183, 16, v161
	v_lshlrev_b32_e32 v182, 16, v160
	s_waitcnt vmcnt(7)
	v_lshlrev_b32_e32 v146, 16, v167
	v_mov_b32_e32 v167, v158
	s_waitcnt vmcnt(6)
	v_lshlrev_b32_e32 v142, 16, v168
	s_waitcnt vmcnt(5)
	v_lshlrev_b32_e32 v140, 16, v169
	s_waitcnt vmcnt(4)
	v_lshlrev_b32_e32 v139, 16, v170
	s_waitcnt vmcnt(3)
	v_lshlrev_b32_e32 v136, 16, v171
	v_lshlrev_b32_e32 v174, 16, v131
	s_waitcnt vmcnt(1)
	v_lshlrev_b32_e32 v129, 16, v173
	v_lshlrev_b32_e32 v131, 16, v172
	s_waitcnt vmcnt(0)
	v_lshlrev_b32_e32 v166, 16, v137
	global_load_ushort v165, v[134:135], off offset:2112
	s_waitcnt vmcnt(1)
	global_load_ushort v164, v[144:145], off offset:64
	s_waitcnt vmcnt(2)
	global_load_ushort v163, v[144:145], off offset:2112
	v_add_co_u32_e64 v144, s[0:1], s94, v134
	s_waitcnt vmcnt(3)
	v_addc_co_u32_e64 v145, s[0:1], 0, v135, s[0:1]
	global_load_ushort v162, v[144:145], off offset:64
	s_waitcnt vmcnt(4)
	global_load_ushort v159, v[144:145], off offset:2112
	v_add_co_u32_e64 v144, s[0:1], s57, v134
	s_waitcnt vmcnt(5)
	v_addc_co_u32_e64 v145, s[0:1], 0, v135, s[0:1]
	global_load_ushort v161, v[144:145], off offset:64
	s_waitcnt vmcnt(6)
	global_load_ushort v160, v[144:145], off offset:2112
	v_add_co_u32_e64 v144, s[0:1], s35, v134
	s_waitcnt vmcnt(7)
	v_addc_co_u32_e64 v145, s[0:1], 0, v135, s[0:1]
	global_load_ushort v150, v[144:145], off offset:64
	v_add_co_u32_e64 v148, s[0:1], s58, v134
	s_waitcnt vmcnt(8)
	global_load_ushort v137, v[144:145], off offset:2112
	v_addc_co_u32_e64 v149, s[0:1], 0, v135, s[0:1]
	s_waitcnt vmcnt(0)
	v_lshlrev_b32_e32 v144, 16, v137
	global_load_ushort v151, v[148:149], off offset:64
	s_waitcnt vmcnt(1)
	global_load_ushort v145, v[148:149], off offset:2112
	v_add_co_u32_e64 v148, s[0:1], s95, v134
	s_waitcnt vmcnt(2)
	v_addc_co_u32_e64 v149, s[0:1], 0, v135, s[0:1]
	v_add_co_u32_e64 v134, s[0:1], s59, v134
	global_load_ushort v137, v[148:149], off offset:64
	s_nop 0
	v_addc_co_u32_e64 v135, s[0:1], 0, v135, s[0:1]
	global_load_ushort v138, v[134:135], off offset:64
	s_waitcnt vmcnt(1)
	v_lshlrev_b32_e32 v143, 16, v137
	global_load_ushort v134, v[134:135], off offset:2112
	s_waitcnt vmcnt(1)
	v_lshlrev_b32_e32 v141, 16, v138
	global_load_ushort v137, v[148:149], off offset:2112
	s_waitcnt vmcnt(1)
	v_lshlrev_b32_e32 v138, 16, v134
	v_mov_b32_e32 v134, v128
	s_waitcnt vmcnt(0)
	v_lshlrev_b32_e32 v137, 16, v137
	v_add_u32_e32 v134, s68, v134
	v_ashrrev_i32_e32 v135, 31, v134
	v_lshl_add_u64 v[148:149], v[134:135], 2, s[50:51]
	global_load_dword v188, v[148:149], off
	v_lshl_add_u32 v148, v167, 2, s36
	v_lshl_add_u32 v167, v167, 4, s37
	ds_read_b128 v[168:171], v167
	ds_read_b128 v[178:181], v167 offset:32
	v_ashrrev_i32_e32 v149, 31, v148
	v_lshlrev_b64 v[148:149], 11, v[148:149]
	v_lshl_add_u64 v[148:149], s[66:67], 0, v[148:149]
	s_waitcnt lgkmcnt(1)
	v_mul_f32_e32 v112, v112, v168
	v_lshl_add_u64 v[134:135], v[134:135], 1, v[148:149]
	s_waitcnt vmcnt(0)
	v_fmac_f32_e32 v174, v188, v112
	v_cvt_pk_bf16_f32 v112, v174, s0
	v_lshlrev_b32_e32 v177, 16, v112
	global_store_short v[134:135], v112, off
	v_mul_f32_e32 v112, v113, v169
	v_fmac_f32_e32 v175, v188, v112
	v_cvt_pk_bf16_f32 v112, v175, s0
	v_lshlrev_b32_e32 v176, 16, v112
	global_store_short v[134:135], v112, off offset:2048
	v_mul_f32_e32 v112, v114, v170
	v_fmac_f32_e32 v182, v188, v112
	v_cvt_pk_bf16_f32 v114, v182, s0
	v_add_co_u32_e64 v112, s[0:1], s96, v134
	v_lshlrev_b32_e32 v175, 16, v114
	s_nop 0
	v_addc_co_u32_e64 v113, s[0:1], 0, v135, s[0:1]
	global_store_short v[112:113], v114, off
	v_mul_f32_e32 v114, v115, v171
	v_fmac_f32_e32 v183, v188, v114
	v_cvt_pk_bf16_f32 v114, v183, s0
	global_store_short v[112:113], v114, off offset:2048
	s_waitcnt lgkmcnt(0)
	v_mul_f32_e32 v112, v116, v178
	v_fmac_f32_e32 v184, v188, v112
	v_cvt_pk_bf16_f32 v116, v184, s0
	v_add_co_u32_e64 v112, s[0:1], s94, v134
	v_lshlrev_b32_e32 v174, 16, v114
	s_nop 0
	v_addc_co_u32_e64 v113, s[0:1], 0, v135, s[0:1]
	v_add_co_u32_e64 v114, s[0:1], s57, v134
	v_lshlrev_b32_e32 v173, 16, v116
	s_nop 0
	v_addc_co_u32_e64 v115, s[0:1], 0, v135, s[0:1]
	global_store_short v[114:115], v116, off offset:-4096
	v_mul_f32_e32 v116, v117, v179
	v_fmac_f32_e32 v185, v188, v116
	v_cvt_pk_bf16_f32 v117, v185, s0
	global_store_short v[112:113], v117, off offset:2048
	v_mul_f32_e32 v112, v118, v180
	v_fmac_f32_e32 v186, v188, v112
	v_cvt_pk_bf16_f32 v112, v186, s0
	v_lshlrev_b32_e32 v172, 16, v112
	global_store_short v[114:115], v112, off
	v_mul_f32_e32 v112, v119, v181
	v_fmac_f32_e32 v187, v188, v112
	v_cvt_pk_bf16_f32 v112, v187, s0
	v_lshlrev_b32_e32 v116, 16, v117
	v_lshlrev_b32_e32 v117, 16, v112
	global_store_short v[114:115], v112, off offset:2048
	ds_read_b128 v[112:115], v167 offset:64
	s_waitcnt lgkmcnt(0)
	v_mul_f32_e32 v112, v120, v112
	v_fmac_f32_e32 v147, v188, v112
	v_cvt_pk_bf16_f32 v112, v147, s0
	v_add_co_u32_e64 v118, s[0:1], s35, v134
	v_lshlrev_b32_e32 v170, 16, v112
	s_nop 0
	v_addc_co_u32_e64 v119, s[0:1], 0, v135, s[0:1]
	v_add_co_u32_e64 v148, s[0:1], s58, v134
	s_nop 1
	v_addc_co_u32_e64 v149, s[0:1], 0, v135, s[0:1]
	global_store_short v[148:149], v112, off offset:-4096
	v_mul_f32_e32 v112, v121, v113
	v_fmac_f32_e32 v146, v188, v112
	v_cvt_pk_bf16_f32 v112, v146, s0
	v_lshlrev_b32_e32 v171, 16, v112
	global_store_short v[118:119], v112, off offset:2048
	v_mul_f32_e32 v112, v122, v114
	v_fmac_f32_e32 v142, v188, v112
	v_cvt_pk_bf16_f32 v112, v142, s0
	v_lshlrev_b32_e32 v169, 16, v112
	global_store_short v[148:149], v112, off
	v_mul_f32_e32 v112, v123, v115
	v_fmac_f32_e32 v140, v188, v112
	v_cvt_pk_bf16_f32 v112, v140, s0
	v_lshlrev_b32_e32 v168, 16, v112
	global_store_short v[148:149], v112, off offset:2048
	ds_read_b128 v[112:115], v167 offset:96
	s_waitcnt lgkmcnt(0)
	v_mul_f32_e32 v112, v124, v112
	v_fmac_f32_e32 v139, v188, v112
	v_cvt_pk_bf16_f32 v112, v139, s0
	v_add_co_u32_e64 v118, s[0:1], s95, v134
	v_lshlrev_b32_e32 v167, 16, v112
	s_nop 0
	v_addc_co_u32_e64 v119, s[0:1], 0, v135, s[0:1]
	v_add_co_u32_e64 v120, s[0:1], s59, v134
	s_nop 1
	v_addc_co_u32_e64 v121, s[0:1], 0, v135, s[0:1]
	global_store_short v[120:121], v112, off offset:-4096
	v_mul_f32_e32 v112, v125, v113
	v_fmac_f32_e32 v136, v188, v112
	v_cvt_pk_bf16_f32 v112, v136, s0
	v_lshlrev_b32_e32 v124, 16, v112
	global_store_short v[118:119], v112, off offset:2048
	v_mul_f32_e32 v112, v126, v114
	v_fmac_f32_e32 v131, v188, v112
	v_cvt_pk_bf16_f32 v112, v131, s0
	v_lshlrev_b32_e32 v123, 16, v112
	global_store_short v[120:121], v112, off
	v_mul_f32_e32 v112, v127, v115
	v_fmac_f32_e32 v129, v188, v112
	v_cvt_pk_bf16_f32 v112, v129, s0
	v_lshlrev_b32_e32 v122, 16, v112
	global_store_short v[120:121], v112, off offset:2048
	v_mov_b32_e32 v112, v130
	v_mov_b32_e32 v127, v158
	v_ashrrev_i32_e32 v113, 31, v112
	v_lshl_add_u64 v[112:113], v[112:113], 1, s[28:29]
	global_load_ushort v149, v[112:113], off offset:128
	s_waitcnt vmcnt(17)
	global_load_ushort v147, v[112:113], off offset:2176
	s_waitcnt vmcnt(18)
	v_add_co_u32_e64 v114, s[0:1], s96, v112
	s_nop 1
	v_addc_co_u32_e64 v115, s[0:1], 0, v113, s[0:1]
	global_load_ushort v148, v[114:115], off offset:128
	s_waitcnt vmcnt(19)
	global_load_ushort v139, v[114:115], off offset:2176
	s_waitcnt vmcnt(20)
	v_add_co_u32_e64 v114, s[0:1], s94, v112
	s_nop 1
	v_addc_co_u32_e64 v115, s[0:1], 0, v113, s[0:1]
	global_load_ushort v142, v[114:115], off offset:128
	s_waitcnt vmcnt(21)
	global_load_ushort v136, v[114:115], off offset:2176
	s_waitcnt vmcnt(22)
	v_add_co_u32_e64 v114, s[0:1], s57, v112
	s_nop 1
	v_addc_co_u32_e64 v115, s[0:1], 0, v113, s[0:1]
	global_load_ushort v146, v[114:115], off offset:128
	s_waitcnt vmcnt(23)
	global_load_ushort v140, v[114:115], off offset:2176
	s_waitcnt vmcnt(24)
	v_add_co_u32_e64 v114, s[0:1], s35, v112
	s_nop 1
	v_addc_co_u32_e64 v115, s[0:1], 0, v113, s[0:1]
	global_load_ushort v129, v[114:115], off offset:128
	s_waitcnt vmcnt(25)
	global_load_ushort v125, v[114:115], off offset:2176
	s_waitcnt vmcnt(26)
	v_add_co_u32_e64 v114, s[0:1], s58, v112
	s_nop 1
	v_addc_co_u32_e64 v115, s[0:1], 0, v113, s[0:1]
	global_load_ushort v135, v[114:115], off offset:128
	s_waitcnt vmcnt(27)
	global_load_ushort v131, v[114:115], off offset:2176
	s_waitcnt vmcnt(28)
	v_add_co_u32_e64 v114, s[0:1], s95, v112
	s_nop 1
	v_addc_co_u32_e64 v115, s[0:1], 0, v113, s[0:1]
	global_load_ushort v118, v[114:115], off offset:128
	v_add_co_u32_e64 v112, s[0:1], s59, v112
	global_load_ushort v114, v[114:115], off offset:2176
	s_nop 0
	v_addc_co_u32_e64 v113, s[0:1], 0, v113, s[0:1]
	s_waitcnt vmcnt(1)
	v_lshlrev_b32_e32 v120, 16, v118
	s_waitcnt vmcnt(0)
	v_lshlrev_b32_e32 v118, 16, v114
	global_load_ushort v121, v[112:113], off offset:128
	s_waitcnt vmcnt(1)
	global_load_ushort v119, v[112:113], off offset:2176
	s_waitcnt vmcnt(2)
	v_mov_b32_e32 v112, v128
	s_nop 0
	v_ashrrev_i32_e32 v113, 31, v112
	v_lshl_add_u64 v[112:113], v[112:113], 0, s[68:69]
	v_lshl_add_u64 v[114:115], v[112:113], 2, s[50:51]
	global_load_dword v126, v[114:115], off offset:128
	v_lshl_add_u32 v114, v127, 2, s36
	v_lshl_add_u32 v127, v127, 4, s37
	ds_read_b128 v[178:181], v127
	ds_read_b128 v[182:185], v127 offset:32
	v_ashrrev_i32_e32 v115, 31, v114
	v_lshlrev_b64 v[114:115], 11, v[114:115]
	v_lshl_add_u64 v[114:115], s[66:67], 0, v[114:115]
	s_waitcnt lgkmcnt(1)
	v_mul_f32_e32 v96, v96, v178
	v_lshl_add_u64 v[112:113], v[112:113], 1, v[114:115]
	v_mul_f32_e32 v99, v99, v181
	s_waitcnt lgkmcnt(0)
	v_mul_f32_e32 v101, v101, v183
	s_waitcnt vmcnt(0)
	v_fmac_f32_e32 v166, v126, v96
	v_cvt_pk_bf16_f32 v96, v166, s0
	v_lshlrev_b32_e32 v114, 16, v96
	global_store_short v[112:113], v96, off offset:64
	v_mul_f32_e32 v96, v97, v179
	s_waitcnt vmcnt(49)
	v_lshlrev_b32_e32 v165, 16, v165
	v_fmac_f32_e32 v165, v126, v96
	v_cvt_pk_bf16_f32 v96, v165, s0
	v_lshlrev_b32_e32 v97, 16, v96
	global_store_short v[112:113], v96, off offset:2112
	v_mul_f32_e32 v96, v98, v180
	s_waitcnt vmcnt(49)
	v_lshlrev_b32_e32 v164, 16, v164
	v_fmac_f32_e32 v164, v126, v96
	v_cvt_pk_bf16_f32 v98, v164, s0
	v_add_co_u32_e64 v96, s[0:1], s96, v112
	v_mul_f32_e32 v115, v97, v97
	s_nop 0
	v_addc_co_u32_e64 v97, s[0:1], 0, v113, s[0:1]
	s_waitcnt vmcnt(48)
	v_lshlrev_b32_e32 v163, 16, v163
	v_fmac_f32_e32 v163, v126, v99
	s_nop 0
	v_cvt_pk_bf16_f32 v99, v163, s0
	global_store_short v[96:97], v98, off offset:64
	global_store_short v[96:97], v99, off offset:2112
	v_mul_f32_e32 v96, v100, v182
	s_waitcnt vmcnt(49)
	v_lshlrev_b32_e32 v162, 16, v162
	v_fmac_f32_e32 v162, v126, v96
	v_cvt_pk_bf16_f32 v100, v162, s0
	v_add_co_u32_e64 v96, s[0:1], s94, v112
	s_waitcnt vmcnt(48)
	v_lshlrev_b32_e32 v159, 16, v159
	v_fmac_f32_e32 v159, v126, v101
	s_nop 0
	v_addc_co_u32_e64 v97, s[0:1], 0, v113, s[0:1]
	v_lshlrev_b32_e32 v134, 16, v98
	s_nop 0
	v_cvt_pk_bf16_f32 v101, v159, s0
	v_mul_f32_e32 v98, v134, v134
	v_lshlrev_b32_e32 v134, 16, v99
	global_store_short v[96:97], v100, off offset:64
	global_store_short v[96:97], v101, off offset:2112
	v_mul_f32_e32 v96, v102, v184
	v_mul_f32_e32 v99, v134, v134
	v_lshlrev_b32_e32 v134, 16, v100
	s_waitcnt vmcnt(49)
	v_lshlrev_b32_e32 v161, 16, v161
	v_fmac_f32_e32 v161, v126, v96
	v_mul_f32_e32 v100, v134, v134
	v_lshlrev_b32_e32 v134, 16, v101
	v_cvt_pk_bf16_f32 v102, v161, s0
	v_add_co_u32_e64 v96, s[0:1], s57, v112
	v_mul_f32_e32 v101, v134, v134
	s_nop 0
	v_addc_co_u32_e64 v97, s[0:1], 0, v113, s[0:1]
	v_fmac_f32_e32 v101, v116, v116
	v_lshlrev_b32_e32 v116, 16, v102
	global_store_short v[96:97], v102, off offset:64
	v_mul_f32_e32 v102, v103, v185
	s_waitcnt vmcnt(49)
	v_lshlrev_b32_e32 v160, 16, v160
	v_fmac_f32_e32 v160, v126, v102
	v_cvt_pk_bf16_f32 v102, v160, s0
	ds_read_b128 v[160:163], v127 offset:64
	global_store_short v[96:97], v102, off offset:2112
	v_lshlrev_b32_e32 v103, 16, v102
	v_mul_f32_e32 v102, v103, v103
	v_fmac_f32_e32 v102, v117, v117
	s_waitcnt lgkmcnt(0)
	v_mul_f32_e32 v96, v104, v160
	s_waitcnt vmcnt(49)
	v_lshlrev_b32_e32 v150, 16, v150
	v_fmac_f32_e32 v150, v126, v96
	v_cvt_pk_bf16_f32 v103, v150, s0
	v_add_co_u32_e64 v96, s[0:1], s35, v112
	v_lshlrev_b32_e32 v104, 16, v103
	s_nop 0
	v_addc_co_u32_e64 v97, s[0:1], 0, v113, s[0:1]
	global_store_short v[96:97], v103, off offset:64
	v_mul_f32_e32 v103, v105, v161
	v_fmac_f32_e32 v144, v126, v103
	v_cvt_pk_bf16_f32 v103, v144, s0
	global_store_short v[96:97], v103, off offset:2112
	v_mul_f32_e32 v96, v106, v162
	s_waitcnt vmcnt(49)
	v_lshlrev_b32_e32 v151, 16, v151
	v_fmac_f32_e32 v151, v126, v96
	v_mul_f32_e32 v117, v104, v104
	v_lshlrev_b32_e32 v104, 16, v103
	v_cvt_pk_bf16_f32 v103, v151, s0
	v_add_co_u32_e64 v96, s[0:1], s58, v112
	v_mul_f32_e32 v105, v104, v104
	s_nop 0
	v_addc_co_u32_e64 v97, s[0:1], 0, v113, s[0:1]
	v_lshlrev_b32_e32 v104, 16, v103
	global_store_short v[96:97], v103, off offset:64
	v_mul_f32_e32 v103, v107, v163
	ds_read_b128 v[160:163], v127 offset:96
	s_waitcnt vmcnt(49)
	v_lshlrev_b32_e32 v145, 16, v145
	v_fmac_f32_e32 v145, v126, v103
	v_cvt_pk_bf16_f32 v103, v145, s0
	global_store_short v[96:97], v103, off offset:2112
	v_lshlrev_b32_e32 v106, 16, v103
	s_waitcnt lgkmcnt(0)
	v_mul_f32_e32 v96, v108, v160
	v_fmac_f32_e32 v143, v126, v96
	v_mul_f32_e32 v103, v106, v106
	v_cvt_pk_bf16_f32 v106, v143, s0
	v_add_co_u32_e64 v96, s[0:1], s95, v112
	v_lshlrev_b32_e32 v107, 16, v106
	s_nop 0
	v_addc_co_u32_e64 v97, s[0:1], 0, v113, s[0:1]
	global_store_short v[96:97], v106, off offset:64
	v_mul_f32_e32 v106, v107, v107
	v_mul_f32_e32 v107, v109, v161
	v_fmac_f32_e32 v137, v126, v107
	v_cvt_pk_bf16_f32 v107, v137, s0
	global_store_short v[96:97], v107, off offset:2112
	v_mul_f32_e32 v96, v110, v162
	v_lshlrev_b32_e32 v108, 16, v107
	v_fmac_f32_e32 v141, v126, v96
	v_mul_f32_e32 v107, v108, v108
	v_cvt_pk_bf16_f32 v108, v141, s0
	v_add_co_u32_e64 v96, s[0:1], s59, v112
	v_lshlrev_b32_e32 v109, 16, v108
	s_nop 0
	v_addc_co_u32_e64 v97, s[0:1], 0, v113, s[0:1]
	global_store_short v[96:97], v108, off offset:64
	v_mul_f32_e32 v108, v109, v109
	v_mul_f32_e32 v109, v111, v163
	v_fmac_f32_e32 v138, v126, v109
	v_cvt_pk_bf16_f32 v109, v138, s0
	global_store_short v[96:97], v109, off offset:2112
	v_mov_b32_e32 v96, v130
	v_lshlrev_b32_e32 v110, 16, v109
	v_ashrrev_i32_e32 v97, 31, v96
	v_lshl_add_u64 v[96:97], v[96:97], 1, s[28:29]
	v_mul_f32_e32 v109, v110, v110
	global_load_ushort v110, v[96:97], off offset:192
	v_fmac_f32_e32 v108, v123, v123
	v_fmac_f32_e32 v109, v122, v122
	v_fmac_f32_e32 v107, v124, v124
	v_mov_b32_e32 v159, v158
	v_fmac_f32_e32 v106, v167, v167
	v_fmac_f32_e32 v115, v176, v176
	v_fmac_f32_e32 v99, v174, v174
	v_fmac_f32_e32 v100, v173, v173
	v_mul_f32_e32 v116, v116, v116
	v_fmac_f32_e32 v116, v172, v172
	v_fmac_f32_e32 v105, v171, v171
	v_fmac_f32_e32 v103, v168, v168
	v_mul_f32_e32 v104, v104, v104
	v_fmac_f32_e32 v104, v169, v169
	v_fmac_f32_e32 v117, v170, v170
	s_or_b32 s28, s36, 32
	s_ashr_i32 s29, s28, 31
	v_mul_f32_e32 v114, v114, v114
	v_fmac_f32_e32 v114, v177, v177
	v_fmac_f32_e32 v98, v175, v175
	s_waitcnt vmcnt(0)
	v_lshlrev_b32_e32 v123, 16, v110
	global_load_ushort v122, v[96:97], off offset:2240
	s_waitcnt vmcnt(1)
	v_add_co_u32_e64 v110, s[0:1], s96, v96
	s_nop 1
	v_addc_co_u32_e64 v111, s[0:1], 0, v97, s[0:1]
	global_load_ushort v126, v[110:111], off offset:192
	s_waitcnt vmcnt(2)
	global_load_ushort v124, v[110:111], off offset:2240
	s_waitcnt vmcnt(3)
	v_add_co_u32_e64 v110, s[0:1], s94, v96
	s_nop 1
	v_addc_co_u32_e64 v111, s[0:1], 0, v97, s[0:1]
	global_load_ushort v134, v[110:111], off offset:192
	s_waitcnt vmcnt(4)
	global_load_ushort v127, v[110:111], off offset:2240
	s_waitcnt vmcnt(5)
	v_add_co_u32_e64 v110, s[0:1], s57, v96
	s_nop 1
	v_addc_co_u32_e64 v111, s[0:1], 0, v97, s[0:1]
	global_load_ushort v145, v[110:111], off offset:192
	s_waitcnt vmcnt(6)
	global_load_ushort v143, v[110:111], off offset:2240
	s_waitcnt vmcnt(7)
	v_add_co_u32_e64 v110, s[0:1], s35, v96
	s_nop 1
	v_addc_co_u32_e64 v111, s[0:1], 0, v97, s[0:1]
	global_load_ushort v138, v[110:111], off offset:192
	s_waitcnt vmcnt(8)
	global_load_ushort v137, v[110:111], off offset:2240
	s_waitcnt vmcnt(9)
	v_add_co_u32_e64 v110, s[0:1], s58, v96
	s_nop 1
	v_addc_co_u32_e64 v111, s[0:1], 0, v97, s[0:1]
	global_load_ushort v144, v[110:111], off offset:192
	s_waitcnt vmcnt(10)
	global_load_ushort v141, v[110:111], off offset:2240
	v_add_co_u32_e64 v112, s[0:1], s95, v96
	s_waitcnt vmcnt(11)
	v_addc_co_u32_e64 v113, s[0:1], 0, v97, s[0:1]
	global_load_ushort v111, v[112:113], off offset:192
	v_add_co_u32_e64 v96, s[0:1], s59, v96
	s_waitcnt vmcnt(12)
	v_addc_co_u32_e64 v97, s[0:1], 0, v97, s[0:1]
	global_load_ushort v110, v[112:113], off offset:2240
	s_waitcnt vmcnt(13)
	global_load_ushort v113, v[96:97], off offset:192
	s_waitcnt vmcnt(14)
	global_load_ushort v112, v[96:97], off offset:2240
	s_waitcnt vmcnt(15)
	v_mov_b32_e32 v96, v128
	s_nop 0
	v_ashrrev_i32_e32 v97, 31, v96
	v_lshl_add_u64 v[96:97], v[96:97], 0, s[68:69]
	v_lshl_add_u64 v[150:151], v[96:97], 2, s[50:51]
	global_load_dword v150, v[150:151], off offset:256
	v_lshl_add_u32 v160, v159, 2, s36
	v_ashrrev_i32_e32 v161, 31, v160
	v_lshlrev_b64 v[160:161], 11, v[160:161]
	v_lshl_add_u64 v[160:161], s[66:67], 0, v[160:161]
	v_lshl_add_u32 v151, v159, 4, s37
	v_lshl_add_u64 v[96:97], v[96:97], 1, v[160:161]
	ds_read_b128 v[160:163], v151
	ds_read_b128 v[164:167], v151 offset:32
	s_waitcnt lgkmcnt(1)
	v_mul_f32_e32 v80, v80, v160
	s_waitcnt vmcnt(0)
	s_waitcnt vmcnt(49)
	v_lshlrev_b32_e32 v149, 16, v149
	v_fmac_f32_e32 v149, v150, v80
	v_cvt_pk_bf16_f32 v80, v149, s0
	v_lshlrev_b32_e32 v149, 16, v80
	global_store_short v[96:97], v80, off offset:128
	v_mul_f32_e32 v80, v81, v161
	s_waitcnt vmcnt(49)
	v_lshlrev_b32_e32 v147, 16, v147
	v_fmac_f32_e32 v147, v150, v80
	v_cvt_pk_bf16_f32 v80, v147, s0
	v_lshlrev_b32_e32 v81, 16, v80
	global_store_short v[96:97], v80, off offset:2176
	v_mul_f32_e32 v80, v82, v162
	s_waitcnt vmcnt(49)
	v_lshlrev_b32_e32 v148, 16, v148
	v_fmac_f32_e32 v148, v150, v80
	v_cvt_pk_bf16_f32 v82, v148, s0
	v_add_co_u32_e64 v80, s[0:1], s96, v96
	v_fmac_f32_e32 v115, v81, v81
	s_nop 0
	v_addc_co_u32_e64 v81, s[0:1], 0, v97, s[0:1]
	v_lshlrev_b32_e32 v147, 16, v82
	global_store_short v[80:81], v82, off offset:128
	v_mul_f32_e32 v82, v83, v163
	s_waitcnt vmcnt(49)
	v_lshlrev_b32_e32 v139, 16, v139
	v_fmac_f32_e32 v139, v150, v82
	v_cvt_pk_bf16_f32 v82, v139, s0
	global_store_short v[80:81], v82, off offset:2176
	s_waitcnt lgkmcnt(0)
	v_mul_f32_e32 v80, v84, v164
	s_waitcnt vmcnt(49)
	v_lshlrev_b32_e32 v142, 16, v142
	v_fmac_f32_e32 v142, v150, v80
	v_lshlrev_b32_e32 v83, 16, v82
	v_cvt_pk_bf16_f32 v82, v142, s0
	v_add_co_u32_e64 v80, s[0:1], s94, v96
	v_fmac_f32_e32 v99, v83, v83
	s_nop 0
	v_addc_co_u32_e64 v81, s[0:1], 0, v97, s[0:1]
	v_lshlrev_b32_e32 v83, 16, v82
	global_store_short v[80:81], v82, off offset:128
	v_mul_f32_e32 v82, v85, v165
	s_waitcnt vmcnt(49)
	v_lshlrev_b32_e32 v136, 16, v136
	v_fmac_f32_e32 v136, v150, v82
	v_cvt_pk_bf16_f32 v82, v136, s0
	global_store_short v[80:81], v82, off offset:2176
	v_mul_f32_e32 v80, v86, v166
	s_waitcnt vmcnt(49)
	v_lshlrev_b32_e32 v146, 16, v146
	v_fmac_f32_e32 v146, v150, v80
	v_fmac_f32_e32 v100, v83, v83
	v_lshlrev_b32_e32 v83, 16, v82
	v_cvt_pk_bf16_f32 v82, v146, s0
	v_add_co_u32_e64 v80, s[0:1], s57, v96
	v_fmac_f32_e32 v101, v83, v83
	s_nop 0
	v_addc_co_u32_e64 v81, s[0:1], 0, v97, s[0:1]
	v_lshlrev_b32_e32 v83, 16, v82
	global_store_short v[80:81], v82, off offset:128
	v_mul_f32_e32 v82, v87, v167
	s_waitcnt vmcnt(49)
	v_lshlrev_b32_e32 v140, 16, v140
	v_fmac_f32_e32 v140, v150, v82
	v_cvt_pk_bf16_f32 v82, v140, s0
	v_fmac_f32_e32 v116, v83, v83
	v_lshlrev_b32_e32 v83, 16, v82
	global_store_short v[80:81], v82, off offset:2176
	v_fmac_f32_e32 v102, v83, v83
	ds_read_b128 v[80:83], v151 offset:64
	v_fmac_f32_e32 v114, v149, v149
	v_fmac_f32_e32 v98, v147, v147
	s_waitcnt lgkmcnt(0)
	v_mul_f32_e32 v80, v88, v80
	s_waitcnt vmcnt(49)
	v_lshlrev_b32_e32 v129, 16, v129
	v_fmac_f32_e32 v129, v150, v80
	v_cvt_pk_bf16_f32 v80, v129, s0
	v_add_co_u32_e64 v84, s[0:1], s35, v96
	v_lshlrev_b32_e32 v86, 16, v80
	s_nop 0
	v_addc_co_u32_e64 v85, s[0:1], 0, v97, s[0:1]
	global_store_short v[84:85], v80, off offset:128
	v_mul_f32_e32 v80, v89, v81
	s_waitcnt vmcnt(49)
	v_lshlrev_b32_e32 v125, 16, v125
	v_fmac_f32_e32 v125, v150, v80
	v_cvt_pk_bf16_f32 v80, v125, s0
	v_lshlrev_b32_e32 v81, 16, v80
	global_store_short v[84:85], v80, off offset:2176
	v_mul_f32_e32 v80, v90, v82
	s_waitcnt vmcnt(49)
	v_lshlrev_b32_e32 v135, 16, v135
	v_fmac_f32_e32 v135, v150, v80
	v_cvt_pk_bf16_f32 v82, v135, s0
	v_add_co_u32_e64 v80, s[0:1], s58, v96
	v_fmac_f32_e32 v105, v81, v81
	s_nop 0
	v_addc_co_u32_e64 v81, s[0:1], 0, v97, s[0:1]
	v_lshlrev_b32_e32 v84, 16, v82
	global_store_short v[80:81], v82, off offset:128
	v_mul_f32_e32 v82, v91, v83
	s_waitcnt vmcnt(49)
	v_lshlrev_b32_e32 v131, 16, v131
	v_fmac_f32_e32 v131, v150, v82
	v_cvt_pk_bf16_f32 v82, v131, s0
	v_lshlrev_b32_e32 v83, 16, v82
	global_store_short v[80:81], v82, off offset:2176
	v_fmac_f32_e32 v103, v83, v83
	ds_read_b128 v[80:83], v151 offset:96
	v_fmac_f32_e32 v104, v84, v84
	v_fmac_f32_e32 v117, v86, v86
	v_mov_b32_e32 v125, v158
	s_waitcnt lgkmcnt(0)
	v_mul_f32_e32 v80, v92, v80
	v_fmac_f32_e32 v120, v150, v80
	v_cvt_pk_bf16_f32 v80, v120, s0
	v_add_co_u32_e64 v84, s[0:1], s95, v96
	v_lshlrev_b32_e32 v86, 16, v80
	s_nop 0
	v_addc_co_u32_e64 v85, s[0:1], 0, v97, s[0:1]
	global_store_short v[84:85], v80, off offset:128
	v_mul_f32_e32 v80, v93, v81
	v_fmac_f32_e32 v118, v150, v80
	v_cvt_pk_bf16_f32 v80, v118, s0
	v_lshlrev_b32_e32 v81, 16, v80
	global_store_short v[84:85], v80, off offset:2176
	v_mul_f32_e32 v80, v94, v82
	s_waitcnt vmcnt(49)
	v_lshlrev_b32_e32 v121, 16, v121
	v_fmac_f32_e32 v121, v150, v80
	v_cvt_pk_bf16_f32 v82, v121, s0
	v_add_co_u32_e64 v80, s[0:1], s59, v96
	v_fmac_f32_e32 v107, v81, v81
	s_nop 0
	v_addc_co_u32_e64 v81, s[0:1], 0, v97, s[0:1]
	v_lshlrev_b32_e32 v84, 16, v82
	global_store_short v[80:81], v82, off offset:128
	v_mul_f32_e32 v82, v95, v83
	s_waitcnt vmcnt(49)
	v_lshlrev_b32_e32 v119, 16, v119
	v_fmac_f32_e32 v119, v150, v82
	v_cvt_pk_bf16_f32 v82, v119, s0
	s_lshl_b64 s[0:1], s[28:29], 11
	global_store_short v[80:81], v82, off offset:2176
	v_mov_b32_e32 v80, v130
	s_add_u32 s46, s46, s0
	s_addc_u32 s47, s47, s1
	v_ashrrev_i32_e32 v81, 31, v80
	v_lshl_add_u64 v[80:81], v[80:81], 1, s[46:47]
	v_fmac_f32_e32 v106, v86, v86
	v_add_co_u32_e64 v86, s[0:1], s96, v80
	v_lshlrev_b32_e32 v83, 16, v82
	s_nop 0
	v_addc_co_u32_e64 v87, s[0:1], 0, v81, s[0:1]
	v_add_co_u32_e64 v88, s[0:1], s94, v80
	v_fmac_f32_e32 v109, v83, v83
	s_nop 0
	v_addc_co_u32_e64 v89, s[0:1], 0, v81, s[0:1]
	v_add_co_u32_e64 v90, s[0:1], s57, v80
	global_load_ushort v82, v[80:81], off
	global_load_ushort v83, v[80:81], off offset:2048
	v_addc_co_u32_e64 v91, s[0:1], 0, v81, s[0:1]
	v_add_co_u32_e64 v92, s[0:1], s35, v80
	v_fmac_f32_e32 v108, v84, v84
	s_nop 0
	v_addc_co_u32_e64 v93, s[0:1], 0, v81, s[0:1]
	v_add_co_u32_e64 v94, s[0:1], s58, v80
	global_load_ushort v84, v[86:87], off
	global_load_ushort v85, v[86:87], off offset:2048
	v_addc_co_u32_e64 v95, s[0:1], 0, v81, s[0:1]
	v_add_co_u32_e64 v96, s[0:1], s95, v80
	global_load_ushort v86, v[90:91], off offset:-4096
	global_load_ushort v87, v[88:89], off offset:2048
	s_nop 0
	global_load_ushort v88, v[90:91], off
	global_load_ushort v89, v[90:91], off offset:2048
	v_addc_co_u32_e64 v97, s[0:1], 0, v81, s[0:1]
	v_add_co_u32_e64 v80, s[0:1], s59, v80
	global_load_ushort v90, v[94:95], off offset:-4096
	global_load_ushort v91, v[92:93], off offset:2048
	s_nop 0
	global_load_ushort v92, v[94:95], off
	global_load_ushort v93, v[94:95], off offset:2048
	v_addc_co_u32_e64 v81, s[0:1], 0, v81, s[0:1]
	global_load_ushort v94, v[80:81], off offset:-4096
	global_load_ushort v95, v[96:97], off offset:2048
	s_nop 0
	global_load_ushort v96, v[80:81], off
	global_load_ushort v97, v[80:81], off offset:2048
	v_mov_b32_e32 v80, v128
	s_nop 0
	v_ashrrev_i32_e32 v81, 31, v80
	v_lshl_add_u64 v[80:81], v[80:81], 0, s[68:69]
	v_lshl_add_u64 v[118:119], v[80:81], 2, s[50:51]
	global_load_dword v118, v[118:119], off offset:384
	v_lshl_add_u32 v119, v125, 4, s37
	ds_read_b128 v[146:149], v119
	ds_read_b128 v[160:163], v119 offset:32
	v_lshl_add_u32 v120, v125, 2, s36
	v_ashrrev_i32_e32 v121, 31, v120
	v_lshlrev_b64 v[120:121], 11, v[120:121]
	s_waitcnt lgkmcnt(1)
	v_mul_f32_e32 v64, v64, v146
	v_lshl_add_u64 v[120:121], s[66:67], 0, v[120:121]
	v_lshl_add_u64 v[80:81], v[80:81], 1, v[120:121]
	s_waitcnt vmcnt(0)
	v_fmac_f32_e32 v123, v118, v64
	v_mul_f32_e32 v64, v65, v147
	s_waitcnt vmcnt(48)
	v_lshlrev_b32_e32 v122, 16, v122
	v_fmac_f32_e32 v122, v118, v64
	v_mul_f32_e32 v64, v66, v148
	s_waitcnt vmcnt(47)
	v_lshlrev_b32_e32 v126, 16, v126
	v_fmac_f32_e32 v126, v118, v64
	v_cvt_pk_bf16_f32 v120, v123, s0
	v_cvt_pk_bf16_f32 v121, v122, s0
	v_cvt_pk_bf16_f32 v122, v126, s0
	v_add_co_u32_e64 v64, s[0:1], s96, v80
	v_mul_f32_e32 v66, v67, v149
	s_nop 0
	v_addc_co_u32_e64 v65, s[0:1], 0, v81, s[0:1]
	s_waitcnt vmcnt(46)
	v_lshlrev_b32_e32 v124, 16, v124
	v_fmac_f32_e32 v124, v118, v66
	s_nop 0
	v_cvt_pk_bf16_f32 v123, v124, s0
	global_store_short v[64:65], v122, off offset:192
	global_store_short v[64:65], v123, off offset:2240
	s_waitcnt lgkmcnt(0)
	v_mul_f32_e32 v64, v68, v160
	s_waitcnt vmcnt(47)
	v_lshlrev_b32_e32 v134, 16, v134
	v_fmac_f32_e32 v134, v118, v64
	v_cvt_pk_bf16_f32 v124, v134, s0
	v_add_co_u32_e64 v64, s[0:1], s94, v80
	v_mul_f32_e32 v66, v69, v161
	s_nop 0
	v_addc_co_u32_e64 v65, s[0:1], 0, v81, s[0:1]
	s_waitcnt vmcnt(46)
	v_lshlrev_b32_e32 v127, 16, v127
	v_fmac_f32_e32 v127, v118, v66
	s_nop 0
	v_cvt_pk_bf16_f32 v125, v127, s0
	global_store_short v[64:65], v124, off offset:192
	global_store_short v[64:65], v125, off offset:2240
	v_mul_f32_e32 v64, v70, v162
	s_waitcnt vmcnt(47)
	v_lshlrev_b32_e32 v145, 16, v145
	v_fmac_f32_e32 v145, v118, v64
	v_cvt_pk_bf16_f32 v70, v145, s0
	v_add_co_u32_e64 v64, s[0:1], s57, v80
	v_mul_f32_e32 v66, v71, v163
	s_nop 0
	v_addc_co_u32_e64 v65, s[0:1], 0, v81, s[0:1]
	s_waitcnt vmcnt(46)
	v_lshlrev_b32_e32 v143, 16, v143
	v_fmac_f32_e32 v143, v118, v66
	s_nop 0
	v_cvt_pk_bf16_f32 v71, v143, s0
	global_store_short v[64:65], v70, off offset:192
	global_store_short v[64:65], v71, off offset:2240
	ds_read_b128 v[64:67], v119 offset:64
	global_store_short v[80:81], v120, off offset:192
	global_store_short v[80:81], v121, off offset:2240
	s_waitcnt lgkmcnt(0)
	v_mul_f32_e32 v64, v72, v64
	s_waitcnt vmcnt(49)
	v_lshlrev_b32_e32 v138, 16, v138
	v_fmac_f32_e32 v138, v118, v64
	v_mul_f32_e32 v64, v73, v65
	v_cvt_pk_bf16_f32 v72, v138, s0
	v_add_co_u32_e64 v68, s[0:1], s35, v80
	s_waitcnt vmcnt(48)
	v_lshlrev_b32_e32 v137, 16, v137
	v_fmac_f32_e32 v137, v118, v64
	v_mul_f32_e32 v64, v74, v66
	v_addc_co_u32_e64 v69, s[0:1], 0, v81, s[0:1]
	s_waitcnt vmcnt(47)
	v_lshlrev_b32_e32 v144, 16, v144
	v_fmac_f32_e32 v144, v118, v64
	s_nop 0
	v_cvt_pk_bf16_f32 v73, v137, s0
	v_cvt_pk_bf16_f32 v74, v144, s0
	v_add_co_u32_e64 v64, s[0:1], s58, v80
	v_mul_f32_e32 v66, v75, v67
	s_nop 0
	v_addc_co_u32_e64 v65, s[0:1], 0, v81, s[0:1]
	s_waitcnt vmcnt(46)
	v_lshlrev_b32_e32 v141, 16, v141
	v_fmac_f32_e32 v141, v118, v66
	s_nop 0
	v_cvt_pk_bf16_f32 v75, v141, s0
	global_store_short v[64:65], v74, off offset:192
	global_store_short v[64:65], v75, off offset:2240
	ds_read_b128 v[64:67], v119 offset:96
	global_store_short v[68:69], v72, off offset:192
	global_store_short v[68:69], v73, off offset:2240
	s_waitcnt lgkmcnt(0)
	v_mul_f32_e32 v64, v76, v64
	s_waitcnt vmcnt(49)
	v_lshlrev_b32_e32 v111, 16, v111
	v_fmac_f32_e32 v111, v118, v64
	v_mul_f32_e32 v64, v77, v65
	v_cvt_pk_bf16_f32 v76, v111, s0
	v_add_co_u32_e64 v68, s[0:1], s95, v80
	s_waitcnt vmcnt(48)
	v_lshlrev_b32_e32 v110, 16, v110
	v_fmac_f32_e32 v110, v118, v64
	v_mul_f32_e32 v64, v78, v66
	v_addc_co_u32_e64 v69, s[0:1], 0, v81, s[0:1]
	s_waitcnt vmcnt(47)
	v_lshlrev_b32_e32 v113, 16, v113
	v_fmac_f32_e32 v113, v118, v64
	s_nop 0
	v_cvt_pk_bf16_f32 v77, v110, s0
	v_cvt_pk_bf16_f32 v66, v113, s0
	v_add_co_u32_e64 v64, s[0:1], s59, v80
	v_mul_f32_e32 v67, v79, v67
	s_nop 0
	v_addc_co_u32_e64 v65, s[0:1], 0, v81, s[0:1]
	s_waitcnt vmcnt(46)
	v_lshlrev_b32_e32 v112, 16, v112
	v_fmac_f32_e32 v112, v118, v67
	s_nop 0
	v_cvt_pk_bf16_f32 v67, v112, s0
	global_store_short v[64:65], v66, off offset:192
	global_store_short v[64:65], v67, off offset:2240
	v_lshlrev_b32_e32 v64, 16, v67
	v_fmac_f32_e32 v109, v64, v64
	v_lshlrev_b32_e32 v64, 16, v66
	v_fmac_f32_e32 v108, v64, v64
	v_lshlrev_b32_e32 v64, 16, v77
	v_fmac_f32_e32 v107, v64, v64
	v_lshlrev_b32_e32 v64, 16, v76
	v_fmac_f32_e32 v106, v64, v64
	v_lshlrev_b32_e32 v64, 16, v75
	v_fmac_f32_e32 v103, v64, v64
	v_lshlrev_b32_e32 v64, 16, v74
	v_fmac_f32_e32 v104, v64, v64
	v_lshlrev_b32_e32 v64, 16, v73
	v_fmac_f32_e32 v105, v64, v64
	v_lshlrev_b32_e32 v64, 16, v72
	v_fmac_f32_e32 v117, v64, v64
	v_lshlrev_b32_e32 v64, 16, v71
	v_fmac_f32_e32 v102, v64, v64
	v_lshlrev_b32_e32 v64, 16, v70
	v_fmac_f32_e32 v116, v64, v64
	v_lshlrev_b32_e32 v64, 16, v125
	v_fmac_f32_e32 v101, v64, v64
	v_lshlrev_b32_e32 v64, 16, v124
	v_fmac_f32_e32 v100, v64, v64
	v_lshlrev_b32_e32 v64, 16, v123
	v_fmac_f32_e32 v99, v64, v64
	v_lshlrev_b32_e32 v64, 16, v122
	v_fmac_f32_e32 v98, v64, v64
	v_lshlrev_b32_e32 v64, 16, v121
	v_fmac_f32_e32 v115, v64, v64
	v_lshlrev_b32_e32 v64, 16, v120
	v_fmac_f32_e32 v114, v64, v64
	v_cndmask_b32_e64 v65, v114, v117, s[44:45]
	ds_bpermute_b32 v65, v157, v65
	v_cndmask_b32_e64 v66, v115, v105, s[44:45]
	ds_bpermute_b32 v66, v157, v66
	v_cndmask_b32_e64 v67, v98, v104, s[44:45]
	global_store_short v[68:69], v76, off offset:192
	global_store_short v[68:69], v77, off offset:2240
	ds_bpermute_b32 v67, v157, v67
	v_cndmask_b32_e64 v68, v99, v103, s[44:45]
	ds_bpermute_b32 v68, v157, v68
	v_cndmask_b32_e64 v69, v100, v106, s[44:45]
	v_cndmask_b32_e64 v64, v117, v114, s[44:45]
	ds_bpermute_b32 v69, v157, v69
	v_cndmask_b32_e64 v70, v101, v107, s[44:45]
	s_waitcnt lgkmcnt(4)
	v_add_f32_e32 v64, v64, v65
	v_cndmask_b32_e64 v65, v105, v115, s[44:45]
	ds_bpermute_b32 v70, v157, v70
	v_cndmask_b32_e64 v71, v116, v108, s[44:45]
	s_waitcnt lgkmcnt(4)
	v_add_f32_e32 v65, v65, v66
	v_cndmask_b32_e64 v66, v104, v98, s[44:45]
	ds_bpermute_b32 v71, v157, v71
	v_cndmask_b32_e64 v72, v102, v109, s[44:45]
	s_waitcnt lgkmcnt(4)
	v_add_f32_e32 v66, v66, v67
	v_cndmask_b32_e64 v67, v103, v99, s[44:45]
	ds_bpermute_b32 v72, v157, v72
	s_waitcnt lgkmcnt(4)
	v_add_f32_e32 v67, v67, v68
	v_cndmask_b32_e64 v68, v106, v100, s[44:45]
	s_waitcnt lgkmcnt(3)
	v_add_f32_e32 v68, v68, v69
	v_cndmask_b32_e64 v69, v107, v101, s[44:45]
	s_waitcnt lgkmcnt(2)
	v_add_f32_e32 v69, v69, v70
	v_cndmask_b32_e64 v70, v108, v116, s[44:45]
	s_waitcnt lgkmcnt(1)
	v_add_f32_e32 v70, v70, v71
	v_cndmask_b32_e64 v71, v109, v102, s[44:45]
	s_waitcnt lgkmcnt(0)
	v_add_f32_e32 v71, v71, v72
	v_cndmask_b32_e64 v72, v68, v64, s[42:43]
	v_cndmask_b32_e64 v64, v64, v68, s[42:43]
	v_cndmask_b32_e64 v68, v69, v65, s[42:43]
	v_cndmask_b32_e64 v65, v65, v69, s[42:43]
	ds_bpermute_b32 v65, v156, v65
	ds_bpermute_b32 v64, v156, v64
	s_waitcnt lgkmcnt(1)
	v_add_f32_e32 v65, v68, v65
	v_cndmask_b32_e64 v68, v70, v66, s[42:43]
	v_cndmask_b32_e64 v66, v66, v70, s[42:43]
	ds_bpermute_b32 v66, v156, v66
	s_waitcnt lgkmcnt(1)
	v_add_f32_e32 v64, v72, v64
	s_waitcnt lgkmcnt(0)
	v_add_f32_e32 v66, v68, v66
	v_cndmask_b32_e64 v68, v71, v67, s[42:43]
	v_cndmask_b32_e64 v67, v67, v71, s[42:43]
	ds_bpermute_b32 v67, v156, v67
	s_waitcnt lgkmcnt(0)
	v_add_f32_e32 v67, v68, v67
	v_cndmask_b32_e64 v68, v66, v64, s[40:41]
	v_cndmask_b32_e64 v64, v64, v66, s[40:41]
	v_cndmask_b32_e64 v66, v67, v65, s[40:41]
	v_cndmask_b32_e64 v65, v65, v67, s[40:41]
	ds_bpermute_b32 v64, v155, v64
	ds_bpermute_b32 v65, v155, v65
	s_waitcnt lgkmcnt(1)
	v_add_f32_e32 v64, v68, v64
	s_waitcnt lgkmcnt(0)
	v_add_f32_e32 v65, v66, v65
	v_cndmask_b32_e64 v66, v65, v64, s[38:39]
	v_cndmask_b32_e64 v64, v64, v65, s[38:39]
	ds_bpermute_b32 v64, v154, v64
	s_waitcnt lgkmcnt(0)
	v_add_f32_e32 v64, v66, v64
	ds_bpermute_b32 v65, v153, v64
	s_and_saveexec_b64 s[0:1], vcc
	s_cbranch_execz .LBB0_571
	v_lshlrev_b64 v[66:67], 6, v[132:133]
	v_lshl_add_u64 v[66:67], s[26:27], 0, v[66:67]
	s_waitcnt lgkmcnt(0)
	v_add_f32_e32 v64, v64, v65
	global_store_dword v[66:67], v64, off
.LBB0_571:
	s_or_b64 exec, exec, s[0:1]
	v_mov_b32_e32 v64, v130
	v_lshlrev_b32_e32 v108, 16, v85
	s_waitcnt lgkmcnt(0)
	v_ashrrev_i32_e32 v65, 31, v64
	v_lshl_add_u64 v[64:65], v[64:65], 1, s[46:47]
	global_load_ushort v66, v[64:65], off offset:64
	v_lshlrev_b32_e32 v103, 16, v84
	v_lshlrev_b32_e32 v98, 16, v82
	v_lshlrev_b32_e32 v99, 16, v83
	v_lshlrev_b32_e32 v102, 16, v87
	v_lshlrev_b32_e32 v101, 16, v88
	v_lshlrev_b32_e32 v100, 16, v89
	v_lshlrev_b32_e32 v89, 16, v90
	v_lshlrev_b32_e32 v88, 16, v91
	v_lshlrev_b32_e32 v87, 16, v92
	v_mov_b32_e32 v92, v158
	v_lshlrev_b32_e32 v109, 16, v86
	v_lshlrev_b32_e32 v86, 16, v93
	v_lshlrev_b32_e32 v68, 16, v97
	v_lshlrev_b32_e32 v71, 16, v95
	v_lshlrev_b32_e32 v73, 16, v94
	v_lshlrev_b32_e32 v70, 16, v96
	s_waitcnt vmcnt(0)
	v_lshlrev_b32_e32 v85, 16, v66
	global_load_ushort v84, v[64:65], off offset:2112
	s_waitcnt vmcnt(1)
	v_add_co_u32_e64 v66, s[0:1], s96, v64
	s_nop 1
	v_addc_co_u32_e64 v67, s[0:1], 0, v65, s[0:1]
	global_load_ushort v83, v[66:67], off offset:64
	s_waitcnt vmcnt(2)
	global_load_ushort v82, v[66:67], off offset:2112
	s_waitcnt vmcnt(3)
	v_add_co_u32_e64 v66, s[0:1], s94, v64
	s_nop 1
	v_addc_co_u32_e64 v67, s[0:1], 0, v65, s[0:1]
	global_load_ushort v81, v[66:67], off offset:64
	s_waitcnt vmcnt(4)
	global_load_ushort v78, v[66:67], off offset:2112
	s_waitcnt vmcnt(5)
	v_add_co_u32_e64 v66, s[0:1], s57, v64
	s_nop 1
	v_addc_co_u32_e64 v67, s[0:1], 0, v65, s[0:1]
	global_load_ushort v80, v[66:67], off offset:64
	s_waitcnt vmcnt(6)
	global_load_ushort v79, v[66:67], off offset:2112
	s_waitcnt vmcnt(7)
	v_add_co_u32_e64 v66, s[0:1], s35, v64
	s_nop 1
	v_addc_co_u32_e64 v67, s[0:1], 0, v65, s[0:1]
	global_load_ushort v76, v[66:67], off offset:64
	s_waitcnt vmcnt(8)
	global_load_ushort v74, v[66:67], off offset:2112
	s_waitcnt vmcnt(9)
	v_add_co_u32_e64 v66, s[0:1], s58, v64
	s_nop 1
	v_addc_co_u32_e64 v67, s[0:1], 0, v65, s[0:1]
	global_load_ushort v77, v[66:67], off offset:64
	s_waitcnt vmcnt(10)
	global_load_ushort v75, v[66:67], off offset:2112
	s_waitcnt vmcnt(11)
	v_add_co_u32_e64 v66, s[0:1], s95, v64
	s_nop 1
	v_addc_co_u32_e64 v67, s[0:1], 0, v65, s[0:1]
	v_add_co_u32_e64 v64, s[0:1], s59, v64
	global_load_ushort v69, v[66:67], off offset:64
	s_nop 0
	v_addc_co_u32_e64 v65, s[0:1], 0, v65, s[0:1]
	global_load_ushort v66, v[66:67], off offset:2112
	s_waitcnt vmcnt(1)
	v_lshlrev_b32_e32 v72, 16, v69
	global_load_ushort v67, v[64:65], off offset:64
	s_waitcnt vmcnt(1)
	v_lshlrev_b32_e32 v66, 16, v66
	global_load_ushort v64, v[64:65], off offset:2112
	s_waitcnt vmcnt(1)
	v_lshlrev_b32_e32 v69, 16, v67
	s_waitcnt vmcnt(0)
	v_lshlrev_b32_e32 v67, 16, v64
	v_mov_b32_e32 v64, v128
	s_nop 0
	v_add_u32_e32 v64, s68, v64
	v_ashrrev_i32_e32 v65, 31, v64
	v_lshl_add_u64 v[90:91], v[64:65], 2, s[50:51]
	global_load_dword v110, v[90:91], off
	v_lshl_add_u32 v90, v92, 2, s28
	v_ashrrev_i32_e32 v91, 31, v90
	v_lshlrev_b64 v[90:91], 11, v[90:91]
	v_lshl_add_u64 v[90:91], s[66:67], 0, v[90:91]
	v_lshl_add_u32 v111, v92, 4, s37
	v_lshl_add_u64 v[64:65], v[64:65], 1, v[90:91]
	ds_read_b128 v[90:93], v111 offset:128
	ds_read_b128 v[104:107], v111 offset:160
	s_waitcnt lgkmcnt(1)
	v_mul_f32_e32 v48, v48, v90
	s_waitcnt vmcnt(0)
	v_fmac_f32_e32 v98, v110, v48
	v_cvt_pk_bf16_f32 v48, v98, s0
	v_lshlrev_b32_e32 v97, 16, v48
	global_store_short v[64:65], v48, off
	v_mul_f32_e32 v48, v49, v91
	v_fmac_f32_e32 v99, v110, v48
	v_cvt_pk_bf16_f32 v48, v99, s0
	v_lshlrev_b32_e32 v95, 16, v48
	global_store_short v[64:65], v48, off offset:2048
	v_mul_f32_e32 v48, v50, v92
	v_fmac_f32_e32 v103, v110, v48
	v_cvt_pk_bf16_f32 v50, v103, s0
	v_add_co_u32_e64 v48, s[0:1], s96, v64
	v_lshlrev_b32_e32 v94, 16, v50
	s_nop 0
	v_addc_co_u32_e64 v49, s[0:1], 0, v65, s[0:1]
	global_store_short v[48:49], v50, off
	v_mul_f32_e32 v50, v51, v93
	v_fmac_f32_e32 v108, v110, v50
	v_cvt_pk_bf16_f32 v50, v108, s0
	global_store_short v[48:49], v50, off offset:2048
	s_waitcnt lgkmcnt(0)
	v_mul_f32_e32 v48, v52, v104
	v_fmac_f32_e32 v109, v110, v48
	v_cvt_pk_bf16_f32 v52, v109, s0
	v_add_co_u32_e64 v48, s[0:1], s94, v64
	v_lshlrev_b32_e32 v99, 16, v50
	s_nop 0
	v_addc_co_u32_e64 v49, s[0:1], 0, v65, s[0:1]
	v_add_co_u32_e64 v50, s[0:1], s57, v64
	v_lshlrev_b32_e32 v98, 16, v52
	s_nop 0
	v_addc_co_u32_e64 v51, s[0:1], 0, v65, s[0:1]
	global_store_short v[50:51], v52, off offset:-4096
	v_mul_f32_e32 v52, v53, v105
	v_fmac_f32_e32 v102, v110, v52
	v_cvt_pk_bf16_f32 v53, v102, s0
	global_store_short v[48:49], v53, off offset:2048
	v_mul_f32_e32 v48, v54, v106
	v_fmac_f32_e32 v101, v110, v48
	v_cvt_pk_bf16_f32 v48, v101, s0
	v_lshlrev_b32_e32 v96, 16, v48
	global_store_short v[50:51], v48, off
	v_mul_f32_e32 v48, v55, v107
	v_fmac_f32_e32 v100, v110, v48
	v_cvt_pk_bf16_f32 v48, v100, s0
	v_lshlrev_b32_e32 v52, 16, v53
	v_lshlrev_b32_e32 v53, 16, v48
	global_store_short v[50:51], v48, off offset:2048
	ds_read_b128 v[48:51], v111 offset:192
	s_waitcnt lgkmcnt(0)
	v_mul_f32_e32 v48, v56, v48
	v_fmac_f32_e32 v89, v110, v48
	v_cvt_pk_bf16_f32 v48, v89, s0
	v_add_co_u32_e64 v54, s[0:1], s35, v64
	v_lshlrev_b32_e32 v92, 16, v48
	s_nop 0
	v_addc_co_u32_e64 v55, s[0:1], 0, v65, s[0:1]
	v_add_co_u32_e64 v100, s[0:1], s58, v64
	s_nop 1
	v_addc_co_u32_e64 v101, s[0:1], 0, v65, s[0:1]
	global_store_short v[100:101], v48, off offset:-4096
	v_mul_f32_e32 v48, v57, v49
	v_fmac_f32_e32 v88, v110, v48
	v_cvt_pk_bf16_f32 v48, v88, s0
	v_lshlrev_b32_e32 v93, 16, v48
	global_store_short v[54:55], v48, off offset:2048
	v_mul_f32_e32 v48, v58, v50
	v_fmac_f32_e32 v87, v110, v48
	v_cvt_pk_bf16_f32 v48, v87, s0
	v_lshlrev_b32_e32 v91, 16, v48
	global_store_short v[100:101], v48, off
	v_mul_f32_e32 v48, v59, v51
	v_fmac_f32_e32 v86, v110, v48
	v_cvt_pk_bf16_f32 v48, v86, s0
	v_lshlrev_b32_e32 v90, 16, v48
	global_store_short v[100:101], v48, off offset:2048
	ds_read_b128 v[48:51], v111 offset:224
	v_mov_b32_e32 v101, v158
	s_waitcnt lgkmcnt(0)
	v_mul_f32_e32 v48, v60, v48
	v_fmac_f32_e32 v73, v110, v48
	v_cvt_pk_bf16_f32 v48, v73, s0
	v_add_co_u32_e64 v54, s[0:1], s95, v64
	v_lshlrev_b32_e32 v89, 16, v48
	s_nop 0
	v_addc_co_u32_e64 v55, s[0:1], 0, v65, s[0:1]
	v_add_co_u32_e64 v56, s[0:1], s59, v64
	s_nop 1
	v_addc_co_u32_e64 v57, s[0:1], 0, v65, s[0:1]
	global_store_short v[56:57], v48, off offset:-4096
	v_mul_f32_e32 v48, v61, v49
	v_fmac_f32_e32 v71, v110, v48
	v_cvt_pk_bf16_f32 v48, v71, s0
	v_lshlrev_b32_e32 v88, 16, v48
	global_store_short v[54:55], v48, off offset:2048
	v_mul_f32_e32 v48, v62, v50
	v_fmac_f32_e32 v70, v110, v48
	v_cvt_pk_bf16_f32 v48, v70, s0
	v_lshlrev_b32_e32 v87, 16, v48
	global_store_short v[56:57], v48, off
	v_mul_f32_e32 v48, v63, v51
	v_fmac_f32_e32 v68, v110, v48
	v_cvt_pk_bf16_f32 v48, v68, s0
	v_lshlrev_b32_e32 v86, 16, v48
	global_store_short v[56:57], v48, off offset:2048
	v_mov_b32_e32 v48, v130
	s_nop 0
	v_ashrrev_i32_e32 v49, 31, v48
	v_lshl_add_u64 v[48:49], v[48:49], 1, s[46:47]
	global_load_ushort v73, v[48:49], off offset:128
	s_waitcnt vmcnt(17)
	global_load_ushort v70, v[48:49], off offset:2176
	s_waitcnt vmcnt(18)
	v_add_co_u32_e64 v50, s[0:1], s96, v48
	s_nop 1
	v_addc_co_u32_e64 v51, s[0:1], 0, v49, s[0:1]
	global_load_ushort v71, v[50:51], off offset:128
	s_waitcnt vmcnt(19)
	global_load_ushort v63, v[50:51], off offset:2176
	s_waitcnt vmcnt(20)
	v_add_co_u32_e64 v50, s[0:1], s94, v48
	s_nop 1
	v_addc_co_u32_e64 v51, s[0:1], 0, v49, s[0:1]
	global_load_ushort v65, v[50:51], off offset:128
	s_waitcnt vmcnt(21)
	global_load_ushort v62, v[50:51], off offset:2176
	s_waitcnt vmcnt(22)
	v_add_co_u32_e64 v50, s[0:1], s57, v48
	s_nop 1
	v_addc_co_u32_e64 v51, s[0:1], 0, v49, s[0:1]
	global_load_ushort v68, v[50:51], off offset:128
	s_waitcnt vmcnt(23)
	global_load_ushort v64, v[50:51], off offset:2176
	s_waitcnt vmcnt(24)
	v_add_co_u32_e64 v50, s[0:1], s35, v48
	s_nop 1
	v_addc_co_u32_e64 v51, s[0:1], 0, v49, s[0:1]
	global_load_ushort v59, v[50:51], off offset:128
	s_waitcnt vmcnt(25)
	global_load_ushort v58, v[50:51], off offset:2176
	s_waitcnt vmcnt(26)
	v_add_co_u32_e64 v50, s[0:1], s58, v48
	s_nop 1
	v_addc_co_u32_e64 v51, s[0:1], 0, v49, s[0:1]
	global_load_ushort v61, v[50:51], off offset:128
	s_waitcnt vmcnt(27)
	global_load_ushort v60, v[50:51], off offset:2176
	s_waitcnt vmcnt(28)
	v_add_co_u32_e64 v50, s[0:1], s95, v48
	s_nop 1
	v_addc_co_u32_e64 v51, s[0:1], 0, v49, s[0:1]
	global_load_ushort v54, v[50:51], off offset:128
	v_add_co_u32_e64 v48, s[0:1], s59, v48
	global_load_ushort v50, v[50:51], off offset:2176
	s_nop 0
	v_addc_co_u32_e64 v49, s[0:1], 0, v49, s[0:1]
	s_waitcnt vmcnt(1)
	v_lshlrev_b32_e32 v56, 16, v54
	s_waitcnt vmcnt(0)
	v_lshlrev_b32_e32 v54, 16, v50
	global_load_ushort v57, v[48:49], off offset:128
	s_waitcnt vmcnt(1)
	global_load_ushort v55, v[48:49], off offset:2176
	s_waitcnt vmcnt(2)
	v_mov_b32_e32 v48, v128
	s_nop 0
	v_ashrrev_i32_e32 v49, 31, v48
	v_lshl_add_u64 v[48:49], v[48:49], 0, s[68:69]
	v_lshl_add_u64 v[50:51], v[48:49], 2, s[50:51]
	global_load_dword v100, v[50:51], off offset:128
	v_lshl_add_u32 v50, v101, 2, s28
	v_lshl_add_u32 v101, v101, 4, s37
	ds_read_b128 v[102:105], v101 offset:128
	ds_read_b128 v[106:109], v101 offset:160
	v_ashrrev_i32_e32 v51, 31, v50
	v_lshlrev_b64 v[50:51], 11, v[50:51]
	v_lshl_add_u64 v[50:51], s[66:67], 0, v[50:51]
	s_waitcnt lgkmcnt(1)
	v_mul_f32_e32 v32, v32, v102
	v_lshl_add_u64 v[48:49], v[48:49], 1, v[50:51]
	v_mul_f32_e32 v35, v35, v105
	s_waitcnt lgkmcnt(0)
	v_mul_f32_e32 v37, v37, v107
	s_waitcnt vmcnt(0)
	v_fmac_f32_e32 v85, v100, v32
	v_cvt_pk_bf16_f32 v32, v85, s0
	v_lshlrev_b32_e32 v50, 16, v32
	global_store_short v[48:49], v32, off offset:64
	v_mul_f32_e32 v32, v33, v103
	s_waitcnt vmcnt(49)
	v_lshlrev_b32_e32 v84, 16, v84
	v_fmac_f32_e32 v84, v100, v32
	v_cvt_pk_bf16_f32 v32, v84, s0
	v_lshlrev_b32_e32 v33, 16, v32
	global_store_short v[48:49], v32, off offset:2112
	v_mul_f32_e32 v32, v34, v104
	s_waitcnt vmcnt(49)
	v_lshlrev_b32_e32 v83, 16, v83
	v_fmac_f32_e32 v83, v100, v32
	v_cvt_pk_bf16_f32 v34, v83, s0
	v_add_co_u32_e64 v32, s[0:1], s96, v48
	v_mul_f32_e32 v51, v33, v33
	s_nop 0
	v_addc_co_u32_e64 v33, s[0:1], 0, v49, s[0:1]
	s_waitcnt vmcnt(48)
	v_lshlrev_b32_e32 v82, 16, v82
	v_fmac_f32_e32 v82, v100, v35
	s_nop 0
	v_cvt_pk_bf16_f32 v35, v82, s0
	global_store_short v[32:33], v34, off offset:64
	global_store_short v[32:33], v35, off offset:2112
	v_mul_f32_e32 v32, v36, v106
	s_waitcnt vmcnt(49)
	v_lshlrev_b32_e32 v81, 16, v81
	v_fmac_f32_e32 v81, v100, v32
	v_cvt_pk_bf16_f32 v36, v81, s0
	v_add_co_u32_e64 v32, s[0:1], s94, v48
	s_waitcnt vmcnt(48)
	v_lshlrev_b32_e32 v78, 16, v78
	v_fmac_f32_e32 v78, v100, v37
	s_nop 0
	v_addc_co_u32_e64 v33, s[0:1], 0, v49, s[0:1]
	global_store_short v[32:33], v36, off offset:64
	s_nop 0
	v_cvt_pk_bf16_f32 v37, v78, s0
	global_store_short v[32:33], v37, off offset:2112
	v_mul_f32_e32 v32, v38, v108
	s_waitcnt vmcnt(49)
	v_lshlrev_b32_e32 v80, 16, v80
	v_fmac_f32_e32 v80, v100, v32
	v_lshlrev_b32_e32 v78, 16, v37
	v_cvt_pk_bf16_f32 v38, v80, s0
	v_add_co_u32_e64 v32, s[0:1], s57, v48
	v_mul_f32_e32 v37, v78, v78
	s_nop 0
	v_addc_co_u32_e64 v33, s[0:1], 0, v49, s[0:1]
	v_fmac_f32_e32 v37, v52, v52
	v_lshlrev_b32_e32 v52, 16, v38
	global_store_short v[32:33], v38, off offset:64
	v_mul_f32_e32 v38, v39, v109
	v_lshlrev_b32_e32 v81, 16, v36
	s_waitcnt vmcnt(49)
	v_lshlrev_b32_e32 v79, 16, v79
	v_fmac_f32_e32 v79, v100, v38
	v_mul_f32_e32 v36, v81, v81
	v_cvt_pk_bf16_f32 v38, v79, s0
	ds_read_b128 v[78:81], v101 offset:192
	global_store_short v[32:33], v38, off offset:2112
	v_lshlrev_b32_e32 v39, 16, v38
	v_mul_f32_e32 v38, v39, v39
	v_fmac_f32_e32 v38, v53, v53
	s_waitcnt lgkmcnt(0)
	v_mul_f32_e32 v32, v40, v78
	s_waitcnt vmcnt(49)
	v_lshlrev_b32_e32 v76, 16, v76
	v_fmac_f32_e32 v76, v100, v32
	v_cvt_pk_bf16_f32 v39, v76, s0
	v_add_co_u32_e64 v32, s[0:1], s35, v48
	v_lshlrev_b32_e32 v40, 16, v39
	s_nop 0
	v_addc_co_u32_e64 v33, s[0:1], 0, v49, s[0:1]
	global_store_short v[32:33], v39, off offset:64
	v_mul_f32_e32 v39, v41, v79
	s_waitcnt vmcnt(49)
	v_lshlrev_b32_e32 v74, 16, v74
	v_fmac_f32_e32 v74, v100, v39
	v_cvt_pk_bf16_f32 v39, v74, s0
	global_store_short v[32:33], v39, off offset:2112
	v_mul_f32_e32 v32, v42, v80
	s_waitcnt vmcnt(49)
	v_lshlrev_b32_e32 v77, 16, v77
	v_fmac_f32_e32 v77, v100, v32
	v_mul_f32_e32 v53, v40, v40
	v_lshlrev_b32_e32 v40, 16, v39
	v_cvt_pk_bf16_f32 v39, v77, s0
	v_add_co_u32_e64 v32, s[0:1], s58, v48
	v_mul_f32_e32 v41, v40, v40
	s_nop 0
	v_addc_co_u32_e64 v33, s[0:1], 0, v49, s[0:1]
	v_lshlrev_b32_e32 v40, 16, v39
	global_store_short v[32:33], v39, off offset:64
	v_mul_f32_e32 v39, v43, v81
	s_waitcnt vmcnt(49)
	v_lshlrev_b32_e32 v75, 16, v75
	v_fmac_f32_e32 v75, v100, v39
	v_cvt_pk_bf16_f32 v39, v75, s0
	ds_read_b128 v[74:77], v101 offset:224
	global_store_short v[32:33], v39, off offset:2112
	v_lshlrev_b32_e32 v42, 16, v39
	v_mul_f32_e32 v39, v42, v42
	v_lshlrev_b32_e32 v83, 16, v34
	s_waitcnt lgkmcnt(0)
	v_mul_f32_e32 v32, v44, v74
	v_fmac_f32_e32 v72, v100, v32
	v_cvt_pk_bf16_f32 v42, v72, s0
	v_add_co_u32_e64 v32, s[0:1], s95, v48
	v_lshlrev_b32_e32 v43, 16, v42
	s_nop 0
	v_addc_co_u32_e64 v33, s[0:1], 0, v49, s[0:1]
	global_store_short v[32:33], v42, off offset:64
	v_mul_f32_e32 v42, v43, v43
	v_mul_f32_e32 v43, v45, v75
	v_fmac_f32_e32 v66, v100, v43
	v_cvt_pk_bf16_f32 v43, v66, s0
	global_store_short v[32:33], v43, off offset:2112
	v_mul_f32_e32 v32, v46, v76
	v_lshlrev_b32_e32 v44, 16, v43
	v_fmac_f32_e32 v69, v100, v32
	v_mul_f32_e32 v43, v44, v44
	v_cvt_pk_bf16_f32 v44, v69, s0
	v_add_co_u32_e64 v32, s[0:1], s59, v48
	v_lshlrev_b32_e32 v45, 16, v44
	s_nop 0
	v_addc_co_u32_e64 v33, s[0:1], 0, v49, s[0:1]
	global_store_short v[32:33], v44, off offset:64
	v_mul_f32_e32 v44, v45, v45
	v_mul_f32_e32 v45, v47, v77
	v_fmac_f32_e32 v67, v100, v45
	v_cvt_pk_bf16_f32 v45, v67, s0
	global_store_short v[32:33], v45, off offset:2112
	v_lshlrev_b32_e32 v46, 16, v45
	v_ashrrev_i32_e32 v131, 31, v130
	v_lshl_add_u64 v[32:33], v[130:131], 1, s[46:47]
	v_mul_f32_e32 v45, v46, v46
	global_load_ushort v46, v[32:33], off offset:192
	v_lshlrev_b32_e32 v82, 16, v35
	v_mul_f32_e32 v34, v83, v83
	v_mul_f32_e32 v35, v82, v82
	v_fmac_f32_e32 v45, v86, v86
	v_mov_b32_e32 v86, v158
	v_mul_f32_e32 v40, v40, v40
	v_fmac_f32_e32 v40, v91, v91
	v_fmac_f32_e32 v39, v90, v90
	v_fmac_f32_e32 v42, v89, v89
	v_fmac_f32_e32 v43, v88, v88
	v_fmac_f32_e32 v44, v87, v87
	v_fmac_f32_e32 v51, v95, v95
	v_fmac_f32_e32 v35, v99, v99
	v_fmac_f32_e32 v36, v98, v98
	v_mul_f32_e32 v52, v52, v52
	v_fmac_f32_e32 v52, v96, v96
	v_fmac_f32_e32 v41, v93, v93
	v_fmac_f32_e32 v53, v92, v92
	v_mul_f32_e32 v50, v50, v50
	v_fmac_f32_e32 v50, v97, v97
	v_fmac_f32_e32 v34, v94, v94
	s_waitcnt vmcnt(0)
	v_lshlrev_b32_e32 v67, 16, v46
	global_load_ushort v66, v[32:33], off offset:2240
	s_waitcnt vmcnt(1)
	v_add_co_u32_e64 v46, s[0:1], s96, v32
	s_nop 1
	v_addc_co_u32_e64 v47, s[0:1], 0, v33, s[0:1]
	global_load_ushort v72, v[46:47], off offset:192
	s_waitcnt vmcnt(2)
	global_load_ushort v69, v[46:47], off offset:2240
	s_waitcnt vmcnt(3)
	v_add_co_u32_e64 v46, s[0:1], s94, v32
	s_nop 1
	v_addc_co_u32_e64 v47, s[0:1], 0, v33, s[0:1]
	global_load_ushort v75, v[46:47], off offset:192
	s_waitcnt vmcnt(4)
	global_load_ushort v74, v[46:47], off offset:2240
	s_waitcnt vmcnt(5)
	v_add_co_u32_e64 v46, s[0:1], s57, v32
	s_nop 1
	v_addc_co_u32_e64 v47, s[0:1], 0, v33, s[0:1]
	global_load_ushort v81, v[46:47], off offset:192
	s_waitcnt vmcnt(6)
	global_load_ushort v79, v[46:47], off offset:2240
	s_waitcnt vmcnt(7)
	v_add_co_u32_e64 v46, s[0:1], s35, v32
	s_nop 1
	v_addc_co_u32_e64 v47, s[0:1], 0, v33, s[0:1]
	global_load_ushort v77, v[46:47], off offset:192
	s_waitcnt vmcnt(8)
	global_load_ushort v76, v[46:47], off offset:2240
	s_waitcnt vmcnt(9)
	v_add_co_u32_e64 v46, s[0:1], s58, v32
	s_nop 1
	v_addc_co_u32_e64 v47, s[0:1], 0, v33, s[0:1]
	global_load_ushort v80, v[46:47], off offset:192
	s_waitcnt vmcnt(10)
	global_load_ushort v78, v[46:47], off offset:2240
	v_add_co_u32_e64 v48, s[0:1], s95, v32
	s_waitcnt vmcnt(11)
	v_addc_co_u32_e64 v49, s[0:1], 0, v33, s[0:1]
	global_load_ushort v47, v[48:49], off offset:192
	v_add_co_u32_e64 v32, s[0:1], s59, v32
	s_waitcnt vmcnt(12)
	v_addc_co_u32_e64 v33, s[0:1], 0, v33, s[0:1]
	global_load_ushort v46, v[48:49], off offset:2240
	s_waitcnt vmcnt(13)
	global_load_ushort v49, v[32:33], off offset:192
	s_waitcnt vmcnt(14)
	global_load_ushort v48, v[32:33], off offset:2240
	s_waitcnt vmcnt(15)
	v_mov_b32_e32 v32, v128
	s_nop 0
	v_ashrrev_i32_e32 v33, 31, v32
	v_lshl_add_u64 v[32:33], v[32:33], 0, s[68:69]
	v_lshl_add_u64 v[82:83], v[32:33], 2, s[50:51]
	global_load_dword v82, v[82:83], off offset:256
	v_lshl_add_u32 v84, v86, 2, s28
	v_ashrrev_i32_e32 v85, 31, v84
	v_lshlrev_b64 v[84:85], 11, v[84:85]
	v_lshl_add_u64 v[84:85], s[66:67], 0, v[84:85]
	v_lshl_add_u32 v83, v86, 4, s37
	v_lshl_add_u64 v[32:33], v[32:33], 1, v[84:85]
	ds_read_b128 v[84:87], v83 offset:128
	ds_read_b128 v[88:91], v83 offset:160
	s_waitcnt lgkmcnt(1)
	v_mul_f32_e32 v16, v16, v84
	s_waitcnt vmcnt(0)
	s_waitcnt vmcnt(49)
	v_lshlrev_b32_e32 v73, 16, v73
	v_fmac_f32_e32 v73, v82, v16
	v_cvt_pk_bf16_f32 v16, v73, s0
	v_lshlrev_b32_e32 v73, 16, v16
	global_store_short v[32:33], v16, off offset:128
	v_mul_f32_e32 v16, v17, v85
	s_waitcnt vmcnt(49)
	v_lshlrev_b32_e32 v70, 16, v70
	v_fmac_f32_e32 v70, v82, v16
	v_cvt_pk_bf16_f32 v16, v70, s0
	v_lshlrev_b32_e32 v17, 16, v16
	global_store_short v[32:33], v16, off offset:2176
	v_mul_f32_e32 v16, v18, v86
	s_waitcnt vmcnt(49)
	v_lshlrev_b32_e32 v71, 16, v71
	v_fmac_f32_e32 v71, v82, v16
	v_cvt_pk_bf16_f32 v18, v71, s0
	v_add_co_u32_e64 v16, s[0:1], s96, v32
	v_fmac_f32_e32 v51, v17, v17
	s_nop 0
	v_addc_co_u32_e64 v17, s[0:1], 0, v33, s[0:1]
	v_lshlrev_b32_e32 v70, 16, v18
	global_store_short v[16:17], v18, off offset:128
	v_mul_f32_e32 v18, v19, v87
	s_waitcnt vmcnt(49)
	v_lshlrev_b32_e32 v63, 16, v63
	v_fmac_f32_e32 v63, v82, v18
	v_cvt_pk_bf16_f32 v18, v63, s0
	global_store_short v[16:17], v18, off offset:2176
	s_waitcnt lgkmcnt(0)
	v_mul_f32_e32 v16, v20, v88
	s_waitcnt vmcnt(49)
	v_lshlrev_b32_e32 v65, 16, v65
	v_fmac_f32_e32 v65, v82, v16
	v_lshlrev_b32_e32 v19, 16, v18
	v_cvt_pk_bf16_f32 v18, v65, s0
	v_add_co_u32_e64 v16, s[0:1], s94, v32
	v_fmac_f32_e32 v35, v19, v19
	s_nop 0
	v_addc_co_u32_e64 v17, s[0:1], 0, v33, s[0:1]
	v_lshlrev_b32_e32 v19, 16, v18
	global_store_short v[16:17], v18, off offset:128
	v_mul_f32_e32 v18, v21, v89
	s_waitcnt vmcnt(49)
	v_lshlrev_b32_e32 v62, 16, v62
	v_fmac_f32_e32 v62, v82, v18
	v_cvt_pk_bf16_f32 v18, v62, s0
	global_store_short v[16:17], v18, off offset:2176
	v_mul_f32_e32 v16, v22, v90
	s_waitcnt vmcnt(49)
	v_lshlrev_b32_e32 v68, 16, v68
	v_fmac_f32_e32 v68, v82, v16
	v_fmac_f32_e32 v36, v19, v19
	v_lshlrev_b32_e32 v19, 16, v18
	v_cvt_pk_bf16_f32 v18, v68, s0
	v_add_co_u32_e64 v16, s[0:1], s57, v32
	v_fmac_f32_e32 v37, v19, v19
	s_nop 0
	v_addc_co_u32_e64 v17, s[0:1], 0, v33, s[0:1]
	v_lshlrev_b32_e32 v19, 16, v18
	global_store_short v[16:17], v18, off offset:128
	v_mul_f32_e32 v18, v23, v91
	s_waitcnt vmcnt(49)
	v_lshlrev_b32_e32 v64, 16, v64
	v_fmac_f32_e32 v64, v82, v18
	v_cvt_pk_bf16_f32 v18, v64, s0
	v_fmac_f32_e32 v52, v19, v19
	v_lshlrev_b32_e32 v19, 16, v18
	global_store_short v[16:17], v18, off offset:2176
	v_fmac_f32_e32 v38, v19, v19
	ds_read_b128 v[16:19], v83 offset:192
	v_fmac_f32_e32 v50, v73, v73
	v_fmac_f32_e32 v34, v70, v70
	s_waitcnt lgkmcnt(0)
	v_mul_f32_e32 v16, v24, v16
	s_waitcnt vmcnt(49)
	v_lshlrev_b32_e32 v59, 16, v59
	v_fmac_f32_e32 v59, v82, v16
	v_cvt_pk_bf16_f32 v16, v59, s0
	v_add_co_u32_e64 v20, s[0:1], s35, v32
	v_lshlrev_b32_e32 v22, 16, v16
	s_nop 0
	v_addc_co_u32_e64 v21, s[0:1], 0, v33, s[0:1]
	global_store_short v[20:21], v16, off offset:128
	v_mul_f32_e32 v16, v25, v17
	s_waitcnt vmcnt(49)
	v_lshlrev_b32_e32 v58, 16, v58
	v_fmac_f32_e32 v58, v82, v16
	v_cvt_pk_bf16_f32 v16, v58, s0
	v_lshlrev_b32_e32 v17, 16, v16
	global_store_short v[20:21], v16, off offset:2176
	v_mul_f32_e32 v16, v26, v18
	s_waitcnt vmcnt(49)
	v_lshlrev_b32_e32 v61, 16, v61
	v_fmac_f32_e32 v61, v82, v16
	v_cvt_pk_bf16_f32 v18, v61, s0
	v_add_co_u32_e64 v16, s[0:1], s58, v32
	v_fmac_f32_e32 v41, v17, v17
	s_nop 0
	v_addc_co_u32_e64 v17, s[0:1], 0, v33, s[0:1]
	v_lshlrev_b32_e32 v20, 16, v18
	global_store_short v[16:17], v18, off offset:128
	v_mul_f32_e32 v18, v27, v19
	s_waitcnt vmcnt(49)
	v_lshlrev_b32_e32 v60, 16, v60
	v_fmac_f32_e32 v60, v82, v18
	v_cvt_pk_bf16_f32 v18, v60, s0
	v_lshlrev_b32_e32 v19, 16, v18
	global_store_short v[16:17], v18, off offset:2176
	v_fmac_f32_e32 v39, v19, v19
	ds_read_b128 v[16:19], v83 offset:224
	v_fmac_f32_e32 v40, v20, v20
	v_fmac_f32_e32 v53, v22, v22
	s_waitcnt lgkmcnt(0)
	v_mul_f32_e32 v16, v28, v16
	v_fmac_f32_e32 v56, v82, v16
	v_cvt_pk_bf16_f32 v16, v56, s0
	v_add_co_u32_e64 v20, s[0:1], s95, v32
	v_lshlrev_b32_e32 v22, 16, v16
	s_nop 0
	v_addc_co_u32_e64 v21, s[0:1], 0, v33, s[0:1]
	global_store_short v[20:21], v16, off offset:128
	v_mul_f32_e32 v16, v29, v17
	v_fmac_f32_e32 v54, v82, v16
	v_cvt_pk_bf16_f32 v16, v54, s0
	v_lshlrev_b32_e32 v17, 16, v16
	global_store_short v[20:21], v16, off offset:2176
	v_mul_f32_e32 v16, v30, v18
	s_waitcnt vmcnt(49)
	v_lshlrev_b32_e32 v57, 16, v57
	v_fmac_f32_e32 v57, v82, v16
	v_cvt_pk_bf16_f32 v18, v57, s0
	v_add_co_u32_e64 v16, s[0:1], s59, v32
	v_fmac_f32_e32 v43, v17, v17
	s_nop 0
	v_addc_co_u32_e64 v17, s[0:1], 0, v33, s[0:1]
	v_lshlrev_b32_e32 v20, 16, v18
	global_store_short v[16:17], v18, off offset:128
	v_mul_f32_e32 v18, v31, v19
	s_waitcnt vmcnt(49)
	v_lshlrev_b32_e32 v55, 16, v55
	v_fmac_f32_e32 v55, v82, v18
	v_cvt_pk_bf16_f32 v18, v55, s0
	global_store_short v[16:17], v18, off offset:2176
	v_lshlrev_b32_e32 v19, 16, v18
	v_ashrrev_i32_e32 v129, 31, v128
	v_lshl_add_u64 v[16:17], v[128:129], 0, s[68:69]
	v_fmac_f32_e32 v45, v19, v19
	v_lshl_add_u64 v[18:19], v[16:17], 2, s[50:51]
	global_load_dword v18, v[18:19], off offset:384
	v_fmac_f32_e32 v44, v20, v20
	v_lshl_add_u32 v20, v158, 2, s28
	v_ashrrev_i32_e32 v21, 31, v20
	v_lshlrev_b64 v[20:21], 11, v[20:21]
	v_lshl_add_u64 v[20:21], s[66:67], 0, v[20:21]
	v_lshl_add_u32 v19, v158, 4, s37
	v_fmac_f32_e32 v42, v22, v22
	v_lshl_add_u64 v[16:17], v[16:17], 1, v[20:21]
	ds_read_b128 v[20:23], v19 offset:128
	ds_read_b128 v[24:27], v19 offset:160
	s_waitcnt lgkmcnt(1)
	v_mul_f32_e32 v0, v0, v20
	s_waitcnt vmcnt(0)
	v_fmac_f32_e32 v67, v18, v0
	v_mul_f32_e32 v0, v1, v21
	s_waitcnt vmcnt(32)
	v_lshlrev_b32_e32 v66, 16, v66
	v_fmac_f32_e32 v66, v18, v0
	v_mul_f32_e32 v0, v2, v22
	s_waitcnt vmcnt(31)
	v_lshlrev_b32_e32 v72, 16, v72
	v_fmac_f32_e32 v72, v18, v0
	v_cvt_pk_bf16_f32 v20, v67, s0
	v_cvt_pk_bf16_f32 v21, v66, s0
	v_cvt_pk_bf16_f32 v22, v72, s0
	v_add_co_u32_e64 v0, s[0:1], s96, v16
	v_mul_f32_e32 v2, v3, v23
	s_nop 0
	v_addc_co_u32_e64 v1, s[0:1], 0, v17, s[0:1]
	s_waitcnt vmcnt(30)
	v_lshlrev_b32_e32 v69, 16, v69
	v_fmac_f32_e32 v69, v18, v2
	s_nop 0
	v_cvt_pk_bf16_f32 v23, v69, s0
	global_store_short v[0:1], v22, off offset:192
	global_store_short v[0:1], v23, off offset:2240
	s_waitcnt lgkmcnt(0)
	v_mul_f32_e32 v0, v4, v24
	s_waitcnt vmcnt(31)
	v_lshlrev_b32_e32 v75, 16, v75
	v_fmac_f32_e32 v75, v18, v0
	v_cvt_pk_bf16_f32 v24, v75, s0
	v_add_co_u32_e64 v0, s[0:1], s94, v16
	v_mul_f32_e32 v2, v5, v25
	s_nop 0
	v_addc_co_u32_e64 v1, s[0:1], 0, v17, s[0:1]
	s_waitcnt vmcnt(30)
	v_lshlrev_b32_e32 v74, 16, v74
	v_fmac_f32_e32 v74, v18, v2
	s_nop 0
	v_cvt_pk_bf16_f32 v25, v74, s0
	global_store_short v[0:1], v24, off offset:192
	global_store_short v[0:1], v25, off offset:2240
	v_mul_f32_e32 v0, v6, v26
	s_waitcnt vmcnt(31)
	v_lshlrev_b32_e32 v81, 16, v81
	v_fmac_f32_e32 v81, v18, v0
	v_cvt_pk_bf16_f32 v6, v81, s0
	v_add_co_u32_e64 v0, s[0:1], s57, v16
	v_mul_f32_e32 v2, v7, v27
	s_nop 0
	v_addc_co_u32_e64 v1, s[0:1], 0, v17, s[0:1]
	s_waitcnt vmcnt(30)
	v_lshlrev_b32_e32 v79, 16, v79
	v_fmac_f32_e32 v79, v18, v2
	s_nop 0
	v_cvt_pk_bf16_f32 v7, v79, s0
	global_store_short v[0:1], v6, off offset:192
	global_store_short v[0:1], v7, off offset:2240
	ds_read_b128 v[0:3], v19 offset:192
	global_store_short v[16:17], v20, off offset:192
	global_store_short v[16:17], v21, off offset:2240
	s_waitcnt lgkmcnt(0)
	v_mul_f32_e32 v0, v8, v0
	s_waitcnt vmcnt(33)
	v_lshlrev_b32_e32 v77, 16, v77
	v_fmac_f32_e32 v77, v18, v0
	v_mul_f32_e32 v0, v9, v1
	v_cvt_pk_bf16_f32 v8, v77, s0
	v_add_co_u32_e64 v4, s[0:1], s35, v16
	s_waitcnt vmcnt(32)
	v_lshlrev_b32_e32 v76, 16, v76
	v_fmac_f32_e32 v76, v18, v0
	v_mul_f32_e32 v0, v10, v2
	v_addc_co_u32_e64 v5, s[0:1], 0, v17, s[0:1]
	s_waitcnt vmcnt(31)
	v_lshlrev_b32_e32 v80, 16, v80
	v_fmac_f32_e32 v80, v18, v0
	s_nop 0
	v_cvt_pk_bf16_f32 v9, v76, s0
	v_cvt_pk_bf16_f32 v10, v80, s0
	v_add_co_u32_e64 v0, s[0:1], s58, v16
	v_mul_f32_e32 v2, v11, v3
	s_nop 0
	v_addc_co_u32_e64 v1, s[0:1], 0, v17, s[0:1]
	s_waitcnt vmcnt(30)
	v_lshlrev_b32_e32 v78, 16, v78
	v_fmac_f32_e32 v78, v18, v2
	s_nop 0
	v_cvt_pk_bf16_f32 v11, v78, s0
	global_store_short v[0:1], v10, off offset:192
	global_store_short v[0:1], v11, off offset:2240
	ds_read_b128 v[0:3], v19 offset:224
	global_store_short v[4:5], v8, off offset:192
	global_store_short v[4:5], v9, off offset:2240
	s_waitcnt lgkmcnt(0)
	v_mul_f32_e32 v0, v12, v0
	s_waitcnt vmcnt(33)
	v_lshlrev_b32_e32 v47, 16, v47
	v_fmac_f32_e32 v47, v18, v0
	v_mul_f32_e32 v0, v13, v1
	v_cvt_pk_bf16_f32 v12, v47, s0
	v_add_co_u32_e64 v4, s[0:1], s95, v16
	s_waitcnt vmcnt(32)
	v_lshlrev_b32_e32 v46, 16, v46
	v_fmac_f32_e32 v46, v18, v0
	v_mul_f32_e32 v0, v14, v2
	v_addc_co_u32_e64 v5, s[0:1], 0, v17, s[0:1]
	s_waitcnt vmcnt(31)
	v_lshlrev_b32_e32 v49, 16, v49
	v_fmac_f32_e32 v49, v18, v0
	s_nop 0
	v_cvt_pk_bf16_f32 v13, v46, s0
	v_cvt_pk_bf16_f32 v2, v49, s0
	v_add_co_u32_e64 v0, s[0:1], s59, v16
	v_mul_f32_e32 v3, v15, v3
	s_nop 0
	v_addc_co_u32_e64 v1, s[0:1], 0, v17, s[0:1]
	s_waitcnt vmcnt(30)
	v_lshlrev_b32_e32 v48, 16, v48
	v_fmac_f32_e32 v48, v18, v3
	s_nop 0
	v_cvt_pk_bf16_f32 v3, v48, s0
	global_store_short v[0:1], v2, off offset:192
	global_store_short v[0:1], v3, off offset:2240
	v_lshlrev_b32_e32 v0, 16, v20
	v_fmac_f32_e32 v50, v0, v0
	v_lshlrev_b32_e32 v0, 16, v21
	v_fmac_f32_e32 v51, v0, v0
	v_lshlrev_b32_e32 v0, 16, v22
	v_fmac_f32_e32 v34, v0, v0
	v_lshlrev_b32_e32 v0, 16, v23
	v_fmac_f32_e32 v35, v0, v0
	v_lshlrev_b32_e32 v0, 16, v24
	v_fmac_f32_e32 v36, v0, v0
	v_lshlrev_b32_e32 v0, 16, v25
	v_fmac_f32_e32 v37, v0, v0
	v_lshlrev_b32_e32 v0, 16, v6
	v_fmac_f32_e32 v52, v0, v0
	v_lshlrev_b32_e32 v0, 16, v7
	v_fmac_f32_e32 v38, v0, v0
	v_lshlrev_b32_e32 v0, 16, v8
	v_fmac_f32_e32 v53, v0, v0
	v_lshlrev_b32_e32 v0, 16, v9
	v_fmac_f32_e32 v41, v0, v0
	v_lshlrev_b32_e32 v0, 16, v10
	v_fmac_f32_e32 v40, v0, v0
	v_lshlrev_b32_e32 v0, 16, v11
	v_fmac_f32_e32 v39, v0, v0
	v_lshlrev_b32_e32 v0, 16, v12
	v_fmac_f32_e32 v42, v0, v0
	v_lshlrev_b32_e32 v0, 16, v13
	v_cndmask_b32_e64 v1, v50, v53, s[44:45]
	v_fmac_f32_e32 v43, v0, v0
	v_lshlrev_b32_e32 v0, 16, v2
	ds_bpermute_b32 v1, v157, v1
	v_cndmask_b32_e64 v2, v51, v41, s[44:45]
	v_fmac_f32_e32 v44, v0, v0
	v_lshlrev_b32_e32 v0, 16, v3
	ds_bpermute_b32 v2, v157, v2
	v_cndmask_b32_e64 v3, v34, v40, s[44:45]
	global_store_short v[4:5], v12, off offset:192
	global_store_short v[4:5], v13, off offset:2240
	ds_bpermute_b32 v3, v157, v3
	v_cndmask_b32_e64 v4, v35, v39, s[44:45]
	ds_bpermute_b32 v4, v157, v4
	v_cndmask_b32_e64 v5, v36, v42, s[44:45]
	v_fmac_f32_e32 v45, v0, v0
	v_cndmask_b32_e64 v0, v53, v50, s[44:45]
	ds_bpermute_b32 v5, v157, v5
	v_cndmask_b32_e64 v6, v37, v43, s[44:45]
	s_waitcnt lgkmcnt(4)
	v_add_f32_e32 v0, v0, v1
	v_cndmask_b32_e64 v1, v41, v51, s[44:45]
	ds_bpermute_b32 v6, v157, v6
	v_cndmask_b32_e64 v7, v52, v44, s[44:45]
	s_waitcnt lgkmcnt(4)
	v_add_f32_e32 v1, v1, v2
	v_cndmask_b32_e64 v2, v40, v34, s[44:45]
	ds_bpermute_b32 v7, v157, v7
	v_cndmask_b32_e64 v8, v38, v45, s[44:45]
	s_waitcnt lgkmcnt(4)
	v_add_f32_e32 v2, v2, v3
	v_cndmask_b32_e64 v3, v39, v35, s[44:45]
	ds_bpermute_b32 v8, v157, v8
	s_waitcnt lgkmcnt(4)
	v_add_f32_e32 v3, v3, v4
	v_cndmask_b32_e64 v4, v42, v36, s[44:45]
	s_waitcnt lgkmcnt(3)
	v_add_f32_e32 v4, v4, v5
	v_cndmask_b32_e64 v5, v43, v37, s[44:45]
	s_waitcnt lgkmcnt(2)
	v_add_f32_e32 v5, v5, v6
	v_cndmask_b32_e64 v6, v44, v52, s[44:45]
	s_waitcnt lgkmcnt(1)
	v_add_f32_e32 v6, v6, v7
	v_cndmask_b32_e64 v7, v45, v38, s[44:45]
	s_waitcnt lgkmcnt(0)
	v_add_f32_e32 v7, v7, v8
	v_cndmask_b32_e64 v8, v4, v0, s[42:43]
	v_cndmask_b32_e64 v0, v0, v4, s[42:43]
	v_cndmask_b32_e64 v4, v5, v1, s[42:43]
	v_cndmask_b32_e64 v1, v1, v5, s[42:43]
	ds_bpermute_b32 v1, v156, v1
	ds_bpermute_b32 v0, v156, v0
	s_waitcnt lgkmcnt(1)
	v_add_f32_e32 v1, v4, v1
	v_cndmask_b32_e64 v4, v6, v2, s[42:43]
	v_cndmask_b32_e64 v2, v2, v6, s[42:43]
	ds_bpermute_b32 v2, v156, v2
	s_waitcnt lgkmcnt(1)
	v_add_f32_e32 v0, v8, v0
	s_waitcnt lgkmcnt(0)
	v_add_f32_e32 v2, v4, v2
	v_cndmask_b32_e64 v4, v7, v3, s[42:43]
	v_cndmask_b32_e64 v3, v3, v7, s[42:43]
	ds_bpermute_b32 v3, v156, v3
	s_waitcnt lgkmcnt(0)
	v_add_f32_e32 v3, v4, v3
	v_cndmask_b32_e64 v4, v2, v0, s[40:41]
	v_cndmask_b32_e64 v0, v0, v2, s[40:41]
	v_cndmask_b32_e64 v2, v3, v1, s[40:41]
	v_cndmask_b32_e64 v1, v1, v3, s[40:41]
	ds_bpermute_b32 v0, v155, v0
	ds_bpermute_b32 v1, v155, v1
	s_waitcnt lgkmcnt(1)
	v_add_f32_e32 v0, v4, v0
	s_waitcnt lgkmcnt(0)
	v_add_f32_e32 v1, v2, v1
	v_cndmask_b32_e64 v2, v1, v0, s[38:39]
	v_cndmask_b32_e64 v0, v0, v1, s[38:39]
	ds_bpermute_b32 v0, v154, v0
	s_waitcnt lgkmcnt(0)
	v_add_f32_e32 v0, v2, v0
	ds_bpermute_b32 v1, v153, v0
	s_and_saveexec_b64 s[0:1], vcc
	s_cbranch_execz .LBB0_550
	v_or_b32_e32 v2, s28, v152
	v_ashrrev_i32_e32 v3, 31, v2
	v_lshlrev_b64 v[2:3], 6, v[2:3]
	v_lshl_add_u64 v[2:3], s[26:27], 0, v[2:3]
	s_waitcnt lgkmcnt(0)
	v_add_f32_e32 v0, v0, v1
	global_store_dword v[2:3], v0, off
	s_branch .LBB0_550

.LBB0_630:
	s_or_b64 exec, exec, s[36:37]
	s_lshl_b32 s6, s68, 7
	v_mov_b32_e32 v64, v197
	s_and_b32 s93, s6, 0x380
	s_lshl_b64 s[6:7], s[0:1], 10
	s_add_u32 s6, s80, s6
	v_and_b32_e32 v49, 7, v64
	v_ashrrev_i32_e32 v48, 3, v64
	v_lshlrev_b32_e32 v0, 3, v49
	s_addc_u32 s7, s81, s7
	s_lshl_b32 s8, s93, 9
	v_lshl_or_b32 v198, v48, 8, v0
	s_add_u32 s8, s4, s8
	v_lshl_add_u64 v[160:161], v[198:199], 2, s[6:7]
	s_addc_u32 s9, s5, 0
	v_add_co_u32_e32 v164, vcc, s35, v160
	v_lshl_add_u64 v[162:163], v[198:199], 1, s[8:9]
	s_nop 0
	v_addc_co_u32_e32 v165, vcc, 0, v161, vcc
	v_add_co_u32_e32 v166, vcc, s94, v162
	s_mov_b32 s36, 0x10000
	s_nop 0
	v_addc_co_u32_e32 v167, vcc, 0, v163, vcc
	v_add_co_u32_e32 v168, vcc, s36, v160
	s_mov_b64 s[6:7], 0x8000
	s_nop 0
	v_addc_co_u32_e32 v169, vcc, 0, v161, vcc
	v_lshl_add_u64 v[24:25], v[160:161], 0, s[6:7]
	s_mov_b64 s[6:7], 0x18000
	v_add_co_u32_e32 v170, vcc, s35, v162
	v_lshl_add_u64 v[40:41], v[160:161], 0, s[6:7]
	s_nop 0
	v_addc_co_u32_e32 v171, vcc, 0, v163, vcc
	s_mov_b32 s6, 0x18000
	s_mov_b64 s[40:41], 0x10000
	v_add_co_u32_e32 v172, vcc, s6, v160
	v_lshl_add_u64 v[28:29], v[160:161], 0, s[40:41]
	global_load_dwordx4 v[0:3], v[160:161], off offset:16
	global_load_dwordx4 v[4:7], v[160:161], off
	global_load_dwordx4 v[8:11], v[162:163], off
	global_load_dwordx4 v[12:15], v[164:165], off
	v_addc_co_u32_e32 v173, vcc, 0, v161, vcc
	global_load_dwordx4 v[16:19], v[166:167], off
	global_load_dwordx4 v[20:23], v[168:169], off
	s_nop 0
	global_load_dwordx4 v[24:27], v[24:25], off offset:16
	s_nop 0
	global_load_dwordx4 v[28:31], v[28:29], off offset:16
	v_add_co_u32_e32 v174, vcc, s95, v162
	global_load_dwordx4 v[32:35], v[170:171], off
	global_load_dwordx4 v[36:39], v[172:173], off
	s_nop 0
	global_load_dwordx4 v[40:43], v[40:41], off offset:16
	v_addc_co_u32_e32 v175, vcc, 0, v163, vcc
	global_load_dwordx4 v[44:47], v[174:175], off
	v_mul_lo_u32 v48, v48, s97
	v_lshlrev_b32_e32 v49, 4, v49
	s_mov_b64 s[6:7], 0x8100
	v_add3_u32 v178, v48, v49, 0
	v_lshl_add_u64 v[48:49], v[160:161], 0, s[6:7]
	s_mov_b64 s[6:7], 0x10100
	v_lshl_add_u64 v[50:51], v[160:161], 0, s[6:7]
	s_mov_b64 s[6:7], 0x18100
	v_lshl_add_u64 v[52:53], v[160:161], 0, s[6:7]
	global_load_dwordx4 v[148:151], v[160:161], off offset:272
	global_load_dwordx4 v[156:159], v[160:161], off offset:256
	global_load_dwordx4 v[144:147], v[162:163], off offset:128
	global_load_dwordx4 v[136:139], v[164:165], off offset:256
	global_load_dwordx4 v[140:143], v[48:49], off offset:16
	global_load_dwordx4 v[124:127], v[168:169], off offset:256
	global_load_dwordx4 v[112:115], v[172:173], off offset:256
	global_load_dwordx4 v[128:131], v[50:51], off offset:16
	global_load_dwordx4 v[116:119], v[52:53], off offset:16
	global_load_dwordx4 v[152:155], v[166:167], off offset:128
	global_load_dwordx4 v[132:135], v[170:171], off offset:128
	global_load_dwordx4 v[120:123], v[174:175], off offset:128
	s_mov_b64 s[6:7], 0x18200
	v_add_u32_e32 v179, 0xd800, v178
	s_waitcnt vmcnt(22)
	v_cvt_pk_bf16_f32 v4, v4, v5
	v_cvt_pk_bf16_f32 v5, v6, v7
	v_cvt_pk_bf16_f32 v6, v0, v1
	v_cvt_pk_bf16_f32 v7, v2, v3
	s_waitcnt vmcnt(20)
	v_cvt_pk_bf16_f32 v0, v12, v13
	v_cvt_pk_bf16_f32 v1, v14, v15
	s_waitcnt vmcnt(17)
	v_cvt_pk_bf16_f32 v2, v24, v25
	v_cvt_pk_bf16_f32 v3, v26, v27
	ds_write_b128 v178, v[4:7]
	ds_write_b128 v178, v[8:11] offset:18432
	v_cvt_pk_bf16_f32 v4, v20, v21
	v_cvt_pk_bf16_f32 v5, v22, v23
	s_waitcnt vmcnt(16)
	v_cvt_pk_bf16_f32 v6, v28, v29
	v_cvt_pk_bf16_f32 v7, v30, v31
	ds_write_b128 v178, v[0:3] offset:4608
	ds_write_b128 v178, v[16:19] offset:23040
	ds_write_b128 v178, v[4:7] offset:9216
	s_waitcnt vmcnt(15)
	ds_write_b128 v178, v[32:35] offset:27648
	s_waitcnt vmcnt(14)
	v_cvt_pk_bf16_f32 v0, v36, v37
	v_cvt_pk_bf16_f32 v1, v38, v39
	s_waitcnt vmcnt(13)
	v_cvt_pk_bf16_f32 v2, v40, v41
	v_cvt_pk_bf16_f32 v3, v42, v43
	ds_write_b128 v178, v[0:3] offset:13824
	s_waitcnt vmcnt(12)
	ds_write_b128 v178, v[44:47] offset:32256
	v_lshl_add_u64 v[0:1], v[160:161], 0, s[6:7]
	s_mov_b64 s[6:7], 0x10200
	v_lshl_add_u64 v[2:3], v[160:161], 0, s[6:7]
	s_mov_b64 s[6:7], 0x8200
	s_waitcnt lgkmcnt(0)
	s_barrier
	v_lshl_add_u64 v[4:5], v[160:161], 0, s[6:7]
	global_load_dwordx4 v[104:107], v[160:161], off offset:528
	global_load_dwordx4 v[108:111], v[160:161], off offset:512
	global_load_dwordx4 v[100:103], v[162:163], off offset:256
	global_load_dwordx4 v[96:99], v[164:165], off offset:512
	global_load_dwordx4 v[60:63], v[4:5], off offset:16
	global_load_dwordx4 v[52:55], v[166:167], off offset:256
	global_load_dwordx4 v[48:51], v[168:169], off offset:512
	global_load_dwordx4 v[44:47], v[170:171], off offset:256
	global_load_dwordx4 v[36:39], v[172:173], off offset:512
	global_load_dwordx4 v[56:59], v[2:3], off offset:16
	global_load_dwordx4 v[40:43], v[0:1], off offset:16
	global_load_dwordx4 v[32:35], v[174:175], off offset:256
	v_readfirstlane_b32 s6, v64
	s_lshr_b32 s7, s6, 1
	v_and_b32_e32 v0, 31, v64
	s_and_b32 s7, s7, 0xfffffc0
	v_or_b32_e32 v1, s7, v0
	v_and_or_b32 v0, s6, 64, v0
	s_mov_b64 s[6:7], 0x8300
	v_lshrrev_b32_e32 v2, 1, v64
	v_lshl_add_u64 v[194:195], v[160:161], 0, s[6:7]
	s_mov_b64 s[6:7], 0x10300
	v_mul_lo_u32 v1, v1, s97
	v_and_b32_e32 v2, 16, v2
	v_lshl_add_u64 v[200:201], v[160:161], 0, s[6:7]
	s_mov_b64 s[6:7], 0x18300
	v_mul_u32_u24_e32 v0, 0x90, v0
	v_add3_u32 v176, v1, v2, 0
	v_lshl_add_u64 v[202:203], v[160:161], 0, s[6:7]
	v_add3_u32 v177, v0, v2, 0
	s_setprio 1
	ds_read_b128 v[0:3], v176
	ds_read_b128 v[4:7], v177 offset:18432
	ds_read_b128 v[8:11], v177 offset:23040
	s_waitcnt lgkmcnt(1)
	v_mfma_f32_32x32x16_bf16 v[80:95], v[0:3], v[4:7], 0
	s_waitcnt lgkmcnt(0)
	v_mfma_f32_32x32x16_bf16 v[64:79], v[0:3], v[8:11], 0
	ds_read_b128 v[0:3], v176 offset:4608
	ds_read_b128 v[180:183], v176 offset:32
	ds_read_b128 v[184:187], v177 offset:18464
	ds_read_b128 v[188:191], v177 offset:23072
	s_waitcnt lgkmcnt(1)
	v_mfma_f32_32x32x16_bf16 v[80:95], v[180:183], v[184:187], v[80:95]
	s_waitcnt lgkmcnt(0)
	v_mfma_f32_32x32x16_bf16 v[64:79], v[180:183], v[188:191], v[64:79]
	ds_read_b128 v[180:183], v176 offset:4640
	v_mfma_f32_32x32x16_bf16 v[16:31], v[0:3], v[4:7], 0
	v_mfma_f32_32x32x16_bf16 v[0:15], v[0:3], v[8:11], 0
	s_waitcnt lgkmcnt(0)
	v_mfma_f32_32x32x16_bf16 v[16:31], v[180:183], v[184:187], v[16:31]
	v_mfma_f32_32x32x16_bf16 v[0:15], v[180:183], v[188:191], v[0:15]
	ds_read_b128 v[180:183], v176 offset:64
	ds_read_b128 v[184:187], v177 offset:18496
	ds_read_b128 v[188:191], v177 offset:23104
	s_waitcnt lgkmcnt(1)
	v_mfma_f32_32x32x16_bf16 v[80:95], v[180:183], v[184:187], v[80:95]
	s_waitcnt lgkmcnt(0)
	v_mfma_f32_32x32x16_bf16 v[64:79], v[180:183], v[188:191], v[64:79]
	ds_read_b128 v[180:183], v176 offset:4672
	s_waitcnt lgkmcnt(0)
	v_mfma_f32_32x32x16_bf16 v[16:31], v[180:183], v[184:187], v[16:31]
	v_mfma_f32_32x32x16_bf16 v[0:15], v[180:183], v[188:191], v[0:15]
	ds_read_b128 v[180:183], v176 offset:96
	ds_read_b128 v[184:187], v177 offset:18528
	ds_read_b128 v[188:191], v177 offset:23136
	s_waitcnt lgkmcnt(1)
	v_mfma_f32_32x32x16_bf16 v[80:95], v[180:183], v[184:187], v[80:95]
	s_waitcnt lgkmcnt(0)
	v_mfma_f32_32x32x16_bf16 v[64:79], v[180:183], v[188:191], v[64:79]
	ds_read_b128 v[180:183], v176 offset:4704
	s_waitcnt lgkmcnt(0)
	v_mfma_f32_32x32x16_bf16 v[16:31], v[180:183], v[184:187], v[16:31]
	v_mfma_f32_32x32x16_bf16 v[0:15], v[180:183], v[188:191], v[0:15]
	s_setprio 0
	s_waitcnt vmcnt(22)
	v_cvt_pk_bf16_f32 v156, v156, v157
	v_cvt_pk_bf16_f32 v157, v158, v159
	v_cvt_pk_bf16_f32 v158, v148, v149
	v_cvt_pk_bf16_f32 v159, v150, v151
	s_waitcnt vmcnt(20)
	v_cvt_pk_bf16_f32 v136, v136, v137
	v_cvt_pk_bf16_f32 v137, v138, v139
	s_waitcnt vmcnt(19)
	v_cvt_pk_bf16_f32 v138, v140, v141
	v_cvt_pk_bf16_f32 v139, v142, v143
	s_waitcnt vmcnt(18)
	v_cvt_pk_bf16_f32 v124, v124, v125
	v_cvt_pk_bf16_f32 v125, v126, v127
	s_waitcnt vmcnt(16)
	v_cvt_pk_bf16_f32 v126, v128, v129
	v_cvt_pk_bf16_f32 v127, v130, v131
	v_cvt_pk_bf16_f32 v112, v112, v113
	v_cvt_pk_bf16_f32 v113, v114, v115
	s_waitcnt vmcnt(15)
	v_cvt_pk_bf16_f32 v114, v116, v117
	v_cvt_pk_bf16_f32 v115, v118, v119
	ds_write_b128 v178, v[156:159] offset:36864
	ds_write_b128 v178, v[144:147] offset:55296
	ds_write_b128 v178, v[136:139] offset:41472
	s_waitcnt vmcnt(14)
	ds_write_b128 v178, v[152:155] offset:59904
	ds_write_b128 v178, v[124:127] offset:46080
	s_waitcnt vmcnt(13)
	ds_write_b128 v178, v[132:135] offset:64512
	ds_write_b128 v178, v[112:115] offset:50688
	s_waitcnt vmcnt(12)
	ds_write_b128 v179, v[120:123] offset:13824
	s_waitcnt lgkmcnt(0)
	s_barrier
	global_load_dwordx4 v[148:151], v[160:161], off offset:784
	global_load_dwordx4 v[152:155], v[160:161], off offset:768
	global_load_dwordx4 v[140:143], v[162:163], off offset:384
	global_load_dwordx4 v[136:139], v[166:167], off offset:384
	global_load_dwordx4 v[128:131], v[168:169], off offset:768
	global_load_dwordx4 v[144:147], v[194:195], off offset:16
	global_load_dwordx4 v[132:135], v[200:201], off offset:16
	global_load_dwordx4 v[124:127], v[170:171], off offset:384
	global_load_dwordx4 v[116:119], v[172:173], off offset:768
	global_load_dwordx4 v[156:159], v[164:165], off offset:768
	global_load_dwordx4 v[120:123], v[202:203], off offset:16
	global_load_dwordx4 v[112:115], v[174:175], off offset:384
	s_setprio 1
	ds_read_b128 v[160:163], v176 offset:36864
	ds_read_b128 v[164:167], v177 offset:55296
	ds_read_b128 v[168:171], v177 offset:59904
	s_waitcnt lgkmcnt(1)
	v_mfma_f32_32x32x16_bf16 v[80:95], v[160:163], v[164:167], v[80:95]
	s_waitcnt lgkmcnt(0)
	v_mfma_f32_32x32x16_bf16 v[64:79], v[160:163], v[168:171], v[64:79]
	ds_read_b128 v[160:163], v176 offset:41472
	s_waitcnt lgkmcnt(0)
	v_mfma_f32_32x32x16_bf16 v[16:31], v[160:163], v[164:167], v[16:31]
	v_mfma_f32_32x32x16_bf16 v[0:15], v[160:163], v[168:171], v[0:15]
	ds_read_b128 v[160:163], v176 offset:36896
	ds_read_b128 v[164:167], v177 offset:55328
	ds_read_b128 v[168:171], v177 offset:59936
	s_waitcnt lgkmcnt(1)
	v_mfma_f32_32x32x16_bf16 v[80:95], v[160:163], v[164:167], v[80:95]
	s_waitcnt lgkmcnt(0)
	v_mfma_f32_32x32x16_bf16 v[64:79], v[160:163], v[168:171], v[64:79]
	ds_read_b128 v[160:163], v176 offset:41504
	s_waitcnt lgkmcnt(0)
	v_mfma_f32_32x32x16_bf16 v[16:31], v[160:163], v[164:167], v[16:31]
	v_mfma_f32_32x32x16_bf16 v[0:15], v[160:163], v[168:171], v[0:15]
	ds_read_b128 v[160:163], v176 offset:36928
	ds_read_b128 v[164:167], v177 offset:55360
	ds_read_b128 v[168:171], v177 offset:59968
	s_waitcnt lgkmcnt(1)
	v_mfma_f32_32x32x16_bf16 v[80:95], v[160:163], v[164:167], v[80:95]
	s_waitcnt lgkmcnt(0)
	v_mfma_f32_32x32x16_bf16 v[64:79], v[160:163], v[168:171], v[64:79]
	ds_read_b128 v[160:163], v176 offset:41536
	s_waitcnt lgkmcnt(0)
	v_mfma_f32_32x32x16_bf16 v[16:31], v[160:163], v[164:167], v[16:31]
	v_mfma_f32_32x32x16_bf16 v[0:15], v[160:163], v[168:171], v[0:15]
	ds_read_b128 v[160:163], v176 offset:36960
	ds_read_b128 v[164:167], v177 offset:55392
	ds_read_b128 v[168:171], v177 offset:60000
	s_waitcnt lgkmcnt(1)
	v_mfma_f32_32x32x16_bf16 v[80:95], v[160:163], v[164:167], v[80:95]
	s_waitcnt lgkmcnt(0)
	v_mfma_f32_32x32x16_bf16 v[64:79], v[160:163], v[168:171], v[64:79]
	ds_read_b128 v[160:163], v176 offset:41568
	s_waitcnt lgkmcnt(0)
	v_mfma_f32_32x32x16_bf16 v[16:31], v[160:163], v[164:167], v[16:31]
	v_mfma_f32_32x32x16_bf16 v[0:15], v[160:163], v[168:171], v[0:15]
	s_setprio 0
	s_waitcnt vmcnt(22)
	v_cvt_pk_bf16_f32 v108, v108, v109
	v_cvt_pk_bf16_f32 v109, v110, v111
	v_cvt_pk_bf16_f32 v110, v104, v105
	v_cvt_pk_bf16_f32 v111, v106, v107
	s_waitcnt vmcnt(20)
	v_cvt_pk_bf16_f32 v96, v96, v97
	v_cvt_pk_bf16_f32 v97, v98, v99
	s_waitcnt vmcnt(19)
	v_cvt_pk_bf16_f32 v98, v60, v61
	v_cvt_pk_bf16_f32 v99, v62, v63
	s_waitcnt vmcnt(17)
	v_cvt_pk_bf16_f32 v48, v48, v49
	v_cvt_pk_bf16_f32 v49, v50, v51
	s_waitcnt vmcnt(14)
	v_cvt_pk_bf16_f32 v50, v56, v57
	v_cvt_pk_bf16_f32 v51, v58, v59
	v_cvt_pk_bf16_f32 v36, v36, v37
	v_cvt_pk_bf16_f32 v37, v38, v39
	s_waitcnt vmcnt(13)
	v_cvt_pk_bf16_f32 v38, v40, v41
	v_cvt_pk_bf16_f32 v39, v42, v43
	ds_write_b128 v178, v[108:111]
	ds_write_b128 v178, v[100:103] offset:18432
	ds_write_b128 v178, v[96:99] offset:4608
	ds_write_b128 v178, v[52:55] offset:23040
	ds_write_b128 v178, v[48:51] offset:9216
	ds_write_b128 v178, v[44:47] offset:27648
	ds_write_b128 v178, v[36:39] offset:13824
	s_waitcnt vmcnt(12)
	ds_write_b128 v178, v[32:35] offset:32256
	s_waitcnt lgkmcnt(0)
	s_barrier
	s_setprio 1
	ds_read_b128 v[32:35], v176
	ds_read_b128 v[36:39], v177 offset:18432
	ds_read_b128 v[40:43], v177 offset:23040
	s_waitcnt lgkmcnt(1)
	v_mfma_f32_32x32x16_bf16 v[80:95], v[32:35], v[36:39], v[80:95]
	s_waitcnt lgkmcnt(0)
	v_mfma_f32_32x32x16_bf16 v[64:79], v[32:35], v[40:43], v[64:79]
	ds_read_b128 v[32:35], v176 offset:4608
	s_waitcnt lgkmcnt(0)
	v_mfma_f32_32x32x16_bf16 v[16:31], v[32:35], v[36:39], v[16:31]
	v_mfma_f32_32x32x16_bf16 v[0:15], v[32:35], v[40:43], v[0:15]
	ds_read_b128 v[32:35], v176 offset:32
	ds_read_b128 v[36:39], v177 offset:18464
	ds_read_b128 v[40:43], v177 offset:23072
	s_waitcnt lgkmcnt(1)
	v_mfma_f32_32x32x16_bf16 v[80:95], v[32:35], v[36:39], v[80:95]
	s_waitcnt lgkmcnt(0)
	v_mfma_f32_32x32x16_bf16 v[64:79], v[32:35], v[40:43], v[64:79]
	ds_read_b128 v[32:35], v176 offset:4640
	s_waitcnt lgkmcnt(0)
	v_mfma_f32_32x32x16_bf16 v[16:31], v[32:35], v[36:39], v[16:31]
	v_mfma_f32_32x32x16_bf16 v[0:15], v[32:35], v[40:43], v[0:15]
	ds_read_b128 v[32:35], v176 offset:64
	ds_read_b128 v[36:39], v177 offset:18496
	ds_read_b128 v[40:43], v177 offset:23104
	s_waitcnt lgkmcnt(1)
	v_mfma_f32_32x32x16_bf16 v[80:95], v[32:35], v[36:39], v[80:95]
	s_waitcnt lgkmcnt(0)
	v_mfma_f32_32x32x16_bf16 v[64:79], v[32:35], v[40:43], v[64:79]
	ds_read_b128 v[32:35], v176 offset:4672
	s_waitcnt lgkmcnt(0)
	v_mfma_f32_32x32x16_bf16 v[16:31], v[32:35], v[36:39], v[16:31]
	v_mfma_f32_32x32x16_bf16 v[0:15], v[32:35], v[40:43], v[0:15]
	ds_read_b128 v[32:35], v176 offset:96
	ds_read_b128 v[36:39], v177 offset:18528
	ds_read_b128 v[40:43], v177 offset:23136
	s_waitcnt lgkmcnt(1)
	v_mfma_f32_32x32x16_bf16 v[80:95], v[32:35], v[36:39], v[80:95]
	s_waitcnt lgkmcnt(0)
	v_mfma_f32_32x32x16_bf16 v[64:79], v[32:35], v[40:43], v[64:79]
	ds_read_b128 v[32:35], v176 offset:4704
	s_waitcnt lgkmcnt(0)
	v_mfma_f32_32x32x16_bf16 v[16:31], v[32:35], v[36:39], v[16:31]
	v_mfma_f32_32x32x16_bf16 v[0:15], v[32:35], v[40:43], v[0:15]
	s_setprio 0
	s_waitcnt vmcnt(10)
	v_cvt_pk_bf16_f32 v32, v152, v153
	v_cvt_pk_bf16_f32 v33, v154, v155
	v_cvt_pk_bf16_f32 v34, v148, v149
	v_cvt_pk_bf16_f32 v35, v150, v151
	ds_write_b128 v178, v[32:35] offset:36864
	s_waitcnt vmcnt(9)
	ds_write_b128 v178, v[140:143] offset:55296
	s_waitcnt vmcnt(2)
	v_cvt_pk_bf16_f32 v32, v156, v157
	v_cvt_pk_bf16_f32 v33, v158, v159
	v_cvt_pk_bf16_f32 v34, v144, v145
	v_cvt_pk_bf16_f32 v35, v146, v147
	ds_write_b128 v178, v[32:35] offset:41472
	ds_write_b128 v178, v[136:139] offset:59904
	v_cvt_pk_bf16_f32 v32, v128, v129
	v_cvt_pk_bf16_f32 v33, v130, v131
	v_cvt_pk_bf16_f32 v34, v132, v133
	v_cvt_pk_bf16_f32 v35, v134, v135
	ds_write_b128 v178, v[32:35] offset:46080
	ds_write_b128 v178, v[124:127] offset:64512
	v_cvt_pk_bf16_f32 v32, v116, v117
	v_cvt_pk_bf16_f32 v33, v118, v119
	s_waitcnt vmcnt(1)
	v_cvt_pk_bf16_f32 v34, v120, v121
	v_cvt_pk_bf16_f32 v35, v122, v123
	ds_write_b128 v178, v[32:35] offset:50688
	s_waitcnt vmcnt(0)
	ds_write_b128 v179, v[112:115] offset:13824
	s_waitcnt lgkmcnt(0)
	s_barrier
	s_setprio 1
	ds_read_b128 v[32:35], v176 offset:36864
	ds_read_b128 v[36:39], v177 offset:55296
	ds_read_b128 v[40:43], v177 offset:59904
	s_waitcnt lgkmcnt(1)
	v_mfma_f32_32x32x16_bf16 v[80:95], v[32:35], v[36:39], v[80:95]
	s_waitcnt lgkmcnt(0)
	v_mfma_f32_32x32x16_bf16 v[64:79], v[32:35], v[40:43], v[64:79]
	ds_read_b128 v[32:35], v176 offset:41472
	s_waitcnt lgkmcnt(0)
	v_mfma_f32_32x32x16_bf16 v[16:31], v[32:35], v[36:39], v[16:31]
	v_mfma_f32_32x32x16_bf16 v[0:15], v[32:35], v[40:43], v[0:15]
	ds_read_b128 v[32:35], v176 offset:36896
	ds_read_b128 v[36:39], v177 offset:55328
	ds_read_b128 v[40:43], v177 offset:59936
	s_waitcnt lgkmcnt(1)
	v_mfma_f32_32x32x16_bf16 v[80:95], v[32:35], v[36:39], v[80:95]
	s_waitcnt lgkmcnt(0)
	v_mfma_f32_32x32x16_bf16 v[64:79], v[32:35], v[40:43], v[64:79]
	ds_read_b128 v[32:35], v176 offset:41504
	s_waitcnt lgkmcnt(0)
	v_mfma_f32_32x32x16_bf16 v[16:31], v[32:35], v[36:39], v[16:31]
	v_mfma_f32_32x32x16_bf16 v[0:15], v[32:35], v[40:43], v[0:15]
	ds_read_b128 v[32:35], v176 offset:36928
	ds_read_b128 v[36:39], v177 offset:55360
	ds_read_b128 v[40:43], v177 offset:59968
	s_waitcnt lgkmcnt(1)
	v_mfma_f32_32x32x16_bf16 v[80:95], v[32:35], v[36:39], v[80:95]
	s_waitcnt lgkmcnt(0)
	v_mfma_f32_32x32x16_bf16 v[64:79], v[32:35], v[40:43], v[64:79]
	ds_read_b128 v[32:35], v176 offset:41536
	s_waitcnt lgkmcnt(0)
	v_mfma_f32_32x32x16_bf16 v[16:31], v[32:35], v[36:39], v[16:31]
	v_mfma_f32_32x32x16_bf16 v[0:15], v[32:35], v[40:43], v[0:15]
	ds_read_b128 v[32:35], v176 offset:36960
	ds_read_b128 v[36:39], v177 offset:55392
	ds_read_b128 v[40:43], v177 offset:60000
	s_waitcnt lgkmcnt(1)
	v_mfma_f32_32x32x16_bf16 v[80:95], v[32:35], v[36:39], v[80:95]
	s_waitcnt lgkmcnt(0)
	v_mfma_f32_32x32x16_bf16 v[64:79], v[32:35], v[40:43], v[64:79]
	ds_read_b128 v[32:35], v176 offset:41568
	s_waitcnt lgkmcnt(0)
	v_mfma_f32_32x32x16_bf16 v[16:31], v[32:35], v[36:39], v[16:31]
	v_mfma_f32_32x32x16_bf16 v[0:15], v[32:35], v[40:43], v[0:15]
	s_setprio 0
	v_mov_b32_e32 v108, v197
	s_barrier
	s_lshl_b64 s[6:7], s[0:1], 11
	s_add_u32 s6, s66, s6
	s_addc_u32 s7, s67, s7
	s_lshl_b32 s101, s93, 11
	s_add_u32 s8, s2, s101
	s_addc_u32 s9, s3, 0
	v_lshrrev_b32_e32 v213, 3, v197
	v_and_b32_e32 v214, 7, v197
	v_lshlrev_b32_e32 v200, 11, v213
	v_lshl_or_b32 v200, v214, 4, v200
	v_add_u32_e32 v201, 0x10000, v200
	v_add_u32_e32 v202, 0x20000, v200
	v_add_u32_e32 v203, 0x30000, v200
	global_load_dwordx4 v[128:131], v200, s[6:7]
	global_load_dwordx4 v[132:135], v201, s[6:7]
	global_load_dwordx4 v[136:139], v202, s[6:7]
	global_load_dwordx4 v[140:143], v203, s[6:7]
	global_load_dwordx4 v[144:147], v200, s[8:9]
	global_load_dwordx4 v[148:151], v201, s[8:9]
	global_load_dwordx4 v[152:155], v202, s[8:9]
	global_load_dwordx4 v[156:159], v203, s[8:9]
	s_add_u32 s6, s6, 0x80
	s_addc_u32 s7, s7, 0
	s_add_u32 s8, s8, 0x80
	s_addc_u32 s9, s9, 0
	v_bfe_u32 v215, v197, 5, 2
	v_and_b32_e32 v198, 3, v214
	v_xor_b32_e32 v198, v198, v215
	v_lshlrev_b32_e32 v198, 4, v198
	v_lshl_or_b32 v204, v213, 6, v198
	v_lshrrev_b32_e32 v215, 2, v214
	v_lshlrev_b32_e32 v198, 6, v215
	v_xor_b32_e32 v204, v204, v198
	v_mul_u32_u24_e32 v215, 0x4000, v215
	v_add_u32_e32 v204, v204, v215
	v_and_b32_e32 v213, 31, v197
	v_bfe_u32 v214, v197, 5, 1
	v_bfe_u32 v215, v197, 2, 2
	v_xor_b32_e32 v198, v214, v215
	v_xor_b32_e32 v222, 2, v198
	v_lshrrev_b32_e32 v214, 7, v197
	v_lshl_or_b32 v214, v214, 6, v213
	v_lshlrev_b32_e32 v214, 6, v214
	v_lshl_or_b32 v205, v198, 4, v214
	v_lshl_or_b32 v206, v222, 4, v214
	v_bfe_u32 v214, v197, 6, 1
	v_mul_u32_u24_e32 v214, 64, v214
	v_add_u32_e32 v214, v214, v213
	v_lshlrev_b32_e32 v214, 6, v214
	v_add_u32_e32 v214, 0x2000, v214
	v_lshl_or_b32 v207, v198, 4, v214
	v_lshl_or_b32 v208, v222, 4, v214
	v_mov_b64_e32 v[32:33], 0
	v_mov_b64_e32 v[34:35], 0
	v_mov_b64_e32 v[36:37], 0
	v_mov_b64_e32 v[38:39], 0
	v_mov_b64_e32 v[40:41], 0
	v_mov_b64_e32 v[42:43], 0
	v_mov_b64_e32 v[44:45], 0
	v_mov_b64_e32 v[46:47], 0
	v_mov_b64_e32 v[48:49], 0
	v_mov_b64_e32 v[50:51], 0
	v_mov_b64_e32 v[52:53], 0
	v_mov_b64_e32 v[54:55], 0
	v_mov_b64_e32 v[56:57], 0
	v_mov_b64_e32 v[58:59], 0
	v_mov_b64_e32 v[60:61], 0
	v_mov_b64_e32 v[62:63], 0
	v_mov_b64_e32 v[96:97], 0
	v_mov_b64_e32 v[98:99], 0
	v_mov_b64_e32 v[100:101], 0
	v_mov_b64_e32 v[102:103], 0
	v_mov_b64_e32 v[104:105], 0
	v_mov_b64_e32 v[106:107], 0
	v_mov_b64_e32 v[108:109], 0
	v_mov_b64_e32 v[110:111], 0
	v_mov_b64_e32 v[112:113], 0
	v_mov_b64_e32 v[114:115], 0
	v_mov_b64_e32 v[116:117], 0
	v_mov_b64_e32 v[118:119], 0
	v_mov_b64_e32 v[120:121], 0
	v_mov_b64_e32 v[122:123], 0
	v_mov_b64_e32 v[124:125], 0
	v_mov_b64_e32 v[126:127], 0
	s_mov_b32 s98, 0
	s_mov_b32 s99, 0x4000
	s_mov_b32 s100, 0
	s_waitcnt vmcnt(7)
	ds_write_b128 v204, v[128:131]
	s_waitcnt vmcnt(6)
	ds_write_b128 v204, v[132:135] offset:2048
	s_waitcnt vmcnt(5)
	ds_write_b128 v204, v[136:139] offset:4096
	s_waitcnt vmcnt(4)
	ds_write_b128 v204, v[140:143] offset:6144
	s_waitcnt vmcnt(3)
	ds_write_b128 v204, v[144:147] offset:8192
	s_waitcnt vmcnt(2)
	ds_write_b128 v204, v[148:151] offset:10240
	s_waitcnt vmcnt(1)
	ds_write_b128 v204, v[152:155] offset:12288
	s_waitcnt vmcnt(0)
	ds_write_b128 v204, v[156:159] offset:14336
	v_subrev_u32_e32 v213, 0x4000, v204
	v_add_u32_e32 v214, 0x8000, v204
	v_min_u32_e32 v204, v213, v214
	s_waitcnt lgkmcnt(0)
	s_barrier
.Lg7_loop:
	v_add_u32_e32 v209, s98, v205
	v_add_u32_e32 v210, s98, v206
	v_add_u32_e32 v211, s98, v207
	v_add_u32_e32 v212, s98, v208
	ds_read_b128 v[160:163], v209
	ds_read_b128 v[164:167], v209 offset:2048
	ds_read_b128 v[168:171], v211
	ds_read_b128 v[172:175], v211 offset:2048
	s_setprio 1
	s_waitcnt lgkmcnt(1)
	v_mfma_f32_32x32x16_bf16 v[112:127], v[160:163], v[168:171], v[112:127]
	global_load_dwordx4 v[128:131], v200, s[6:7]
	ds_read_b128 v[176:179], v210
	v_mfma_f32_32x32x16_bf16 v[48:63], v[164:167], v[168:171], v[48:63]
	global_load_dwordx4 v[132:135], v201, s[6:7]
	ds_read_b128 v[180:183], v210 offset:2048
	s_waitcnt lgkmcnt(2)
	v_mfma_f32_32x32x16_bf16 v[96:111], v[160:163], v[172:175], v[96:111]
	global_load_dwordx4 v[136:139], v202, s[6:7]
	ds_read_b128 v[184:187], v212
	v_mfma_f32_32x32x16_bf16 v[32:47], v[164:167], v[172:175], v[32:47]
	global_load_dwordx4 v[140:143], v203, s[6:7]
	ds_read_b128 v[188:191], v212 offset:2048
	v_xad_u32 v209, v205, 64, s99
	v_xad_u32 v211, v207, 64, s99
	s_waitcnt lgkmcnt(1)
	v_mfma_f32_32x32x16_bf16 v[112:127], v[176:179], v[184:187], v[112:127]
	global_load_dwordx4 v[144:147], v200, s[8:9]
	ds_read_b128 v[160:163], v209
	v_mfma_f32_32x32x16_bf16 v[48:63], v[180:183], v[184:187], v[48:63]
	global_load_dwordx4 v[148:151], v201, s[8:9]
	ds_read_b128 v[164:167], v209 offset:2048
	s_waitcnt lgkmcnt(2)
	v_mfma_f32_32x32x16_bf16 v[96:111], v[176:179], v[188:191], v[96:111]
	global_load_dwordx4 v[152:155], v202, s[8:9]
	ds_read_b128 v[168:171], v211
	v_mfma_f32_32x32x16_bf16 v[32:47], v[180:183], v[188:191], v[32:47]
	global_load_dwordx4 v[156:159], v203, s[8:9]
	ds_read_b128 v[172:175], v211 offset:2048
	s_setprio 0
	s_barrier
	v_xad_u32 v210, v206, 64, s99
	v_xad_u32 v212, v208, 64, s99
	s_setprio 1
	s_waitcnt lgkmcnt(1)
	v_mfma_f32_32x32x16_bf16 v[112:127], v[160:163], v[168:171], v[112:127]
	ds_read_b128 v[176:179], v210
	v_mfma_f32_32x32x16_bf16 v[48:63], v[164:167], v[168:171], v[48:63]
	ds_read_b128 v[180:183], v210 offset:2048
	s_waitcnt lgkmcnt(2)
	v_mfma_f32_32x32x16_bf16 v[96:111], v[160:163], v[172:175], v[96:111]
	ds_read_b128 v[184:187], v212
	s_waitcnt vmcnt(7)
	ds_write_b128 v204, v[128:131]
	v_mfma_f32_32x32x16_bf16 v[32:47], v[164:167], v[172:175], v[32:47]
	ds_read_b128 v[188:191], v212 offset:2048
	s_waitcnt vmcnt(6)
	ds_write_b128 v204, v[132:135] offset:2048
	s_waitcnt lgkmcnt(3)
	v_mfma_f32_32x32x16_bf16 v[112:127], v[176:179], v[184:187], v[112:127]
	s_waitcnt vmcnt(5)
	ds_write_b128 v204, v[136:139] offset:4096
	v_mfma_f32_32x32x16_bf16 v[48:63], v[180:183], v[184:187], v[48:63]
	s_waitcnt vmcnt(4)
	ds_write_b128 v204, v[140:143] offset:6144
	s_waitcnt lgkmcnt(3)
	v_mfma_f32_32x32x16_bf16 v[96:111], v[176:179], v[188:191], v[96:111]
	s_waitcnt vmcnt(3)
	ds_write_b128 v204, v[144:147] offset:8192
	v_mfma_f32_32x32x16_bf16 v[32:47], v[180:183], v[188:191], v[32:47]
	s_waitcnt vmcnt(2)
	ds_write_b128 v204, v[148:151] offset:10240
	s_waitcnt vmcnt(1)
	ds_write_b128 v204, v[152:155] offset:12288
	s_waitcnt vmcnt(0)
	ds_write_b128 v204, v[156:159] offset:14336
	s_setprio 0
	s_add_u32 s6, s6, 0x80
	s_addc_u32 s7, s7, 0
	s_add_u32 s8, s8, 0x80
	s_addc_u32 s9, s9, 0
	s_sub_i32 s98, s98, 0x4000
	s_cmp_lt_i32 s98, 0
	s_cselect_b32 s101, 0xc000, 0
	s_add_i32 s98, s98, s101
	s_sub_i32 s99, s99, 0x4000
	s_cmp_lt_i32 s99, 0
	s_cselect_b32 s101, 0xc000, 0
	s_add_i32 s99, s99, s101
	v_subrev_u32_e32 v213, 0x4000, v204
	v_add_u32_e32 v214, 0x8000, v204
	v_min_u32_e32 v204, v213, v214
	s_add_i32 s100, s100, 1
	s_cmp_lt_u32 s100, 15
	s_waitcnt lgkmcnt(0)
	s_barrier
	s_cbranch_scc1 .Lg7_loop
	v_add_u32_e32 v209, s98, v205
	v_add_u32_e32 v210, s98, v206
	v_add_u32_e32 v211, s98, v207
	v_add_u32_e32 v212, s98, v208
	ds_read_b128 v[160:163], v209
	ds_read_b128 v[164:167], v209 offset:2048
	ds_read_b128 v[168:171], v211
	ds_read_b128 v[172:175], v211 offset:2048
	s_setprio 1
	s_waitcnt lgkmcnt(1)
	v_mfma_f32_32x32x16_bf16 v[112:127], v[160:163], v[168:171], v[112:127]
	ds_read_b128 v[176:179], v210
	v_mfma_f32_32x32x16_bf16 v[48:63], v[164:167], v[168:171], v[48:63]
	ds_read_b128 v[180:183], v210 offset:2048
	s_waitcnt lgkmcnt(2)
	v_mfma_f32_32x32x16_bf16 v[96:111], v[160:163], v[172:175], v[96:111]
	ds_read_b128 v[184:187], v212
	v_mfma_f32_32x32x16_bf16 v[32:47], v[164:167], v[172:175], v[32:47]
	ds_read_b128 v[188:191], v212 offset:2048
	v_xad_u32 v209, v205, 64, s99
	v_xad_u32 v211, v207, 64, s99
	s_waitcnt lgkmcnt(1)
	v_mfma_f32_32x32x16_bf16 v[112:127], v[176:179], v[184:187], v[112:127]
	ds_read_b128 v[160:163], v209
	v_mfma_f32_32x32x16_bf16 v[48:63], v[180:183], v[184:187], v[48:63]
	ds_read_b128 v[164:167], v209 offset:2048
	s_waitcnt lgkmcnt(2)
	v_mfma_f32_32x32x16_bf16 v[96:111], v[176:179], v[188:191], v[96:111]
	ds_read_b128 v[168:171], v211
	v_mfma_f32_32x32x16_bf16 v[32:47], v[180:183], v[188:191], v[32:47]
	ds_read_b128 v[172:175], v211 offset:2048
	s_setprio 0
	v_xad_u32 v210, v206, 64, s99
	v_xad_u32 v212, v208, 64, s99
	s_setprio 1
	s_waitcnt lgkmcnt(1)
	v_mfma_f32_32x32x16_bf16 v[112:127], v[160:163], v[168:171], v[112:127]
	ds_read_b128 v[176:179], v210
	v_mfma_f32_32x32x16_bf16 v[48:63], v[164:167], v[168:171], v[48:63]
	ds_read_b128 v[180:183], v210 offset:2048
	s_waitcnt lgkmcnt(2)
	v_mfma_f32_32x32x16_bf16 v[96:111], v[160:163], v[172:175], v[96:111]
	ds_read_b128 v[184:187], v212
	v_mfma_f32_32x32x16_bf16 v[32:47], v[164:167], v[172:175], v[32:47]
	ds_read_b128 v[188:191], v212 offset:2048
	s_waitcnt lgkmcnt(1)
	v_mfma_f32_32x32x16_bf16 v[112:127], v[176:179], v[184:187], v[112:127]
	v_mfma_f32_32x32x16_bf16 v[48:63], v[180:183], v[184:187], v[48:63]
	s_waitcnt lgkmcnt(0)
	v_mfma_f32_32x32x16_bf16 v[96:111], v[176:179], v[188:191], v[96:111]
	v_mfma_f32_32x32x16_bf16 v[32:47], v[180:183], v[188:191], v[32:47]
	s_setprio 0
	s_nop 7
	s_nop 7
	s_lshl_b32 s1, s38, 1
	s_and_b32 s1, s1, 0xffffff00
	v_lshrrev_b32_e32 v128, 1, v192
	s_add_i32 s1, s1, 0
	v_and_b32_e32 v128, 16, v128
	v_add_u32_e32 v128, s1, v128
	v_add_u32_e32 v163, 0x12000, v128
	s_barrier
	ds_read_b128 v[140:143], v163
	ds_read_b128 v[136:139], v163 offset:32
	ds_read_b128 v[132:135], v163 offset:64
	ds_read_b128 v[128:131], v163 offset:96
	v_mov_b32_e32 v208, v197
	s_waitcnt lgkmcnt(3)
	v_mul_f32_e32 v112, v112, v140
	v_mul_f32_e32 v112, 0xbfb8aa3b, v112
	v_exp_f32_e32 v112, v112
	s_nop 0
	v_add_f32_e32 v112, 1.0, v112
	v_rcp_f32_e32 v112, v112
	s_nop 0
	v_mul_f32_e32 v159, v80, v112
	v_mul_f32_e32 v80, v113, v141
	v_mul_f32_e32 v80, 0xbfb8aa3b, v80
	v_exp_f32_e32 v80, v80
	s_nop 0
	v_add_f32_e32 v80, 1.0, v80
	v_rcp_f32_e32 v80, v80
	s_nop 0
	v_mul_f32_e32 v161, v81, v80
	v_mul_f32_e32 v80, v114, v142
	v_mul_f32_e32 v80, 0xbfb8aa3b, v80
	v_exp_f32_e32 v80, v80
	s_nop 0
	v_add_f32_e32 v80, 1.0, v80
	v_rcp_f32_e32 v80, v80
	s_nop 0
	v_mul_f32_e32 v162, v82, v80
	v_mul_f32_e32 v80, v115, v143
	v_mul_f32_e32 v80, 0xbfb8aa3b, v80
	v_exp_f32_e32 v80, v80
	s_nop 0
	v_add_f32_e32 v80, 1.0, v80
	v_rcp_f32_e32 v80, v80
	s_nop 0
	v_mul_f32_e32 v160, v83, v80
	s_waitcnt lgkmcnt(2)
	v_mul_f32_e32 v80, v116, v136
	v_mul_f32_e32 v80, 0xbfb8aa3b, v80
	v_exp_f32_e32 v80, v80
	s_nop 0
	v_add_f32_e32 v80, 1.0, v80
	v_rcp_f32_e32 v80, v80
	s_nop 0
	v_mul_f32_e32 v158, v84, v80
	v_mul_f32_e32 v80, v117, v137
	v_mul_f32_e32 v80, 0xbfb8aa3b, v80
	v_exp_f32_e32 v80, v80
	s_nop 0
	v_add_f32_e32 v80, 1.0, v80
	v_rcp_f32_e32 v80, v80
	s_nop 0
	v_mul_f32_e32 v157, v85, v80
	v_mul_f32_e32 v80, v118, v138
	v_mul_f32_e32 v80, 0xbfb8aa3b, v80
	v_exp_f32_e32 v80, v80
	s_nop 0
	v_add_f32_e32 v80, 1.0, v80
	v_rcp_f32_e32 v80, v80
	s_nop 0
	v_mul_f32_e32 v156, v86, v80
	v_mul_f32_e32 v80, v119, v139
	v_mul_f32_e32 v80, 0xbfb8aa3b, v80
	v_exp_f32_e32 v80, v80
	s_nop 0
	v_add_f32_e32 v80, 1.0, v80
	v_rcp_f32_e32 v80, v80
	s_nop 0
	v_mul_f32_e32 v155, v87, v80
	s_waitcnt lgkmcnt(1)
	v_mul_f32_e32 v80, v120, v132
	v_mul_f32_e32 v80, 0xbfb8aa3b, v80
	v_exp_f32_e32 v80, v80
	s_nop 0
	v_add_f32_e32 v80, 1.0, v80
	v_rcp_f32_e32 v80, v80
	s_nop 0
	v_mul_f32_e32 v154, v88, v80
	v_mul_f32_e32 v80, v121, v133
	v_mul_f32_e32 v80, 0xbfb8aa3b, v80
	v_exp_f32_e32 v80, v80
	s_nop 0
	v_add_f32_e32 v80, 1.0, v80
	v_rcp_f32_e32 v80, v80
	s_nop 0
	v_mul_f32_e32 v153, v89, v80
	v_mul_f32_e32 v80, v122, v134
	v_mul_f32_e32 v80, 0xbfb8aa3b, v80
	v_exp_f32_e32 v80, v80
	s_nop 0
	v_add_f32_e32 v80, 1.0, v80
	v_rcp_f32_e32 v80, v80
	s_nop 0
	v_mul_f32_e32 v152, v90, v80
	v_mul_f32_e32 v80, v123, v135
	v_mul_f32_e32 v80, 0xbfb8aa3b, v80
	v_exp_f32_e32 v80, v80
	s_nop 0
	v_add_f32_e32 v80, 1.0, v80
	v_rcp_f32_e32 v80, v80
	s_nop 0
	v_mul_f32_e32 v151, v91, v80
	s_waitcnt lgkmcnt(0)
	v_mul_f32_e32 v80, v124, v128
	v_mul_f32_e32 v80, 0xbfb8aa3b, v80
	v_exp_f32_e32 v80, v80
	s_nop 0
	v_add_f32_e32 v80, 1.0, v80
	v_rcp_f32_e32 v80, v80
	s_nop 0
	v_mul_f32_e32 v150, v92, v80
	v_mul_f32_e32 v80, v125, v129
	v_mul_f32_e32 v80, 0xbfb8aa3b, v80
	v_exp_f32_e32 v80, v80
	s_nop 0
	v_add_f32_e32 v80, 1.0, v80
	v_rcp_f32_e32 v80, v80
	s_nop 0
	v_mul_f32_e32 v149, v93, v80
	v_mul_f32_e32 v80, v126, v130
	v_mul_f32_e32 v80, 0xbfb8aa3b, v80
	v_exp_f32_e32 v80, v80
	s_nop 0
	v_add_f32_e32 v80, 1.0, v80
	v_rcp_f32_e32 v80, v80
	s_nop 0
	v_mul_f32_e32 v148, v94, v80
	v_mul_f32_e32 v80, v127, v131
	v_mul_f32_e32 v80, 0xbfb8aa3b, v80
	v_exp_f32_e32 v80, v80
	s_nop 0
	v_add_f32_e32 v80, 1.0, v80
	v_rcp_f32_e32 v80, v80
	s_nop 0
	v_mul_f32_e32 v147, v95, v80
	v_mul_f32_e32 v80, v96, v140
	v_mul_f32_e32 v80, 0xbfb8aa3b, v80
	v_exp_f32_e32 v80, v80
	s_nop 0
	v_add_f32_e32 v80, 1.0, v80
	v_rcp_f32_e32 v80, v80
	s_nop 0
	v_mul_f32_e32 v144, v64, v80
	v_mul_f32_e32 v64, v97, v141
	v_mul_f32_e32 v64, 0xbfb8aa3b, v64
	v_exp_f32_e32 v64, v64
	s_nop 0
	v_add_f32_e32 v64, 1.0, v64
	v_rcp_f32_e32 v64, v64
	s_nop 0
	v_mul_f32_e32 v146, v65, v64
	v_mul_f32_e32 v64, v98, v142
	v_mul_f32_e32 v64, 0xbfb8aa3b, v64
	v_exp_f32_e32 v64, v64
	v_mul_f32_e32 v169, v146, v146
	v_fmac_f32_e32 v169, v161, v161
	v_add_f32_e32 v64, 1.0, v64
	v_rcp_f32_e32 v64, v64
	s_nop 0
	v_mul_f32_e32 v145, v66, v64
	v_mul_f32_e32 v64, v99, v143
	v_mul_f32_e32 v64, 0xbfb8aa3b, v64
	v_exp_f32_e32 v64, v64
	s_nop 0
	v_add_f32_e32 v64, 1.0, v64
	v_rcp_f32_e32 v64, v64
	s_nop 0
	v_mul_f32_e32 v143, v67, v64
	v_mul_f32_e32 v64, v100, v136
	v_mul_f32_e32 v64, 0xbfb8aa3b, v64
	v_exp_f32_e32 v64, v64
	s_nop 0
	v_add_f32_e32 v64, 1.0, v64
	v_rcp_f32_e32 v64, v64
	s_nop 0
	v_mul_f32_e32 v142, v68, v64
	v_mul_f32_e32 v64, v101, v137
	v_mul_f32_e32 v64, 0xbfb8aa3b, v64
	v_exp_f32_e32 v64, v64
	v_mul_f32_e32 v177, v142, v142
	v_fmac_f32_e32 v177, v158, v158
	v_add_f32_e32 v64, 1.0, v64
	v_rcp_f32_e32 v64, v64
	s_nop 0
	v_mul_f32_e32 v141, v69, v64
	v_mul_f32_e32 v64, v102, v138
	v_mul_f32_e32 v64, 0xbfb8aa3b, v64
	v_exp_f32_e32 v64, v64
	v_mul_f32_e32 v179, v141, v141
	v_fmac_f32_e32 v179, v157, v157
	v_add_f32_e32 v64, 1.0, v64
	v_rcp_f32_e32 v64, v64
	s_nop 0
	v_mul_f32_e32 v140, v70, v64
	v_mul_f32_e32 v64, v103, v139
	v_mul_f32_e32 v64, 0xbfb8aa3b, v64
	v_exp_f32_e32 v64, v64
	v_mul_f32_e32 v180, v140, v140
	v_fmac_f32_e32 v180, v156, v156
	v_add_f32_e32 v64, 1.0, v64
	v_rcp_f32_e32 v64, v64
	s_nop 0
	v_mul_f32_e32 v138, v71, v64
	v_mul_f32_e32 v64, v104, v132
	v_mul_f32_e32 v64, 0xbfb8aa3b, v64
	v_exp_f32_e32 v64, v64
	v_mul_f32_e32 v182, v138, v138
	v_fmac_f32_e32 v182, v155, v155
	v_add_f32_e32 v64, 1.0, v64
	v_rcp_f32_e32 v64, v64
	s_nop 0
	v_mul_f32_e32 v137, v72, v64
	v_mul_f32_e32 v64, v105, v133
	v_mul_f32_e32 v64, 0xbfb8aa3b, v64
	v_exp_f32_e32 v64, v64
	v_mul_f32_e32 v184, v137, v137
	v_fmac_f32_e32 v184, v154, v154
	v_add_f32_e32 v64, 1.0, v64
	v_rcp_f32_e32 v64, v64
	s_nop 0
	v_mul_f32_e32 v136, v73, v64
	v_mul_f32_e32 v64, v106, v134
	v_mul_f32_e32 v64, 0xbfb8aa3b, v64
	v_exp_f32_e32 v64, v64
	s_nop 0
	v_add_f32_e32 v64, 1.0, v64
	v_rcp_f32_e32 v64, v64
	s_nop 0
	v_mul_f32_e32 v134, v74, v64
	v_mul_f32_e32 v64, v107, v135
	v_mul_f32_e32 v64, 0xbfb8aa3b, v64
	v_exp_f32_e32 v64, v64
	s_nop 0
	v_add_f32_e32 v64, 1.0, v64
	v_rcp_f32_e32 v64, v64
	s_nop 0
	v_mul_f32_e32 v133, v75, v64
	v_mul_f32_e32 v64, v108, v128
	v_mul_f32_e32 v64, 0xbfb8aa3b, v64
	v_exp_f32_e32 v64, v64
	v_mul_f32_e32 v189, v133, v133
	v_fmac_f32_e32 v189, v151, v151
	v_add_f32_e32 v64, 1.0, v64
	v_rcp_f32_e32 v64, v64
	s_nop 0
	v_mul_f32_e32 v132, v76, v64
	v_mul_f32_e32 v64, v109, v129
	v_mul_f32_e32 v64, 0xbfb8aa3b, v64
	v_exp_f32_e32 v64, v64
	v_mul_f32_e32 v196, v132, v132
	v_fmac_f32_e32 v196, v150, v150
	v_add_f32_e32 v64, 1.0, v64
	v_rcp_f32_e32 v64, v64
	s_nop 0
	v_mul_f32_e32 v128, v77, v64
	v_mul_f32_e32 v64, v110, v130
	v_mul_f32_e32 v64, 0xbfb8aa3b, v64
	v_exp_f32_e32 v64, v64
	s_nop 0
	v_add_f32_e32 v64, 1.0, v64
	v_rcp_f32_e32 v64, v64
	s_nop 0
	v_mul_f32_e32 v125, v78, v64
	v_mul_f32_e32 v64, v111, v131
	v_mul_f32_e32 v64, 0xbfb8aa3b, v64
	v_exp_f32_e32 v64, v64
	v_mul_f32_e32 v209, v125, v125
	v_fmac_f32_e32 v209, v148, v148
	v_add_f32_e32 v64, 1.0, v64
	v_rcp_f32_e32 v64, v64
	s_nop 0
	v_mul_f32_e32 v127, v79, v64
	ds_read_b128 v[76:79], v163 offset:128
	ds_read_b128 v[72:75], v163 offset:160
	ds_read_b128 v[68:71], v163 offset:192
	ds_read_b128 v[64:67], v163 offset:224
	s_nop 0
	v_readfirstlane_b32 s1, v208
	s_ashr_i32 s7, s1, 7
	s_bfe_u32 s8, s1, 0x10006
	s_lshl_b32 s1, s68, 1
	v_bfe_u32 v205, v208, 5, 1
	s_and_b32 s6, s1, 14
	s_lshl_b32 s1, s7, 6
	s_add_i32 s9, s1, s0
	v_lshlrev_b32_e32 v84, 2, v205
	v_or_b32_e32 v86, s9, v84
	s_lshl_b32 s9, s93, 1
	s_add_u32 s9, s66, s9
	s_addc_u32 s37, s67, 0
	s_lshl_b32 s36, s8, 7
	v_and_b32_e32 v206, 31, v208
	s_add_u32 s36, s9, s36
	s_addc_u32 s37, s37, 0
	v_lshlrev_b32_e32 v198, 1, v206
	v_ashrrev_i32_e32 v87, 31, v86
	v_lshl_add_u64 v[90:91], s[36:37], 0, v[198:199]
	v_lshlrev_b64 v[88:89], 11, v[86:87]
	v_lshl_add_u64 v[80:81], v[90:91], 0, v[88:89]
	v_add_co_u32_e32 v82, vcc, s96, v80
	global_load_ushort v207, v[80:81], off
	global_load_ushort v204, v[80:81], off offset:2048
	v_addc_co_u32_e32 v83, vcc, 0, v81, vcc
	v_add_co_u32_e32 v92, vcc, s94, v80
	global_load_ushort v203, v[82:83], off
	global_load_ushort v202, v[82:83], off offset:2048
	v_addc_co_u32_e32 v93, vcc, 0, v81, vcc
	v_add_co_u32_e32 v94, vcc, s57, v80
	v_and_b32_e32 v85, 16, v208
	s_nop 0
	v_addc_co_u32_e32 v95, vcc, 0, v81, vcc
	v_add_co_u32_e32 v96, vcc, s35, v80
	global_load_ushort v201, v[94:95], off offset:-4096
	global_load_ushort v200, v[92:93], off offset:2048
	global_load_ushort v195, v[94:95], off
	global_load_ushort v194, v[94:95], off offset:2048
	v_addc_co_u32_e32 v97, vcc, 0, v81, vcc
	v_add_co_u32_e32 v98, vcc, s58, v80
	v_cmp_eq_u32_e64 s[42:43], 0, v85
	s_nop 0
	v_addc_co_u32_e32 v99, vcc, 0, v81, vcc
	v_add_co_u32_e32 v100, vcc, s95, v80
	global_load_ushort v193, v[98:99], off offset:-4096
	global_load_ushort v192, v[96:97], off offset:2048
	global_load_ushort v191, v[98:99], off
	global_load_ushort v190, v[98:99], off offset:2048
	v_addc_co_u32_e32 v101, vcc, 0, v81, vcc
	v_add_co_u32_e32 v102, vcc, s59, v80
	v_and_b32_e32 v85, 8, v208
	s_nop 0
	v_addc_co_u32_e32 v103, vcc, 0, v81, vcc
	global_load_ushort v188, v[102:103], off offset:-4096
	global_load_ushort v185, v[100:101], off offset:2048
	global_load_ushort v183, v[102:103], off
	global_load_ushort v181, v[102:103], off offset:2048
	global_load_ushort v178, v[80:81], off offset:64
	global_load_ushort v176, v[80:81], off offset:2112
	global_load_ushort v174, v[82:83], off offset:64
	global_load_ushort v175, v[82:83], off offset:2112
	global_load_ushort v171, v[92:93], off offset:64
	global_load_ushort v170, v[92:93], off offset:2112
	global_load_ushort v168, v[94:95], off offset:64
	global_load_ushort v167, v[94:95], off offset:2112
	global_load_ushort v166, v[96:97], off offset:64
	global_load_ushort v165, v[96:97], off offset:2112
	global_load_ushort v164, v[98:99], off offset:64
	global_load_ushort v163, v[98:99], off offset:2112
	global_load_ushort v139, v[100:101], off offset:64
	global_load_ushort v135, v[100:101], off offset:2112
	global_load_ushort v131, v[102:103], off offset:64
	global_load_ushort v130, v[102:103], off offset:2112
	v_or_b32_e32 v80, 32, v86
	v_ashrrev_i32_e32 v81, 31, v80
	v_lshlrev_b64 v[82:83], 11, v[80:81]
	v_lshl_add_u64 v[90:91], v[90:91], 0, v[82:83]
	v_add_co_u32_e32 v92, vcc, s96, v90
	global_load_ushort v129, v[90:91], off
	global_load_ushort v126, v[90:91], off offset:2048
	v_addc_co_u32_e32 v93, vcc, 0, v91, vcc
	v_add_co_u32_e32 v94, vcc, s94, v90
	global_load_ushort v124, v[92:93], off
	global_load_ushort v123, v[92:93], off offset:2048
	v_addc_co_u32_e32 v95, vcc, 0, v91, vcc
	v_add_co_u32_e32 v96, vcc, s57, v90
	v_cmp_eq_u32_e64 s[38:39], 0, v85
	s_nop 0
	v_addc_co_u32_e32 v97, vcc, 0, v91, vcc
	v_add_co_u32_e32 v98, vcc, s35, v90
	global_load_ushort v122, v[96:97], off offset:-4096
	global_load_ushort v121, v[94:95], off offset:2048
	global_load_ushort v120, v[96:97], off
	global_load_ushort v119, v[96:97], off offset:2048
	v_addc_co_u32_e32 v99, vcc, 0, v91, vcc
	v_add_co_u32_e32 v172, vcc, s58, v90
	v_xor_b32_e32 v85, 8, v219
	s_nop 0
	v_addc_co_u32_e32 v173, vcc, 0, v91, vcc
	v_add_co_u32_e32 v186, vcc, s95, v90
	global_load_ushort v118, v[172:173], off offset:-4096
	global_load_ushort v117, v[98:99], off offset:2048
	global_load_ushort v116, v[172:173], off
	global_load_ushort v115, v[172:173], off offset:2048
	v_addc_co_u32_e32 v187, vcc, 0, v91, vcc
	v_add_co_u32_e32 v210, vcc, s59, v90
	v_mul_f32_e32 v198, v128, v128
	s_nop 0
	v_addc_co_u32_e32 v211, vcc, 0, v91, vcc
	global_load_ushort v114, v[210:211], off offset:-4096
	global_load_ushort v113, v[186:187], off offset:2048
	global_load_ushort v112, v[210:211], off
	global_load_ushort v111, v[210:211], off offset:2048
	global_load_ushort v110, v[90:91], off offset:64
	global_load_ushort v108, v[90:91], off offset:2112
	global_load_ushort v109, v[92:93], off offset:64
	global_load_ushort v107, v[92:93], off offset:2112
	global_load_ushort v106, v[94:95], off offset:64
	global_load_ushort v105, v[94:95], off offset:2112
	global_load_ushort v104, v[96:97], off offset:64
	global_load_ushort v103, v[96:97], off offset:2112
	global_load_ushort v102, v[98:99], off offset:64
	global_load_ushort v101, v[98:99], off offset:2112
	global_load_ushort v100, v[172:173], off offset:64
	s_nop 0
	global_load_ushort v99, v[172:173], off offset:2112
	global_load_ushort v98, v[186:187], off offset:64
	global_load_ushort v97, v[186:187], off offset:2112
	global_load_ushort v95, v[210:211], off offset:64
	global_load_ushort v96, v[210:211], off offset:2112
	v_and_b32_e32 v92, 64, v219
	v_xor_b32_e32 v91, 16, v219
	v_add_u32_e32 v92, 64, v92
	v_cmp_lt_i32_e32 vcc, v91, v92
	v_and_b32_e32 v90, 4, v208
	v_cmp_eq_u32_e64 s[36:37], 0, v90
	v_cndmask_b32_e32 v91, v219, v91, vcc
	v_cmp_lt_i32_e32 vcc, v85, v92
	v_lshlrev_b32_e32 v94, 2, v91
	v_mul_f32_e32 v186, v136, v136
	v_cndmask_b32_e32 v85, v219, v85, vcc
	v_lshlrev_b32_e32 v93, 2, v85
	v_xor_b32_e32 v85, 4, v219
	v_cmp_lt_i32_e32 vcc, v85, v92
	v_fmac_f32_e32 v186, v153, v153
	v_mul_f32_e32 v172, v145, v145
	v_cndmask_b32_e32 v85, v219, v85, vcc
	v_lshlrev_b32_e32 v90, 2, v85
	v_and_b32_e32 v85, 2, v208
	v_cmp_eq_u32_e64 s[40:41], 0, v85
	v_xor_b32_e32 v85, 2, v219
	v_cmp_lt_i32_e32 vcc, v85, v92
	v_mul_f32_e32 v187, v134, v134
	v_fmac_f32_e32 v172, v162, v162
	v_cndmask_b32_e32 v85, v219, v85, vcc
	v_lshlrev_b32_e32 v91, 2, v85
	v_xor_b32_e32 v85, 1, v219
	v_cmp_lt_i32_e32 vcc, v85, v92
	v_fmac_f32_e32 v187, v152, v152
	v_mul_f32_e32 v173, v143, v143
	v_cndmask_b32_e32 v85, v219, v85, vcc
	v_lshlrev_b32_e32 v92, 2, v85
	v_and_b32_e32 v85, 1, v208
	v_cmp_eq_u32_e64 s[44:45], 0, v85
	v_bfe_u32 v85, v208, 1, 2
	v_and_or_b32 v85, v208, 24, v85
	v_or3_b32 v84, v85, s0, v84
	v_mul_f32_e32 v85, v144, v144
	v_fmac_f32_e32 v85, v159, v159
	v_cndmask_b32_e64 v211, v184, v85, s[42:43]
	v_cndmask_b32_e64 v85, v85, v184, s[42:43]
	v_cndmask_b32_e64 v184, v186, v169, s[42:43]
	v_cndmask_b32_e64 v169, v169, v186, s[42:43]
	ds_bpermute_b32 v169, v94, v169
	v_fmac_f32_e32 v173, v160, v160
	v_fmac_f32_e32 v198, v149, v149
	v_mul_f32_e32 v210, v127, v127
	v_fmac_f32_e32 v210, v147, v147
	s_waitcnt lgkmcnt(0)
	v_add_f32_e32 v169, v184, v169
	v_cndmask_b32_e64 v184, v187, v172, s[42:43]
	v_cndmask_b32_e64 v172, v172, v187, s[42:43]
	ds_bpermute_b32 v172, v94, v172
	ds_bpermute_b32 v85, v94, v85
	s_or_b32 s6, s8, s6
	v_add_u32_e32 v84, s1, v84
	s_lshl_b32 s1, s6, 3
	s_waitcnt lgkmcnt(1)
	v_add_f32_e32 v172, v184, v172
	v_cndmask_b32_e64 v184, v189, v173, s[42:43]
	v_cndmask_b32_e64 v173, v173, v189, s[42:43]
	ds_bpermute_b32 v173, v94, v173
	s_waitcnt lgkmcnt(1)
	v_add_f32_e32 v85, v211, v85
	s_add_u32 s46, s30, s1
	s_addc_u32 s47, s31, 0
	s_waitcnt lgkmcnt(0)
	v_add_f32_e32 v173, v184, v173
	v_cndmask_b32_e64 v184, v196, v177, s[42:43]
	v_cndmask_b32_e64 v177, v177, v196, s[42:43]
	ds_bpermute_b32 v177, v94, v177
	s_waitcnt lgkmcnt(0)
	v_add_f32_e32 v177, v184, v177
	v_cndmask_b32_e64 v184, v198, v179, s[42:43]
	v_cndmask_b32_e64 v179, v179, v198, s[42:43]
	ds_bpermute_b32 v179, v94, v179
	s_waitcnt lgkmcnt(0)
	v_add_f32_e32 v179, v184, v179
	v_cndmask_b32_e64 v184, v209, v180, s[42:43]
	v_cndmask_b32_e64 v180, v180, v209, s[42:43]
	ds_bpermute_b32 v180, v94, v180
	s_waitcnt lgkmcnt(0)
	v_add_f32_e32 v180, v184, v180
	v_cndmask_b32_e64 v184, v210, v182, s[42:43]
	v_cndmask_b32_e64 v182, v182, v210, s[42:43]
	ds_bpermute_b32 v182, v94, v182
	s_waitcnt lgkmcnt(0)
	v_add_f32_e32 v182, v184, v182
	v_cndmask_b32_e64 v184, v177, v85, s[38:39]
	v_cndmask_b32_e64 v85, v85, v177, s[38:39]
	v_cndmask_b32_e64 v177, v179, v169, s[38:39]
	v_cndmask_b32_e64 v169, v169, v179, s[38:39]
	ds_bpermute_b32 v169, v93, v169
	ds_bpermute_b32 v85, v93, v85
	s_waitcnt lgkmcnt(1)
	v_add_f32_e32 v169, v177, v169
	v_cndmask_b32_e64 v177, v180, v172, s[38:39]
	v_cndmask_b32_e64 v172, v172, v180, s[38:39]
	ds_bpermute_b32 v172, v93, v172
	s_waitcnt lgkmcnt(1)
	v_add_f32_e32 v85, v184, v85
	s_waitcnt lgkmcnt(0)
	v_add_f32_e32 v172, v177, v172
	v_cndmask_b32_e64 v177, v182, v173, s[38:39]
	v_cndmask_b32_e64 v173, v173, v182, s[38:39]
	ds_bpermute_b32 v173, v93, v173
	s_waitcnt lgkmcnt(0)
	v_add_f32_e32 v173, v177, v173
	v_cndmask_b32_e64 v177, v172, v85, s[36:37]
	v_cndmask_b32_e64 v85, v85, v172, s[36:37]
	v_cndmask_b32_e64 v172, v173, v169, s[36:37]
	v_cndmask_b32_e64 v169, v169, v173, s[36:37]
	ds_bpermute_b32 v85, v90, v85
	ds_bpermute_b32 v169, v90, v169
	s_waitcnt lgkmcnt(1)
	v_add_f32_e32 v85, v177, v85
	s_waitcnt lgkmcnt(0)
	v_add_f32_e32 v169, v172, v169
	v_cndmask_b32_e64 v172, v169, v85, s[40:41]
	v_cndmask_b32_e64 v85, v85, v169, s[40:41]
	ds_bpermute_b32 v85, v91, v85
	s_waitcnt lgkmcnt(0)
	v_add_f32_e32 v169, v172, v85
	ds_bpermute_b32 v172, v92, v169
	v_ashrrev_i32_e32 v85, 31, v84
	s_and_saveexec_b64 s[48:49], s[44:45]
	s_cbranch_execz .LBB0_632
	v_lshlrev_b64 v[186:187], 7, v[84:85]
	s_waitcnt lgkmcnt(0)
	v_add_f32_e32 v172, v169, v172
	v_lshl_add_u64 v[186:187], s[46:47], 0, v[186:187]
	v_mov_b32_e32 v173, s92
	global_store_dwordx2 v[186:187], v[172:173], off sc1

	.amdhsa_kernel _Z4mega6Params
		.amdhsa_group_segment_fixed_size 0
		.amdhsa_private_segment_fixed_size 0
		.amdhsa_kernarg_size 440
		.amdhsa_user_sgpr_count 2
		.amdhsa_user_sgpr_dispatch_ptr 0
		.amdhsa_user_sgpr_queue_ptr 0
		.amdhsa_user_sgpr_kernarg_segment_ptr 1
		.amdhsa_user_sgpr_dispatch_id 0
		.amdhsa_user_sgpr_kernarg_preload_length 0
		.amdhsa_user_sgpr_kernarg_preload_offset 0
		.amdhsa_user_sgpr_private_segment_size 0
		.amdhsa_uses_dynamic_stack 0
		.amdhsa_enable_private_segment 0
		.amdhsa_system_sgpr_workgroup_id_x 1
		.amdhsa_system_sgpr_workgroup_id_y 0
		.amdhsa_system_sgpr_workgroup_id_z 0
		.amdhsa_system_sgpr_workgroup_info 0
		.amdhsa_system_vgpr_workitem_id 2
		.amdhsa_next_free_vgpr 256
		.amdhsa_next_free_sgpr 102
		.amdhsa_accum_offset 256
		.amdhsa_reserve_vcc 1
		.amdhsa_float_round_mode_32 0
		.amdhsa_float_round_mode_16_64 0
		.amdhsa_float_denorm_mode_32 3
		.amdhsa_float_denorm_mode_16_64 3
		.amdhsa_dx10_clamp 1
		.amdhsa_ieee_mode 1
		.amdhsa_fp16_overflow 0
		.amdhsa_tg_split 0
		.amdhsa_exception_fp_ieee_invalid_op 0
		.amdhsa_exception_fp_denorm_src 0
		.amdhsa_exception_fp_ieee_div_zero 0
		.amdhsa_exception_fp_ieee_overflow 0
		.amdhsa_exception_fp_ieee_underflow 0
		.amdhsa_exception_fp_ieee_inexact 0
		.amdhsa_exception_int_div_zero 0
	.end_amdhsa_kernel

amdhsa.kernels:
  - .agpr_count:     0
    .args:
      - .offset:         0
        .size:           184
        .value_kind:     by_value
      - .offset:         184
        .size:           4
        .value_kind:     hidden_block_count_x
      - .offset:         188
        .size:           4
        .value_kind:     hidden_block_count_y
      - .offset:         192
        .size:           4
        .value_kind:     hidden_block_count_z
      - .offset:         196
        .size:           2
        .value_kind:     hidden_group_size_x
      - .offset:         198
        .size:           2
        .value_kind:     hidden_group_size_y
      - .offset:         200
        .size:           2
        .value_kind:     hidden_group_size_z
      - .offset:         202
        .size:           2
        .value_kind:     hidden_remainder_x
      - .offset:         204
        .size:           2
        .value_kind:     hidden_remainder_y
      - .offset:         206
        .size:           2
        .value_kind:     hidden_remainder_z
      - .offset:         224
        .size:           8
        .value_kind:     hidden_global_offset_x
      - .offset:         232
        .size:           8
        .value_kind:     hidden_global_offset_y
      - .offset:         240
        .size:           8
        .value_kind:     hidden_global_offset_z
      - .offset:         248
        .size:           2
        .value_kind:     hidden_grid_dims
      - .offset:         272
        .size:           8
        .value_kind:     hidden_multigrid_sync_arg
      - .offset:         304
        .size:           4
        .value_kind:     hidden_dynamic_lds_size
    .group_segment_fixed_size: 0
    .kernarg_segment_align: 8
    .kernarg_segment_size: 440
    .language:       OpenCL C
    .language_version:
      - 2
      - 0
    .max_flat_workgroup_size: 256
    .name:           _Z4mega6Params
    .private_segment_fixed_size: 0
    .sgpr_count:     108
    .sgpr_spill_count: 275
    .symbol:         _Z4mega6Params.kd
    .uniform_work_group_size: 1
    .uses_dynamic_stack: false
    .vgpr_count:     256
    .vgpr_spill_count: 0
    .wavefront_size: 64
